# v108 with per-segment s_setprio toggles replaced by one static priority raise for blocks >= 256 (the co-resident second block)
# baseline (speedup 1.0000x reference)
.LBB0_2:
	s_or_b64 exec, exec, s[4:5]
	s_load_dwordx2 s[16:17], s[0:1], 0x148
	s_load_dwordx4 s[12:15], s[0:1], 0x138
	s_waitcnt lgkmcnt(0)
	s_barrier
	s_bitcmp1_b32 s2, 8
	s_cbranch_scc0 .Lstatic_prio_done
	s_setprio 1
.Lstatic_prio_done:
	s_cmp_lt_i32 s16, 1
	s_cselect_b64 s[18:19], -1, 0
	s_cmp_gt_i32 s17, 0
	s_cselect_b64 s[0:1], -1, 0
	s_and_b64 s[0:1], s[18:19], s[0:1]
	s_andn2_b64 vcc, exec, s[0:1]
	s_cbranch_vccnz .LBB0_189
	v_lshlrev_b32_e32 v22, 2, v199
	v_add_u32_e32 v1, 0, v22
	s_mov_b64 s[0:1], 0
	s_movk_i32 s3, 0x3ff
	s_add_i32 s8, 0, 0x12048
	s_movk_i32 s9, 0xc00
	s_add_i32 s10, 0, 0x12050
	v_mov_b32_e32 v3, 0
	s_movk_i32 s11, 0xaff
	v_mov_b32_e32 v6, v199
	s_branch .LBB0_5

.Lgk_loop_p2:
	s_waitcnt vmcnt(8)
	s_barrier
	ds_read_b128 v[64:67], v213
	ds_read_b128 v[76:79], v221 offset:16384
	ds_read_b128 v[80:83], v221 offset:20480
	ds_read_b128 v[84:87], v221 offset:24576
	ds_read_b128 v[88:91], v221 offset:28672
	ds_read_b128 v[92:95], v226
	ds_read_b128 v[96:99], v227 offset:16384
	ds_read_b128 v[100:103], v227 offset:20480
	ds_read_b128 v[104:107], v227 offset:24576
	ds_read_b128 v[108:111], v227 offset:28672
	ds_read_b128 v[112:115], v229
	ds_read_b128 v[222:225], v255 offset:16384
	ds_read_b128 v[230:233], v255 offset:20480
	ds_read_b128 v[234:237], v255 offset:24576
	ds_read_b128 v[238:241], v255 offset:28672
	ds_read_b128 v[242:245], v162
	ds_read_b128 v[246:249], v163 offset:16384
	ds_read_b128 v[250:253], v163 offset:20480
	ds_read_b128 v[194:197], v163 offset:24576
	ds_read_b128 v[202:205], v163 offset:28672
	s_waitcnt lgkmcnt(0)
	s_barrier
	s_mov_b32 m0, s54
	v_mfma_f32_32x32x16_bf16 v[48:63], v[64:67], v[76:79], v[48:63]
	v_mfma_f32_32x32x16_bf16 v[32:47], v[64:67], v[80:83], v[32:47]
	global_load_lds_dwordx4 v254, s[38:39]
	s_add_u32 m0, m0, 0x1000
	v_mfma_f32_32x32x16_bf16 v[16:31], v[64:67], v[84:87], v[16:31]
	v_mfma_f32_32x32x16_bf16 v[0:15], v[64:67], v[88:91], v[0:15]
	global_load_lds_dwordx4 v254, s[40:41]
	s_add_u32 m0, m0, 0x1000
	v_mfma_f32_32x32x16_bf16 v[48:63], v[92:95], v[96:99], v[48:63]
	v_mfma_f32_32x32x16_bf16 v[32:47], v[92:95], v[100:103], v[32:47]
	global_load_lds_dwordx4 v254, s[42:43]
	s_add_u32 m0, m0, 0x1000
	v_mfma_f32_32x32x16_bf16 v[16:31], v[92:95], v[104:107], v[16:31]
	v_mfma_f32_32x32x16_bf16 v[0:15], v[92:95], v[108:111], v[0:15]
	global_load_lds_dwordx4 v254, s[44:45]
	s_add_u32 m0, m0, 0x1000
	v_mfma_f32_32x32x16_bf16 v[48:63], v[112:115], v[222:225], v[48:63]
	v_mfma_f32_32x32x16_bf16 v[32:47], v[112:115], v[230:233], v[32:47]
	global_load_lds_dwordx4 v254, s[46:47]
	s_add_u32 m0, m0, 0x1000
	v_mfma_f32_32x32x16_bf16 v[16:31], v[112:115], v[234:237], v[16:31]
	v_mfma_f32_32x32x16_bf16 v[0:15], v[112:115], v[238:241], v[0:15]
	global_load_lds_dwordx4 v254, s[48:49]
	s_add_u32 m0, m0, 0x1000
	v_mfma_f32_32x32x16_bf16 v[48:63], v[242:245], v[246:249], v[48:63]
	v_mfma_f32_32x32x16_bf16 v[32:47], v[242:245], v[250:253], v[32:47]
	global_load_lds_dwordx4 v254, s[50:51]
	s_add_u32 m0, m0, 0x1000
	v_mfma_f32_32x32x16_bf16 v[16:31], v[242:245], v[194:197], v[16:31]
	v_mfma_f32_32x32x16_bf16 v[0:15], v[242:245], v[202:205], v[0:15]
	global_load_lds_dwordx4 v254, s[52:53]
	v_add_u32_e32 v254, 0x80, v254
	s_waitcnt vmcnt(8)
	s_barrier
	ds_read_b128 v[64:67], v213 offset:32768
	ds_read_b128 v[76:79], v221 offset:49152
	ds_read_b128 v[80:83], v221 offset:53248
	ds_read_b128 v[84:87], v221 offset:57344
	ds_read_b128 v[88:91], v221 offset:61440
	ds_read_b128 v[92:95], v226 offset:32768
	ds_read_b128 v[96:99], v227 offset:49152
	ds_read_b128 v[100:103], v227 offset:53248
	ds_read_b128 v[104:107], v227 offset:57344
	ds_read_b128 v[108:111], v227 offset:61440
	ds_read_b128 v[112:115], v229 offset:32768
	ds_read_b128 v[222:225], v255 offset:49152
	ds_read_b128 v[230:233], v255 offset:53248
	ds_read_b128 v[234:237], v255 offset:57344
	ds_read_b128 v[238:241], v255 offset:61440
	ds_read_b128 v[242:245], v162 offset:32768
	ds_read_b128 v[246:249], v163 offset:49152
	ds_read_b128 v[250:253], v163 offset:53248
	ds_read_b128 v[194:197], v163 offset:57344
	ds_read_b128 v[202:205], v163 offset:61440
	s_waitcnt lgkmcnt(0)
	s_barrier
	s_add_u32 m0, s54, 0x8000
	v_mfma_f32_32x32x16_bf16 v[48:63], v[64:67], v[76:79], v[48:63]
	v_mfma_f32_32x32x16_bf16 v[32:47], v[64:67], v[80:83], v[32:47]
	global_load_lds_dwordx4 v254, s[38:39]
	s_add_u32 m0, m0, 0x1000
	v_mfma_f32_32x32x16_bf16 v[16:31], v[64:67], v[84:87], v[16:31]
	v_mfma_f32_32x32x16_bf16 v[0:15], v[64:67], v[88:91], v[0:15]
	global_load_lds_dwordx4 v254, s[40:41]
	s_add_u32 m0, m0, 0x1000
	v_mfma_f32_32x32x16_bf16 v[48:63], v[92:95], v[96:99], v[48:63]
	v_mfma_f32_32x32x16_bf16 v[32:47], v[92:95], v[100:103], v[32:47]
	global_load_lds_dwordx4 v254, s[42:43]
	s_add_u32 m0, m0, 0x1000
	v_mfma_f32_32x32x16_bf16 v[16:31], v[92:95], v[104:107], v[16:31]
	v_mfma_f32_32x32x16_bf16 v[0:15], v[92:95], v[108:111], v[0:15]
	global_load_lds_dwordx4 v254, s[44:45]
	s_add_u32 m0, m0, 0x1000
	v_mfma_f32_32x32x16_bf16 v[48:63], v[112:115], v[222:225], v[48:63]
	v_mfma_f32_32x32x16_bf16 v[32:47], v[112:115], v[230:233], v[32:47]
	global_load_lds_dwordx4 v254, s[46:47]
	s_add_u32 m0, m0, 0x1000
	v_mfma_f32_32x32x16_bf16 v[16:31], v[112:115], v[234:237], v[16:31]
	v_mfma_f32_32x32x16_bf16 v[0:15], v[112:115], v[238:241], v[0:15]
	global_load_lds_dwordx4 v254, s[48:49]
	s_add_u32 m0, m0, 0x1000
	v_mfma_f32_32x32x16_bf16 v[48:63], v[242:245], v[246:249], v[48:63]
	v_mfma_f32_32x32x16_bf16 v[32:47], v[242:245], v[250:253], v[32:47]
	global_load_lds_dwordx4 v254, s[50:51]
	s_add_u32 m0, m0, 0x1000
	v_mfma_f32_32x32x16_bf16 v[16:31], v[242:245], v[194:197], v[16:31]
	v_mfma_f32_32x32x16_bf16 v[0:15], v[242:245], v[202:205], v[0:15]
	global_load_lds_dwordx4 v254, s[52:53]
	v_add_u32_e32 v254, 0x80, v254
	s_sub_u32 s55, s55, 1
	s_cmp_lg_u32 s55, 0
	s_cbranch_scc1 .Lgk_loop_p2
	s_add_u32 s58, s3, s33
	s_cmp_gt_u32 s58, 0x2ff
	s_cbranch_scc1 .Lgk_tailplain_p2
.LBB0_258_pf_p2:
	s_mul_hi_i32 s60, s58, 0x2aaaaaab
	s_lshr_b32 s61, s60, 31
	s_ashr_i32 s60, s60, 3
	s_add_i32 s60, s60, s61
	s_mul_i32 s67, s60, 0xffffffd0
	s_add_i32 s67, s67, s58
	s_lshl_b32 s61, s60, 3
	s_ashr_i32 s60, s67, 31
	s_lshr_b32 s60, s60, 29
	s_add_i32 s60, s67, s60
	s_ashr_i32 s64, s60, 3
	s_and_b32 s60, s60, -8
	s_sub_i32 s59, s67, s60
	s_add_i32 s59, s59, s61
	s_lshl_b32 s62, s59, 7
	s_ashr_i32 s63, s62, 31
	s_lshl_b32 s65, s64, 7
	s_lshl_b64 s[60:61], s[62:63], 11
	s_ashr_i32 s66, s65, 31
	s_lshl_b32 s56, s62, 11
	s_add_u32 s38, s14, s56
	s_addc_u32 s39, s15, 0
	s_add_u32 s38, s38, 0x679f000
	s_addc_u32 s39, s39, 0
	s_add_u32 s40, s38, 0x10000
	s_addc_u32 s41, s39, 0
	s_add_u32 s42, s40, 0x10000
	s_addc_u32 s43, s41, 0
	s_add_u32 s44, s42, 0x10000
	s_addc_u32 s45, s43, 0
	s_lshl_b32 s56, s65, 11
	s_add_u32 s46, s14, s56
	s_addc_u32 s47, s15, 0
	s_add_u32 s46, s46, 0x0
	s_addc_u32 s47, s47, 0
	s_add_u32 s48, s46, 0x10000
	s_addc_u32 s49, s47, 0
	s_add_u32 s50, s48, 0x10000
	s_addc_u32 s51, s49, 0
	s_add_u32 s52, s50, 0x10000
	s_addc_u32 s53, s51, 0
	v_mov_b32_e32 v254, v158
	s_mov_b32 s57, 1
	s_waitcnt vmcnt(8)
	s_barrier
	ds_read_b128 v[64:67], v213
	ds_read_b128 v[76:79], v221 offset:16384
	ds_read_b128 v[80:83], v221 offset:20480
	ds_read_b128 v[84:87], v221 offset:24576
	ds_read_b128 v[88:91], v221 offset:28672
	ds_read_b128 v[92:95], v226
	ds_read_b128 v[96:99], v227 offset:16384
	ds_read_b128 v[100:103], v227 offset:20480
	ds_read_b128 v[104:107], v227 offset:24576
	ds_read_b128 v[108:111], v227 offset:28672
	ds_read_b128 v[112:115], v229
	ds_read_b128 v[222:225], v255 offset:16384
	ds_read_b128 v[230:233], v255 offset:20480
	ds_read_b128 v[234:237], v255 offset:24576
	ds_read_b128 v[238:241], v255 offset:28672
	ds_read_b128 v[242:245], v162
	ds_read_b128 v[246:249], v163 offset:16384
	ds_read_b128 v[250:253], v163 offset:20480
	ds_read_b128 v[194:197], v163 offset:24576
	ds_read_b128 v[202:205], v163 offset:28672
	s_waitcnt lgkmcnt(0)
	s_barrier
	s_mov_b32 m0, s54
	v_mfma_f32_32x32x16_bf16 v[48:63], v[64:67], v[76:79], v[48:63]
	v_mfma_f32_32x32x16_bf16 v[32:47], v[64:67], v[80:83], v[32:47]
	global_load_lds_dwordx4 v254, s[38:39]
	s_add_u32 m0, m0, 0x1000
	v_mfma_f32_32x32x16_bf16 v[16:31], v[64:67], v[84:87], v[16:31]
	v_mfma_f32_32x32x16_bf16 v[0:15], v[64:67], v[88:91], v[0:15]
	global_load_lds_dwordx4 v254, s[40:41]
	s_add_u32 m0, m0, 0x1000
	v_mfma_f32_32x32x16_bf16 v[48:63], v[92:95], v[96:99], v[48:63]
	v_mfma_f32_32x32x16_bf16 v[32:47], v[92:95], v[100:103], v[32:47]
	global_load_lds_dwordx4 v254, s[42:43]
	s_add_u32 m0, m0, 0x1000
	v_mfma_f32_32x32x16_bf16 v[16:31], v[92:95], v[104:107], v[16:31]
	v_mfma_f32_32x32x16_bf16 v[0:15], v[92:95], v[108:111], v[0:15]
	global_load_lds_dwordx4 v254, s[44:45]
	s_add_u32 m0, m0, 0x1000
	v_mfma_f32_32x32x16_bf16 v[48:63], v[112:115], v[222:225], v[48:63]
	v_mfma_f32_32x32x16_bf16 v[32:47], v[112:115], v[230:233], v[32:47]
	global_load_lds_dwordx4 v254, s[46:47]
	s_add_u32 m0, m0, 0x1000
	v_mfma_f32_32x32x16_bf16 v[16:31], v[112:115], v[234:237], v[16:31]
	v_mfma_f32_32x32x16_bf16 v[0:15], v[112:115], v[238:241], v[0:15]
	global_load_lds_dwordx4 v254, s[48:49]
	s_add_u32 m0, m0, 0x1000
	v_mfma_f32_32x32x16_bf16 v[48:63], v[242:245], v[246:249], v[48:63]
	v_mfma_f32_32x32x16_bf16 v[32:47], v[242:245], v[250:253], v[32:47]
	global_load_lds_dwordx4 v254, s[50:51]
	s_add_u32 m0, m0, 0x1000
	v_mfma_f32_32x32x16_bf16 v[16:31], v[242:245], v[194:197], v[16:31]
	v_mfma_f32_32x32x16_bf16 v[0:15], v[242:245], v[202:205], v[0:15]
	global_load_lds_dwordx4 v254, s[52:53]
	v_add_u32_e32 v254, 0x80, v254
	s_waitcnt vmcnt(8)
	s_barrier
	ds_read_b128 v[64:67], v213 offset:32768
	ds_read_b128 v[76:79], v221 offset:49152
	ds_read_b128 v[80:83], v221 offset:53248
	ds_read_b128 v[84:87], v221 offset:57344
	ds_read_b128 v[88:91], v221 offset:61440
	ds_read_b128 v[92:95], v226 offset:32768
	ds_read_b128 v[96:99], v227 offset:49152
	ds_read_b128 v[100:103], v227 offset:53248
	ds_read_b128 v[104:107], v227 offset:57344
	ds_read_b128 v[108:111], v227 offset:61440
	ds_read_b128 v[112:115], v229 offset:32768
	ds_read_b128 v[222:225], v255 offset:49152
	ds_read_b128 v[230:233], v255 offset:53248
	ds_read_b128 v[234:237], v255 offset:57344
	ds_read_b128 v[238:241], v255 offset:61440
	ds_read_b128 v[242:245], v162 offset:32768
	ds_read_b128 v[246:249], v163 offset:49152
	ds_read_b128 v[250:253], v163 offset:53248
	ds_read_b128 v[194:197], v163 offset:57344
	ds_read_b128 v[202:205], v163 offset:61440
	s_waitcnt lgkmcnt(0)
	s_barrier
	s_add_u32 m0, s54, 0x8000
	v_mfma_f32_32x32x16_bf16 v[48:63], v[64:67], v[76:79], v[48:63]
	v_mfma_f32_32x32x16_bf16 v[32:47], v[64:67], v[80:83], v[32:47]
	global_load_lds_dwordx4 v254, s[38:39]
	s_add_u32 m0, m0, 0x1000
	v_mfma_f32_32x32x16_bf16 v[16:31], v[64:67], v[84:87], v[16:31]
	v_mfma_f32_32x32x16_bf16 v[0:15], v[64:67], v[88:91], v[0:15]
	global_load_lds_dwordx4 v254, s[40:41]
	s_add_u32 m0, m0, 0x1000
	v_mfma_f32_32x32x16_bf16 v[48:63], v[92:95], v[96:99], v[48:63]
	v_mfma_f32_32x32x16_bf16 v[32:47], v[92:95], v[100:103], v[32:47]
	global_load_lds_dwordx4 v254, s[42:43]
	s_add_u32 m0, m0, 0x1000
	v_mfma_f32_32x32x16_bf16 v[16:31], v[92:95], v[104:107], v[16:31]
	v_mfma_f32_32x32x16_bf16 v[0:15], v[92:95], v[108:111], v[0:15]
	global_load_lds_dwordx4 v254, s[44:45]
	s_add_u32 m0, m0, 0x1000
	v_mfma_f32_32x32x16_bf16 v[48:63], v[112:115], v[222:225], v[48:63]
	v_mfma_f32_32x32x16_bf16 v[32:47], v[112:115], v[230:233], v[32:47]
	global_load_lds_dwordx4 v254, s[46:47]
	s_add_u32 m0, m0, 0x1000
	v_mfma_f32_32x32x16_bf16 v[16:31], v[112:115], v[234:237], v[16:31]
	v_mfma_f32_32x32x16_bf16 v[0:15], v[112:115], v[238:241], v[0:15]
	global_load_lds_dwordx4 v254, s[48:49]
	s_add_u32 m0, m0, 0x1000
	v_mfma_f32_32x32x16_bf16 v[48:63], v[242:245], v[246:249], v[48:63]
	v_mfma_f32_32x32x16_bf16 v[32:47], v[242:245], v[250:253], v[32:47]
	global_load_lds_dwordx4 v254, s[50:51]
	s_add_u32 m0, m0, 0x1000
	v_mfma_f32_32x32x16_bf16 v[16:31], v[242:245], v[194:197], v[16:31]
	v_mfma_f32_32x32x16_bf16 v[0:15], v[242:245], v[202:205], v[0:15]
	global_load_lds_dwordx4 v254, s[52:53]
	v_add_u32_e32 v254, 0x80, v254
	s_branch .LBB0_262
.Lgk_tailplain_p2:
	s_mov_b32 s57, 0
	s_waitcnt vmcnt(8)
	s_barrier
	ds_read_b128 v[64:67], v213
	ds_read_b128 v[76:79], v221 offset:16384
	ds_read_b128 v[80:83], v221 offset:20480
	ds_read_b128 v[84:87], v221 offset:24576
	ds_read_b128 v[88:91], v221 offset:28672
	ds_read_b128 v[92:95], v226
	ds_read_b128 v[96:99], v227 offset:16384
	ds_read_b128 v[100:103], v227 offset:20480
	ds_read_b128 v[104:107], v227 offset:24576
	ds_read_b128 v[108:111], v227 offset:28672
	ds_read_b128 v[112:115], v229
	ds_read_b128 v[222:225], v255 offset:16384
	ds_read_b128 v[230:233], v255 offset:20480
	ds_read_b128 v[234:237], v255 offset:24576
	ds_read_b128 v[238:241], v255 offset:28672
	ds_read_b128 v[242:245], v162
	ds_read_b128 v[246:249], v163 offset:16384
	ds_read_b128 v[250:253], v163 offset:20480
	ds_read_b128 v[194:197], v163 offset:24576
	ds_read_b128 v[202:205], v163 offset:28672
	s_waitcnt lgkmcnt(0)
	s_barrier
	v_mfma_f32_32x32x16_bf16 v[48:63], v[64:67], v[76:79], v[48:63]
	v_mfma_f32_32x32x16_bf16 v[32:47], v[64:67], v[80:83], v[32:47]
	v_mfma_f32_32x32x16_bf16 v[16:31], v[64:67], v[84:87], v[16:31]
	v_mfma_f32_32x32x16_bf16 v[0:15], v[64:67], v[88:91], v[0:15]
	v_mfma_f32_32x32x16_bf16 v[48:63], v[92:95], v[96:99], v[48:63]
	v_mfma_f32_32x32x16_bf16 v[32:47], v[92:95], v[100:103], v[32:47]
	v_mfma_f32_32x32x16_bf16 v[16:31], v[92:95], v[104:107], v[16:31]
	v_mfma_f32_32x32x16_bf16 v[0:15], v[92:95], v[108:111], v[0:15]
	v_mfma_f32_32x32x16_bf16 v[48:63], v[112:115], v[222:225], v[48:63]
	v_mfma_f32_32x32x16_bf16 v[32:47], v[112:115], v[230:233], v[32:47]
	v_mfma_f32_32x32x16_bf16 v[16:31], v[112:115], v[234:237], v[16:31]
	v_mfma_f32_32x32x16_bf16 v[0:15], v[112:115], v[238:241], v[0:15]
	v_mfma_f32_32x32x16_bf16 v[48:63], v[242:245], v[246:249], v[48:63]
	v_mfma_f32_32x32x16_bf16 v[32:47], v[242:245], v[250:253], v[32:47]
	v_mfma_f32_32x32x16_bf16 v[16:31], v[242:245], v[194:197], v[16:31]
	v_mfma_f32_32x32x16_bf16 v[0:15], v[242:245], v[202:205], v[0:15]
	s_waitcnt vmcnt(0)
	s_barrier
	ds_read_b128 v[64:67], v213 offset:32768
	ds_read_b128 v[76:79], v221 offset:49152
	ds_read_b128 v[80:83], v221 offset:53248
	ds_read_b128 v[84:87], v221 offset:57344
	ds_read_b128 v[88:91], v221 offset:61440
	ds_read_b128 v[92:95], v226 offset:32768
	ds_read_b128 v[96:99], v227 offset:49152
	ds_read_b128 v[100:103], v227 offset:53248
	ds_read_b128 v[104:107], v227 offset:57344
	ds_read_b128 v[108:111], v227 offset:61440
	ds_read_b128 v[112:115], v229 offset:32768
	ds_read_b128 v[222:225], v255 offset:49152
	ds_read_b128 v[230:233], v255 offset:53248
	ds_read_b128 v[234:237], v255 offset:57344
	ds_read_b128 v[238:241], v255 offset:61440
	ds_read_b128 v[242:245], v162 offset:32768
	ds_read_b128 v[246:249], v163 offset:49152
	ds_read_b128 v[250:253], v163 offset:53248
	ds_read_b128 v[194:197], v163 offset:57344
	ds_read_b128 v[202:205], v163 offset:61440
	s_waitcnt lgkmcnt(0)
	s_barrier
	v_mfma_f32_32x32x16_bf16 v[48:63], v[64:67], v[76:79], v[48:63]
	v_mfma_f32_32x32x16_bf16 v[32:47], v[64:67], v[80:83], v[32:47]
	v_mfma_f32_32x32x16_bf16 v[16:31], v[64:67], v[84:87], v[16:31]
	v_mfma_f32_32x32x16_bf16 v[0:15], v[64:67], v[88:91], v[0:15]
	v_mfma_f32_32x32x16_bf16 v[48:63], v[92:95], v[96:99], v[48:63]
	v_mfma_f32_32x32x16_bf16 v[32:47], v[92:95], v[100:103], v[32:47]
	v_mfma_f32_32x32x16_bf16 v[16:31], v[92:95], v[104:107], v[16:31]
	v_mfma_f32_32x32x16_bf16 v[0:15], v[92:95], v[108:111], v[0:15]
	v_mfma_f32_32x32x16_bf16 v[48:63], v[112:115], v[222:225], v[48:63]
	v_mfma_f32_32x32x16_bf16 v[32:47], v[112:115], v[230:233], v[32:47]
	v_mfma_f32_32x32x16_bf16 v[16:31], v[112:115], v[234:237], v[16:31]
	v_mfma_f32_32x32x16_bf16 v[0:15], v[112:115], v[238:241], v[0:15]
	v_mfma_f32_32x32x16_bf16 v[48:63], v[242:245], v[246:249], v[48:63]
	v_mfma_f32_32x32x16_bf16 v[32:47], v[242:245], v[250:253], v[32:47]
	v_mfma_f32_32x32x16_bf16 v[16:31], v[242:245], v[194:197], v[16:31]
	v_mfma_f32_32x32x16_bf16 v[0:15], v[242:245], v[202:205], v[0:15]
	s_branch .LBB0_262

.LBB0_576:
	s_mul_hi_i32 s0, s71, 0x2aaaaaab
	s_lshr_b32 s1, s0, 31
	s_ashr_i32 s0, s0, 4
	s_add_i32 s0, s0, s1
	s_lshl_b32 s1, s0, 3
	s_mulk_i32 s0, 0xffa0
	s_add_i32 s66, s71, s0
	s_ashr_i32 s0, s66, 31
	s_lshr_b32 s0, s0, 29
	s_add_i32 s0, s66, s0
	s_ashr_i32 s72, s0, 3
	s_and_b32 s0, s0, -8
	s_sub_i32 s74, s66, s0
	s_add_i32 s74, s74, s1
	s_lshl_b32 s73, s74, 7
	v_readfirstlane_b32 s85, v100
	s_lshl_b32 s67, s72, 7
	v_mad_i64_i32 v[72:73], s[0:1], s73, v99, v[66:67]
	s_mov_b32 m0, s85
	v_readfirstlane_b32 s78, v101
	v_mad_i64_i32 v[70:71], s[0:1], s67, v99, v[68:69]
	global_load_lds_dwordx4 v[72:73], off
	s_mov_b32 m0, s78
	v_readfirstlane_b32 s79, v102
	global_load_lds_dwordx4 v[70:71], off
	v_lshl_add_u64 v[0:1], v[72:73], 0, s[18:19]
	s_mov_b32 m0, s79
	v_readfirstlane_b32 s80, v103
	global_load_lds_dwordx4 v[0:1], off
	v_lshl_add_u64 v[0:1], v[70:71], 0, s[18:19]
	s_mov_b32 m0, s80
	v_readfirstlane_b32 s81, v104
	global_load_lds_dwordx4 v[0:1], off
	v_lshl_add_u64 v[0:1], v[72:73], 0, s[20:21]
	s_mov_b32 m0, s81
	v_readfirstlane_b32 s82, v105
	global_load_lds_dwordx4 v[0:1], off
	v_lshl_add_u64 v[0:1], v[70:71], 0, s[20:21]
	s_mov_b32 m0, s82
	v_readfirstlane_b32 s83, v106
	global_load_lds_dwordx4 v[0:1], off
	v_lshl_add_u64 v[0:1], v[72:73], 0, s[22:23]
	s_mov_b32 m0, s83
	v_readfirstlane_b32 s84, v107
	global_load_lds_dwordx4 v[0:1], off
	v_lshl_add_u64 v[0:1], v[70:71], 0, s[22:23]
	s_mov_b32 m0, s84
	v_readfirstlane_b32 s77, v108
	global_load_lds_dwordx4 v[0:1], off
	v_lshl_add_u64 v[0:1], v[72:73], 0, s[24:25]
	s_mov_b32 m0, s77
	v_readfirstlane_b32 s0, v109
	s_waitcnt vmcnt(0)
	s_waitcnt vmcnt(0) lgkmcnt(0)
	s_barrier
	v_lshl_add_u64 v[2:3], v[70:71], 0, s[24:25]
	global_load_lds_dwordx4 v[0:1], off
	s_mov_b32 m0, s0
	v_readfirstlane_b32 s1, v110
	global_load_lds_dwordx4 v[2:3], off
	v_lshl_add_u64 v[0:1], v[72:73], 0, s[26:27]
	s_mov_b32 m0, s1
	v_readfirstlane_b32 s67, v111
	global_load_lds_dwordx4 v[0:1], off
	v_lshl_add_u64 v[0:1], v[70:71], 0, s[26:27]
	s_mov_b32 m0, s67
	v_readfirstlane_b32 s68, v112
	global_load_lds_dwordx4 v[0:1], off
	v_lshl_add_u64 v[0:1], v[72:73], 0, s[28:29]
	s_mov_b32 m0, s68
	v_readfirstlane_b32 s69, v113
	global_load_lds_dwordx4 v[0:1], off
	v_lshl_add_u64 v[0:1], v[70:71], 0, s[28:29]
	s_mov_b32 m0, s69
	v_readfirstlane_b32 s75, v114
	global_load_lds_dwordx4 v[0:1], off
	v_lshl_add_u64 v[0:1], v[72:73], 0, s[30:31]
	s_mov_b32 m0, s75
	v_readfirstlane_b32 s76, v115
	global_load_lds_dwordx4 v[0:1], off
	v_lshl_add_u64 v[0:1], v[70:71], 0, s[30:31]
	s_mov_b32 m0, s76
	v_add_u32_e32 v121, v75, v77
	global_load_lds_dwordx4 v[0:1], off
	ds_read_b128 v[0:3], v116
	ds_read_b128 v[4:7], v117 offset:16384
	ds_read_b128 v[8:11], v117 offset:20480
	ds_read_b128 v[12:15], v117 offset:24576
	ds_read_b128 v[122:125], v117 offset:28672
	ds_read_b128 v[126:129], v118
	ds_read_b128 v[130:133], v121 offset:16384
	ds_read_b128 v[134:137], v121 offset:20480
	ds_read_b128 v[138:141], v121 offset:24576
	ds_read_b128 v[142:145], v121 offset:28672
	s_waitcnt lgkmcnt(0)
	v_mfma_f32_32x32x16_bf16 v[48:63], v[0:3], v[4:7], 0
	v_mfma_f32_32x32x16_bf16 v[32:47], v[0:3], v[8:11], 0
	v_mfma_f32_32x32x16_bf16 v[16:31], v[0:3], v[12:15], 0
	v_mfma_f32_32x32x16_bf16 v[0:15], v[0:3], v[122:125], 0
	v_add_u32_e32 v162, v76, v78
	v_add_u32_e32 v163, v75, v78
	ds_read_b128 v[122:125], v162
	ds_read_b128 v[146:149], v163 offset:16384
	ds_read_b128 v[150:153], v163 offset:20480
	ds_read_b128 v[154:157], v163 offset:24576
	ds_read_b128 v[158:161], v163 offset:28672
	v_mfma_f32_32x32x16_bf16 v[48:63], v[126:129], v[130:133], v[48:63]
	v_mfma_f32_32x32x16_bf16 v[32:47], v[126:129], v[134:137], v[32:47]
	v_mfma_f32_32x32x16_bf16 v[16:31], v[126:129], v[138:141], v[16:31]
	v_mfma_f32_32x32x16_bf16 v[0:15], v[126:129], v[142:145], v[0:15]
	v_add_u32_e32 v164, v76, v79
	v_add_u32_e32 v165, v75, v79
	ds_read_b128 v[126:129], v164
	ds_read_b128 v[130:133], v165 offset:16384
	ds_read_b128 v[134:137], v165 offset:20480
	ds_read_b128 v[138:141], v165 offset:24576
	ds_read_b128 v[142:145], v165 offset:28672
	s_waitcnt lgkmcnt(0)
	v_mfma_f32_32x32x16_bf16 v[48:63], v[122:125], v[146:149], v[48:63]
	v_mfma_f32_32x32x16_bf16 v[32:47], v[122:125], v[150:153], v[32:47]
	v_mfma_f32_32x32x16_bf16 v[16:31], v[122:125], v[154:157], v[16:31]
	v_mfma_f32_32x32x16_bf16 v[0:15], v[122:125], v[158:161], v[0:15]
	v_mfma_f32_32x32x16_bf16 v[48:63], v[126:129], v[130:133], v[48:63]
	v_mfma_f32_32x32x16_bf16 v[32:47], v[126:129], v[134:137], v[32:47]
	v_mfma_f32_32x32x16_bf16 v[16:31], v[126:129], v[138:141], v[16:31]
	v_mfma_f32_32x32x16_bf16 v[0:15], v[126:129], v[142:145], v[0:15]
	s_mov_b32 m0, s85
	v_lshl_add_u64 v[122:123], v[72:73], 0, s[34:35]
	s_waitcnt vmcnt(0)
	s_waitcnt vmcnt(0)
	s_barrier
	v_lshl_add_u64 v[124:125], v[70:71], 0, s[34:35]
	global_load_lds_dwordx4 v[122:123], off
	s_mov_b32 m0, s78
	v_lshl_add_u64 v[122:123], v[72:73], 0, s[36:37]
	global_load_lds_dwordx4 v[124:125], off
	s_mov_b32 m0, s79
	s_nop 0
	global_load_lds_dwordx4 v[122:123], off
	v_lshl_add_u64 v[122:123], v[70:71], 0, s[36:37]
	s_mov_b32 m0, s80
	s_nop 0
	global_load_lds_dwordx4 v[122:123], off
	v_lshl_add_u64 v[122:123], v[72:73], 0, s[38:39]
	s_mov_b32 m0, s81
	s_nop 0
	global_load_lds_dwordx4 v[122:123], off
	v_lshl_add_u64 v[122:123], v[70:71], 0, s[38:39]
	s_mov_b32 m0, s82
	s_nop 0
	global_load_lds_dwordx4 v[122:123], off
	v_lshl_add_u64 v[122:123], v[72:73], 0, s[40:41]
	s_mov_b32 m0, s83
	s_nop 0
	global_load_lds_dwordx4 v[122:123], off
	v_lshl_add_u64 v[122:123], v[70:71], 0, s[40:41]
	s_mov_b32 m0, s84
	s_nop 0
	global_load_lds_dwordx4 v[122:123], off
	ds_read_b128 v[122:125], v116 offset:32768
	ds_read_b128 v[126:129], v117 offset:49152
	ds_read_b128 v[130:133], v117 offset:53248
	ds_read_b128 v[134:137], v117 offset:57344
	ds_read_b128 v[138:141], v117 offset:61440
	ds_read_b128 v[142:145], v118 offset:32768
	ds_read_b128 v[146:149], v121 offset:49152
	ds_read_b128 v[150:153], v121 offset:53248
	ds_read_b128 v[154:157], v121 offset:57344
	ds_read_b128 v[158:161], v121 offset:61440
	s_waitcnt lgkmcnt(0)
	v_mfma_f32_32x32x16_bf16 v[48:63], v[122:125], v[126:129], v[48:63]
	v_mfma_f32_32x32x16_bf16 v[32:47], v[122:125], v[130:133], v[32:47]
	v_mfma_f32_32x32x16_bf16 v[16:31], v[122:125], v[134:137], v[16:31]
	v_mfma_f32_32x32x16_bf16 v[0:15], v[122:125], v[138:141], v[0:15]
	ds_read_b128 v[122:125], v162 offset:32768
	ds_read_b128 v[126:129], v163 offset:49152
	ds_read_b128 v[130:133], v163 offset:53248
	ds_read_b128 v[134:137], v163 offset:57344
	ds_read_b128 v[138:141], v163 offset:61440
	v_mfma_f32_32x32x16_bf16 v[48:63], v[142:145], v[146:149], v[48:63]
	v_mfma_f32_32x32x16_bf16 v[32:47], v[142:145], v[150:153], v[32:47]
	v_mfma_f32_32x32x16_bf16 v[16:31], v[142:145], v[154:157], v[16:31]
	v_mfma_f32_32x32x16_bf16 v[0:15], v[142:145], v[158:161], v[0:15]
	ds_read_b128 v[142:145], v164 offset:32768
	ds_read_b128 v[146:149], v165 offset:49152
	ds_read_b128 v[150:153], v165 offset:53248
	ds_read_b128 v[154:157], v165 offset:57344
	ds_read_b128 v[158:161], v165 offset:61440
	s_waitcnt lgkmcnt(0)
	v_mfma_f32_32x32x16_bf16 v[48:63], v[122:125], v[126:129], v[48:63]
	v_mfma_f32_32x32x16_bf16 v[32:47], v[122:125], v[130:133], v[32:47]
	v_mfma_f32_32x32x16_bf16 v[16:31], v[122:125], v[134:137], v[16:31]
	v_mfma_f32_32x32x16_bf16 v[0:15], v[122:125], v[138:141], v[0:15]
	v_mfma_f32_32x32x16_bf16 v[48:63], v[142:145], v[146:149], v[48:63]
	v_mfma_f32_32x32x16_bf16 v[32:47], v[142:145], v[150:153], v[32:47]
	v_mfma_f32_32x32x16_bf16 v[16:31], v[142:145], v[154:157], v[16:31]
	v_mfma_f32_32x32x16_bf16 v[0:15], v[142:145], v[158:161], v[0:15]
	s_mov_b32 m0, s77
	v_lshl_add_u64 v[122:123], v[72:73], 0, s[42:43]
	s_waitcnt vmcnt(0)
	s_waitcnt vmcnt(0)
	s_barrier
	v_lshl_add_u64 v[124:125], v[70:71], 0, s[42:43]
	global_load_lds_dwordx4 v[122:123], off
	s_mov_b32 m0, s0
	v_lshl_add_u64 v[122:123], v[72:73], 0, s[44:45]
	global_load_lds_dwordx4 v[124:125], off
	s_mov_b32 m0, s1
	s_nop 0
	global_load_lds_dwordx4 v[122:123], off
	v_lshl_add_u64 v[122:123], v[70:71], 0, s[44:45]
	s_mov_b32 m0, s67
	s_nop 0
	global_load_lds_dwordx4 v[122:123], off
	v_lshl_add_u64 v[122:123], v[72:73], 0, s[46:47]
	s_mov_b32 m0, s68
	s_nop 0
	global_load_lds_dwordx4 v[122:123], off
	v_lshl_add_u64 v[122:123], v[70:71], 0, s[46:47]
	s_mov_b32 m0, s69
	s_nop 0
	global_load_lds_dwordx4 v[122:123], off
	v_lshl_add_u64 v[122:123], v[72:73], 0, s[48:49]
	s_mov_b32 m0, s75
	s_nop 0
	global_load_lds_dwordx4 v[122:123], off
	v_lshl_add_u64 v[122:123], v[70:71], 0, s[48:49]
	s_mov_b32 m0, s76
	s_nop 0
	global_load_lds_dwordx4 v[122:123], off
	ds_read_b128 v[122:125], v116
	ds_read_b128 v[126:129], v117 offset:16384
	ds_read_b128 v[130:133], v117 offset:20480
	ds_read_b128 v[134:137], v117 offset:24576
	ds_read_b128 v[138:141], v117 offset:28672
	ds_read_b128 v[142:145], v118
	ds_read_b128 v[146:149], v121 offset:16384
	ds_read_b128 v[150:153], v121 offset:20480
	ds_read_b128 v[154:157], v121 offset:24576
	ds_read_b128 v[158:161], v121 offset:28672
	s_waitcnt lgkmcnt(0)
	v_mfma_f32_32x32x16_bf16 v[48:63], v[122:125], v[126:129], v[48:63]
	v_mfma_f32_32x32x16_bf16 v[32:47], v[122:125], v[130:133], v[32:47]
	v_mfma_f32_32x32x16_bf16 v[16:31], v[122:125], v[134:137], v[16:31]
	v_mfma_f32_32x32x16_bf16 v[0:15], v[122:125], v[138:141], v[0:15]
	ds_read_b128 v[122:125], v162
	ds_read_b128 v[126:129], v163 offset:16384
	ds_read_b128 v[130:133], v163 offset:20480
	ds_read_b128 v[134:137], v163 offset:24576
	ds_read_b128 v[138:141], v163 offset:28672
	v_mfma_f32_32x32x16_bf16 v[48:63], v[142:145], v[146:149], v[48:63]
	v_mfma_f32_32x32x16_bf16 v[32:47], v[142:145], v[150:153], v[32:47]
	v_mfma_f32_32x32x16_bf16 v[16:31], v[142:145], v[154:157], v[16:31]
	v_mfma_f32_32x32x16_bf16 v[0:15], v[142:145], v[158:161], v[0:15]
	ds_read_b128 v[142:145], v164
	ds_read_b128 v[146:149], v165 offset:16384
	ds_read_b128 v[150:153], v165 offset:20480
	ds_read_b128 v[154:157], v165 offset:24576
	ds_read_b128 v[158:161], v165 offset:28672
	s_waitcnt lgkmcnt(0)
	v_mfma_f32_32x32x16_bf16 v[48:63], v[122:125], v[126:129], v[48:63]
	v_mfma_f32_32x32x16_bf16 v[32:47], v[122:125], v[130:133], v[32:47]
	v_mfma_f32_32x32x16_bf16 v[16:31], v[122:125], v[134:137], v[16:31]
	v_mfma_f32_32x32x16_bf16 v[0:15], v[122:125], v[138:141], v[0:15]
	v_mfma_f32_32x32x16_bf16 v[48:63], v[142:145], v[146:149], v[48:63]
	v_mfma_f32_32x32x16_bf16 v[32:47], v[142:145], v[150:153], v[32:47]
	v_mfma_f32_32x32x16_bf16 v[16:31], v[142:145], v[154:157], v[16:31]
	v_mfma_f32_32x32x16_bf16 v[0:15], v[142:145], v[158:161], v[0:15]
	s_mov_b32 m0, s85
	v_lshl_add_u64 v[122:123], v[72:73], 0, s[50:51]
	s_waitcnt vmcnt(0)
	s_waitcnt vmcnt(0)
	s_barrier
	v_lshl_add_u64 v[124:125], v[70:71], 0, s[50:51]
	global_load_lds_dwordx4 v[122:123], off
	s_mov_b32 m0, s78
	v_lshl_add_u64 v[122:123], v[72:73], 0, s[52:53]
	global_load_lds_dwordx4 v[124:125], off
	s_mov_b32 m0, s79
	s_nop 0
	global_load_lds_dwordx4 v[122:123], off
	v_lshl_add_u64 v[122:123], v[70:71], 0, s[52:53]
	s_mov_b32 m0, s80
	s_nop 0
	global_load_lds_dwordx4 v[122:123], off
	v_lshl_add_u64 v[122:123], v[72:73], 0, s[54:55]
	s_mov_b32 m0, s81
	s_nop 0
	global_load_lds_dwordx4 v[122:123], off
	v_lshl_add_u64 v[122:123], v[70:71], 0, s[54:55]
	s_mov_b32 m0, s82
	s_nop 0
	global_load_lds_dwordx4 v[122:123], off
	v_lshl_add_u64 v[122:123], v[72:73], 0, s[56:57]
	s_mov_b32 m0, s83
	s_nop 0
	global_load_lds_dwordx4 v[122:123], off
	v_lshl_add_u64 v[122:123], v[70:71], 0, s[56:57]
	s_mov_b32 m0, s84
	s_nop 0
	global_load_lds_dwordx4 v[122:123], off
	ds_read_b128 v[122:125], v116 offset:32768
	ds_read_b128 v[126:129], v117 offset:49152
	ds_read_b128 v[130:133], v117 offset:53248
	ds_read_b128 v[134:137], v117 offset:57344
	ds_read_b128 v[138:141], v117 offset:61440
	ds_read_b128 v[142:145], v118 offset:32768
	ds_read_b128 v[146:149], v121 offset:49152
	ds_read_b128 v[150:153], v121 offset:53248
	ds_read_b128 v[154:157], v121 offset:57344
	ds_read_b128 v[158:161], v121 offset:61440
	s_waitcnt lgkmcnt(0)
	v_mfma_f32_32x32x16_bf16 v[48:63], v[122:125], v[126:129], v[48:63]
	v_mfma_f32_32x32x16_bf16 v[32:47], v[122:125], v[130:133], v[32:47]
	v_mfma_f32_32x32x16_bf16 v[16:31], v[122:125], v[134:137], v[16:31]
	v_mfma_f32_32x32x16_bf16 v[0:15], v[122:125], v[138:141], v[0:15]
	ds_read_b128 v[122:125], v162 offset:32768
	ds_read_b128 v[126:129], v163 offset:49152
	ds_read_b128 v[130:133], v163 offset:53248
	ds_read_b128 v[134:137], v163 offset:57344
	ds_read_b128 v[138:141], v163 offset:61440
	v_mfma_f32_32x32x16_bf16 v[48:63], v[142:145], v[146:149], v[48:63]
	v_mfma_f32_32x32x16_bf16 v[32:47], v[142:145], v[150:153], v[32:47]
	v_mfma_f32_32x32x16_bf16 v[16:31], v[142:145], v[154:157], v[16:31]
	v_mfma_f32_32x32x16_bf16 v[0:15], v[142:145], v[158:161], v[0:15]
	ds_read_b128 v[142:145], v164 offset:32768
	ds_read_b128 v[146:149], v165 offset:49152
	ds_read_b128 v[150:153], v165 offset:53248
	ds_read_b128 v[154:157], v165 offset:57344
	ds_read_b128 v[158:161], v165 offset:61440
	s_waitcnt lgkmcnt(0)
	v_mfma_f32_32x32x16_bf16 v[48:63], v[122:125], v[126:129], v[48:63]
	v_mfma_f32_32x32x16_bf16 v[32:47], v[122:125], v[130:133], v[32:47]
	v_mfma_f32_32x32x16_bf16 v[16:31], v[122:125], v[134:137], v[16:31]
	v_mfma_f32_32x32x16_bf16 v[0:15], v[122:125], v[138:141], v[0:15]
	v_mfma_f32_32x32x16_bf16 v[48:63], v[142:145], v[146:149], v[48:63]
	v_mfma_f32_32x32x16_bf16 v[32:47], v[142:145], v[150:153], v[32:47]
	v_mfma_f32_32x32x16_bf16 v[16:31], v[142:145], v[154:157], v[16:31]
	v_mfma_f32_32x32x16_bf16 v[0:15], v[142:145], v[158:161], v[0:15]
	s_mov_b32 m0, s77
	v_lshl_add_u64 v[122:123], v[72:73], 0, s[58:59]
	s_waitcnt vmcnt(0)
	s_waitcnt vmcnt(0)
	s_barrier
	v_lshl_add_u64 v[124:125], v[70:71], 0, s[58:59]
	global_load_lds_dwordx4 v[122:123], off
	s_mov_b32 m0, s0
	v_lshl_add_u64 v[122:123], v[72:73], 0, s[60:61]
	global_load_lds_dwordx4 v[124:125], off
	s_mov_b32 m0, s1
	s_nop 0
	global_load_lds_dwordx4 v[122:123], off
	v_lshl_add_u64 v[122:123], v[70:71], 0, s[60:61]
	s_mov_b32 m0, s67
	s_nop 0
	global_load_lds_dwordx4 v[122:123], off
	v_lshl_add_u64 v[122:123], v[72:73], 0, s[62:63]
	s_mov_b32 m0, s68
	v_lshl_add_u64 v[72:73], v[72:73], 0, s[64:65]
	global_load_lds_dwordx4 v[122:123], off
	v_lshl_add_u64 v[122:123], v[70:71], 0, s[62:63]
	s_mov_b32 m0, s69
	v_lshl_add_u64 v[70:71], v[70:71], 0, s[64:65]
	global_load_lds_dwordx4 v[122:123], off
	s_mov_b32 m0, s75
	s_nop 0
	global_load_lds_dwordx4 v[72:73], off
	s_mov_b32 m0, s76
	s_nop 0
	global_load_lds_dwordx4 v[70:71], off
	ds_read_b128 v[70:73], v116
	ds_read_b128 v[122:125], v117 offset:16384
	ds_read_b128 v[126:129], v117 offset:20480
	ds_read_b128 v[130:133], v117 offset:24576
	ds_read_b128 v[134:137], v117 offset:28672
	ds_read_b128 v[138:141], v118
	ds_read_b128 v[142:145], v121 offset:16384
	ds_read_b128 v[146:149], v121 offset:20480
	ds_read_b128 v[150:153], v121 offset:24576
	ds_read_b128 v[154:157], v121 offset:28672
	s_waitcnt lgkmcnt(0)
	v_mfma_f32_32x32x16_bf16 v[48:63], v[70:73], v[122:125], v[48:63]
	v_mfma_f32_32x32x16_bf16 v[32:47], v[70:73], v[126:129], v[32:47]
	v_mfma_f32_32x32x16_bf16 v[16:31], v[70:73], v[130:133], v[16:31]
	v_mfma_f32_32x32x16_bf16 v[0:15], v[70:73], v[134:137], v[0:15]
	ds_read_b128 v[70:73], v162
	ds_read_b128 v[122:125], v163 offset:16384
	ds_read_b128 v[126:129], v163 offset:20480
	ds_read_b128 v[130:133], v163 offset:24576
	ds_read_b128 v[134:137], v163 offset:28672
	v_mfma_f32_32x32x16_bf16 v[48:63], v[138:141], v[142:145], v[48:63]
	v_mfma_f32_32x32x16_bf16 v[32:47], v[138:141], v[146:149], v[32:47]
	v_mfma_f32_32x32x16_bf16 v[16:31], v[138:141], v[150:153], v[16:31]
	v_mfma_f32_32x32x16_bf16 v[0:15], v[138:141], v[154:157], v[0:15]
	ds_read_b128 v[138:141], v164
	ds_read_b128 v[142:145], v165 offset:16384
	ds_read_b128 v[146:149], v165 offset:20480
	ds_read_b128 v[150:153], v165 offset:24576
	ds_read_b128 v[154:157], v165 offset:28672
	s_waitcnt lgkmcnt(0)
	v_mfma_f32_32x32x16_bf16 v[48:63], v[70:73], v[122:125], v[48:63]
	v_mfma_f32_32x32x16_bf16 v[32:47], v[70:73], v[126:129], v[32:47]
	v_mfma_f32_32x32x16_bf16 v[16:31], v[70:73], v[130:133], v[16:31]
	v_mfma_f32_32x32x16_bf16 v[0:15], v[70:73], v[134:137], v[0:15]
	v_mfma_f32_32x32x16_bf16 v[48:63], v[138:141], v[142:145], v[48:63]
	v_mfma_f32_32x32x16_bf16 v[32:47], v[138:141], v[146:149], v[32:47]
	v_mfma_f32_32x32x16_bf16 v[16:31], v[138:141], v[150:153], v[16:31]
	v_mfma_f32_32x32x16_bf16 v[0:15], v[138:141], v[154:157], v[0:15]
	s_waitcnt vmcnt(0)
	s_waitcnt vmcnt(0)
	s_barrier
	ds_read_b128 v[70:73], v121 offset:61440
	ds_read_b128 v[122:125], v121 offset:57344
	ds_read_b128 v[126:129], v121 offset:53248
	ds_read_b128 v[130:133], v121 offset:49152
	ds_read_b128 v[134:137], v118 offset:32768
	ds_read_b128 v[138:141], v117 offset:61440
	ds_read_b128 v[142:145], v117 offset:57344
	ds_read_b128 v[146:149], v117 offset:53248
	ds_read_b128 v[150:153], v117 offset:49152
	ds_read_b128 v[154:157], v116 offset:32768
	s_waitcnt lgkmcnt(0)
	v_mfma_f32_32x32x16_bf16 v[48:63], v[154:157], v[150:153], v[48:63]
	v_mfma_f32_32x32x16_bf16 v[32:47], v[154:157], v[146:149], v[32:47]
	v_mfma_f32_32x32x16_bf16 v[16:31], v[154:157], v[142:145], v[16:31]
	v_mfma_f32_32x32x16_bf16 v[0:15], v[154:157], v[138:141], v[0:15]
	ds_read_b128 v[138:141], v162 offset:32768
	ds_read_b128 v[142:145], v163 offset:49152
	ds_read_b128 v[146:149], v163 offset:53248
	ds_read_b128 v[150:153], v163 offset:57344
	ds_read_b128 v[154:157], v163 offset:61440
	v_mfma_f32_32x32x16_bf16 v[48:63], v[134:137], v[130:133], v[48:63]
	v_mfma_f32_32x32x16_bf16 v[32:47], v[134:137], v[126:129], v[32:47]
	v_mfma_f32_32x32x16_bf16 v[16:31], v[134:137], v[122:125], v[16:31]
	v_mfma_f32_32x32x16_bf16 v[0:15], v[134:137], v[70:73], v[0:15]
	ds_read_b128 v[70:73], v164 offset:32768
	ds_read_b128 v[122:125], v165 offset:49152
	ds_read_b128 v[126:129], v165 offset:53248
	ds_read_b128 v[130:133], v165 offset:57344
	ds_read_b128 v[134:137], v165 offset:61440
	s_waitcnt lgkmcnt(8)
	v_mfma_f32_32x32x16_bf16 v[48:63], v[138:141], v[142:145], v[48:63]
	s_waitcnt lgkmcnt(7)
	v_mfma_f32_32x32x16_bf16 v[32:47], v[138:141], v[146:149], v[32:47]
	s_waitcnt lgkmcnt(6)
	v_mfma_f32_32x32x16_bf16 v[16:31], v[138:141], v[150:153], v[16:31]
	s_waitcnt lgkmcnt(5)
	v_mfma_f32_32x32x16_bf16 v[0:15], v[138:141], v[154:157], v[0:15]
	s_waitcnt lgkmcnt(3)
	v_mfma_f32_32x32x16_bf16 v[48:63], v[70:73], v[122:125], v[48:63]
	s_waitcnt lgkmcnt(2)
	v_mfma_f32_32x32x16_bf16 v[32:47], v[70:73], v[126:129], v[32:47]
	s_waitcnt lgkmcnt(1)
	v_mfma_f32_32x32x16_bf16 v[16:31], v[70:73], v[130:133], v[16:31]
	s_waitcnt lgkmcnt(0)
	v_mfma_f32_32x32x16_bf16 v[0:15], v[70:73], v[134:137], v[0:15]
	v_mov_b32_e32 v70, s10
	ds_read_b64 v[70:71], v70
	s_mov_b64 s[0:1], -1
	s_cmp_gt_i32 s66, 63
	v_lshlrev_b32_e32 v121, 2, v64
	v_mbcnt_hi_u32_b32 v122, -1, v120
	s_waitcnt lgkmcnt(0)
	v_readfirstlane_b32 s66, v70
	v_readfirstlane_b32 s67, v71
	s_cbranch_scc0 .LBB0_642
	s_nop 3
	global_load_dword v71, v121, s[66:67] offset:512
	global_load_dword v70, v121, s[66:67] offset:640
	v_and_b32_e32 v124, 64, v122
	v_xor_b32_e32 v123, 1, v122
	v_add_u32_e32 v128, 64, v124
	v_mov_b32_e32 v72, v48
	v_mov_b32_e32 v73, v32
	v_cmp_lt_i32_e32 vcc, v123, v128
	v_pk_mul_f32 v[72:73], v[72:73], v[72:73]
	v_xor_b32_e32 v125, 2, v122
	v_cndmask_b32_e32 v123, v122, v123, vcc
	v_add_f32_e32 v72, v72, v73
	v_lshlrev_b32_e32 v123, 2, v123
	v_cmp_lt_i32_e32 vcc, v125, v128
	v_xor_b32_e32 v126, 4, v122
	v_xor_b32_e32 v127, 8, v122
	v_cndmask_b32_e32 v124, v122, v125, vcc
	v_lshlrev_b32_e32 v124, 2, v124
	v_add_f32_dpp v72, v72, v72 quad_perm:[1,0,3,2] row_mask:0xf bank_mask:0xf
	v_cmp_lt_i32_e32 vcc, v126, v128
	v_xor_b32_e32 v129, 16, v122
	s_cmp_gt_i32 s74, 63
	v_cndmask_b32_e32 v125, v122, v126, vcc
	v_lshlrev_b32_e32 v125, 2, v125
	v_add_f32_dpp v73, v72, v72 quad_perm:[2,3,0,1] row_mask:0xf bank_mask:0xf
	v_cmp_lt_i32_e32 vcc, v127, v128
	s_cselect_b64 s[68:69], -1, 0
	s_and_b64 s[0:1], s[68:69], exec
	v_cndmask_b32_e32 v127, v122, v127, vcc
	v_lshlrev_b32_e32 v127, 2, v127
	v_add_f32_dpp v130, v73, v73 row_half_mirror row_mask:0xf bank_mask:0xf
	s_nop 1
	v_mov_b32_dpp v131, v130 row_mirror row_mask:0xf bank_mask:0xf
	v_cmp_lt_i32_e32 vcc, v129, v128
	s_cselect_b32 s0, s11, 0x80
	s_and_b32 s76, s0, s73
	v_cndmask_b32_e32 v126, v122, v129, vcc
	v_lshlrev_b32_e32 v126, 2, v126
	v_add_f32_e32 v128, v130, v131
	v_mov_b32_e32 v129, v128
	s_nop 1
	v_permlane16_swap_b32_e32 v128, v129
	s_nop 0
	v_mov_b32_e32 v72, v32
	v_mov_b32_e32 v73, v48
	v_lshlrev_b32_e32 v142, 3, v64
	v_add_u32_e32 v130, s76, v80
	v_add_f32_e32 v128, v128, v129
	v_fmamk_f32 v128, v128, 0x3c800000, v119
	v_rsq_f32_e32 v128, v128
	s_cmp_lt_i32 s74, 64
	s_waitcnt vmcnt(0)
	v_pk_mul_f32 v[128:129], v[70:71], v[128:129] op_sel_hi:[1,0]
	s_nop 0
	v_pk_mul_f32 v[72:73], v[72:73], v[128:129]
	v_lshl_or_b32 v128, v130, 8, v142
	s_cbranch_scc1 .LBB0_579
	global_load_dwordx2 v[130:131], v128, s[8:9]
	s_waitcnt vmcnt(0)
	v_pk_mul_f32 v[134:135], v[72:73], v[130:131] op_sel_hi:[0,1]
	v_pk_mul_f32 v[132:133], v[72:73], v[130:131] op_sel:[1,1] op_sel_hi:[1,0]
	v_pk_fma_f32 v[72:73], v[72:73], v[130:131], v[134:135] op_sel:[1,1,0] op_sel_hi:[1,0,1] neg_lo:[0,0,1] neg_hi:[0,0,1]
	s_nop 0
	v_add_f32_e32 v72, v132, v134

.LBB0_647:
	s_ashr_i32 s0, s3, 31
	s_lshr_b32 s0, s0, 25
	s_add_i32 s0, s3, s0
	s_ashr_i32 s1, s0, 7
	s_lshl_b32 s68, s1, 3
	s_sub_i32 s1, 0x84, s68
	s_min_u32 s1, s1, 8
	v_cvt_f32_ubyte0_e32 v0, s1
	v_rcp_iflag_f32_e32 v0, v0
	s_sub_i32 s50, 0, s1
	s_and_b32 s0, s0, 0xffffff80
	s_sub_i32 s48, s3, s0
	v_mul_f32_e32 v0, 0x4f7ffffe, v0
	v_cvt_u32_f32_e32 v0, v0
	s_abs_i32 s49, s48
	s_ashr_i32 s0, s48, 31
	v_readfirstlane_b32 s72, v87
	v_readfirstlane_b32 s51, v0
	s_mul_i32 s50, s50, s51
	s_mul_hi_u32 s50, s51, s50
	s_add_i32 s51, s51, s50
	s_mul_hi_u32 s50, s49, s51
	s_mul_i32 s51, s50, s1
	s_sub_i32 s49, s49, s51
	s_add_i32 s69, s50, 1
	s_sub_i32 s51, s49, s1
	s_cmp_ge_u32 s49, s1
	s_cselect_b32 s50, s69, s50
	s_cselect_b32 s49, s51, s49
	s_add_i32 s51, s50, 1
	s_cmp_ge_u32 s49, s1
	s_cselect_b32 s49, s51, s50
	s_xor_b32 s49, s49, s0
	s_sub_i32 s0, s49, s0
	s_mul_i32 s1, s0, s1
	s_sub_i32 s1, s48, s1
	s_add_i32 s68, s68, s1
	s_lshl_b32 s48, s68, 7
	s_lshl_b32 s70, s0, 7
	s_ashr_i32 s49, s48, 31
	s_ashr_i32 s71, s70, 31
	s_lshl_b64 s[50:51], s[48:49], 9
	s_lshl_b64 s[70:71], s[70:71], 9
	s_add_u32 s50, s10, s50
	s_addc_u32 s51, s11, s51
	s_add_u32 s70, s52, s70
	v_readfirstlane_b32 s1, v80
	s_addc_u32 s71, s53, s71
	v_lshl_add_u64 v[70:71], s[50:51], 0, v[66:67]
	s_mov_b32 m0, s1
	v_readfirstlane_b32 s49, v81
	v_lshl_add_u64 v[146:147], s[70:71], 0, v[66:67]
	global_load_lds_dwordx4 v[70:71], off
	s_mov_b32 m0, s49
	v_readfirstlane_b32 s50, v82
	global_load_lds_dwordx4 v[146:147], off
	v_lshl_add_u64 v[0:1], v[70:71], 0, s[8:9]
	s_mov_b32 m0, s50
	v_readfirstlane_b32 s51, v83
	global_load_lds_dwordx4 v[0:1], off
	v_lshl_add_u64 v[0:1], v[146:147], 0, s[8:9]
	s_mov_b32 m0, s51
	v_readfirstlane_b32 s69, v84
	global_load_lds_dwordx4 v[0:1], off
	v_lshl_add_u64 v[0:1], v[70:71], 0, s[18:19]
	s_mov_b32 m0, s69
	v_readfirstlane_b32 s70, v85
	global_load_lds_dwordx4 v[0:1], off
	v_lshl_add_u64 v[0:1], v[146:147], 0, s[18:19]
	s_mov_b32 m0, s70
	v_readfirstlane_b32 s71, v86
	global_load_lds_dwordx4 v[0:1], off
	v_lshl_add_u64 v[0:1], v[70:71], 0, s[20:21]
	s_mov_b32 m0, s71
	v_readfirstlane_b32 s73, v88
	global_load_lds_dwordx4 v[0:1], off
	v_lshl_add_u64 v[0:1], v[146:147], 0, s[20:21]
	s_mov_b32 m0, s72
	v_readfirstlane_b32 s74, v89
	global_load_lds_dwordx4 v[0:1], off
	v_lshl_add_u64 v[0:1], v[70:71], 0, s[22:23]
	s_mov_b32 m0, s73
	s_waitcnt vmcnt(0)
	s_waitcnt vmcnt(0) lgkmcnt(0)
	s_barrier
	v_lshl_add_u64 v[2:3], v[146:147], 0, s[22:23]
	global_load_lds_dwordx4 v[0:1], off
	s_mov_b32 m0, s74
	v_readfirstlane_b32 s75, v90
	global_load_lds_dwordx4 v[2:3], off
	v_lshl_add_u64 v[0:1], v[70:71], 0, s[24:25]
	s_mov_b32 m0, s75
	v_readfirstlane_b32 s76, v91
	global_load_lds_dwordx4 v[0:1], off
	v_lshl_add_u64 v[0:1], v[146:147], 0, s[24:25]
	s_mov_b32 m0, s76
	v_readfirstlane_b32 s77, v92
	global_load_lds_dwordx4 v[0:1], off
	v_lshl_add_u64 v[0:1], v[70:71], 0, s[26:27]
	s_mov_b32 m0, s77
	v_readfirstlane_b32 s78, v93
	global_load_lds_dwordx4 v[0:1], off
	v_lshl_add_u64 v[0:1], v[146:147], 0, s[26:27]
	s_mov_b32 m0, s78
	v_readfirstlane_b32 s79, v94
	global_load_lds_dwordx4 v[0:1], off
	v_lshl_add_u64 v[0:1], v[70:71], 0, s[28:29]
	s_mov_b32 m0, s79
	v_readfirstlane_b32 s80, v95
	global_load_lds_dwordx4 v[0:1], off
	v_lshl_add_u64 v[0:1], v[146:147], 0, s[28:29]
	s_mov_b32 m0, s80
	s_nop 0
	global_load_lds_dwordx4 v[0:1], off
	ds_read_b128 v[0:3], v96
	ds_read_b128 v[4:7], v97 offset:16384
	ds_read_b128 v[8:11], v97 offset:20480
	ds_read_b128 v[12:15], v97 offset:24576
	ds_read_b128 v[106:109], v97 offset:28672
	ds_read_b128 v[110:113], v98
	ds_read_b128 v[114:117], v99 offset:16384
	ds_read_b128 v[118:121], v99 offset:20480
	ds_read_b128 v[122:125], v99 offset:24576
	ds_read_b128 v[126:129], v99 offset:28672
	s_waitcnt lgkmcnt(0)
	v_mfma_f32_32x32x16_bf16 v[48:63], v[0:3], v[4:7], 0
	v_mfma_f32_32x32x16_bf16 v[32:47], v[0:3], v[8:11], 0
	v_mfma_f32_32x32x16_bf16 v[16:31], v[0:3], v[12:15], 0
	v_mfma_f32_32x32x16_bf16 v[0:15], v[0:3], v[106:109], 0
	ds_read_b128 v[106:109], v100
	ds_read_b128 v[130:133], v101 offset:16384
	ds_read_b128 v[134:137], v101 offset:20480
	ds_read_b128 v[138:141], v101 offset:24576
	ds_read_b128 v[142:145], v101 offset:28672
	v_mfma_f32_32x32x16_bf16 v[48:63], v[110:113], v[114:117], v[48:63]
	v_mfma_f32_32x32x16_bf16 v[32:47], v[110:113], v[118:121], v[32:47]
	v_mfma_f32_32x32x16_bf16 v[16:31], v[110:113], v[122:125], v[16:31]
	v_mfma_f32_32x32x16_bf16 v[0:15], v[110:113], v[126:129], v[0:15]
	ds_read_b128 v[110:113], v102
	ds_read_b128 v[114:117], v75 offset:16384
	ds_read_b128 v[118:121], v75 offset:20480
	ds_read_b128 v[122:125], v75 offset:24576
	ds_read_b128 v[126:129], v75 offset:28672
	s_waitcnt lgkmcnt(0)
	v_mfma_f32_32x32x16_bf16 v[48:63], v[106:109], v[130:133], v[48:63]
	v_mfma_f32_32x32x16_bf16 v[32:47], v[106:109], v[134:137], v[32:47]
	v_mfma_f32_32x32x16_bf16 v[16:31], v[106:109], v[138:141], v[16:31]
	v_mfma_f32_32x32x16_bf16 v[0:15], v[106:109], v[142:145], v[0:15]
	v_mfma_f32_32x32x16_bf16 v[48:63], v[110:113], v[114:117], v[48:63]
	v_mfma_f32_32x32x16_bf16 v[32:47], v[110:113], v[118:121], v[32:47]
	v_mfma_f32_32x32x16_bf16 v[16:31], v[110:113], v[122:125], v[16:31]
	v_mfma_f32_32x32x16_bf16 v[0:15], v[110:113], v[126:129], v[0:15]
	s_mov_b32 m0, s1
	v_lshl_add_u64 v[106:107], v[70:71], 0, s[30:31]
	s_waitcnt vmcnt(0)
	s_waitcnt vmcnt(0)
	s_barrier
	global_load_lds_dwordx4 v[106:107], off
	v_lshl_add_u64 v[106:107], v[146:147], 0, s[30:31]
	s_mov_b32 m0, s49
	s_nop 0
	global_load_lds_dwordx4 v[106:107], off
	v_lshl_add_u64 v[106:107], v[70:71], 0, s[34:35]
	s_mov_b32 m0, s50
	s_nop 0
	global_load_lds_dwordx4 v[106:107], off
	v_lshl_add_u64 v[106:107], v[146:147], 0, s[34:35]
	s_mov_b32 m0, s51
	s_nop 0
	global_load_lds_dwordx4 v[106:107], off
	v_lshl_add_u64 v[106:107], v[70:71], 0, s[36:37]
	s_mov_b32 m0, s69
	s_nop 0
	global_load_lds_dwordx4 v[106:107], off
	v_lshl_add_u64 v[106:107], v[146:147], 0, s[36:37]
	s_mov_b32 m0, s70
	s_nop 0
	global_load_lds_dwordx4 v[106:107], off
	v_lshl_add_u64 v[106:107], v[70:71], 0, s[38:39]
	s_mov_b32 m0, s71
	s_nop 0
	global_load_lds_dwordx4 v[106:107], off
	v_lshl_add_u64 v[106:107], v[146:147], 0, s[38:39]
	s_mov_b32 m0, s72
	s_nop 0
	global_load_lds_dwordx4 v[106:107], off
	ds_read_b128 v[106:109], v96 offset:32768
	ds_read_b128 v[110:113], v97 offset:49152
	ds_read_b128 v[114:117], v97 offset:53248
	ds_read_b128 v[118:121], v97 offset:57344
	ds_read_b128 v[122:125], v97 offset:61440
	ds_read_b128 v[126:129], v98 offset:32768
	ds_read_b128 v[130:133], v99 offset:49152
	ds_read_b128 v[134:137], v99 offset:53248
	ds_read_b128 v[138:141], v99 offset:57344
	ds_read_b128 v[142:145], v99 offset:61440
	s_waitcnt lgkmcnt(0)
	v_mfma_f32_32x32x16_bf16 v[48:63], v[106:109], v[110:113], v[48:63]
	v_mfma_f32_32x32x16_bf16 v[32:47], v[106:109], v[114:117], v[32:47]
	v_mfma_f32_32x32x16_bf16 v[16:31], v[106:109], v[118:121], v[16:31]
	v_mfma_f32_32x32x16_bf16 v[0:15], v[106:109], v[122:125], v[0:15]
	ds_read_b128 v[106:109], v100 offset:32768
	ds_read_b128 v[110:113], v101 offset:49152
	ds_read_b128 v[114:117], v101 offset:53248
	ds_read_b128 v[118:121], v101 offset:57344
	ds_read_b128 v[122:125], v101 offset:61440
	v_mfma_f32_32x32x16_bf16 v[48:63], v[126:129], v[130:133], v[48:63]
	v_mfma_f32_32x32x16_bf16 v[32:47], v[126:129], v[134:137], v[32:47]
	v_mfma_f32_32x32x16_bf16 v[16:31], v[126:129], v[138:141], v[16:31]
	v_mfma_f32_32x32x16_bf16 v[0:15], v[126:129], v[142:145], v[0:15]
	ds_read_b128 v[126:129], v102 offset:32768
	ds_read_b128 v[130:133], v75 offset:49152
	ds_read_b128 v[134:137], v75 offset:53248
	ds_read_b128 v[138:141], v75 offset:57344
	ds_read_b128 v[142:145], v75 offset:61440
	s_waitcnt lgkmcnt(0)
	v_mfma_f32_32x32x16_bf16 v[48:63], v[106:109], v[110:113], v[48:63]
	v_mfma_f32_32x32x16_bf16 v[32:47], v[106:109], v[114:117], v[32:47]
	v_mfma_f32_32x32x16_bf16 v[16:31], v[106:109], v[118:121], v[16:31]
	v_mfma_f32_32x32x16_bf16 v[0:15], v[106:109], v[122:125], v[0:15]
	v_mfma_f32_32x32x16_bf16 v[48:63], v[126:129], v[130:133], v[48:63]
	v_mfma_f32_32x32x16_bf16 v[32:47], v[126:129], v[134:137], v[32:47]
	v_mfma_f32_32x32x16_bf16 v[16:31], v[126:129], v[138:141], v[16:31]
	v_mfma_f32_32x32x16_bf16 v[0:15], v[126:129], v[142:145], v[0:15]
	s_mov_b32 m0, s73
	v_lshl_add_u64 v[106:107], v[70:71], 0, s[40:41]
	s_waitcnt vmcnt(0)
	s_waitcnt vmcnt(0)
	s_barrier
	v_lshl_add_u64 v[108:109], v[146:147], 0, s[40:41]
	global_load_lds_dwordx4 v[106:107], off
	s_mov_b32 m0, s74
	v_lshl_add_u64 v[106:107], v[70:71], 0, s[42:43]
	global_load_lds_dwordx4 v[108:109], off
	s_mov_b32 m0, s75
	s_nop 0
	global_load_lds_dwordx4 v[106:107], off
	v_lshl_add_u64 v[106:107], v[146:147], 0, s[42:43]
	s_mov_b32 m0, s76
	s_nop 0
	global_load_lds_dwordx4 v[106:107], off
	v_lshl_add_u64 v[106:107], v[70:71], 0, s[44:45]
	s_mov_b32 m0, s77
	v_lshl_add_u64 v[70:71], v[70:71], 0, s[46:47]
	global_load_lds_dwordx4 v[106:107], off
	v_lshl_add_u64 v[106:107], v[146:147], 0, s[44:45]
	s_mov_b32 m0, s78
	s_nop 0
	global_load_lds_dwordx4 v[106:107], off
	s_mov_b32 m0, s79
	s_nop 0
	global_load_lds_dwordx4 v[70:71], off
	v_lshl_add_u64 v[70:71], v[146:147], 0, s[46:47]
	s_mov_b32 m0, s80
	s_nop 0
	global_load_lds_dwordx4 v[70:71], off
	ds_read_b128 v[106:109], v96
	ds_read_b128 v[110:113], v97 offset:16384
	ds_read_b128 v[114:117], v97 offset:20480
	ds_read_b128 v[118:121], v97 offset:24576
	ds_read_b128 v[122:125], v97 offset:28672
	ds_read_b128 v[126:129], v98
	ds_read_b128 v[130:133], v99 offset:16384
	ds_read_b128 v[134:137], v99 offset:20480
	ds_read_b128 v[138:141], v99 offset:24576
	ds_read_b128 v[142:145], v99 offset:28672
	s_waitcnt lgkmcnt(0)
	v_mfma_f32_32x32x16_bf16 v[48:63], v[106:109], v[110:113], v[48:63]
	v_mfma_f32_32x32x16_bf16 v[32:47], v[106:109], v[114:117], v[32:47]
	v_mfma_f32_32x32x16_bf16 v[16:31], v[106:109], v[118:121], v[16:31]
	v_mfma_f32_32x32x16_bf16 v[0:15], v[106:109], v[122:125], v[0:15]
	ds_read_b128 v[106:109], v100
	ds_read_b128 v[110:113], v101 offset:16384
	ds_read_b128 v[114:117], v101 offset:20480
	ds_read_b128 v[118:121], v101 offset:24576
	ds_read_b128 v[122:125], v101 offset:28672
	v_mfma_f32_32x32x16_bf16 v[48:63], v[126:129], v[130:133], v[48:63]
	v_mfma_f32_32x32x16_bf16 v[32:47], v[126:129], v[134:137], v[32:47]
	v_mfma_f32_32x32x16_bf16 v[16:31], v[126:129], v[138:141], v[16:31]
	v_mfma_f32_32x32x16_bf16 v[0:15], v[126:129], v[142:145], v[0:15]
	ds_read_b128 v[126:129], v102
	ds_read_b128 v[130:133], v75 offset:16384
	ds_read_b128 v[134:137], v75 offset:20480
	ds_read_b128 v[138:141], v75 offset:24576
	ds_read_b128 v[142:145], v75 offset:28672
	s_waitcnt lgkmcnt(0)
	v_mfma_f32_32x32x16_bf16 v[48:63], v[106:109], v[110:113], v[48:63]
	v_mfma_f32_32x32x16_bf16 v[32:47], v[106:109], v[114:117], v[32:47]
	v_mfma_f32_32x32x16_bf16 v[16:31], v[106:109], v[118:121], v[16:31]
	v_mfma_f32_32x32x16_bf16 v[0:15], v[106:109], v[122:125], v[0:15]
	v_mfma_f32_32x32x16_bf16 v[48:63], v[126:129], v[130:133], v[48:63]
	v_mfma_f32_32x32x16_bf16 v[32:47], v[126:129], v[134:137], v[32:47]
	v_mfma_f32_32x32x16_bf16 v[16:31], v[126:129], v[138:141], v[16:31]
	v_mfma_f32_32x32x16_bf16 v[0:15], v[126:129], v[142:145], v[0:15]
	s_waitcnt vmcnt(0)
	s_waitcnt vmcnt(0)
	s_barrier
	ds_read_b128 v[106:109], v99 offset:61440
	ds_read_b128 v[110:113], v99 offset:57344
	ds_read_b128 v[114:117], v99 offset:53248
	ds_read_b128 v[118:121], v99 offset:49152
	ds_read_b128 v[122:125], v98 offset:32768
	ds_read_b128 v[126:129], v97 offset:61440
	ds_read_b128 v[130:133], v97 offset:57344
	ds_read_b128 v[134:137], v97 offset:53248
	ds_read_b128 v[138:141], v97 offset:49152
	ds_read_b128 v[142:145], v96 offset:32768
	s_waitcnt lgkmcnt(0)
	v_mfma_f32_32x32x16_bf16 v[48:63], v[142:145], v[138:141], v[48:63]
	v_mfma_f32_32x32x16_bf16 v[32:47], v[142:145], v[134:137], v[32:47]
	v_mfma_f32_32x32x16_bf16 v[16:31], v[142:145], v[130:133], v[16:31]
	v_mfma_f32_32x32x16_bf16 v[0:15], v[142:145], v[126:129], v[0:15]
	ds_read_b128 v[126:129], v100 offset:32768
	ds_read_b128 v[130:133], v101 offset:49152
	ds_read_b128 v[134:137], v101 offset:53248
	ds_read_b128 v[138:141], v101 offset:57344
	ds_read_b128 v[142:145], v101 offset:61440
	v_mfma_f32_32x32x16_bf16 v[48:63], v[122:125], v[118:121], v[48:63]
	v_mfma_f32_32x32x16_bf16 v[32:47], v[122:125], v[114:117], v[32:47]
	v_mfma_f32_32x32x16_bf16 v[16:31], v[122:125], v[110:113], v[16:31]
	v_mfma_f32_32x32x16_bf16 v[0:15], v[122:125], v[106:109], v[0:15]
	ds_read_b128 v[106:109], v102 offset:32768
	ds_read_b128 v[110:113], v75 offset:49152
	ds_read_b128 v[114:117], v75 offset:53248
	ds_read_b128 v[118:121], v75 offset:57344
	ds_read_b128 v[122:125], v75 offset:61440
	s_waitcnt lgkmcnt(8)
	v_mfma_f32_32x32x16_bf16 v[48:63], v[126:129], v[130:133], v[48:63]
	s_waitcnt lgkmcnt(7)
	v_mfma_f32_32x32x16_bf16 v[32:47], v[126:129], v[134:137], v[32:47]
	s_waitcnt lgkmcnt(6)
	v_mfma_f32_32x32x16_bf16 v[16:31], v[126:129], v[138:141], v[16:31]
	s_waitcnt lgkmcnt(5)
	v_mfma_f32_32x32x16_bf16 v[0:15], v[126:129], v[142:145], v[0:15]
	s_waitcnt lgkmcnt(3)
	v_mfma_f32_32x32x16_bf16 v[48:63], v[106:109], v[110:113], v[48:63]
	s_waitcnt lgkmcnt(2)
	v_mfma_f32_32x32x16_bf16 v[32:47], v[106:109], v[114:117], v[32:47]
	s_waitcnt lgkmcnt(1)
	v_mfma_f32_32x32x16_bf16 v[16:31], v[106:109], v[118:121], v[16:31]
	s_waitcnt lgkmcnt(0)
	v_mfma_f32_32x32x16_bf16 v[0:15], v[106:109], v[122:125], v[0:15]
	s_ashr_i32 s49, s0, 1
	s_bitcmp1_b32 s0, 0
	s_cselect_b64 s[50:51], -1, 0
	s_mov_b64 s[0:1], -1
	s_and_b64 vcc, exec, s[50:51]
	s_cbranch_vccz .LBB0_653
	s_cmp_gt_i32 s68, 63
	s_cselect_b64 s[0:1], -1, 0
	s_cmp_lt_i32 s68, 64
	s_mov_b64 s[50:51], -1
	s_cbranch_scc0 .LBB0_650
	s_ashr_i32 s69, s68, 1
	s_and_b32 s70, s48, 0x80
	s_mov_b64 s[50:51], 0

.Lgk_loop_p6:
	s_waitcnt vmcnt(8)
	s_barrier
	ds_read_b128 v[70:73], v158
	ds_read_b128 v[74:77], v159 offset:16384
	ds_read_b128 v[78:81], v159 offset:20480
	ds_read_b128 v[82:85], v159 offset:24576
	ds_read_b128 v[86:89], v159 offset:28672
	ds_read_b128 v[90:93], v160
	ds_read_b128 v[94:97], v161 offset:16384
	ds_read_b128 v[98:101], v161 offset:20480
	ds_read_b128 v[102:105], v161 offset:24576
	ds_read_b128 v[106:109], v161 offset:28672
	ds_read_b128 v[110:113], v162
	ds_read_b128 v[206:209], v163 offset:16384
	ds_read_b128 v[210:213], v163 offset:20480
	ds_read_b128 v[214:217], v163 offset:24576
	ds_read_b128 v[218:221], v163 offset:28672
	ds_read_b128 v[222:225], v164
	ds_read_b128 v[226:229], v165 offset:16384
	ds_read_b128 v[230:233], v165 offset:20480
	ds_read_b128 v[234:237], v165 offset:24576
	ds_read_b128 v[238:241], v165 offset:28672
	s_waitcnt lgkmcnt(0)
	s_barrier
	s_mov_b32 m0, s36
	v_mfma_f32_32x32x16_bf16 v[48:63], v[70:73], v[74:77], v[48:63]
	v_mfma_f32_32x32x16_bf16 v[32:47], v[70:73], v[78:81], v[32:47]
	global_load_lds_dwordx4 v254, s[18:19]
	s_add_u32 m0, m0, 0x1000
	v_mfma_f32_32x32x16_bf16 v[16:31], v[70:73], v[82:85], v[16:31]
	v_mfma_f32_32x32x16_bf16 v[0:15], v[70:73], v[86:89], v[0:15]
	global_load_lds_dwordx4 v254, s[20:21]
	s_add_u32 m0, m0, 0x1000
	v_mfma_f32_32x32x16_bf16 v[48:63], v[90:93], v[94:97], v[48:63]
	v_mfma_f32_32x32x16_bf16 v[32:47], v[90:93], v[98:101], v[32:47]
	global_load_lds_dwordx4 v254, s[22:23]
	s_add_u32 m0, m0, 0x1000
	v_mfma_f32_32x32x16_bf16 v[16:31], v[90:93], v[102:105], v[16:31]
	v_mfma_f32_32x32x16_bf16 v[0:15], v[90:93], v[106:109], v[0:15]
	global_load_lds_dwordx4 v254, s[24:25]
	s_add_u32 m0, m0, 0x1000
	v_mfma_f32_32x32x16_bf16 v[48:63], v[110:113], v[206:209], v[48:63]
	v_mfma_f32_32x32x16_bf16 v[32:47], v[110:113], v[210:213], v[32:47]
	global_load_lds_dwordx4 v254, s[26:27]
	s_add_u32 m0, m0, 0x1000
	v_mfma_f32_32x32x16_bf16 v[16:31], v[110:113], v[214:217], v[16:31]
	v_mfma_f32_32x32x16_bf16 v[0:15], v[110:113], v[218:221], v[0:15]
	global_load_lds_dwordx4 v254, s[28:29]
	s_add_u32 m0, m0, 0x1000
	v_mfma_f32_32x32x16_bf16 v[48:63], v[222:225], v[226:229], v[48:63]
	v_mfma_f32_32x32x16_bf16 v[32:47], v[222:225], v[230:233], v[32:47]
	global_load_lds_dwordx4 v254, s[30:31]
	s_add_u32 m0, m0, 0x1000
	v_mfma_f32_32x32x16_bf16 v[16:31], v[222:225], v[234:237], v[16:31]
	v_mfma_f32_32x32x16_bf16 v[0:15], v[222:225], v[238:241], v[0:15]
	global_load_lds_dwordx4 v254, s[34:35]
	v_add_u32_e32 v254, 0x80, v254
	s_waitcnt vmcnt(8)
	s_barrier
	ds_read_b128 v[70:73], v158 offset:32768
	ds_read_b128 v[74:77], v159 offset:49152
	ds_read_b128 v[78:81], v159 offset:53248
	ds_read_b128 v[82:85], v159 offset:57344
	ds_read_b128 v[86:89], v159 offset:61440
	ds_read_b128 v[90:93], v160 offset:32768
	ds_read_b128 v[94:97], v161 offset:49152
	ds_read_b128 v[98:101], v161 offset:53248
	ds_read_b128 v[102:105], v161 offset:57344
	ds_read_b128 v[106:109], v161 offset:61440
	ds_read_b128 v[110:113], v162 offset:32768
	ds_read_b128 v[206:209], v163 offset:49152
	ds_read_b128 v[210:213], v163 offset:53248
	ds_read_b128 v[214:217], v163 offset:57344
	ds_read_b128 v[218:221], v163 offset:61440
	ds_read_b128 v[222:225], v164 offset:32768
	ds_read_b128 v[226:229], v165 offset:49152
	ds_read_b128 v[230:233], v165 offset:53248
	ds_read_b128 v[234:237], v165 offset:57344
	ds_read_b128 v[238:241], v165 offset:61440
	s_waitcnt lgkmcnt(0)
	s_barrier
	s_add_u32 m0, s36, 0x8000
	v_mfma_f32_32x32x16_bf16 v[48:63], v[70:73], v[74:77], v[48:63]
	v_mfma_f32_32x32x16_bf16 v[32:47], v[70:73], v[78:81], v[32:47]
	global_load_lds_dwordx4 v254, s[18:19]
	s_add_u32 m0, m0, 0x1000
	v_mfma_f32_32x32x16_bf16 v[16:31], v[70:73], v[82:85], v[16:31]
	v_mfma_f32_32x32x16_bf16 v[0:15], v[70:73], v[86:89], v[0:15]
	global_load_lds_dwordx4 v254, s[20:21]
	s_add_u32 m0, m0, 0x1000
	v_mfma_f32_32x32x16_bf16 v[48:63], v[90:93], v[94:97], v[48:63]
	v_mfma_f32_32x32x16_bf16 v[32:47], v[90:93], v[98:101], v[32:47]
	global_load_lds_dwordx4 v254, s[22:23]
	s_add_u32 m0, m0, 0x1000
	v_mfma_f32_32x32x16_bf16 v[16:31], v[90:93], v[102:105], v[16:31]
	v_mfma_f32_32x32x16_bf16 v[0:15], v[90:93], v[106:109], v[0:15]
	global_load_lds_dwordx4 v254, s[24:25]
	s_add_u32 m0, m0, 0x1000
	v_mfma_f32_32x32x16_bf16 v[48:63], v[110:113], v[206:209], v[48:63]
	v_mfma_f32_32x32x16_bf16 v[32:47], v[110:113], v[210:213], v[32:47]
	global_load_lds_dwordx4 v254, s[26:27]
	s_add_u32 m0, m0, 0x1000
	v_mfma_f32_32x32x16_bf16 v[16:31], v[110:113], v[214:217], v[16:31]
	v_mfma_f32_32x32x16_bf16 v[0:15], v[110:113], v[218:221], v[0:15]
	global_load_lds_dwordx4 v254, s[28:29]
	s_add_u32 m0, m0, 0x1000
	v_mfma_f32_32x32x16_bf16 v[48:63], v[222:225], v[226:229], v[48:63]
	v_mfma_f32_32x32x16_bf16 v[32:47], v[222:225], v[230:233], v[32:47]
	global_load_lds_dwordx4 v254, s[30:31]
	s_add_u32 m0, m0, 0x1000
	v_mfma_f32_32x32x16_bf16 v[16:31], v[222:225], v[234:237], v[16:31]
	v_mfma_f32_32x32x16_bf16 v[0:15], v[222:225], v[238:241], v[0:15]
	global_load_lds_dwordx4 v254, s[34:35]
	v_add_u32_e32 v254, 0x80, v254
	s_sub_u32 s37, s37, 1
	s_cmp_lg_u32 s37, 0
	s_cbranch_scc1 .Lgk_loop_p6
	s_add_u32 s40, s3, s33
	s_cmp_gt_u32 s40, 0x3ff
	s_cbranch_scc1 .Lgk_tailplain_p6
.LBB0_703_pf_p6:
	s_ashr_i32 s41, s40, 31
	s_lshr_b32 s41, s41, 26
	s_add_i32 s41, s40, s41
	s_ashr_i32 s42, s41, 6
	s_andn2_b32 s41, s41, 63
	s_sub_i32 s41, s40, s41
	s_ashr_i32 s43, s41, 31
	s_lshr_b32 s43, s43, 29
	s_add_i32 s43, s41, s43
	s_ashr_i32 s48, s43, 3
	s_and_b32 s43, s43, -8
	s_lshl_b32 s42, s42, 3
	s_sub_i32 s41, s41, s43
	s_add_i32 s41, s41, s42
	s_lshl_b32 s44, s41, 7
	s_ashr_i32 s45, s44, 31
	s_lshl_b32 s46, s48, 7
	s_lshl_b64 s[42:43], s[44:45], 11
	s_ashr_i32 s47, s46, 31
	s_lshl_b32 s38, s44, 11
	s_add_u32 s18, s14, s38
	s_addc_u32 s19, s15, 0
	s_add_u32 s18, s18, 0xb79f000
	s_addc_u32 s19, s19, 0
	s_add_u32 s20, s18, 0x10000
	s_addc_u32 s21, s19, 0
	s_add_u32 s22, s20, 0x10000
	s_addc_u32 s23, s21, 0
	s_add_u32 s24, s22, 0x10000
	s_addc_u32 s25, s23, 0
	s_lshl_b32 s38, s46, 11
	s_add_u32 s26, s14, s38
	s_addc_u32 s27, s15, 0
	s_add_u32 s26, s26, 0x3a0000
	s_addc_u32 s27, s27, 0
	s_add_u32 s28, s26, 0x10000
	s_addc_u32 s29, s27, 0
	s_add_u32 s30, s28, 0x10000
	s_addc_u32 s31, s29, 0
	s_add_u32 s34, s30, 0x10000
	s_addc_u32 s35, s31, 0
	v_mov_b32_e32 v254, v64
	s_mov_b32 s39, 1
	s_waitcnt vmcnt(8)
	s_barrier
	ds_read_b128 v[70:73], v158
	ds_read_b128 v[74:77], v159 offset:16384
	ds_read_b128 v[78:81], v159 offset:20480
	ds_read_b128 v[82:85], v159 offset:24576
	ds_read_b128 v[86:89], v159 offset:28672
	ds_read_b128 v[90:93], v160
	ds_read_b128 v[94:97], v161 offset:16384
	ds_read_b128 v[98:101], v161 offset:20480
	ds_read_b128 v[102:105], v161 offset:24576
	ds_read_b128 v[106:109], v161 offset:28672
	ds_read_b128 v[110:113], v162
	ds_read_b128 v[206:209], v163 offset:16384
	ds_read_b128 v[210:213], v163 offset:20480
	ds_read_b128 v[214:217], v163 offset:24576
	ds_read_b128 v[218:221], v163 offset:28672
	ds_read_b128 v[222:225], v164
	ds_read_b128 v[226:229], v165 offset:16384
	ds_read_b128 v[230:233], v165 offset:20480
	ds_read_b128 v[234:237], v165 offset:24576
	ds_read_b128 v[238:241], v165 offset:28672
	s_waitcnt lgkmcnt(0)
	s_barrier
	s_mov_b32 m0, s36
	v_mfma_f32_32x32x16_bf16 v[48:63], v[70:73], v[74:77], v[48:63]
	v_mfma_f32_32x32x16_bf16 v[32:47], v[70:73], v[78:81], v[32:47]
	global_load_lds_dwordx4 v254, s[18:19]
	s_add_u32 m0, m0, 0x1000
	v_mfma_f32_32x32x16_bf16 v[16:31], v[70:73], v[82:85], v[16:31]
	v_mfma_f32_32x32x16_bf16 v[0:15], v[70:73], v[86:89], v[0:15]
	global_load_lds_dwordx4 v254, s[20:21]
	s_add_u32 m0, m0, 0x1000
	v_mfma_f32_32x32x16_bf16 v[48:63], v[90:93], v[94:97], v[48:63]
	v_mfma_f32_32x32x16_bf16 v[32:47], v[90:93], v[98:101], v[32:47]
	global_load_lds_dwordx4 v254, s[22:23]
	s_add_u32 m0, m0, 0x1000
	v_mfma_f32_32x32x16_bf16 v[16:31], v[90:93], v[102:105], v[16:31]
	v_mfma_f32_32x32x16_bf16 v[0:15], v[90:93], v[106:109], v[0:15]
	global_load_lds_dwordx4 v254, s[24:25]
	s_add_u32 m0, m0, 0x1000
	v_mfma_f32_32x32x16_bf16 v[48:63], v[110:113], v[206:209], v[48:63]
	v_mfma_f32_32x32x16_bf16 v[32:47], v[110:113], v[210:213], v[32:47]
	global_load_lds_dwordx4 v254, s[26:27]
	s_add_u32 m0, m0, 0x1000
	v_mfma_f32_32x32x16_bf16 v[16:31], v[110:113], v[214:217], v[16:31]
	v_mfma_f32_32x32x16_bf16 v[0:15], v[110:113], v[218:221], v[0:15]
	global_load_lds_dwordx4 v254, s[28:29]
	s_add_u32 m0, m0, 0x1000
	v_mfma_f32_32x32x16_bf16 v[48:63], v[222:225], v[226:229], v[48:63]
	v_mfma_f32_32x32x16_bf16 v[32:47], v[222:225], v[230:233], v[32:47]
	global_load_lds_dwordx4 v254, s[30:31]
	s_add_u32 m0, m0, 0x1000
	v_mfma_f32_32x32x16_bf16 v[16:31], v[222:225], v[234:237], v[16:31]
	v_mfma_f32_32x32x16_bf16 v[0:15], v[222:225], v[238:241], v[0:15]
	global_load_lds_dwordx4 v254, s[34:35]
	v_add_u32_e32 v254, 0x80, v254
	s_waitcnt vmcnt(8)
	s_barrier
	ds_read_b128 v[70:73], v158 offset:32768
	ds_read_b128 v[74:77], v159 offset:49152
	ds_read_b128 v[78:81], v159 offset:53248
	ds_read_b128 v[82:85], v159 offset:57344
	ds_read_b128 v[86:89], v159 offset:61440
	ds_read_b128 v[90:93], v160 offset:32768
	ds_read_b128 v[94:97], v161 offset:49152
	ds_read_b128 v[98:101], v161 offset:53248
	ds_read_b128 v[102:105], v161 offset:57344
	ds_read_b128 v[106:109], v161 offset:61440
	ds_read_b128 v[110:113], v162 offset:32768
	ds_read_b128 v[206:209], v163 offset:49152
	ds_read_b128 v[210:213], v163 offset:53248
	ds_read_b128 v[214:217], v163 offset:57344
	ds_read_b128 v[218:221], v163 offset:61440
	ds_read_b128 v[222:225], v164 offset:32768
	ds_read_b128 v[226:229], v165 offset:49152
	ds_read_b128 v[230:233], v165 offset:53248
	ds_read_b128 v[234:237], v165 offset:57344
	ds_read_b128 v[238:241], v165 offset:61440
	s_waitcnt lgkmcnt(0)
	s_barrier
	s_add_u32 m0, s36, 0x8000
	v_mfma_f32_32x32x16_bf16 v[48:63], v[70:73], v[74:77], v[48:63]
	v_mfma_f32_32x32x16_bf16 v[32:47], v[70:73], v[78:81], v[32:47]
	global_load_lds_dwordx4 v254, s[18:19]
	s_add_u32 m0, m0, 0x1000
	v_mfma_f32_32x32x16_bf16 v[16:31], v[70:73], v[82:85], v[16:31]
	v_mfma_f32_32x32x16_bf16 v[0:15], v[70:73], v[86:89], v[0:15]
	global_load_lds_dwordx4 v254, s[20:21]
	s_add_u32 m0, m0, 0x1000
	v_mfma_f32_32x32x16_bf16 v[48:63], v[90:93], v[94:97], v[48:63]
	v_mfma_f32_32x32x16_bf16 v[32:47], v[90:93], v[98:101], v[32:47]
	global_load_lds_dwordx4 v254, s[22:23]
	s_add_u32 m0, m0, 0x1000
	v_mfma_f32_32x32x16_bf16 v[16:31], v[90:93], v[102:105], v[16:31]
	v_mfma_f32_32x32x16_bf16 v[0:15], v[90:93], v[106:109], v[0:15]
	global_load_lds_dwordx4 v254, s[24:25]
	s_add_u32 m0, m0, 0x1000
	v_mfma_f32_32x32x16_bf16 v[48:63], v[110:113], v[206:209], v[48:63]
	v_mfma_f32_32x32x16_bf16 v[32:47], v[110:113], v[210:213], v[32:47]
	global_load_lds_dwordx4 v254, s[26:27]
	s_add_u32 m0, m0, 0x1000
	v_mfma_f32_32x32x16_bf16 v[16:31], v[110:113], v[214:217], v[16:31]
	v_mfma_f32_32x32x16_bf16 v[0:15], v[110:113], v[218:221], v[0:15]
	global_load_lds_dwordx4 v254, s[28:29]
	s_add_u32 m0, m0, 0x1000
	v_mfma_f32_32x32x16_bf16 v[48:63], v[222:225], v[226:229], v[48:63]
	v_mfma_f32_32x32x16_bf16 v[32:47], v[222:225], v[230:233], v[32:47]
	global_load_lds_dwordx4 v254, s[30:31]
	s_add_u32 m0, m0, 0x1000
	v_mfma_f32_32x32x16_bf16 v[16:31], v[222:225], v[234:237], v[16:31]
	v_mfma_f32_32x32x16_bf16 v[0:15], v[222:225], v[238:241], v[0:15]
	global_load_lds_dwordx4 v254, s[34:35]
	v_add_u32_e32 v254, 0x80, v254
	s_branch .LBB0_707
.Lgk_tailplain_p6:
	s_mov_b32 s39, 0
	s_waitcnt vmcnt(8)
	s_barrier
	ds_read_b128 v[70:73], v158
	ds_read_b128 v[74:77], v159 offset:16384
	ds_read_b128 v[78:81], v159 offset:20480
	ds_read_b128 v[82:85], v159 offset:24576
	ds_read_b128 v[86:89], v159 offset:28672
	ds_read_b128 v[90:93], v160
	ds_read_b128 v[94:97], v161 offset:16384
	ds_read_b128 v[98:101], v161 offset:20480
	ds_read_b128 v[102:105], v161 offset:24576
	ds_read_b128 v[106:109], v161 offset:28672
	ds_read_b128 v[110:113], v162
	ds_read_b128 v[206:209], v163 offset:16384
	ds_read_b128 v[210:213], v163 offset:20480
	ds_read_b128 v[214:217], v163 offset:24576
	ds_read_b128 v[218:221], v163 offset:28672
	ds_read_b128 v[222:225], v164
	ds_read_b128 v[226:229], v165 offset:16384
	ds_read_b128 v[230:233], v165 offset:20480
	ds_read_b128 v[234:237], v165 offset:24576
	ds_read_b128 v[238:241], v165 offset:28672
	s_waitcnt lgkmcnt(0)
	s_barrier
	v_mfma_f32_32x32x16_bf16 v[48:63], v[70:73], v[74:77], v[48:63]
	v_mfma_f32_32x32x16_bf16 v[32:47], v[70:73], v[78:81], v[32:47]
	v_mfma_f32_32x32x16_bf16 v[16:31], v[70:73], v[82:85], v[16:31]
	v_mfma_f32_32x32x16_bf16 v[0:15], v[70:73], v[86:89], v[0:15]
	v_mfma_f32_32x32x16_bf16 v[48:63], v[90:93], v[94:97], v[48:63]
	v_mfma_f32_32x32x16_bf16 v[32:47], v[90:93], v[98:101], v[32:47]
	v_mfma_f32_32x32x16_bf16 v[16:31], v[90:93], v[102:105], v[16:31]
	v_mfma_f32_32x32x16_bf16 v[0:15], v[90:93], v[106:109], v[0:15]
	v_mfma_f32_32x32x16_bf16 v[48:63], v[110:113], v[206:209], v[48:63]
	v_mfma_f32_32x32x16_bf16 v[32:47], v[110:113], v[210:213], v[32:47]
	v_mfma_f32_32x32x16_bf16 v[16:31], v[110:113], v[214:217], v[16:31]
	v_mfma_f32_32x32x16_bf16 v[0:15], v[110:113], v[218:221], v[0:15]
	v_mfma_f32_32x32x16_bf16 v[48:63], v[222:225], v[226:229], v[48:63]
	v_mfma_f32_32x32x16_bf16 v[32:47], v[222:225], v[230:233], v[32:47]
	v_mfma_f32_32x32x16_bf16 v[16:31], v[222:225], v[234:237], v[16:31]
	v_mfma_f32_32x32x16_bf16 v[0:15], v[222:225], v[238:241], v[0:15]
	s_waitcnt vmcnt(0)
	s_barrier
	ds_read_b128 v[70:73], v158 offset:32768
	ds_read_b128 v[74:77], v159 offset:49152
	ds_read_b128 v[78:81], v159 offset:53248
	ds_read_b128 v[82:85], v159 offset:57344
	ds_read_b128 v[86:89], v159 offset:61440
	ds_read_b128 v[90:93], v160 offset:32768
	ds_read_b128 v[94:97], v161 offset:49152
	ds_read_b128 v[98:101], v161 offset:53248
	ds_read_b128 v[102:105], v161 offset:57344
	ds_read_b128 v[106:109], v161 offset:61440
	ds_read_b128 v[110:113], v162 offset:32768
	ds_read_b128 v[206:209], v163 offset:49152
	ds_read_b128 v[210:213], v163 offset:53248
	ds_read_b128 v[214:217], v163 offset:57344
	ds_read_b128 v[218:221], v163 offset:61440
	ds_read_b128 v[222:225], v164 offset:32768
	ds_read_b128 v[226:229], v165 offset:49152
	ds_read_b128 v[230:233], v165 offset:53248
	ds_read_b128 v[234:237], v165 offset:57344
	ds_read_b128 v[238:241], v165 offset:61440
	s_waitcnt lgkmcnt(0)
	s_barrier
	v_mfma_f32_32x32x16_bf16 v[48:63], v[70:73], v[74:77], v[48:63]
	v_mfma_f32_32x32x16_bf16 v[32:47], v[70:73], v[78:81], v[32:47]
	v_mfma_f32_32x32x16_bf16 v[16:31], v[70:73], v[82:85], v[16:31]
	v_mfma_f32_32x32x16_bf16 v[0:15], v[70:73], v[86:89], v[0:15]
	v_mfma_f32_32x32x16_bf16 v[48:63], v[90:93], v[94:97], v[48:63]
	v_mfma_f32_32x32x16_bf16 v[32:47], v[90:93], v[98:101], v[32:47]
	v_mfma_f32_32x32x16_bf16 v[16:31], v[90:93], v[102:105], v[16:31]
	v_mfma_f32_32x32x16_bf16 v[0:15], v[90:93], v[106:109], v[0:15]
	v_mfma_f32_32x32x16_bf16 v[48:63], v[110:113], v[206:209], v[48:63]
	v_mfma_f32_32x32x16_bf16 v[32:47], v[110:113], v[210:213], v[32:47]
	v_mfma_f32_32x32x16_bf16 v[16:31], v[110:113], v[214:217], v[16:31]
	v_mfma_f32_32x32x16_bf16 v[0:15], v[110:113], v[218:221], v[0:15]
	v_mfma_f32_32x32x16_bf16 v[48:63], v[222:225], v[226:229], v[48:63]
	v_mfma_f32_32x32x16_bf16 v[32:47], v[222:225], v[230:233], v[32:47]
	v_mfma_f32_32x32x16_bf16 v[16:31], v[222:225], v[234:237], v[16:31]
	v_mfma_f32_32x32x16_bf16 v[0:15], v[222:225], v[238:241], v[0:15]
	s_branch .LBB0_707

.Lgk_loop_p7:
	s_waitcnt vmcnt(8)
	s_barrier
	ds_read_b128 v[64:67], v110
	ds_read_b128 v[68:71], v111 offset:16384
	ds_read_b128 v[72:75], v111 offset:20480
	ds_read_b128 v[82:85], v111 offset:24576
	ds_read_b128 v[86:89], v111 offset:28672
	ds_read_b128 v[120:123], v112
	ds_read_b128 v[124:127], v113 offset:16384
	ds_read_b128 v[128:131], v113 offset:20480
	ds_read_b128 v[132:135], v113 offset:24576
	ds_read_b128 v[136:139], v113 offset:28672
	ds_read_b128 v[140:143], v114
	ds_read_b128 v[218:221], v115 offset:16384
	ds_read_b128 v[222:225], v115 offset:20480
	ds_read_b128 v[226:229], v115 offset:24576
	ds_read_b128 v[230:233], v115 offset:28672
	ds_read_b128 v[234:237], v116
	ds_read_b128 v[238:241], v117 offset:16384
	ds_read_b128 v[242:245], v117 offset:20480
	ds_read_b128 v[246:249], v117 offset:24576
	ds_read_b128 v[250:253], v117 offset:28672
	s_waitcnt lgkmcnt(0)
	s_barrier
	s_mov_b32 m0, s36
	v_mfma_f32_32x32x16_bf16 v[48:63], v[64:67], v[68:71], v[48:63]
	v_mfma_f32_32x32x16_bf16 v[32:47], v[64:67], v[72:75], v[32:47]
	global_load_lds_dwordx4 v254, s[18:19]
	s_add_u32 m0, m0, 0x1000
	v_mfma_f32_32x32x16_bf16 v[16:31], v[64:67], v[82:85], v[16:31]
	v_mfma_f32_32x32x16_bf16 v[0:15], v[64:67], v[86:89], v[0:15]
	global_load_lds_dwordx4 v254, s[20:21]
	s_add_u32 m0, m0, 0x1000
	v_mfma_f32_32x32x16_bf16 v[48:63], v[120:123], v[124:127], v[48:63]
	v_mfma_f32_32x32x16_bf16 v[32:47], v[120:123], v[128:131], v[32:47]
	global_load_lds_dwordx4 v254, s[22:23]
	s_add_u32 m0, m0, 0x1000
	v_mfma_f32_32x32x16_bf16 v[16:31], v[120:123], v[132:135], v[16:31]
	v_mfma_f32_32x32x16_bf16 v[0:15], v[120:123], v[136:139], v[0:15]
	global_load_lds_dwordx4 v254, s[24:25]
	s_add_u32 m0, m0, 0x1000
	v_mfma_f32_32x32x16_bf16 v[48:63], v[140:143], v[218:221], v[48:63]
	v_mfma_f32_32x32x16_bf16 v[32:47], v[140:143], v[222:225], v[32:47]
	global_load_lds_dwordx4 v254, s[26:27]
	s_add_u32 m0, m0, 0x1000
	v_mfma_f32_32x32x16_bf16 v[16:31], v[140:143], v[226:229], v[16:31]
	v_mfma_f32_32x32x16_bf16 v[0:15], v[140:143], v[230:233], v[0:15]
	global_load_lds_dwordx4 v254, s[28:29]
	s_add_u32 m0, m0, 0x1000
	v_mfma_f32_32x32x16_bf16 v[48:63], v[234:237], v[238:241], v[48:63]
	v_mfma_f32_32x32x16_bf16 v[32:47], v[234:237], v[242:245], v[32:47]
	global_load_lds_dwordx4 v254, s[30:31]
	s_add_u32 m0, m0, 0x1000
	v_mfma_f32_32x32x16_bf16 v[16:31], v[234:237], v[246:249], v[16:31]
	v_mfma_f32_32x32x16_bf16 v[0:15], v[234:237], v[250:253], v[0:15]
	global_load_lds_dwordx4 v254, s[34:35]
	v_add_u32_e32 v254, 0x80, v254
	s_waitcnt vmcnt(8)
	s_barrier
	ds_read_b128 v[64:67], v110 offset:32768
	ds_read_b128 v[68:71], v111 offset:49152
	ds_read_b128 v[72:75], v111 offset:53248
	ds_read_b128 v[82:85], v111 offset:57344
	ds_read_b128 v[86:89], v111 offset:61440
	ds_read_b128 v[120:123], v112 offset:32768
	ds_read_b128 v[124:127], v113 offset:49152
	ds_read_b128 v[128:131], v113 offset:53248
	ds_read_b128 v[132:135], v113 offset:57344
	ds_read_b128 v[136:139], v113 offset:61440
	ds_read_b128 v[140:143], v114 offset:32768
	ds_read_b128 v[218:221], v115 offset:49152
	ds_read_b128 v[222:225], v115 offset:53248
	ds_read_b128 v[226:229], v115 offset:57344
	ds_read_b128 v[230:233], v115 offset:61440
	ds_read_b128 v[234:237], v116 offset:32768
	ds_read_b128 v[238:241], v117 offset:49152
	ds_read_b128 v[242:245], v117 offset:53248
	ds_read_b128 v[246:249], v117 offset:57344
	ds_read_b128 v[250:253], v117 offset:61440
	s_waitcnt lgkmcnt(0)
	s_barrier
	s_add_u32 m0, s36, 0x8000
	v_mfma_f32_32x32x16_bf16 v[48:63], v[64:67], v[68:71], v[48:63]
	v_mfma_f32_32x32x16_bf16 v[32:47], v[64:67], v[72:75], v[32:47]
	global_load_lds_dwordx4 v254, s[18:19]
	s_add_u32 m0, m0, 0x1000
	v_mfma_f32_32x32x16_bf16 v[16:31], v[64:67], v[82:85], v[16:31]
	v_mfma_f32_32x32x16_bf16 v[0:15], v[64:67], v[86:89], v[0:15]
	global_load_lds_dwordx4 v254, s[20:21]
	s_add_u32 m0, m0, 0x1000
	v_mfma_f32_32x32x16_bf16 v[48:63], v[120:123], v[124:127], v[48:63]
	v_mfma_f32_32x32x16_bf16 v[32:47], v[120:123], v[128:131], v[32:47]
	global_load_lds_dwordx4 v254, s[22:23]
	s_add_u32 m0, m0, 0x1000
	v_mfma_f32_32x32x16_bf16 v[16:31], v[120:123], v[132:135], v[16:31]
	v_mfma_f32_32x32x16_bf16 v[0:15], v[120:123], v[136:139], v[0:15]
	global_load_lds_dwordx4 v254, s[24:25]
	s_add_u32 m0, m0, 0x1000
	v_mfma_f32_32x32x16_bf16 v[48:63], v[140:143], v[218:221], v[48:63]
	v_mfma_f32_32x32x16_bf16 v[32:47], v[140:143], v[222:225], v[32:47]
	global_load_lds_dwordx4 v254, s[26:27]
	s_add_u32 m0, m0, 0x1000
	v_mfma_f32_32x32x16_bf16 v[16:31], v[140:143], v[226:229], v[16:31]
	v_mfma_f32_32x32x16_bf16 v[0:15], v[140:143], v[230:233], v[0:15]
	global_load_lds_dwordx4 v254, s[28:29]
	s_add_u32 m0, m0, 0x1000
	v_mfma_f32_32x32x16_bf16 v[48:63], v[234:237], v[238:241], v[48:63]
	v_mfma_f32_32x32x16_bf16 v[32:47], v[234:237], v[242:245], v[32:47]
	global_load_lds_dwordx4 v254, s[30:31]
	s_add_u32 m0, m0, 0x1000
	v_mfma_f32_32x32x16_bf16 v[16:31], v[234:237], v[246:249], v[16:31]
	v_mfma_f32_32x32x16_bf16 v[0:15], v[234:237], v[250:253], v[0:15]
	global_load_lds_dwordx4 v254, s[34:35]
	v_add_u32_e32 v254, 0x80, v254
	s_sub_u32 s37, s37, 1
	s_cmp_lg_u32 s37, 0
	s_cbranch_scc1 .Lgk_loop_p7
	s_add_u32 s40, s3, s33
	s_cmp_gt_u32 s40, 0x15ff
	s_cbranch_scc1 .Lgk_tailplain_p7

.Lmap_done_0_pf_p7:
	s_lshl_b32 s44, s41, 7
	s_lshl_b32 s42, s50, 7
	s_ashr_i32 s45, s44, 31
	s_ashr_i32 s43, s42, 31
	s_lshl_b64 s[46:47], s[44:45], 11
	s_lshl_b64 s[48:49], s[42:43], 11
	s_lshl_b32 s38, s44, 11
	s_add_u32 s18, s14, s38
	s_addc_u32 s19, s15, 0
	s_add_u32 s18, s18, 0x679f000
	s_addc_u32 s19, s19, 0
	s_add_u32 s20, s18, 0x10000
	s_addc_u32 s21, s19, 0
	s_add_u32 s22, s20, 0x10000
	s_addc_u32 s23, s21, 0
	s_add_u32 s24, s22, 0x10000
	s_addc_u32 s25, s23, 0
	s_lshl_b32 s38, s42, 11
	s_add_u32 s26, s14, s38
	s_addc_u32 s27, s15, 0
	s_add_u32 s26, s26, 0x19a0000
	s_addc_u32 s27, s27, 0
	s_add_u32 s28, s26, 0x10000
	s_addc_u32 s29, s27, 0
	s_add_u32 s30, s28, 0x10000
	s_addc_u32 s31, s29, 0
	s_add_u32 s34, s30, 0x10000
	s_addc_u32 s35, s31, 0
	v_mov_b32_e32 v254, v76
	s_mov_b32 s39, 1
	s_waitcnt vmcnt(8)
	s_barrier
	ds_read_b128 v[64:67], v110
	ds_read_b128 v[68:71], v111 offset:16384
	ds_read_b128 v[72:75], v111 offset:20480
	ds_read_b128 v[82:85], v111 offset:24576
	ds_read_b128 v[86:89], v111 offset:28672
	ds_read_b128 v[120:123], v112
	ds_read_b128 v[124:127], v113 offset:16384
	ds_read_b128 v[128:131], v113 offset:20480
	ds_read_b128 v[132:135], v113 offset:24576
	ds_read_b128 v[136:139], v113 offset:28672
	ds_read_b128 v[140:143], v114
	ds_read_b128 v[218:221], v115 offset:16384
	ds_read_b128 v[222:225], v115 offset:20480
	ds_read_b128 v[226:229], v115 offset:24576
	ds_read_b128 v[230:233], v115 offset:28672
	ds_read_b128 v[234:237], v116
	ds_read_b128 v[238:241], v117 offset:16384
	ds_read_b128 v[242:245], v117 offset:20480
	ds_read_b128 v[246:249], v117 offset:24576
	ds_read_b128 v[250:253], v117 offset:28672
	s_waitcnt lgkmcnt(0)
	s_barrier
	s_mov_b32 m0, s36
	v_mfma_f32_32x32x16_bf16 v[48:63], v[64:67], v[68:71], v[48:63]
	v_mfma_f32_32x32x16_bf16 v[32:47], v[64:67], v[72:75], v[32:47]
	global_load_lds_dwordx4 v254, s[18:19]
	s_add_u32 m0, m0, 0x1000
	v_mfma_f32_32x32x16_bf16 v[16:31], v[64:67], v[82:85], v[16:31]
	v_mfma_f32_32x32x16_bf16 v[0:15], v[64:67], v[86:89], v[0:15]
	global_load_lds_dwordx4 v254, s[20:21]
	s_add_u32 m0, m0, 0x1000
	v_mfma_f32_32x32x16_bf16 v[48:63], v[120:123], v[124:127], v[48:63]
	v_mfma_f32_32x32x16_bf16 v[32:47], v[120:123], v[128:131], v[32:47]
	global_load_lds_dwordx4 v254, s[22:23]
	s_add_u32 m0, m0, 0x1000
	v_mfma_f32_32x32x16_bf16 v[16:31], v[120:123], v[132:135], v[16:31]
	v_mfma_f32_32x32x16_bf16 v[0:15], v[120:123], v[136:139], v[0:15]
	global_load_lds_dwordx4 v254, s[24:25]
	s_add_u32 m0, m0, 0x1000
	v_mfma_f32_32x32x16_bf16 v[48:63], v[140:143], v[218:221], v[48:63]
	v_mfma_f32_32x32x16_bf16 v[32:47], v[140:143], v[222:225], v[32:47]
	global_load_lds_dwordx4 v254, s[26:27]
	s_add_u32 m0, m0, 0x1000
	v_mfma_f32_32x32x16_bf16 v[16:31], v[140:143], v[226:229], v[16:31]
	v_mfma_f32_32x32x16_bf16 v[0:15], v[140:143], v[230:233], v[0:15]
	global_load_lds_dwordx4 v254, s[28:29]
	s_add_u32 m0, m0, 0x1000
	v_mfma_f32_32x32x16_bf16 v[48:63], v[234:237], v[238:241], v[48:63]
	v_mfma_f32_32x32x16_bf16 v[32:47], v[234:237], v[242:245], v[32:47]
	global_load_lds_dwordx4 v254, s[30:31]
	s_add_u32 m0, m0, 0x1000
	v_mfma_f32_32x32x16_bf16 v[16:31], v[234:237], v[246:249], v[16:31]
	v_mfma_f32_32x32x16_bf16 v[0:15], v[234:237], v[250:253], v[0:15]
	global_load_lds_dwordx4 v254, s[34:35]
	v_add_u32_e32 v254, 0x80, v254
	s_waitcnt vmcnt(8)
	s_barrier
	ds_read_b128 v[64:67], v110 offset:32768
	ds_read_b128 v[68:71], v111 offset:49152
	ds_read_b128 v[72:75], v111 offset:53248
	ds_read_b128 v[82:85], v111 offset:57344
	ds_read_b128 v[86:89], v111 offset:61440
	ds_read_b128 v[120:123], v112 offset:32768
	ds_read_b128 v[124:127], v113 offset:49152
	ds_read_b128 v[128:131], v113 offset:53248
	ds_read_b128 v[132:135], v113 offset:57344
	ds_read_b128 v[136:139], v113 offset:61440
	ds_read_b128 v[140:143], v114 offset:32768
	ds_read_b128 v[218:221], v115 offset:49152
	ds_read_b128 v[222:225], v115 offset:53248
	ds_read_b128 v[226:229], v115 offset:57344
	ds_read_b128 v[230:233], v115 offset:61440
	ds_read_b128 v[234:237], v116 offset:32768
	ds_read_b128 v[238:241], v117 offset:49152
	ds_read_b128 v[242:245], v117 offset:53248
	ds_read_b128 v[246:249], v117 offset:57344
	ds_read_b128 v[250:253], v117 offset:61440
	s_waitcnt lgkmcnt(0)
	s_barrier
	s_add_u32 m0, s36, 0x8000
	v_mfma_f32_32x32x16_bf16 v[48:63], v[64:67], v[68:71], v[48:63]
	v_add_f32_e32 v144, v144, v145
	v_add_f32_e32 v146, v146, v147
	v_mfma_f32_32x32x16_bf16 v[32:47], v[64:67], v[72:75], v[32:47]
	v_add_f32_e32 v148, v148, v149
	v_add_f32_e32 v150, v150, v151
	global_load_lds_dwordx4 v254, s[18:19]
	s_add_u32 m0, m0, 0x1000
	v_mfma_f32_32x32x16_bf16 v[16:31], v[64:67], v[82:85], v[16:31]
	v_add_f32_e32 v144, v144, v146
	v_add_f32_e32 v148, v148, v150
	v_mfma_f32_32x32x16_bf16 v[0:15], v[64:67], v[86:89], v[0:15]
	v_add_f32_e32 v144, v144, v148
	v_fmamk_f32 v144, v144, 0x3a800000, v118
	global_load_lds_dwordx4 v254, s[20:21]
	s_add_u32 m0, m0, 0x1000
	v_mfma_f32_32x32x16_bf16 v[48:63], v[120:123], v[124:127], v[48:63]
	v_rsq_f32_e32 v144, v144
	s_nop 1
	v_mfma_f32_32x32x16_bf16 v[32:47], v[120:123], v[128:131], v[32:47]
	ds_bpermute_b32 v156, v153, v144
	ds_bpermute_b32 v157, v153, v144 offset:4
	global_load_lds_dwordx4 v254, s[22:23]
	s_add_u32 m0, m0, 0x1000
	v_mfma_f32_32x32x16_bf16 v[16:31], v[120:123], v[132:135], v[16:31]
	ds_bpermute_b32 v158, v153, v144 offset:8
	ds_bpermute_b32 v159, v153, v144 offset:12
	v_mfma_f32_32x32x16_bf16 v[0:15], v[120:123], v[136:139], v[0:15]
	ds_bpermute_b32 v160, v153, v144 offset:32
	ds_bpermute_b32 v161, v153, v144 offset:36
	global_load_lds_dwordx4 v254, s[24:25]
	s_add_u32 m0, m0, 0x1000
	v_mfma_f32_32x32x16_bf16 v[48:63], v[140:143], v[218:221], v[48:63]
	ds_bpermute_b32 v162, v153, v144 offset:40
	ds_bpermute_b32 v163, v153, v144 offset:44
	v_mfma_f32_32x32x16_bf16 v[32:47], v[140:143], v[222:225], v[32:47]
	ds_bpermute_b32 v164, v153, v144 offset:64
	ds_bpermute_b32 v165, v153, v144 offset:68
	global_load_lds_dwordx4 v254, s[26:27]
	s_add_u32 m0, m0, 0x1000
	v_mfma_f32_32x32x16_bf16 v[16:31], v[140:143], v[226:229], v[16:31]
	ds_bpermute_b32 v166, v153, v144 offset:72
	ds_bpermute_b32 v167, v153, v144 offset:76
	v_mfma_f32_32x32x16_bf16 v[0:15], v[140:143], v[230:233], v[0:15]
	ds_bpermute_b32 v168, v153, v144 offset:96
	ds_bpermute_b32 v169, v153, v144 offset:100
	global_load_lds_dwordx4 v254, s[28:29]
	s_add_u32 m0, m0, 0x1000
	v_mfma_f32_32x32x16_bf16 v[48:63], v[234:237], v[238:241], v[48:63]
	ds_bpermute_b32 v170, v153, v144 offset:104
	ds_bpermute_b32 v171, v153, v144 offset:108
	v_mfma_f32_32x32x16_bf16 v[32:47], v[234:237], v[242:245], v[32:47]
	global_load_lds_dwordx4 v254, s[30:31]
	s_add_u32 m0, m0, 0x1000
	v_mfma_f32_32x32x16_bf16 v[16:31], v[234:237], v[246:249], v[16:31]
	v_mfma_f32_32x32x16_bf16 v[0:15], v[234:237], v[250:253], v[0:15]
	global_load_lds_dwordx4 v254, s[34:35]
	v_add_u32_e32 v254, 0x80, v254
	s_branch .LBB0_754
.Lgk_tailplain_p7:
	s_mov_b32 s39, 0
	s_waitcnt vmcnt(8)
	s_barrier
	ds_read_b128 v[64:67], v110
	ds_read_b128 v[68:71], v111 offset:16384
	ds_read_b128 v[72:75], v111 offset:20480
	ds_read_b128 v[82:85], v111 offset:24576
	ds_read_b128 v[86:89], v111 offset:28672
	ds_read_b128 v[120:123], v112
	ds_read_b128 v[124:127], v113 offset:16384
	ds_read_b128 v[128:131], v113 offset:20480
	ds_read_b128 v[132:135], v113 offset:24576
	ds_read_b128 v[136:139], v113 offset:28672
	ds_read_b128 v[140:143], v114
	ds_read_b128 v[218:221], v115 offset:16384
	ds_read_b128 v[222:225], v115 offset:20480
	ds_read_b128 v[226:229], v115 offset:24576
	ds_read_b128 v[230:233], v115 offset:28672
	ds_read_b128 v[234:237], v116
	ds_read_b128 v[238:241], v117 offset:16384
	ds_read_b128 v[242:245], v117 offset:20480
	ds_read_b128 v[246:249], v117 offset:24576
	ds_read_b128 v[250:253], v117 offset:28672
	s_waitcnt lgkmcnt(0)
	s_barrier
	v_mfma_f32_32x32x16_bf16 v[48:63], v[64:67], v[68:71], v[48:63]
	v_mfma_f32_32x32x16_bf16 v[32:47], v[64:67], v[72:75], v[32:47]
	v_mfma_f32_32x32x16_bf16 v[16:31], v[64:67], v[82:85], v[16:31]
	v_mfma_f32_32x32x16_bf16 v[0:15], v[64:67], v[86:89], v[0:15]
	v_mfma_f32_32x32x16_bf16 v[48:63], v[120:123], v[124:127], v[48:63]
	v_mfma_f32_32x32x16_bf16 v[32:47], v[120:123], v[128:131], v[32:47]
	v_mfma_f32_32x32x16_bf16 v[16:31], v[120:123], v[132:135], v[16:31]
	v_mfma_f32_32x32x16_bf16 v[0:15], v[120:123], v[136:139], v[0:15]
	v_mfma_f32_32x32x16_bf16 v[48:63], v[140:143], v[218:221], v[48:63]
	v_mfma_f32_32x32x16_bf16 v[32:47], v[140:143], v[222:225], v[32:47]
	v_mfma_f32_32x32x16_bf16 v[16:31], v[140:143], v[226:229], v[16:31]
	v_mfma_f32_32x32x16_bf16 v[0:15], v[140:143], v[230:233], v[0:15]
	v_mfma_f32_32x32x16_bf16 v[48:63], v[234:237], v[238:241], v[48:63]
	v_mfma_f32_32x32x16_bf16 v[32:47], v[234:237], v[242:245], v[32:47]
	v_mfma_f32_32x32x16_bf16 v[16:31], v[234:237], v[246:249], v[16:31]
	v_mfma_f32_32x32x16_bf16 v[0:15], v[234:237], v[250:253], v[0:15]
	s_waitcnt vmcnt(0)
	s_barrier
	ds_read_b128 v[64:67], v110 offset:32768
	ds_read_b128 v[68:71], v111 offset:49152
	ds_read_b128 v[72:75], v111 offset:53248
	ds_read_b128 v[82:85], v111 offset:57344
	ds_read_b128 v[86:89], v111 offset:61440
	ds_read_b128 v[120:123], v112 offset:32768
	ds_read_b128 v[124:127], v113 offset:49152
	ds_read_b128 v[128:131], v113 offset:53248
	ds_read_b128 v[132:135], v113 offset:57344
	ds_read_b128 v[136:139], v113 offset:61440
	ds_read_b128 v[140:143], v114 offset:32768
	ds_read_b128 v[218:221], v115 offset:49152
	ds_read_b128 v[222:225], v115 offset:53248
	ds_read_b128 v[226:229], v115 offset:57344
	ds_read_b128 v[230:233], v115 offset:61440
	ds_read_b128 v[234:237], v116 offset:32768
	ds_read_b128 v[238:241], v117 offset:49152
	ds_read_b128 v[242:245], v117 offset:53248
	ds_read_b128 v[246:249], v117 offset:57344
	ds_read_b128 v[250:253], v117 offset:61440
	s_waitcnt lgkmcnt(0)
	s_barrier
	v_mfma_f32_32x32x16_bf16 v[48:63], v[64:67], v[68:71], v[48:63]
	v_add_f32_e32 v144, v144, v145
	v_add_f32_e32 v146, v146, v147
	v_mfma_f32_32x32x16_bf16 v[32:47], v[64:67], v[72:75], v[32:47]
	v_add_f32_e32 v148, v148, v149
	v_add_f32_e32 v150, v150, v151
	v_mfma_f32_32x32x16_bf16 v[16:31], v[64:67], v[82:85], v[16:31]
	v_add_f32_e32 v144, v144, v146
	v_add_f32_e32 v148, v148, v150
	v_mfma_f32_32x32x16_bf16 v[0:15], v[64:67], v[86:89], v[0:15]
	v_add_f32_e32 v144, v144, v148
	v_fmamk_f32 v144, v144, 0x3a800000, v118
	v_mfma_f32_32x32x16_bf16 v[48:63], v[120:123], v[124:127], v[48:63]
	v_rsq_f32_e32 v144, v144
	s_nop 1
	v_mfma_f32_32x32x16_bf16 v[32:47], v[120:123], v[128:131], v[32:47]
	ds_bpermute_b32 v156, v153, v144
	ds_bpermute_b32 v157, v153, v144 offset:4
	v_mfma_f32_32x32x16_bf16 v[16:31], v[120:123], v[132:135], v[16:31]
	ds_bpermute_b32 v158, v153, v144 offset:8
	ds_bpermute_b32 v159, v153, v144 offset:12
	v_mfma_f32_32x32x16_bf16 v[0:15], v[120:123], v[136:139], v[0:15]
	ds_bpermute_b32 v160, v153, v144 offset:32
	ds_bpermute_b32 v161, v153, v144 offset:36
	v_mfma_f32_32x32x16_bf16 v[48:63], v[140:143], v[218:221], v[48:63]
	ds_bpermute_b32 v162, v153, v144 offset:40
	ds_bpermute_b32 v163, v153, v144 offset:44
	v_mfma_f32_32x32x16_bf16 v[32:47], v[140:143], v[222:225], v[32:47]
	ds_bpermute_b32 v164, v153, v144 offset:64
	ds_bpermute_b32 v165, v153, v144 offset:68
	v_mfma_f32_32x32x16_bf16 v[16:31], v[140:143], v[226:229], v[16:31]
	ds_bpermute_b32 v166, v153, v144 offset:72
	ds_bpermute_b32 v167, v153, v144 offset:76
	v_mfma_f32_32x32x16_bf16 v[0:15], v[140:143], v[230:233], v[0:15]
	ds_bpermute_b32 v168, v153, v144 offset:96
	ds_bpermute_b32 v169, v153, v144 offset:100
	v_mfma_f32_32x32x16_bf16 v[48:63], v[234:237], v[238:241], v[48:63]
	ds_bpermute_b32 v170, v153, v144 offset:104
	ds_bpermute_b32 v171, v153, v144 offset:108
	v_mfma_f32_32x32x16_bf16 v[32:47], v[234:237], v[242:245], v[32:47]
	v_mfma_f32_32x32x16_bf16 v[16:31], v[234:237], v[246:249], v[16:31]
	v_mfma_f32_32x32x16_bf16 v[0:15], v[234:237], v[250:253], v[0:15]
	s_branch .LBB0_754

.Lgk_loop_p8:
	s_waitcnt vmcnt(8)
	s_barrier
	ds_read_b128 v[70:73], v157
	ds_read_b128 v[74:77], v158 offset:16384
	ds_read_b128 v[78:81], v158 offset:20480
	ds_read_b128 v[82:85], v158 offset:24576
	ds_read_b128 v[86:89], v158 offset:28672
	ds_read_b128 v[90:93], v159
	ds_read_b128 v[94:97], v160 offset:16384
	ds_read_b128 v[98:101], v160 offset:20480
	ds_read_b128 v[102:105], v160 offset:24576
	ds_read_b128 v[106:109], v160 offset:28672
	ds_read_b128 v[110:113], v161
	ds_read_b128 v[202:205], v162 offset:16384
	ds_read_b128 v[206:209], v162 offset:20480
	ds_read_b128 v[210:213], v162 offset:24576
	ds_read_b128 v[214:217], v162 offset:28672
	ds_read_b128 v[218:221], v163
	ds_read_b128 v[222:225], v164 offset:16384
	ds_read_b128 v[226:229], v164 offset:20480
	ds_read_b128 v[230:233], v164 offset:24576
	ds_read_b128 v[234:237], v164 offset:28672
	s_waitcnt lgkmcnt(0)
	s_barrier
	s_mov_b32 m0, s36
	v_mfma_f32_32x32x16_bf16 v[48:63], v[70:73], v[74:77], v[48:63]
	v_mfma_f32_32x32x16_bf16 v[32:47], v[70:73], v[78:81], v[32:47]
	global_load_lds_dwordx4 v254, s[18:19]
	s_add_u32 m0, m0, 0x1000
	v_mfma_f32_32x32x16_bf16 v[16:31], v[70:73], v[82:85], v[16:31]
	v_mfma_f32_32x32x16_bf16 v[0:15], v[70:73], v[86:89], v[0:15]
	global_load_lds_dwordx4 v254, s[20:21]
	s_add_u32 m0, m0, 0x1000
	v_mfma_f32_32x32x16_bf16 v[48:63], v[90:93], v[94:97], v[48:63]
	v_mfma_f32_32x32x16_bf16 v[32:47], v[90:93], v[98:101], v[32:47]
	global_load_lds_dwordx4 v254, s[22:23]
	s_add_u32 m0, m0, 0x1000
	v_mfma_f32_32x32x16_bf16 v[16:31], v[90:93], v[102:105], v[16:31]
	v_mfma_f32_32x32x16_bf16 v[0:15], v[90:93], v[106:109], v[0:15]
	global_load_lds_dwordx4 v254, s[24:25]
	s_add_u32 m0, m0, 0x1000
	v_mfma_f32_32x32x16_bf16 v[48:63], v[110:113], v[202:205], v[48:63]
	v_mfma_f32_32x32x16_bf16 v[32:47], v[110:113], v[206:209], v[32:47]
	global_load_lds_dwordx4 v254, s[26:27]
	s_add_u32 m0, m0, 0x1000
	v_mfma_f32_32x32x16_bf16 v[16:31], v[110:113], v[210:213], v[16:31]
	v_mfma_f32_32x32x16_bf16 v[0:15], v[110:113], v[214:217], v[0:15]
	global_load_lds_dwordx4 v254, s[28:29]
	s_add_u32 m0, m0, 0x1000
	v_mfma_f32_32x32x16_bf16 v[48:63], v[218:221], v[222:225], v[48:63]
	v_mfma_f32_32x32x16_bf16 v[32:47], v[218:221], v[226:229], v[32:47]
	global_load_lds_dwordx4 v254, s[30:31]
	s_add_u32 m0, m0, 0x1000
	v_mfma_f32_32x32x16_bf16 v[16:31], v[218:221], v[230:233], v[16:31]
	v_mfma_f32_32x32x16_bf16 v[0:15], v[218:221], v[234:237], v[0:15]
	global_load_lds_dwordx4 v254, s[34:35]
	v_add_u32_e32 v254, 0x80, v254
	s_waitcnt vmcnt(8)
	s_barrier
	ds_read_b128 v[70:73], v157 offset:32768
	ds_read_b128 v[74:77], v158 offset:49152
	ds_read_b128 v[78:81], v158 offset:53248
	ds_read_b128 v[82:85], v158 offset:57344
	ds_read_b128 v[86:89], v158 offset:61440
	ds_read_b128 v[90:93], v159 offset:32768
	ds_read_b128 v[94:97], v160 offset:49152
	ds_read_b128 v[98:101], v160 offset:53248
	ds_read_b128 v[102:105], v160 offset:57344
	ds_read_b128 v[106:109], v160 offset:61440
	ds_read_b128 v[110:113], v161 offset:32768
	ds_read_b128 v[202:205], v162 offset:49152
	ds_read_b128 v[206:209], v162 offset:53248
	ds_read_b128 v[210:213], v162 offset:57344
	ds_read_b128 v[214:217], v162 offset:61440
	ds_read_b128 v[218:221], v163 offset:32768
	ds_read_b128 v[222:225], v164 offset:49152
	ds_read_b128 v[226:229], v164 offset:53248
	ds_read_b128 v[230:233], v164 offset:57344
	ds_read_b128 v[234:237], v164 offset:61440
	s_waitcnt lgkmcnt(0)
	s_barrier
	s_add_u32 m0, s36, 0x8000
	v_mfma_f32_32x32x16_bf16 v[48:63], v[70:73], v[74:77], v[48:63]
	v_mfma_f32_32x32x16_bf16 v[32:47], v[70:73], v[78:81], v[32:47]
	global_load_lds_dwordx4 v254, s[18:19]
	s_add_u32 m0, m0, 0x1000
	v_mfma_f32_32x32x16_bf16 v[16:31], v[70:73], v[82:85], v[16:31]
	v_mfma_f32_32x32x16_bf16 v[0:15], v[70:73], v[86:89], v[0:15]
	global_load_lds_dwordx4 v254, s[20:21]
	s_add_u32 m0, m0, 0x1000
	v_mfma_f32_32x32x16_bf16 v[48:63], v[90:93], v[94:97], v[48:63]
	v_mfma_f32_32x32x16_bf16 v[32:47], v[90:93], v[98:101], v[32:47]
	global_load_lds_dwordx4 v254, s[22:23]
	s_add_u32 m0, m0, 0x1000
	v_mfma_f32_32x32x16_bf16 v[16:31], v[90:93], v[102:105], v[16:31]
	v_mfma_f32_32x32x16_bf16 v[0:15], v[90:93], v[106:109], v[0:15]
	global_load_lds_dwordx4 v254, s[24:25]
	s_add_u32 m0, m0, 0x1000
	v_mfma_f32_32x32x16_bf16 v[48:63], v[110:113], v[202:205], v[48:63]
	v_mfma_f32_32x32x16_bf16 v[32:47], v[110:113], v[206:209], v[32:47]
	global_load_lds_dwordx4 v254, s[26:27]
	s_add_u32 m0, m0, 0x1000
	v_mfma_f32_32x32x16_bf16 v[16:31], v[110:113], v[210:213], v[16:31]
	v_mfma_f32_32x32x16_bf16 v[0:15], v[110:113], v[214:217], v[0:15]
	global_load_lds_dwordx4 v254, s[28:29]
	s_add_u32 m0, m0, 0x1000
	v_mfma_f32_32x32x16_bf16 v[48:63], v[218:221], v[222:225], v[48:63]
	v_mfma_f32_32x32x16_bf16 v[32:47], v[218:221], v[226:229], v[32:47]
	global_load_lds_dwordx4 v254, s[30:31]
	s_add_u32 m0, m0, 0x1000
	v_mfma_f32_32x32x16_bf16 v[16:31], v[218:221], v[230:233], v[16:31]
	v_mfma_f32_32x32x16_bf16 v[0:15], v[218:221], v[234:237], v[0:15]
	global_load_lds_dwordx4 v254, s[34:35]
	v_add_u32_e32 v254, 0x80, v254
	s_sub_u32 s37, s37, 1
	s_cmp_lg_u32 s37, 0
	s_cbranch_scc1 .Lgk_loop_p8
	s_add_u32 s40, s3, s33
	s_cmp_gt_u32 s40, 0x3ff
	s_cbranch_scc1 .Lgk_tailplain_p8
.LBB0_775_pf_p8:
	s_ashr_i32 s41, s40, 31
	s_lshr_b32 s41, s41, 26
	s_add_i32 s41, s40, s41
	s_ashr_i32 s42, s41, 6
	s_andn2_b32 s41, s41, 63
	s_sub_i32 s41, s40, s41
	s_ashr_i32 s43, s41, 31
	s_lshr_b32 s43, s43, 29
	s_add_i32 s43, s41, s43
	s_ashr_i32 s44, s43, 3
	s_and_b32 s43, s43, -8
	s_lshl_b32 s42, s42, 3
	s_sub_i32 s41, s41, s43
	s_add_i32 s41, s41, s42
	s_lshl_b32 s45, s41, 7
	s_lshl_b32 s46, s44, 7
	s_mul_i32 s38, s41, 0xb0000
	s_add_u32 s18, s14, s38
	s_addc_u32 s19, s15, 0
	s_add_u32 s18, s18, 0x879f000
	s_addc_u32 s19, s19, 0
	s_add_u32 s20, s18, 0x2c000
	s_addc_u32 s21, s19, 0
	s_add_u32 s22, s20, 0x2c000
	s_addc_u32 s23, s21, 0
	s_add_u32 s24, s22, 0x2c000
	s_addc_u32 s25, s23, 0
	s_mul_i32 s38, s44, 0xb0000
	s_add_u32 s26, s14, s38
	s_addc_u32 s27, s15, 0
	s_add_u32 s26, s26, 0x45a0000
	s_addc_u32 s27, s27, 0
	s_add_u32 s28, s26, 0x2c000
	s_addc_u32 s29, s27, 0
	s_add_u32 s30, s28, 0x2c000
	s_addc_u32 s31, s29, 0
	s_add_u32 s34, s30, 0x2c000
	s_addc_u32 s35, s31, 0
	v_mov_b32_e32 v254, v64
	s_mov_b32 s39, 1
	s_waitcnt vmcnt(8)
	s_barrier
	ds_read_b128 v[70:73], v157
	ds_read_b128 v[74:77], v158 offset:16384
	ds_read_b128 v[78:81], v158 offset:20480
	ds_read_b128 v[82:85], v158 offset:24576
	ds_read_b128 v[86:89], v158 offset:28672
	ds_read_b128 v[90:93], v159
	ds_read_b128 v[94:97], v160 offset:16384
	ds_read_b128 v[98:101], v160 offset:20480
	ds_read_b128 v[102:105], v160 offset:24576
	ds_read_b128 v[106:109], v160 offset:28672
	ds_read_b128 v[110:113], v161
	ds_read_b128 v[202:205], v162 offset:16384
	ds_read_b128 v[206:209], v162 offset:20480
	ds_read_b128 v[210:213], v162 offset:24576
	ds_read_b128 v[214:217], v162 offset:28672
	ds_read_b128 v[218:221], v163
	ds_read_b128 v[222:225], v164 offset:16384
	ds_read_b128 v[226:229], v164 offset:20480
	ds_read_b128 v[230:233], v164 offset:24576
	ds_read_b128 v[234:237], v164 offset:28672
	s_waitcnt lgkmcnt(0)
	s_barrier
	s_mov_b32 m0, s36
	v_mfma_f32_32x32x16_bf16 v[48:63], v[70:73], v[74:77], v[48:63]
	v_mfma_f32_32x32x16_bf16 v[32:47], v[70:73], v[78:81], v[32:47]
	global_load_lds_dwordx4 v254, s[18:19]
	s_add_u32 m0, m0, 0x1000
	v_mfma_f32_32x32x16_bf16 v[16:31], v[70:73], v[82:85], v[16:31]
	v_mfma_f32_32x32x16_bf16 v[0:15], v[70:73], v[86:89], v[0:15]
	global_load_lds_dwordx4 v254, s[20:21]
	s_add_u32 m0, m0, 0x1000
	v_mfma_f32_32x32x16_bf16 v[48:63], v[90:93], v[94:97], v[48:63]
	v_mfma_f32_32x32x16_bf16 v[32:47], v[90:93], v[98:101], v[32:47]
	global_load_lds_dwordx4 v254, s[22:23]
	s_add_u32 m0, m0, 0x1000
	v_mfma_f32_32x32x16_bf16 v[16:31], v[90:93], v[102:105], v[16:31]
	v_mfma_f32_32x32x16_bf16 v[0:15], v[90:93], v[106:109], v[0:15]
	global_load_lds_dwordx4 v254, s[24:25]
	s_add_u32 m0, m0, 0x1000
	v_mfma_f32_32x32x16_bf16 v[48:63], v[110:113], v[202:205], v[48:63]
	v_mfma_f32_32x32x16_bf16 v[32:47], v[110:113], v[206:209], v[32:47]
	global_load_lds_dwordx4 v254, s[26:27]
	s_add_u32 m0, m0, 0x1000
	v_mfma_f32_32x32x16_bf16 v[16:31], v[110:113], v[210:213], v[16:31]
	v_mfma_f32_32x32x16_bf16 v[0:15], v[110:113], v[214:217], v[0:15]
	global_load_lds_dwordx4 v254, s[28:29]
	s_add_u32 m0, m0, 0x1000
	v_mfma_f32_32x32x16_bf16 v[48:63], v[218:221], v[222:225], v[48:63]
	v_mfma_f32_32x32x16_bf16 v[32:47], v[218:221], v[226:229], v[32:47]
	global_load_lds_dwordx4 v254, s[30:31]
	s_add_u32 m0, m0, 0x1000
	v_mfma_f32_32x32x16_bf16 v[16:31], v[218:221], v[230:233], v[16:31]
	v_mfma_f32_32x32x16_bf16 v[0:15], v[218:221], v[234:237], v[0:15]
	global_load_lds_dwordx4 v254, s[34:35]
	v_add_u32_e32 v254, 0x80, v254
	s_waitcnt vmcnt(8)
	s_barrier
	ds_read_b128 v[70:73], v157 offset:32768
	ds_read_b128 v[74:77], v158 offset:49152
	ds_read_b128 v[78:81], v158 offset:53248
	ds_read_b128 v[82:85], v158 offset:57344
	ds_read_b128 v[86:89], v158 offset:61440
	ds_read_b128 v[90:93], v159 offset:32768
	ds_read_b128 v[94:97], v160 offset:49152
	ds_read_b128 v[98:101], v160 offset:53248
	ds_read_b128 v[102:105], v160 offset:57344
	ds_read_b128 v[106:109], v160 offset:61440
	ds_read_b128 v[110:113], v161 offset:32768
	ds_read_b128 v[202:205], v162 offset:49152
	ds_read_b128 v[206:209], v162 offset:53248
	ds_read_b128 v[210:213], v162 offset:57344
	ds_read_b128 v[214:217], v162 offset:61440
	ds_read_b128 v[218:221], v163 offset:32768
	ds_read_b128 v[222:225], v164 offset:49152
	ds_read_b128 v[226:229], v164 offset:53248
	ds_read_b128 v[230:233], v164 offset:57344
	ds_read_b128 v[234:237], v164 offset:61440
	s_waitcnt lgkmcnt(0)
	s_barrier
	s_add_u32 m0, s36, 0x8000
	v_mfma_f32_32x32x16_bf16 v[48:63], v[70:73], v[74:77], v[48:63]
	v_mfma_f32_32x32x16_bf16 v[32:47], v[70:73], v[78:81], v[32:47]
	global_load_lds_dwordx4 v254, s[18:19]
	s_add_u32 m0, m0, 0x1000
	v_mfma_f32_32x32x16_bf16 v[16:31], v[70:73], v[82:85], v[16:31]
	v_mfma_f32_32x32x16_bf16 v[0:15], v[70:73], v[86:89], v[0:15]
	global_load_lds_dwordx4 v254, s[20:21]
	s_add_u32 m0, m0, 0x1000
	v_mfma_f32_32x32x16_bf16 v[48:63], v[90:93], v[94:97], v[48:63]
	v_mfma_f32_32x32x16_bf16 v[32:47], v[90:93], v[98:101], v[32:47]
	global_load_lds_dwordx4 v254, s[22:23]
	s_add_u32 m0, m0, 0x1000
	v_mfma_f32_32x32x16_bf16 v[16:31], v[90:93], v[102:105], v[16:31]
	v_mfma_f32_32x32x16_bf16 v[0:15], v[90:93], v[106:109], v[0:15]
	global_load_lds_dwordx4 v254, s[24:25]
	s_add_u32 m0, m0, 0x1000
	v_mfma_f32_32x32x16_bf16 v[48:63], v[110:113], v[202:205], v[48:63]
	v_mfma_f32_32x32x16_bf16 v[32:47], v[110:113], v[206:209], v[32:47]
	global_load_lds_dwordx4 v254, s[26:27]
	s_add_u32 m0, m0, 0x1000
	v_mfma_f32_32x32x16_bf16 v[16:31], v[110:113], v[210:213], v[16:31]
	v_mfma_f32_32x32x16_bf16 v[0:15], v[110:113], v[214:217], v[0:15]
	global_load_lds_dwordx4 v254, s[28:29]
	s_add_u32 m0, m0, 0x1000
	v_mfma_f32_32x32x16_bf16 v[48:63], v[218:221], v[222:225], v[48:63]
	v_mfma_f32_32x32x16_bf16 v[32:47], v[218:221], v[226:229], v[32:47]
	global_load_lds_dwordx4 v254, s[30:31]
	s_add_u32 m0, m0, 0x1000
	v_mfma_f32_32x32x16_bf16 v[16:31], v[218:221], v[230:233], v[16:31]
	v_mfma_f32_32x32x16_bf16 v[0:15], v[218:221], v[234:237], v[0:15]
	global_load_lds_dwordx4 v254, s[34:35]
	v_add_u32_e32 v254, 0x80, v254
	s_branch .LBB0_779
.Lgk_tailplain_p8:
	s_mov_b32 s39, 0
	s_waitcnt vmcnt(8)
	s_barrier
	ds_read_b128 v[70:73], v157
	ds_read_b128 v[74:77], v158 offset:16384
	ds_read_b128 v[78:81], v158 offset:20480
	ds_read_b128 v[82:85], v158 offset:24576
	ds_read_b128 v[86:89], v158 offset:28672
	ds_read_b128 v[90:93], v159
	ds_read_b128 v[94:97], v160 offset:16384
	ds_read_b128 v[98:101], v160 offset:20480
	ds_read_b128 v[102:105], v160 offset:24576
	ds_read_b128 v[106:109], v160 offset:28672
	ds_read_b128 v[110:113], v161
	ds_read_b128 v[202:205], v162 offset:16384
	ds_read_b128 v[206:209], v162 offset:20480
	ds_read_b128 v[210:213], v162 offset:24576
	ds_read_b128 v[214:217], v162 offset:28672
	ds_read_b128 v[218:221], v163
	ds_read_b128 v[222:225], v164 offset:16384
	ds_read_b128 v[226:229], v164 offset:20480
	ds_read_b128 v[230:233], v164 offset:24576
	ds_read_b128 v[234:237], v164 offset:28672
	s_waitcnt lgkmcnt(0)
	s_barrier
	v_mfma_f32_32x32x16_bf16 v[48:63], v[70:73], v[74:77], v[48:63]
	v_mfma_f32_32x32x16_bf16 v[32:47], v[70:73], v[78:81], v[32:47]
	v_mfma_f32_32x32x16_bf16 v[16:31], v[70:73], v[82:85], v[16:31]
	v_mfma_f32_32x32x16_bf16 v[0:15], v[70:73], v[86:89], v[0:15]
	v_mfma_f32_32x32x16_bf16 v[48:63], v[90:93], v[94:97], v[48:63]
	v_mfma_f32_32x32x16_bf16 v[32:47], v[90:93], v[98:101], v[32:47]
	v_mfma_f32_32x32x16_bf16 v[16:31], v[90:93], v[102:105], v[16:31]
	v_mfma_f32_32x32x16_bf16 v[0:15], v[90:93], v[106:109], v[0:15]
	v_mfma_f32_32x32x16_bf16 v[48:63], v[110:113], v[202:205], v[48:63]
	v_mfma_f32_32x32x16_bf16 v[32:47], v[110:113], v[206:209], v[32:47]
	v_mfma_f32_32x32x16_bf16 v[16:31], v[110:113], v[210:213], v[16:31]
	v_mfma_f32_32x32x16_bf16 v[0:15], v[110:113], v[214:217], v[0:15]
	v_mfma_f32_32x32x16_bf16 v[48:63], v[218:221], v[222:225], v[48:63]
	v_mfma_f32_32x32x16_bf16 v[32:47], v[218:221], v[226:229], v[32:47]
	v_mfma_f32_32x32x16_bf16 v[16:31], v[218:221], v[230:233], v[16:31]
	v_mfma_f32_32x32x16_bf16 v[0:15], v[218:221], v[234:237], v[0:15]
	s_waitcnt vmcnt(0)
	s_barrier
	ds_read_b128 v[70:73], v157 offset:32768
	ds_read_b128 v[74:77], v158 offset:49152
	ds_read_b128 v[78:81], v158 offset:53248
	ds_read_b128 v[82:85], v158 offset:57344
	ds_read_b128 v[86:89], v158 offset:61440
	ds_read_b128 v[90:93], v159 offset:32768
	ds_read_b128 v[94:97], v160 offset:49152
	ds_read_b128 v[98:101], v160 offset:53248
	ds_read_b128 v[102:105], v160 offset:57344
	ds_read_b128 v[106:109], v160 offset:61440
	ds_read_b128 v[110:113], v161 offset:32768
	ds_read_b128 v[202:205], v162 offset:49152
	ds_read_b128 v[206:209], v162 offset:53248
	ds_read_b128 v[210:213], v162 offset:57344
	ds_read_b128 v[214:217], v162 offset:61440
	ds_read_b128 v[218:221], v163 offset:32768
	ds_read_b128 v[222:225], v164 offset:49152
	ds_read_b128 v[226:229], v164 offset:53248
	ds_read_b128 v[230:233], v164 offset:57344
	ds_read_b128 v[234:237], v164 offset:61440
	s_waitcnt lgkmcnt(0)
	s_barrier
	v_mfma_f32_32x32x16_bf16 v[48:63], v[70:73], v[74:77], v[48:63]
	v_mfma_f32_32x32x16_bf16 v[32:47], v[70:73], v[78:81], v[32:47]
	v_mfma_f32_32x32x16_bf16 v[16:31], v[70:73], v[82:85], v[16:31]
	v_mfma_f32_32x32x16_bf16 v[0:15], v[70:73], v[86:89], v[0:15]
	v_mfma_f32_32x32x16_bf16 v[48:63], v[90:93], v[94:97], v[48:63]
	v_mfma_f32_32x32x16_bf16 v[32:47], v[90:93], v[98:101], v[32:47]
	v_mfma_f32_32x32x16_bf16 v[16:31], v[90:93], v[102:105], v[16:31]
	v_mfma_f32_32x32x16_bf16 v[0:15], v[90:93], v[106:109], v[0:15]
	v_mfma_f32_32x32x16_bf16 v[48:63], v[110:113], v[202:205], v[48:63]
	v_mfma_f32_32x32x16_bf16 v[32:47], v[110:113], v[206:209], v[32:47]
	v_mfma_f32_32x32x16_bf16 v[16:31], v[110:113], v[210:213], v[16:31]
	v_mfma_f32_32x32x16_bf16 v[0:15], v[110:113], v[214:217], v[0:15]
	v_mfma_f32_32x32x16_bf16 v[48:63], v[218:221], v[222:225], v[48:63]
	v_mfma_f32_32x32x16_bf16 v[32:47], v[218:221], v[226:229], v[32:47]
	v_mfma_f32_32x32x16_bf16 v[16:31], v[218:221], v[230:233], v[16:31]
	v_mfma_f32_32x32x16_bf16 v[0:15], v[218:221], v[234:237], v[0:15]
	s_branch .LBB0_779

.Lgk_loop_p9:
	s_waitcnt vmcnt(8)
	s_barrier
	ds_read_b128 v[64:67], v255
	ds_read_b128 v[76:79], v188 offset:16384
	ds_read_b128 v[80:83], v188 offset:20480
	ds_read_b128 v[84:87], v188 offset:24576
	ds_read_b128 v[88:91], v188 offset:28672
	ds_read_b128 v[92:95], v189
	ds_read_b128 v[96:99], v190 offset:16384
	ds_read_b128 v[100:103], v190 offset:20480
	ds_read_b128 v[104:107], v190 offset:24576
	ds_read_b128 v[108:111], v190 offset:28672
	ds_read_b128 v[112:115], v191
	ds_read_b128 v[226:229], v192 offset:16384
	ds_read_b128 v[230:233], v192 offset:20480
	ds_read_b128 v[234:237], v192 offset:24576
	ds_read_b128 v[238:241], v192 offset:28672
	ds_read_b128 v[242:245], v193
	ds_read_b128 v[246:249], v194 offset:16384
	ds_read_b128 v[250:253], v194 offset:20480
	ds_read_b128 v[144:147], v194 offset:24576
	ds_read_b128 v[184:187], v194 offset:28672
	s_waitcnt lgkmcnt(0)
	s_barrier
	s_mov_b32 m0, s46
	v_mfma_f32_32x32x16_bf16 v[48:63], v[64:67], v[76:79], v[48:63]
	v_mfma_f32_32x32x16_bf16 v[32:47], v[64:67], v[80:83], v[32:47]
	global_load_lds_dwordx4 v254, s[28:29]
	s_add_u32 m0, m0, 0x1000
	v_mfma_f32_32x32x16_bf16 v[16:31], v[64:67], v[84:87], v[16:31]
	v_mfma_f32_32x32x16_bf16 v[0:15], v[64:67], v[88:91], v[0:15]
	global_load_lds_dwordx4 v254, s[30:31]
	s_add_u32 m0, m0, 0x1000
	v_mfma_f32_32x32x16_bf16 v[48:63], v[92:95], v[96:99], v[48:63]
	v_mfma_f32_32x32x16_bf16 v[32:47], v[92:95], v[100:103], v[32:47]
	global_load_lds_dwordx4 v254, s[34:35]
	s_add_u32 m0, m0, 0x1000
	v_mfma_f32_32x32x16_bf16 v[16:31], v[92:95], v[104:107], v[16:31]
	v_mfma_f32_32x32x16_bf16 v[0:15], v[92:95], v[108:111], v[0:15]
	global_load_lds_dwordx4 v254, s[36:37]
	s_add_u32 m0, m0, 0x1000
	v_mfma_f32_32x32x16_bf16 v[48:63], v[112:115], v[226:229], v[48:63]
	v_mfma_f32_32x32x16_bf16 v[32:47], v[112:115], v[230:233], v[32:47]
	global_load_lds_dwordx4 v254, s[38:39]
	s_add_u32 m0, m0, 0x1000
	v_mfma_f32_32x32x16_bf16 v[16:31], v[112:115], v[234:237], v[16:31]
	v_mfma_f32_32x32x16_bf16 v[0:15], v[112:115], v[238:241], v[0:15]
	global_load_lds_dwordx4 v254, s[40:41]
	s_add_u32 m0, m0, 0x1000
	v_mfma_f32_32x32x16_bf16 v[48:63], v[242:245], v[246:249], v[48:63]
	v_mfma_f32_32x32x16_bf16 v[32:47], v[242:245], v[250:253], v[32:47]
	global_load_lds_dwordx4 v254, s[42:43]
	s_add_u32 m0, m0, 0x1000
	v_mfma_f32_32x32x16_bf16 v[16:31], v[242:245], v[144:147], v[16:31]
	v_mfma_f32_32x32x16_bf16 v[0:15], v[242:245], v[184:187], v[0:15]
	global_load_lds_dwordx4 v254, s[44:45]
	v_add_u32_e32 v254, 0x80, v254
	s_waitcnt vmcnt(8)
	s_barrier
	ds_read_b128 v[64:67], v255 offset:32768
	ds_read_b128 v[76:79], v188 offset:49152
	ds_read_b128 v[80:83], v188 offset:53248
	ds_read_b128 v[84:87], v188 offset:57344
	ds_read_b128 v[88:91], v188 offset:61440
	ds_read_b128 v[92:95], v189 offset:32768
	ds_read_b128 v[96:99], v190 offset:49152
	ds_read_b128 v[100:103], v190 offset:53248
	ds_read_b128 v[104:107], v190 offset:57344
	ds_read_b128 v[108:111], v190 offset:61440
	ds_read_b128 v[112:115], v191 offset:32768
	ds_read_b128 v[226:229], v192 offset:49152
	ds_read_b128 v[230:233], v192 offset:53248
	ds_read_b128 v[234:237], v192 offset:57344
	ds_read_b128 v[238:241], v192 offset:61440
	ds_read_b128 v[242:245], v193 offset:32768
	ds_read_b128 v[246:249], v194 offset:49152
	ds_read_b128 v[250:253], v194 offset:53248
	ds_read_b128 v[144:147], v194 offset:57344
	ds_read_b128 v[184:187], v194 offset:61440
	s_waitcnt lgkmcnt(0)
	s_barrier
	s_add_u32 m0, s46, 0x8000
	v_mfma_f32_32x32x16_bf16 v[48:63], v[64:67], v[76:79], v[48:63]
	v_mfma_f32_32x32x16_bf16 v[32:47], v[64:67], v[80:83], v[32:47]
	global_load_lds_dwordx4 v254, s[28:29]
	s_add_u32 m0, m0, 0x1000
	v_mfma_f32_32x32x16_bf16 v[16:31], v[64:67], v[84:87], v[16:31]
	v_mfma_f32_32x32x16_bf16 v[0:15], v[64:67], v[88:91], v[0:15]
	global_load_lds_dwordx4 v254, s[30:31]
	s_add_u32 m0, m0, 0x1000
	v_mfma_f32_32x32x16_bf16 v[48:63], v[92:95], v[96:99], v[48:63]
	v_mfma_f32_32x32x16_bf16 v[32:47], v[92:95], v[100:103], v[32:47]
	global_load_lds_dwordx4 v254, s[34:35]
	s_add_u32 m0, m0, 0x1000
	v_mfma_f32_32x32x16_bf16 v[16:31], v[92:95], v[104:107], v[16:31]
	v_mfma_f32_32x32x16_bf16 v[0:15], v[92:95], v[108:111], v[0:15]
	global_load_lds_dwordx4 v254, s[36:37]
	s_add_u32 m0, m0, 0x1000
	v_mfma_f32_32x32x16_bf16 v[48:63], v[112:115], v[226:229], v[48:63]
	v_mfma_f32_32x32x16_bf16 v[32:47], v[112:115], v[230:233], v[32:47]
	global_load_lds_dwordx4 v254, s[38:39]
	s_add_u32 m0, m0, 0x1000
	v_mfma_f32_32x32x16_bf16 v[16:31], v[112:115], v[234:237], v[16:31]
	v_mfma_f32_32x32x16_bf16 v[0:15], v[112:115], v[238:241], v[0:15]
	global_load_lds_dwordx4 v254, s[40:41]
	s_add_u32 m0, m0, 0x1000
	v_mfma_f32_32x32x16_bf16 v[48:63], v[242:245], v[246:249], v[48:63]
	v_mfma_f32_32x32x16_bf16 v[32:47], v[242:245], v[250:253], v[32:47]
	global_load_lds_dwordx4 v254, s[42:43]
	s_add_u32 m0, m0, 0x1000
	v_mfma_f32_32x32x16_bf16 v[16:31], v[242:245], v[144:147], v[16:31]
	v_mfma_f32_32x32x16_bf16 v[0:15], v[242:245], v[184:187], v[0:15]
	global_load_lds_dwordx4 v254, s[44:45]
	v_add_u32_e32 v254, 0x80, v254
	s_sub_u32 s47, s47, 1
	s_cmp_lg_u32 s47, 0
	s_cbranch_scc1 .Lgk_loop_p9
	s_add_u32 s50, s3, s33
	s_cmp_gt_u32 s50, 0xbff
	s_cbranch_scc1 .Lgk_tailplain_p9
.LBB0_828_pf_p9:
	s_mul_hi_i32 s52, s50, 0x2aaaaaab
	s_lshr_b32 s53, s52, 31
	s_ashr_i32 s52, s52, 5
	s_add_i32 s52, s52, s53
	s_lshl_b32 s53, s52, 3
	s_mulk_i32 s52, 0xff40
	s_add_i32 s52, s52, s50
	s_ashr_i32 s54, s52, 31
	s_lshr_b32 s54, s54, 29
	s_add_i32 s54, s52, s54
	s_ashr_i32 s60, s54, 3
	s_and_b32 s54, s54, -8
	s_sub_i32 s51, s52, s54
	s_add_i32 s51, s51, s53
	s_lshl_b32 s56, s51, 7
	s_lshl_b32 s52, s60, 7
	s_ashr_i32 s57, s56, 31
	s_ashr_i32 s53, s52, 31
	s_lshl_b64 s[54:55], s[56:57], 11
	s_lshl_b64 s[58:59], s[52:53], 11
	s_lshl_b32 s48, s56, 11
	s_add_u32 s28, s14, s48
	s_addc_u32 s29, s15, 0
	s_add_u32 s28, s28, 0x679f000
	s_addc_u32 s29, s29, 0
	s_add_u32 s30, s28, 0x10000
	s_addc_u32 s31, s29, 0
	s_add_u32 s34, s30, 0x10000
	s_addc_u32 s35, s31, 0
	s_add_u32 s36, s34, 0x10000
	s_addc_u32 s37, s35, 0
	s_lshl_b32 s48, s52, 11
	s_add_u32 s38, s14, s48
	s_addc_u32 s39, s15, 0
	s_add_u32 s38, s38, 0x5a0000
	s_addc_u32 s39, s39, 0
	s_add_u32 s40, s38, 0x10000
	s_addc_u32 s41, s39, 0
	s_add_u32 s42, s40, 0x10000
	s_addc_u32 s43, s41, 0
	s_add_u32 s44, s42, 0x10000
	s_addc_u32 s45, s43, 0
	v_mov_b32_e32 v254, v142
	s_mov_b32 s49, 1
	s_waitcnt vmcnt(8)
	s_barrier
	ds_read_b128 v[64:67], v255
	ds_read_b128 v[76:79], v188 offset:16384
	ds_read_b128 v[80:83], v188 offset:20480
	ds_read_b128 v[84:87], v188 offset:24576
	ds_read_b128 v[88:91], v188 offset:28672
	ds_read_b128 v[92:95], v189
	ds_read_b128 v[96:99], v190 offset:16384
	ds_read_b128 v[100:103], v190 offset:20480
	ds_read_b128 v[104:107], v190 offset:24576
	ds_read_b128 v[108:111], v190 offset:28672
	ds_read_b128 v[112:115], v191
	ds_read_b128 v[226:229], v192 offset:16384
	ds_read_b128 v[230:233], v192 offset:20480
	ds_read_b128 v[234:237], v192 offset:24576
	ds_read_b128 v[238:241], v192 offset:28672
	ds_read_b128 v[242:245], v193
	ds_read_b128 v[246:249], v194 offset:16384
	ds_read_b128 v[250:253], v194 offset:20480
	ds_read_b128 v[144:147], v194 offset:24576
	ds_read_b128 v[184:187], v194 offset:28672
	s_waitcnt lgkmcnt(0)
	s_barrier
	s_mov_b32 m0, s46
	v_mfma_f32_32x32x16_bf16 v[48:63], v[64:67], v[76:79], v[48:63]
	v_mfma_f32_32x32x16_bf16 v[32:47], v[64:67], v[80:83], v[32:47]
	global_load_lds_dwordx4 v254, s[28:29]
	s_add_u32 m0, m0, 0x1000
	v_mfma_f32_32x32x16_bf16 v[16:31], v[64:67], v[84:87], v[16:31]
	v_mfma_f32_32x32x16_bf16 v[0:15], v[64:67], v[88:91], v[0:15]
	global_load_lds_dwordx4 v254, s[30:31]
	s_add_u32 m0, m0, 0x1000
	v_mfma_f32_32x32x16_bf16 v[48:63], v[92:95], v[96:99], v[48:63]
	v_mfma_f32_32x32x16_bf16 v[32:47], v[92:95], v[100:103], v[32:47]
	global_load_lds_dwordx4 v254, s[34:35]
	s_add_u32 m0, m0, 0x1000
	v_mfma_f32_32x32x16_bf16 v[16:31], v[92:95], v[104:107], v[16:31]
	v_mfma_f32_32x32x16_bf16 v[0:15], v[92:95], v[108:111], v[0:15]
	global_load_lds_dwordx4 v254, s[36:37]
	s_add_u32 m0, m0, 0x1000
	v_mfma_f32_32x32x16_bf16 v[48:63], v[112:115], v[226:229], v[48:63]
	v_mfma_f32_32x32x16_bf16 v[32:47], v[112:115], v[230:233], v[32:47]
	global_load_lds_dwordx4 v254, s[38:39]
	s_add_u32 m0, m0, 0x1000
	v_mfma_f32_32x32x16_bf16 v[16:31], v[112:115], v[234:237], v[16:31]
	v_mfma_f32_32x32x16_bf16 v[0:15], v[112:115], v[238:241], v[0:15]
	global_load_lds_dwordx4 v254, s[40:41]
	s_add_u32 m0, m0, 0x1000
	v_mfma_f32_32x32x16_bf16 v[48:63], v[242:245], v[246:249], v[48:63]
	v_mfma_f32_32x32x16_bf16 v[32:47], v[242:245], v[250:253], v[32:47]
	global_load_lds_dwordx4 v254, s[42:43]
	s_add_u32 m0, m0, 0x1000
	v_mfma_f32_32x32x16_bf16 v[16:31], v[242:245], v[144:147], v[16:31]
	v_mfma_f32_32x32x16_bf16 v[0:15], v[242:245], v[184:187], v[0:15]
	global_load_lds_dwordx4 v254, s[44:45]
	v_add_u32_e32 v254, 0x80, v254
	s_waitcnt vmcnt(8)
	s_barrier
	ds_read_b128 v[64:67], v255 offset:32768
	ds_read_b128 v[76:79], v188 offset:49152
	ds_read_b128 v[80:83], v188 offset:53248
	ds_read_b128 v[84:87], v188 offset:57344
	ds_read_b128 v[88:91], v188 offset:61440
	ds_read_b128 v[92:95], v189 offset:32768
	ds_read_b128 v[96:99], v190 offset:49152
	ds_read_b128 v[100:103], v190 offset:53248
	ds_read_b128 v[104:107], v190 offset:57344
	ds_read_b128 v[108:111], v190 offset:61440
	ds_read_b128 v[112:115], v191 offset:32768
	ds_read_b128 v[226:229], v192 offset:49152
	ds_read_b128 v[230:233], v192 offset:53248
	ds_read_b128 v[234:237], v192 offset:57344
	ds_read_b128 v[238:241], v192 offset:61440
	ds_read_b128 v[242:245], v193 offset:32768
	ds_read_b128 v[246:249], v194 offset:49152
	ds_read_b128 v[250:253], v194 offset:53248
	ds_read_b128 v[144:147], v194 offset:57344
	ds_read_b128 v[184:187], v194 offset:61440
	s_waitcnt lgkmcnt(0)
	s_barrier
	s_add_u32 m0, s46, 0x8000
	v_mfma_f32_32x32x16_bf16 v[48:63], v[64:67], v[76:79], v[48:63]
	v_mfma_f32_32x32x16_bf16 v[32:47], v[64:67], v[80:83], v[32:47]
	global_load_lds_dwordx4 v254, s[28:29]
	s_add_u32 m0, m0, 0x1000
	v_mfma_f32_32x32x16_bf16 v[16:31], v[64:67], v[84:87], v[16:31]
	v_mfma_f32_32x32x16_bf16 v[0:15], v[64:67], v[88:91], v[0:15]
	global_load_lds_dwordx4 v254, s[30:31]
	s_add_u32 m0, m0, 0x1000
	v_mfma_f32_32x32x16_bf16 v[48:63], v[92:95], v[96:99], v[48:63]
	v_mfma_f32_32x32x16_bf16 v[32:47], v[92:95], v[100:103], v[32:47]
	global_load_lds_dwordx4 v254, s[34:35]
	s_add_u32 m0, m0, 0x1000
	v_mfma_f32_32x32x16_bf16 v[16:31], v[92:95], v[104:107], v[16:31]
	v_mfma_f32_32x32x16_bf16 v[0:15], v[92:95], v[108:111], v[0:15]
	global_load_lds_dwordx4 v254, s[36:37]
	s_add_u32 m0, m0, 0x1000
	v_mfma_f32_32x32x16_bf16 v[48:63], v[112:115], v[226:229], v[48:63]
	v_mfma_f32_32x32x16_bf16 v[32:47], v[112:115], v[230:233], v[32:47]
	global_load_lds_dwordx4 v254, s[38:39]
	s_add_u32 m0, m0, 0x1000
	v_mfma_f32_32x32x16_bf16 v[16:31], v[112:115], v[234:237], v[16:31]
	v_mfma_f32_32x32x16_bf16 v[0:15], v[112:115], v[238:241], v[0:15]
	global_load_lds_dwordx4 v254, s[40:41]
	s_add_u32 m0, m0, 0x1000
	v_mfma_f32_32x32x16_bf16 v[48:63], v[242:245], v[246:249], v[48:63]
	v_mfma_f32_32x32x16_bf16 v[32:47], v[242:245], v[250:253], v[32:47]
	global_load_lds_dwordx4 v254, s[42:43]
	s_add_u32 m0, m0, 0x1000
	v_mfma_f32_32x32x16_bf16 v[16:31], v[242:245], v[144:147], v[16:31]
	v_mfma_f32_32x32x16_bf16 v[0:15], v[242:245], v[184:187], v[0:15]
	global_load_lds_dwordx4 v254, s[44:45]
	v_add_u32_e32 v254, 0x80, v254
	s_branch .LBB0_832
.Lgk_tailplain_p9:
	s_mov_b32 s49, 0
	s_waitcnt vmcnt(8)
	s_barrier
	ds_read_b128 v[64:67], v255
	ds_read_b128 v[76:79], v188 offset:16384
	ds_read_b128 v[80:83], v188 offset:20480
	ds_read_b128 v[84:87], v188 offset:24576
	ds_read_b128 v[88:91], v188 offset:28672
	ds_read_b128 v[92:95], v189
	ds_read_b128 v[96:99], v190 offset:16384
	ds_read_b128 v[100:103], v190 offset:20480
	ds_read_b128 v[104:107], v190 offset:24576
	ds_read_b128 v[108:111], v190 offset:28672
	ds_read_b128 v[112:115], v191
	ds_read_b128 v[226:229], v192 offset:16384
	ds_read_b128 v[230:233], v192 offset:20480
	ds_read_b128 v[234:237], v192 offset:24576
	ds_read_b128 v[238:241], v192 offset:28672
	ds_read_b128 v[242:245], v193
	ds_read_b128 v[246:249], v194 offset:16384
	ds_read_b128 v[250:253], v194 offset:20480
	ds_read_b128 v[144:147], v194 offset:24576
	ds_read_b128 v[184:187], v194 offset:28672
	s_waitcnt lgkmcnt(0)
	s_barrier
	v_mfma_f32_32x32x16_bf16 v[48:63], v[64:67], v[76:79], v[48:63]
	v_mfma_f32_32x32x16_bf16 v[32:47], v[64:67], v[80:83], v[32:47]
	v_mfma_f32_32x32x16_bf16 v[16:31], v[64:67], v[84:87], v[16:31]
	v_mfma_f32_32x32x16_bf16 v[0:15], v[64:67], v[88:91], v[0:15]
	v_mfma_f32_32x32x16_bf16 v[48:63], v[92:95], v[96:99], v[48:63]
	v_mfma_f32_32x32x16_bf16 v[32:47], v[92:95], v[100:103], v[32:47]
	v_mfma_f32_32x32x16_bf16 v[16:31], v[92:95], v[104:107], v[16:31]
	v_mfma_f32_32x32x16_bf16 v[0:15], v[92:95], v[108:111], v[0:15]
	v_mfma_f32_32x32x16_bf16 v[48:63], v[112:115], v[226:229], v[48:63]
	v_mfma_f32_32x32x16_bf16 v[32:47], v[112:115], v[230:233], v[32:47]
	v_mfma_f32_32x32x16_bf16 v[16:31], v[112:115], v[234:237], v[16:31]
	v_mfma_f32_32x32x16_bf16 v[0:15], v[112:115], v[238:241], v[0:15]
	v_mfma_f32_32x32x16_bf16 v[48:63], v[242:245], v[246:249], v[48:63]
	v_mfma_f32_32x32x16_bf16 v[32:47], v[242:245], v[250:253], v[32:47]
	v_mfma_f32_32x32x16_bf16 v[16:31], v[242:245], v[144:147], v[16:31]
	v_mfma_f32_32x32x16_bf16 v[0:15], v[242:245], v[184:187], v[0:15]
	s_waitcnt vmcnt(0)
	s_barrier
	ds_read_b128 v[64:67], v255 offset:32768
	ds_read_b128 v[76:79], v188 offset:49152
	ds_read_b128 v[80:83], v188 offset:53248
	ds_read_b128 v[84:87], v188 offset:57344
	ds_read_b128 v[88:91], v188 offset:61440
	ds_read_b128 v[92:95], v189 offset:32768
	ds_read_b128 v[96:99], v190 offset:49152
	ds_read_b128 v[100:103], v190 offset:53248
	ds_read_b128 v[104:107], v190 offset:57344
	ds_read_b128 v[108:111], v190 offset:61440
	ds_read_b128 v[112:115], v191 offset:32768
	ds_read_b128 v[226:229], v192 offset:49152
	ds_read_b128 v[230:233], v192 offset:53248
	ds_read_b128 v[234:237], v192 offset:57344
	ds_read_b128 v[238:241], v192 offset:61440
	ds_read_b128 v[242:245], v193 offset:32768
	ds_read_b128 v[246:249], v194 offset:49152
	ds_read_b128 v[250:253], v194 offset:53248
	ds_read_b128 v[144:147], v194 offset:57344
	ds_read_b128 v[184:187], v194 offset:61440
	s_waitcnt lgkmcnt(0)
	s_barrier
	v_mfma_f32_32x32x16_bf16 v[48:63], v[64:67], v[76:79], v[48:63]
	v_mfma_f32_32x32x16_bf16 v[32:47], v[64:67], v[80:83], v[32:47]
	v_mfma_f32_32x32x16_bf16 v[16:31], v[64:67], v[84:87], v[16:31]
	v_mfma_f32_32x32x16_bf16 v[0:15], v[64:67], v[88:91], v[0:15]
	v_mfma_f32_32x32x16_bf16 v[48:63], v[92:95], v[96:99], v[48:63]
	v_mfma_f32_32x32x16_bf16 v[32:47], v[92:95], v[100:103], v[32:47]
	v_mfma_f32_32x32x16_bf16 v[16:31], v[92:95], v[104:107], v[16:31]
	v_mfma_f32_32x32x16_bf16 v[0:15], v[92:95], v[108:111], v[0:15]
	v_mfma_f32_32x32x16_bf16 v[48:63], v[112:115], v[226:229], v[48:63]
	v_mfma_f32_32x32x16_bf16 v[32:47], v[112:115], v[230:233], v[32:47]
	v_mfma_f32_32x32x16_bf16 v[16:31], v[112:115], v[234:237], v[16:31]
	v_mfma_f32_32x32x16_bf16 v[0:15], v[112:115], v[238:241], v[0:15]
	v_mfma_f32_32x32x16_bf16 v[48:63], v[242:245], v[246:249], v[48:63]
	v_mfma_f32_32x32x16_bf16 v[32:47], v[242:245], v[250:253], v[32:47]
	v_mfma_f32_32x32x16_bf16 v[16:31], v[242:245], v[144:147], v[16:31]
	v_mfma_f32_32x32x16_bf16 v[0:15], v[242:245], v[184:187], v[0:15]
	s_branch .LBB0_832

.Lgk_loop_p11:
	s_waitcnt vmcnt(8)
	s_barrier
	ds_read_b128 v[70:73], v156
	ds_read_b128 v[74:77], v157 offset:16384
	ds_read_b128 v[78:81], v157 offset:20480
	ds_read_b128 v[82:85], v157 offset:24576
	ds_read_b128 v[86:89], v157 offset:28672
	ds_read_b128 v[90:93], v158
	ds_read_b128 v[94:97], v159 offset:16384
	ds_read_b128 v[98:101], v159 offset:20480
	ds_read_b128 v[102:105], v159 offset:24576
	ds_read_b128 v[106:109], v159 offset:28672
	ds_read_b128 v[110:113], v160
	ds_read_b128 v[202:205], v161 offset:16384
	ds_read_b128 v[206:209], v161 offset:20480
	ds_read_b128 v[210:213], v161 offset:24576
	ds_read_b128 v[214:217], v161 offset:28672
	ds_read_b128 v[218:221], v162
	ds_read_b128 v[222:225], v163 offset:16384
	ds_read_b128 v[226:229], v163 offset:20480
	ds_read_b128 v[230:233], v163 offset:24576
	ds_read_b128 v[234:237], v163 offset:28672
	s_waitcnt lgkmcnt(0)
	s_barrier
	s_mov_b32 m0, s36
	v_mfma_f32_32x32x16_bf16 v[48:63], v[70:73], v[74:77], v[48:63]
	v_mfma_f32_32x32x16_bf16 v[32:47], v[70:73], v[78:81], v[32:47]
	global_load_lds_dwordx4 v254, s[18:19]
	s_add_u32 m0, m0, 0x1000
	v_mfma_f32_32x32x16_bf16 v[16:31], v[70:73], v[82:85], v[16:31]
	v_mfma_f32_32x32x16_bf16 v[0:15], v[70:73], v[86:89], v[0:15]
	global_load_lds_dwordx4 v254, s[20:21]
	s_add_u32 m0, m0, 0x1000
	v_mfma_f32_32x32x16_bf16 v[48:63], v[90:93], v[94:97], v[48:63]
	v_mfma_f32_32x32x16_bf16 v[32:47], v[90:93], v[98:101], v[32:47]
	global_load_lds_dwordx4 v254, s[22:23]
	s_add_u32 m0, m0, 0x1000
	v_mfma_f32_32x32x16_bf16 v[16:31], v[90:93], v[102:105], v[16:31]
	v_mfma_f32_32x32x16_bf16 v[0:15], v[90:93], v[106:109], v[0:15]
	global_load_lds_dwordx4 v254, s[24:25]
	s_add_u32 m0, m0, 0x1000
	v_mfma_f32_32x32x16_bf16 v[48:63], v[110:113], v[202:205], v[48:63]
	v_mfma_f32_32x32x16_bf16 v[32:47], v[110:113], v[206:209], v[32:47]
	global_load_lds_dwordx4 v254, s[26:27]
	s_add_u32 m0, m0, 0x1000
	v_mfma_f32_32x32x16_bf16 v[16:31], v[110:113], v[210:213], v[16:31]
	v_mfma_f32_32x32x16_bf16 v[0:15], v[110:113], v[214:217], v[0:15]
	global_load_lds_dwordx4 v254, s[28:29]
	s_add_u32 m0, m0, 0x1000
	v_mfma_f32_32x32x16_bf16 v[48:63], v[218:221], v[222:225], v[48:63]
	v_mfma_f32_32x32x16_bf16 v[32:47], v[218:221], v[226:229], v[32:47]
	global_load_lds_dwordx4 v254, s[30:31]
	s_add_u32 m0, m0, 0x1000
	v_mfma_f32_32x32x16_bf16 v[16:31], v[218:221], v[230:233], v[16:31]
	v_mfma_f32_32x32x16_bf16 v[0:15], v[218:221], v[234:237], v[0:15]
	global_load_lds_dwordx4 v254, s[34:35]
	v_add_u32_e32 v254, 0x80, v254
	s_waitcnt vmcnt(8)
	s_barrier
	ds_read_b128 v[70:73], v156 offset:32768
	ds_read_b128 v[74:77], v157 offset:49152
	ds_read_b128 v[78:81], v157 offset:53248
	ds_read_b128 v[82:85], v157 offset:57344
	ds_read_b128 v[86:89], v157 offset:61440
	ds_read_b128 v[90:93], v158 offset:32768
	ds_read_b128 v[94:97], v159 offset:49152
	ds_read_b128 v[98:101], v159 offset:53248
	ds_read_b128 v[102:105], v159 offset:57344
	ds_read_b128 v[106:109], v159 offset:61440
	ds_read_b128 v[110:113], v160 offset:32768
	ds_read_b128 v[202:205], v161 offset:49152
	ds_read_b128 v[206:209], v161 offset:53248
	ds_read_b128 v[210:213], v161 offset:57344
	ds_read_b128 v[214:217], v161 offset:61440
	ds_read_b128 v[218:221], v162 offset:32768
	ds_read_b128 v[222:225], v163 offset:49152
	ds_read_b128 v[226:229], v163 offset:53248
	ds_read_b128 v[230:233], v163 offset:57344
	ds_read_b128 v[234:237], v163 offset:61440
	s_waitcnt lgkmcnt(0)
	s_barrier
	s_add_u32 m0, s36, 0x8000
	v_mfma_f32_32x32x16_bf16 v[48:63], v[70:73], v[74:77], v[48:63]
	v_mfma_f32_32x32x16_bf16 v[32:47], v[70:73], v[78:81], v[32:47]
	global_load_lds_dwordx4 v254, s[18:19]
	s_add_u32 m0, m0, 0x1000
	v_mfma_f32_32x32x16_bf16 v[16:31], v[70:73], v[82:85], v[16:31]
	v_mfma_f32_32x32x16_bf16 v[0:15], v[70:73], v[86:89], v[0:15]
	global_load_lds_dwordx4 v254, s[20:21]
	s_add_u32 m0, m0, 0x1000
	v_mfma_f32_32x32x16_bf16 v[48:63], v[90:93], v[94:97], v[48:63]
	v_mfma_f32_32x32x16_bf16 v[32:47], v[90:93], v[98:101], v[32:47]
	global_load_lds_dwordx4 v254, s[22:23]
	s_add_u32 m0, m0, 0x1000
	v_mfma_f32_32x32x16_bf16 v[16:31], v[90:93], v[102:105], v[16:31]
	v_mfma_f32_32x32x16_bf16 v[0:15], v[90:93], v[106:109], v[0:15]
	global_load_lds_dwordx4 v254, s[24:25]
	s_add_u32 m0, m0, 0x1000
	v_mfma_f32_32x32x16_bf16 v[48:63], v[110:113], v[202:205], v[48:63]
	v_mfma_f32_32x32x16_bf16 v[32:47], v[110:113], v[206:209], v[32:47]
	global_load_lds_dwordx4 v254, s[26:27]
	s_add_u32 m0, m0, 0x1000
	v_mfma_f32_32x32x16_bf16 v[16:31], v[110:113], v[210:213], v[16:31]
	v_mfma_f32_32x32x16_bf16 v[0:15], v[110:113], v[214:217], v[0:15]
	global_load_lds_dwordx4 v254, s[28:29]
	s_add_u32 m0, m0, 0x1000
	v_mfma_f32_32x32x16_bf16 v[48:63], v[218:221], v[222:225], v[48:63]
	v_mfma_f32_32x32x16_bf16 v[32:47], v[218:221], v[226:229], v[32:47]
	global_load_lds_dwordx4 v254, s[30:31]
	s_add_u32 m0, m0, 0x1000
	v_mfma_f32_32x32x16_bf16 v[16:31], v[218:221], v[230:233], v[16:31]
	v_mfma_f32_32x32x16_bf16 v[0:15], v[218:221], v[234:237], v[0:15]
	global_load_lds_dwordx4 v254, s[34:35]
	v_add_u32_e32 v254, 0x80, v254
	s_sub_u32 s37, s37, 1
	s_cmp_lg_u32 s37, 0
	s_cbranch_scc1 .Lgk_loop_p11
	s_add_u32 s40, s3, s33
	s_cmp_gt_u32 s40, 0x3ff
	s_cbranch_scc1 .Lgk_tailplain_p11
.LBB0_1046_pf_p11:
	s_ashr_i32 s41, s40, 31
	s_lshr_b32 s41, s41, 26
	s_add_i32 s41, s40, s41
	s_ashr_i32 s42, s41, 6
	s_andn2_b32 s41, s41, 63
	s_sub_i32 s41, s40, s41
	s_ashr_i32 s43, s41, 31
	s_lshr_b32 s43, s43, 29
	s_add_i32 s43, s41, s43
	s_ashr_i32 s46, s43, 3
	s_and_b32 s43, s43, -8
	s_lshl_b32 s42, s42, 3
	s_sub_i32 s41, s41, s43
	s_add_i32 s41, s41, s42
	s_lshl_b32 s44, s41, 7
	s_ashr_i32 s45, s44, 31
	s_lshl_b32 s47, s46, 7
	s_lshl_b64 s[42:43], s[44:45], 11
	s_ashr_i32 s48, s47, 31
	s_lshl_b32 s38, s44, 11
	s_add_u32 s18, s14, s38
	s_addc_u32 s19, s15, 0
	s_add_u32 s18, s18, 0xb79f000
	s_addc_u32 s19, s19, 0
	s_add_u32 s20, s18, 0x10000
	s_addc_u32 s21, s19, 0
	s_add_u32 s22, s20, 0x10000
	s_addc_u32 s23, s21, 0
	s_add_u32 s24, s22, 0x10000
	s_addc_u32 s25, s23, 0
	s_lshl_b32 s38, s47, 11
	s_add_u32 s26, s14, s38
	s_addc_u32 s27, s15, 0
	s_add_u32 s26, s26, 0xba0000
	s_addc_u32 s27, s27, 0
	s_add_u32 s28, s26, 0x10000
	s_addc_u32 s29, s27, 0
	s_add_u32 s30, s28, 0x10000
	s_addc_u32 s31, s29, 0
	s_add_u32 s34, s30, 0x10000
	s_addc_u32 s35, s31, 0
	v_mov_b32_e32 v254, v64
	s_mov_b32 s39, 1
	s_waitcnt vmcnt(8)
	s_barrier
	ds_read_b128 v[70:73], v156
	ds_read_b128 v[74:77], v157 offset:16384
	ds_read_b128 v[78:81], v157 offset:20480
	ds_read_b128 v[82:85], v157 offset:24576
	ds_read_b128 v[86:89], v157 offset:28672
	ds_read_b128 v[90:93], v158
	ds_read_b128 v[94:97], v159 offset:16384
	ds_read_b128 v[98:101], v159 offset:20480
	ds_read_b128 v[102:105], v159 offset:24576
	ds_read_b128 v[106:109], v159 offset:28672
	ds_read_b128 v[110:113], v160
	ds_read_b128 v[202:205], v161 offset:16384
	ds_read_b128 v[206:209], v161 offset:20480
	ds_read_b128 v[210:213], v161 offset:24576
	ds_read_b128 v[214:217], v161 offset:28672
	ds_read_b128 v[218:221], v162
	ds_read_b128 v[222:225], v163 offset:16384
	ds_read_b128 v[226:229], v163 offset:20480
	ds_read_b128 v[230:233], v163 offset:24576
	ds_read_b128 v[234:237], v163 offset:28672
	s_waitcnt lgkmcnt(0)
	s_barrier
	s_mov_b32 m0, s36
	v_mfma_f32_32x32x16_bf16 v[48:63], v[70:73], v[74:77], v[48:63]
	v_mfma_f32_32x32x16_bf16 v[32:47], v[70:73], v[78:81], v[32:47]
	global_load_lds_dwordx4 v254, s[18:19]
	s_add_u32 m0, m0, 0x1000
	v_mfma_f32_32x32x16_bf16 v[16:31], v[70:73], v[82:85], v[16:31]
	v_mfma_f32_32x32x16_bf16 v[0:15], v[70:73], v[86:89], v[0:15]
	global_load_lds_dwordx4 v254, s[20:21]
	s_add_u32 m0, m0, 0x1000
	v_mfma_f32_32x32x16_bf16 v[48:63], v[90:93], v[94:97], v[48:63]
	v_mfma_f32_32x32x16_bf16 v[32:47], v[90:93], v[98:101], v[32:47]
	global_load_lds_dwordx4 v254, s[22:23]
	s_add_u32 m0, m0, 0x1000
	v_mfma_f32_32x32x16_bf16 v[16:31], v[90:93], v[102:105], v[16:31]
	v_mfma_f32_32x32x16_bf16 v[0:15], v[90:93], v[106:109], v[0:15]
	global_load_lds_dwordx4 v254, s[24:25]
	s_add_u32 m0, m0, 0x1000
	v_mfma_f32_32x32x16_bf16 v[48:63], v[110:113], v[202:205], v[48:63]
	v_mfma_f32_32x32x16_bf16 v[32:47], v[110:113], v[206:209], v[32:47]
	global_load_lds_dwordx4 v254, s[26:27]
	s_add_u32 m0, m0, 0x1000
	v_mfma_f32_32x32x16_bf16 v[16:31], v[110:113], v[210:213], v[16:31]
	v_mfma_f32_32x32x16_bf16 v[0:15], v[110:113], v[214:217], v[0:15]
	global_load_lds_dwordx4 v254, s[28:29]
	s_add_u32 m0, m0, 0x1000
	v_mfma_f32_32x32x16_bf16 v[48:63], v[218:221], v[222:225], v[48:63]
	v_mfma_f32_32x32x16_bf16 v[32:47], v[218:221], v[226:229], v[32:47]
	global_load_lds_dwordx4 v254, s[30:31]
	s_add_u32 m0, m0, 0x1000
	v_mfma_f32_32x32x16_bf16 v[16:31], v[218:221], v[230:233], v[16:31]
	v_mfma_f32_32x32x16_bf16 v[0:15], v[218:221], v[234:237], v[0:15]
	global_load_lds_dwordx4 v254, s[34:35]
	v_add_u32_e32 v254, 0x80, v254
	s_waitcnt vmcnt(8)
	s_barrier
	ds_read_b128 v[70:73], v156 offset:32768
	ds_read_b128 v[74:77], v157 offset:49152
	ds_read_b128 v[78:81], v157 offset:53248
	ds_read_b128 v[82:85], v157 offset:57344
	ds_read_b128 v[86:89], v157 offset:61440
	ds_read_b128 v[90:93], v158 offset:32768
	ds_read_b128 v[94:97], v159 offset:49152
	ds_read_b128 v[98:101], v159 offset:53248
	ds_read_b128 v[102:105], v159 offset:57344
	ds_read_b128 v[106:109], v159 offset:61440
	ds_read_b128 v[110:113], v160 offset:32768
	ds_read_b128 v[202:205], v161 offset:49152
	ds_read_b128 v[206:209], v161 offset:53248
	ds_read_b128 v[210:213], v161 offset:57344
	ds_read_b128 v[214:217], v161 offset:61440
	ds_read_b128 v[218:221], v162 offset:32768
	ds_read_b128 v[222:225], v163 offset:49152
	ds_read_b128 v[226:229], v163 offset:53248
	ds_read_b128 v[230:233], v163 offset:57344
	ds_read_b128 v[234:237], v163 offset:61440
	s_waitcnt lgkmcnt(0)
	s_barrier
	s_add_u32 m0, s36, 0x8000
	v_mfma_f32_32x32x16_bf16 v[48:63], v[70:73], v[74:77], v[48:63]
	v_mfma_f32_32x32x16_bf16 v[32:47], v[70:73], v[78:81], v[32:47]
	global_load_lds_dwordx4 v254, s[18:19]
	s_add_u32 m0, m0, 0x1000
	v_mfma_f32_32x32x16_bf16 v[16:31], v[70:73], v[82:85], v[16:31]
	v_mfma_f32_32x32x16_bf16 v[0:15], v[70:73], v[86:89], v[0:15]
	global_load_lds_dwordx4 v254, s[20:21]
	s_add_u32 m0, m0, 0x1000
	v_mfma_f32_32x32x16_bf16 v[48:63], v[90:93], v[94:97], v[48:63]
	v_mfma_f32_32x32x16_bf16 v[32:47], v[90:93], v[98:101], v[32:47]
	global_load_lds_dwordx4 v254, s[22:23]
	s_add_u32 m0, m0, 0x1000
	v_mfma_f32_32x32x16_bf16 v[16:31], v[90:93], v[102:105], v[16:31]
	v_mfma_f32_32x32x16_bf16 v[0:15], v[90:93], v[106:109], v[0:15]
	global_load_lds_dwordx4 v254, s[24:25]
	s_add_u32 m0, m0, 0x1000
	v_mfma_f32_32x32x16_bf16 v[48:63], v[110:113], v[202:205], v[48:63]
	v_mfma_f32_32x32x16_bf16 v[32:47], v[110:113], v[206:209], v[32:47]
	global_load_lds_dwordx4 v254, s[26:27]
	s_add_u32 m0, m0, 0x1000
	v_mfma_f32_32x32x16_bf16 v[16:31], v[110:113], v[210:213], v[16:31]
	v_mfma_f32_32x32x16_bf16 v[0:15], v[110:113], v[214:217], v[0:15]
	global_load_lds_dwordx4 v254, s[28:29]
	s_add_u32 m0, m0, 0x1000
	v_mfma_f32_32x32x16_bf16 v[48:63], v[218:221], v[222:225], v[48:63]
	v_mfma_f32_32x32x16_bf16 v[32:47], v[218:221], v[226:229], v[32:47]
	global_load_lds_dwordx4 v254, s[30:31]
	s_add_u32 m0, m0, 0x1000
	v_mfma_f32_32x32x16_bf16 v[16:31], v[218:221], v[230:233], v[16:31]
	v_mfma_f32_32x32x16_bf16 v[0:15], v[218:221], v[234:237], v[0:15]
	global_load_lds_dwordx4 v254, s[34:35]
	v_add_u32_e32 v254, 0x80, v254
	s_branch .LBB0_1050
.Lgk_tailplain_p11:
	s_mov_b32 s39, 0
	s_waitcnt vmcnt(8)
	s_barrier
	ds_read_b128 v[70:73], v156
	ds_read_b128 v[74:77], v157 offset:16384
	ds_read_b128 v[78:81], v157 offset:20480
	ds_read_b128 v[82:85], v157 offset:24576
	ds_read_b128 v[86:89], v157 offset:28672
	ds_read_b128 v[90:93], v158
	ds_read_b128 v[94:97], v159 offset:16384
	ds_read_b128 v[98:101], v159 offset:20480
	ds_read_b128 v[102:105], v159 offset:24576
	ds_read_b128 v[106:109], v159 offset:28672
	ds_read_b128 v[110:113], v160
	ds_read_b128 v[202:205], v161 offset:16384
	ds_read_b128 v[206:209], v161 offset:20480
	ds_read_b128 v[210:213], v161 offset:24576
	ds_read_b128 v[214:217], v161 offset:28672
	ds_read_b128 v[218:221], v162
	ds_read_b128 v[222:225], v163 offset:16384
	ds_read_b128 v[226:229], v163 offset:20480
	ds_read_b128 v[230:233], v163 offset:24576
	ds_read_b128 v[234:237], v163 offset:28672
	s_waitcnt lgkmcnt(0)
	s_barrier
	v_mfma_f32_32x32x16_bf16 v[48:63], v[70:73], v[74:77], v[48:63]
	v_mfma_f32_32x32x16_bf16 v[32:47], v[70:73], v[78:81], v[32:47]
	v_mfma_f32_32x32x16_bf16 v[16:31], v[70:73], v[82:85], v[16:31]
	v_mfma_f32_32x32x16_bf16 v[0:15], v[70:73], v[86:89], v[0:15]
	v_mfma_f32_32x32x16_bf16 v[48:63], v[90:93], v[94:97], v[48:63]
	v_mfma_f32_32x32x16_bf16 v[32:47], v[90:93], v[98:101], v[32:47]
	v_mfma_f32_32x32x16_bf16 v[16:31], v[90:93], v[102:105], v[16:31]
	v_mfma_f32_32x32x16_bf16 v[0:15], v[90:93], v[106:109], v[0:15]
	v_mfma_f32_32x32x16_bf16 v[48:63], v[110:113], v[202:205], v[48:63]
	v_mfma_f32_32x32x16_bf16 v[32:47], v[110:113], v[206:209], v[32:47]
	v_mfma_f32_32x32x16_bf16 v[16:31], v[110:113], v[210:213], v[16:31]
	v_mfma_f32_32x32x16_bf16 v[0:15], v[110:113], v[214:217], v[0:15]
	v_mfma_f32_32x32x16_bf16 v[48:63], v[218:221], v[222:225], v[48:63]
	v_mfma_f32_32x32x16_bf16 v[32:47], v[218:221], v[226:229], v[32:47]
	v_mfma_f32_32x32x16_bf16 v[16:31], v[218:221], v[230:233], v[16:31]
	v_mfma_f32_32x32x16_bf16 v[0:15], v[218:221], v[234:237], v[0:15]
	s_waitcnt vmcnt(0)
	s_barrier
	ds_read_b128 v[70:73], v156 offset:32768
	ds_read_b128 v[74:77], v157 offset:49152
	ds_read_b128 v[78:81], v157 offset:53248
	ds_read_b128 v[82:85], v157 offset:57344
	ds_read_b128 v[86:89], v157 offset:61440
	ds_read_b128 v[90:93], v158 offset:32768
	ds_read_b128 v[94:97], v159 offset:49152
	ds_read_b128 v[98:101], v159 offset:53248
	ds_read_b128 v[102:105], v159 offset:57344
	ds_read_b128 v[106:109], v159 offset:61440
	ds_read_b128 v[110:113], v160 offset:32768
	ds_read_b128 v[202:205], v161 offset:49152
	ds_read_b128 v[206:209], v161 offset:53248
	ds_read_b128 v[210:213], v161 offset:57344
	ds_read_b128 v[214:217], v161 offset:61440
	ds_read_b128 v[218:221], v162 offset:32768
	ds_read_b128 v[222:225], v163 offset:49152
	ds_read_b128 v[226:229], v163 offset:53248
	ds_read_b128 v[230:233], v163 offset:57344
	ds_read_b128 v[234:237], v163 offset:61440
	s_waitcnt lgkmcnt(0)
	s_barrier
	v_mfma_f32_32x32x16_bf16 v[48:63], v[70:73], v[74:77], v[48:63]
	v_mfma_f32_32x32x16_bf16 v[32:47], v[70:73], v[78:81], v[32:47]
	v_mfma_f32_32x32x16_bf16 v[16:31], v[70:73], v[82:85], v[16:31]
	v_mfma_f32_32x32x16_bf16 v[0:15], v[70:73], v[86:89], v[0:15]
	v_mfma_f32_32x32x16_bf16 v[48:63], v[90:93], v[94:97], v[48:63]
	v_mfma_f32_32x32x16_bf16 v[32:47], v[90:93], v[98:101], v[32:47]
	v_mfma_f32_32x32x16_bf16 v[16:31], v[90:93], v[102:105], v[16:31]
	v_mfma_f32_32x32x16_bf16 v[0:15], v[90:93], v[106:109], v[0:15]
	v_mfma_f32_32x32x16_bf16 v[48:63], v[110:113], v[202:205], v[48:63]
	v_mfma_f32_32x32x16_bf16 v[32:47], v[110:113], v[206:209], v[32:47]
	v_mfma_f32_32x32x16_bf16 v[16:31], v[110:113], v[210:213], v[16:31]
	v_mfma_f32_32x32x16_bf16 v[0:15], v[110:113], v[214:217], v[0:15]
	v_mfma_f32_32x32x16_bf16 v[48:63], v[218:221], v[222:225], v[48:63]
	v_mfma_f32_32x32x16_bf16 v[32:47], v[218:221], v[226:229], v[32:47]
	v_mfma_f32_32x32x16_bf16 v[16:31], v[218:221], v[230:233], v[16:31]
	v_mfma_f32_32x32x16_bf16 v[0:15], v[218:221], v[234:237], v[0:15]
	s_branch .LBB0_1050

.Lmap_done_1_pf_p12:
	s_lshl_b32 s44, s41, 7
	s_lshl_b32 s42, s50, 7
	s_ashr_i32 s45, s44, 31
	s_ashr_i32 s43, s42, 31
	s_lshl_b64 s[46:47], s[44:45], 11
	s_lshl_b64 s[48:49], s[42:43], 11
	s_lshl_b32 s38, s44, 11
	s_add_u32 s18, s14, s38
	s_addc_u32 s19, s15, 0
	s_add_u32 s18, s18, 0x679f000
	s_addc_u32 s19, s19, 0
	s_add_u32 s20, s18, 0x10000
	s_addc_u32 s21, s19, 0
	s_add_u32 s22, s20, 0x10000
	s_addc_u32 s23, s21, 0
	s_add_u32 s24, s22, 0x10000
	s_addc_u32 s25, s23, 0
	s_lshl_b32 s38, s42, 11
	s_add_u32 s26, s14, s38
	s_addc_u32 s27, s15, 0
	s_add_u32 s26, s26, 0x24a0000
	s_addc_u32 s27, s27, 0
	s_add_u32 s28, s26, 0x10000
	s_addc_u32 s29, s27, 0
	s_add_u32 s30, s28, 0x10000
	s_addc_u32 s31, s29, 0
	s_add_u32 s34, s30, 0x10000
	s_addc_u32 s35, s31, 0
	v_mov_b32_e32 v254, v76
	s_mov_b32 s39, 1
	s_waitcnt vmcnt(8)
	s_barrier
	ds_read_b128 v[64:67], v110
	ds_read_b128 v[68:71], v111 offset:16384
	ds_read_b128 v[72:75], v111 offset:20480
	ds_read_b128 v[82:85], v111 offset:24576
	ds_read_b128 v[86:89], v111 offset:28672
	ds_read_b128 v[120:123], v112
	ds_read_b128 v[124:127], v113 offset:16384
	ds_read_b128 v[128:131], v113 offset:20480
	ds_read_b128 v[132:135], v113 offset:24576
	ds_read_b128 v[136:139], v113 offset:28672
	ds_read_b128 v[140:143], v114
	ds_read_b128 v[218:221], v115 offset:16384
	ds_read_b128 v[222:225], v115 offset:20480
	ds_read_b128 v[226:229], v115 offset:24576
	ds_read_b128 v[230:233], v115 offset:28672
	ds_read_b128 v[234:237], v116
	ds_read_b128 v[238:241], v117 offset:16384
	ds_read_b128 v[242:245], v117 offset:20480
	ds_read_b128 v[246:249], v117 offset:24576
	ds_read_b128 v[250:253], v117 offset:28672
	s_waitcnt lgkmcnt(0)
	s_barrier
	s_mov_b32 m0, s36
	v_mfma_f32_32x32x16_bf16 v[48:63], v[64:67], v[68:71], v[48:63]
	v_mfma_f32_32x32x16_bf16 v[32:47], v[64:67], v[72:75], v[32:47]
	global_load_lds_dwordx4 v254, s[18:19]
	s_add_u32 m0, m0, 0x1000
	v_mfma_f32_32x32x16_bf16 v[16:31], v[64:67], v[82:85], v[16:31]
	v_mfma_f32_32x32x16_bf16 v[0:15], v[64:67], v[86:89], v[0:15]
	global_load_lds_dwordx4 v254, s[20:21]
	s_add_u32 m0, m0, 0x1000
	v_mfma_f32_32x32x16_bf16 v[48:63], v[120:123], v[124:127], v[48:63]
	v_mfma_f32_32x32x16_bf16 v[32:47], v[120:123], v[128:131], v[32:47]
	global_load_lds_dwordx4 v254, s[22:23]
	s_add_u32 m0, m0, 0x1000
	v_mfma_f32_32x32x16_bf16 v[16:31], v[120:123], v[132:135], v[16:31]
	v_mfma_f32_32x32x16_bf16 v[0:15], v[120:123], v[136:139], v[0:15]
	global_load_lds_dwordx4 v254, s[24:25]
	s_add_u32 m0, m0, 0x1000
	v_mfma_f32_32x32x16_bf16 v[48:63], v[140:143], v[218:221], v[48:63]
	v_mfma_f32_32x32x16_bf16 v[32:47], v[140:143], v[222:225], v[32:47]
	global_load_lds_dwordx4 v254, s[26:27]
	s_add_u32 m0, m0, 0x1000
	v_mfma_f32_32x32x16_bf16 v[16:31], v[140:143], v[226:229], v[16:31]
	v_mfma_f32_32x32x16_bf16 v[0:15], v[140:143], v[230:233], v[0:15]
	global_load_lds_dwordx4 v254, s[28:29]
	s_add_u32 m0, m0, 0x1000
	v_mfma_f32_32x32x16_bf16 v[48:63], v[234:237], v[238:241], v[48:63]
	v_mfma_f32_32x32x16_bf16 v[32:47], v[234:237], v[242:245], v[32:47]
	global_load_lds_dwordx4 v254, s[30:31]
	s_add_u32 m0, m0, 0x1000
	v_mfma_f32_32x32x16_bf16 v[16:31], v[234:237], v[246:249], v[16:31]
	v_mfma_f32_32x32x16_bf16 v[0:15], v[234:237], v[250:253], v[0:15]
	global_load_lds_dwordx4 v254, s[34:35]
	v_add_u32_e32 v254, 0x80, v254
	s_waitcnt vmcnt(8)
	s_barrier
	ds_read_b128 v[64:67], v110 offset:32768
	ds_read_b128 v[68:71], v111 offset:49152
	ds_read_b128 v[72:75], v111 offset:53248
	ds_read_b128 v[82:85], v111 offset:57344
	ds_read_b128 v[86:89], v111 offset:61440
	ds_read_b128 v[120:123], v112 offset:32768
	ds_read_b128 v[124:127], v113 offset:49152
	ds_read_b128 v[128:131], v113 offset:53248
	ds_read_b128 v[132:135], v113 offset:57344
	ds_read_b128 v[136:139], v113 offset:61440
	ds_read_b128 v[140:143], v114 offset:32768
	ds_read_b128 v[218:221], v115 offset:49152
	ds_read_b128 v[222:225], v115 offset:53248
	ds_read_b128 v[226:229], v115 offset:57344
	ds_read_b128 v[230:233], v115 offset:61440
	ds_read_b128 v[234:237], v116 offset:32768
	ds_read_b128 v[238:241], v117 offset:49152
	ds_read_b128 v[242:245], v117 offset:53248
	ds_read_b128 v[246:249], v117 offset:57344
	ds_read_b128 v[250:253], v117 offset:61440
	s_waitcnt lgkmcnt(0)
	s_barrier
	s_add_u32 m0, s36, 0x8000
	v_mfma_f32_32x32x16_bf16 v[48:63], v[64:67], v[68:71], v[48:63]
	v_add_f32_e32 v144, v144, v145
	v_add_f32_e32 v146, v146, v147
	v_mfma_f32_32x32x16_bf16 v[32:47], v[64:67], v[72:75], v[32:47]
	v_add_f32_e32 v148, v148, v149
	v_add_f32_e32 v150, v150, v151
	global_load_lds_dwordx4 v254, s[18:19]
	s_add_u32 m0, m0, 0x1000
	v_mfma_f32_32x32x16_bf16 v[16:31], v[64:67], v[82:85], v[16:31]
	v_add_f32_e32 v144, v144, v146
	v_add_f32_e32 v148, v148, v150
	v_mfma_f32_32x32x16_bf16 v[0:15], v[64:67], v[86:89], v[0:15]
	v_add_f32_e32 v144, v144, v148
	v_fmamk_f32 v144, v144, 0x3a800000, v118
	global_load_lds_dwordx4 v254, s[20:21]
	s_add_u32 m0, m0, 0x1000
	v_mfma_f32_32x32x16_bf16 v[48:63], v[120:123], v[124:127], v[48:63]
	v_rsq_f32_e32 v144, v144
	s_nop 1
	v_mfma_f32_32x32x16_bf16 v[32:47], v[120:123], v[128:131], v[32:47]
	ds_bpermute_b32 v156, v153, v144
	ds_bpermute_b32 v157, v153, v144 offset:4
	global_load_lds_dwordx4 v254, s[22:23]
	s_add_u32 m0, m0, 0x1000
	v_mfma_f32_32x32x16_bf16 v[16:31], v[120:123], v[132:135], v[16:31]
	ds_bpermute_b32 v158, v153, v144 offset:8
	ds_bpermute_b32 v159, v153, v144 offset:12
	v_mfma_f32_32x32x16_bf16 v[0:15], v[120:123], v[136:139], v[0:15]
	ds_bpermute_b32 v160, v153, v144 offset:32
	ds_bpermute_b32 v161, v153, v144 offset:36
	global_load_lds_dwordx4 v254, s[24:25]
	s_add_u32 m0, m0, 0x1000
	v_mfma_f32_32x32x16_bf16 v[48:63], v[140:143], v[218:221], v[48:63]
	ds_bpermute_b32 v162, v153, v144 offset:40
	ds_bpermute_b32 v163, v153, v144 offset:44
	v_mfma_f32_32x32x16_bf16 v[32:47], v[140:143], v[222:225], v[32:47]
	ds_bpermute_b32 v164, v153, v144 offset:64
	ds_bpermute_b32 v165, v153, v144 offset:68
	global_load_lds_dwordx4 v254, s[26:27]
	s_add_u32 m0, m0, 0x1000
	v_mfma_f32_32x32x16_bf16 v[16:31], v[140:143], v[226:229], v[16:31]
	ds_bpermute_b32 v166, v153, v144 offset:72
	ds_bpermute_b32 v167, v153, v144 offset:76
	v_mfma_f32_32x32x16_bf16 v[0:15], v[140:143], v[230:233], v[0:15]
	ds_bpermute_b32 v168, v153, v144 offset:96
	ds_bpermute_b32 v169, v153, v144 offset:100
	global_load_lds_dwordx4 v254, s[28:29]
	s_add_u32 m0, m0, 0x1000
	v_mfma_f32_32x32x16_bf16 v[48:63], v[234:237], v[238:241], v[48:63]
	ds_bpermute_b32 v170, v153, v144 offset:104
	ds_bpermute_b32 v171, v153, v144 offset:108
	v_mfma_f32_32x32x16_bf16 v[32:47], v[234:237], v[242:245], v[32:47]
	global_load_lds_dwordx4 v254, s[30:31]
	s_add_u32 m0, m0, 0x1000
	v_mfma_f32_32x32x16_bf16 v[16:31], v[234:237], v[246:249], v[16:31]
	v_mfma_f32_32x32x16_bf16 v[0:15], v[234:237], v[250:253], v[0:15]
	global_load_lds_dwordx4 v254, s[34:35]
	v_add_u32_e32 v254, 0x80, v254
	s_branch .LBB0_1097

.LBB0_1118_pf_p13:
	s_ashr_i32 s41, s40, 31
	s_lshr_b32 s41, s41, 26
	s_add_i32 s41, s40, s41
	s_ashr_i32 s42, s41, 6
	s_andn2_b32 s41, s41, 63
	s_sub_i32 s41, s40, s41
	s_ashr_i32 s43, s41, 31
	s_lshr_b32 s43, s43, 29
	s_add_i32 s43, s41, s43
	s_ashr_i32 s44, s43, 3
	s_and_b32 s43, s43, -8
	s_lshl_b32 s42, s42, 3
	s_sub_i32 s41, s41, s43
	s_add_i32 s41, s41, s42
	s_lshl_b32 s45, s41, 7
	s_lshl_b32 s46, s44, 7
	s_mul_i32 s38, s41, 0xb0000
	s_add_u32 s18, s14, s38
	s_addc_u32 s19, s15, 0
	s_add_u32 s18, s18, 0x879f000
	s_addc_u32 s19, s19, 0
	s_add_u32 s20, s18, 0x2c000
	s_addc_u32 s21, s19, 0
	s_add_u32 s22, s20, 0x2c000
	s_addc_u32 s23, s21, 0
	s_add_u32 s24, s22, 0x2c000
	s_addc_u32 s25, s23, 0
	s_mul_i32 s38, s44, 0xb0000
	s_add_u32 s26, s14, s38
	s_addc_u32 s27, s15, 0
	s_add_u32 s26, s26, 0x4b20000
	s_addc_u32 s27, s27, 0
	s_add_u32 s28, s26, 0x2c000
	s_addc_u32 s29, s27, 0
	s_add_u32 s30, s28, 0x2c000
	s_addc_u32 s31, s29, 0
	s_add_u32 s34, s30, 0x2c000
	s_addc_u32 s35, s31, 0
	v_mov_b32_e32 v254, v64
	s_mov_b32 s39, 1
	s_waitcnt vmcnt(8)
	s_barrier
	ds_read_b128 v[70:73], v157
	ds_read_b128 v[74:77], v158 offset:16384
	ds_read_b128 v[78:81], v158 offset:20480
	ds_read_b128 v[82:85], v158 offset:24576
	ds_read_b128 v[86:89], v158 offset:28672
	ds_read_b128 v[90:93], v159
	ds_read_b128 v[94:97], v160 offset:16384
	ds_read_b128 v[98:101], v160 offset:20480
	ds_read_b128 v[102:105], v160 offset:24576
	ds_read_b128 v[106:109], v160 offset:28672
	ds_read_b128 v[110:113], v161
	ds_read_b128 v[202:205], v162 offset:16384
	ds_read_b128 v[206:209], v162 offset:20480
	ds_read_b128 v[210:213], v162 offset:24576
	ds_read_b128 v[214:217], v162 offset:28672
	ds_read_b128 v[218:221], v163
	ds_read_b128 v[222:225], v164 offset:16384
	ds_read_b128 v[226:229], v164 offset:20480
	ds_read_b128 v[230:233], v164 offset:24576
	ds_read_b128 v[234:237], v164 offset:28672
	s_waitcnt lgkmcnt(0)
	s_barrier
	s_mov_b32 m0, s36
	v_mfma_f32_32x32x16_bf16 v[48:63], v[70:73], v[74:77], v[48:63]
	v_mfma_f32_32x32x16_bf16 v[32:47], v[70:73], v[78:81], v[32:47]
	global_load_lds_dwordx4 v254, s[18:19]
	s_add_u32 m0, m0, 0x1000
	v_mfma_f32_32x32x16_bf16 v[16:31], v[70:73], v[82:85], v[16:31]
	v_mfma_f32_32x32x16_bf16 v[0:15], v[70:73], v[86:89], v[0:15]
	global_load_lds_dwordx4 v254, s[20:21]
	s_add_u32 m0, m0, 0x1000
	v_mfma_f32_32x32x16_bf16 v[48:63], v[90:93], v[94:97], v[48:63]
	v_mfma_f32_32x32x16_bf16 v[32:47], v[90:93], v[98:101], v[32:47]
	global_load_lds_dwordx4 v254, s[22:23]
	s_add_u32 m0, m0, 0x1000
	v_mfma_f32_32x32x16_bf16 v[16:31], v[90:93], v[102:105], v[16:31]
	v_mfma_f32_32x32x16_bf16 v[0:15], v[90:93], v[106:109], v[0:15]
	global_load_lds_dwordx4 v254, s[24:25]
	s_add_u32 m0, m0, 0x1000
	v_mfma_f32_32x32x16_bf16 v[48:63], v[110:113], v[202:205], v[48:63]
	v_mfma_f32_32x32x16_bf16 v[32:47], v[110:113], v[206:209], v[32:47]
	global_load_lds_dwordx4 v254, s[26:27]
	s_add_u32 m0, m0, 0x1000
	v_mfma_f32_32x32x16_bf16 v[16:31], v[110:113], v[210:213], v[16:31]
	v_mfma_f32_32x32x16_bf16 v[0:15], v[110:113], v[214:217], v[0:15]
	global_load_lds_dwordx4 v254, s[28:29]
	s_add_u32 m0, m0, 0x1000
	v_mfma_f32_32x32x16_bf16 v[48:63], v[218:221], v[222:225], v[48:63]
	v_mfma_f32_32x32x16_bf16 v[32:47], v[218:221], v[226:229], v[32:47]
	global_load_lds_dwordx4 v254, s[30:31]
	s_add_u32 m0, m0, 0x1000
	v_mfma_f32_32x32x16_bf16 v[16:31], v[218:221], v[230:233], v[16:31]
	v_mfma_f32_32x32x16_bf16 v[0:15], v[218:221], v[234:237], v[0:15]
	global_load_lds_dwordx4 v254, s[34:35]
	v_add_u32_e32 v254, 0x80, v254
	s_waitcnt vmcnt(8)
	s_barrier
	ds_read_b128 v[70:73], v157 offset:32768
	ds_read_b128 v[74:77], v158 offset:49152
	ds_read_b128 v[78:81], v158 offset:53248
	ds_read_b128 v[82:85], v158 offset:57344
	ds_read_b128 v[86:89], v158 offset:61440
	ds_read_b128 v[90:93], v159 offset:32768
	ds_read_b128 v[94:97], v160 offset:49152
	ds_read_b128 v[98:101], v160 offset:53248
	ds_read_b128 v[102:105], v160 offset:57344
	ds_read_b128 v[106:109], v160 offset:61440
	ds_read_b128 v[110:113], v161 offset:32768
	ds_read_b128 v[202:205], v162 offset:49152
	ds_read_b128 v[206:209], v162 offset:53248
	ds_read_b128 v[210:213], v162 offset:57344
	ds_read_b128 v[214:217], v162 offset:61440
	ds_read_b128 v[218:221], v163 offset:32768
	ds_read_b128 v[222:225], v164 offset:49152
	ds_read_b128 v[226:229], v164 offset:53248
	ds_read_b128 v[230:233], v164 offset:57344
	ds_read_b128 v[234:237], v164 offset:61440
	s_waitcnt lgkmcnt(0)
	s_barrier
	s_add_u32 m0, s36, 0x8000
	v_mfma_f32_32x32x16_bf16 v[48:63], v[70:73], v[74:77], v[48:63]
	v_mfma_f32_32x32x16_bf16 v[32:47], v[70:73], v[78:81], v[32:47]
	global_load_lds_dwordx4 v254, s[18:19]
	s_add_u32 m0, m0, 0x1000
	v_mfma_f32_32x32x16_bf16 v[16:31], v[70:73], v[82:85], v[16:31]
	v_mfma_f32_32x32x16_bf16 v[0:15], v[70:73], v[86:89], v[0:15]
	global_load_lds_dwordx4 v254, s[20:21]
	s_add_u32 m0, m0, 0x1000
	v_mfma_f32_32x32x16_bf16 v[48:63], v[90:93], v[94:97], v[48:63]
	v_mfma_f32_32x32x16_bf16 v[32:47], v[90:93], v[98:101], v[32:47]
	global_load_lds_dwordx4 v254, s[22:23]
	s_add_u32 m0, m0, 0x1000
	v_mfma_f32_32x32x16_bf16 v[16:31], v[90:93], v[102:105], v[16:31]
	v_mfma_f32_32x32x16_bf16 v[0:15], v[90:93], v[106:109], v[0:15]
	global_load_lds_dwordx4 v254, s[24:25]
	s_add_u32 m0, m0, 0x1000
	v_mfma_f32_32x32x16_bf16 v[48:63], v[110:113], v[202:205], v[48:63]
	v_mfma_f32_32x32x16_bf16 v[32:47], v[110:113], v[206:209], v[32:47]
	global_load_lds_dwordx4 v254, s[26:27]
	s_add_u32 m0, m0, 0x1000
	v_mfma_f32_32x32x16_bf16 v[16:31], v[110:113], v[210:213], v[16:31]
	v_mfma_f32_32x32x16_bf16 v[0:15], v[110:113], v[214:217], v[0:15]
	global_load_lds_dwordx4 v254, s[28:29]
	s_add_u32 m0, m0, 0x1000
	v_mfma_f32_32x32x16_bf16 v[48:63], v[218:221], v[222:225], v[48:63]
	v_mfma_f32_32x32x16_bf16 v[32:47], v[218:221], v[226:229], v[32:47]
	global_load_lds_dwordx4 v254, s[30:31]
	s_add_u32 m0, m0, 0x1000
	v_mfma_f32_32x32x16_bf16 v[16:31], v[218:221], v[230:233], v[16:31]
	v_mfma_f32_32x32x16_bf16 v[0:15], v[218:221], v[234:237], v[0:15]
	global_load_lds_dwordx4 v254, s[34:35]
	v_add_u32_e32 v254, 0x80, v254
	s_branch .LBB0_1122

.Lgk_loop_p14:
	s_waitcnt vmcnt(8)
	s_barrier
	ds_read_b128 v[64:67], v255
	ds_read_b128 v[76:79], v157 offset:16384
	ds_read_b128 v[80:83], v157 offset:20480
	ds_read_b128 v[84:87], v157 offset:24576
	ds_read_b128 v[88:91], v157 offset:28672
	ds_read_b128 v[92:95], v162
	ds_read_b128 v[96:99], v163 offset:16384
	ds_read_b128 v[100:103], v163 offset:20480
	ds_read_b128 v[118:121], v163 offset:24576
	ds_read_b128 v[122:125], v163 offset:28672
	ds_read_b128 v[172:175], v164
	ds_read_b128 v[226:229], v165 offset:16384
	ds_read_b128 v[230:233], v165 offset:20480
	ds_read_b128 v[234:237], v165 offset:24576
	ds_read_b128 v[238:241], v165 offset:28672
	ds_read_b128 v[242:245], v167
	ds_read_b128 v[246:249], v168 offset:16384
	ds_read_b128 v[250:253], v168 offset:20480
	ds_read_b128 v[112:115], v168 offset:24576
	ds_read_b128 v[158:161], v168 offset:28672
	s_waitcnt lgkmcnt(0)
	s_barrier
	s_mov_b32 m0, s46
	v_mfma_f32_32x32x16_bf16 v[48:63], v[64:67], v[76:79], v[48:63]
	v_mfma_f32_32x32x16_bf16 v[32:47], v[64:67], v[80:83], v[32:47]
	global_load_lds_dwordx4 v254, s[28:29]
	s_add_u32 m0, m0, 0x1000
	v_mfma_f32_32x32x16_bf16 v[16:31], v[64:67], v[84:87], v[16:31]
	v_mfma_f32_32x32x16_bf16 v[0:15], v[64:67], v[88:91], v[0:15]
	global_load_lds_dwordx4 v254, s[30:31]
	s_add_u32 m0, m0, 0x1000
	v_mfma_f32_32x32x16_bf16 v[48:63], v[92:95], v[96:99], v[48:63]
	v_mfma_f32_32x32x16_bf16 v[32:47], v[92:95], v[100:103], v[32:47]
	global_load_lds_dwordx4 v254, s[34:35]
	s_add_u32 m0, m0, 0x1000
	v_mfma_f32_32x32x16_bf16 v[16:31], v[92:95], v[118:121], v[16:31]
	v_mfma_f32_32x32x16_bf16 v[0:15], v[92:95], v[122:125], v[0:15]
	global_load_lds_dwordx4 v254, s[36:37]
	s_add_u32 m0, m0, 0x1000
	v_mfma_f32_32x32x16_bf16 v[48:63], v[172:175], v[226:229], v[48:63]
	v_mfma_f32_32x32x16_bf16 v[32:47], v[172:175], v[230:233], v[32:47]
	global_load_lds_dwordx4 v254, s[38:39]
	s_add_u32 m0, m0, 0x1000
	v_mfma_f32_32x32x16_bf16 v[16:31], v[172:175], v[234:237], v[16:31]
	v_mfma_f32_32x32x16_bf16 v[0:15], v[172:175], v[238:241], v[0:15]
	global_load_lds_dwordx4 v254, s[40:41]
	s_add_u32 m0, m0, 0x1000
	v_mfma_f32_32x32x16_bf16 v[48:63], v[242:245], v[246:249], v[48:63]
	v_mfma_f32_32x32x16_bf16 v[32:47], v[242:245], v[250:253], v[32:47]
	global_load_lds_dwordx4 v254, s[42:43]
	s_add_u32 m0, m0, 0x1000
	v_mfma_f32_32x32x16_bf16 v[16:31], v[242:245], v[112:115], v[16:31]
	v_mfma_f32_32x32x16_bf16 v[0:15], v[242:245], v[158:161], v[0:15]
	global_load_lds_dwordx4 v254, s[44:45]
	v_add_u32_e32 v254, 0x80, v254
	s_waitcnt vmcnt(8)
	s_barrier
	ds_read_b128 v[64:67], v255 offset:32768
	ds_read_b128 v[76:79], v157 offset:49152
	ds_read_b128 v[80:83], v157 offset:53248
	ds_read_b128 v[84:87], v157 offset:57344
	ds_read_b128 v[88:91], v157 offset:61440
	ds_read_b128 v[92:95], v162 offset:32768
	ds_read_b128 v[96:99], v163 offset:49152
	ds_read_b128 v[100:103], v163 offset:53248
	ds_read_b128 v[118:121], v163 offset:57344
	ds_read_b128 v[122:125], v163 offset:61440
	ds_read_b128 v[172:175], v164 offset:32768
	ds_read_b128 v[226:229], v165 offset:49152
	ds_read_b128 v[230:233], v165 offset:53248
	ds_read_b128 v[234:237], v165 offset:57344
	ds_read_b128 v[238:241], v165 offset:61440
	ds_read_b128 v[242:245], v167 offset:32768
	ds_read_b128 v[246:249], v168 offset:49152
	ds_read_b128 v[250:253], v168 offset:53248
	ds_read_b128 v[112:115], v168 offset:57344
	ds_read_b128 v[158:161], v168 offset:61440
	s_waitcnt lgkmcnt(0)
	s_barrier
	s_add_u32 m0, s46, 0x8000
	v_mfma_f32_32x32x16_bf16 v[48:63], v[64:67], v[76:79], v[48:63]
	v_mfma_f32_32x32x16_bf16 v[32:47], v[64:67], v[80:83], v[32:47]
	global_load_lds_dwordx4 v254, s[28:29]
	s_add_u32 m0, m0, 0x1000
	v_mfma_f32_32x32x16_bf16 v[16:31], v[64:67], v[84:87], v[16:31]
	v_mfma_f32_32x32x16_bf16 v[0:15], v[64:67], v[88:91], v[0:15]
	global_load_lds_dwordx4 v254, s[30:31]
	s_add_u32 m0, m0, 0x1000
	v_mfma_f32_32x32x16_bf16 v[48:63], v[92:95], v[96:99], v[48:63]
	v_mfma_f32_32x32x16_bf16 v[32:47], v[92:95], v[100:103], v[32:47]
	global_load_lds_dwordx4 v254, s[34:35]
	s_add_u32 m0, m0, 0x1000
	v_mfma_f32_32x32x16_bf16 v[16:31], v[92:95], v[118:121], v[16:31]
	v_mfma_f32_32x32x16_bf16 v[0:15], v[92:95], v[122:125], v[0:15]
	global_load_lds_dwordx4 v254, s[36:37]
	s_add_u32 m0, m0, 0x1000
	v_mfma_f32_32x32x16_bf16 v[48:63], v[172:175], v[226:229], v[48:63]
	v_mfma_f32_32x32x16_bf16 v[32:47], v[172:175], v[230:233], v[32:47]
	global_load_lds_dwordx4 v254, s[38:39]
	s_add_u32 m0, m0, 0x1000
	v_mfma_f32_32x32x16_bf16 v[16:31], v[172:175], v[234:237], v[16:31]
	v_mfma_f32_32x32x16_bf16 v[0:15], v[172:175], v[238:241], v[0:15]
	global_load_lds_dwordx4 v254, s[40:41]
	s_add_u32 m0, m0, 0x1000
	v_mfma_f32_32x32x16_bf16 v[48:63], v[242:245], v[246:249], v[48:63]
	v_mfma_f32_32x32x16_bf16 v[32:47], v[242:245], v[250:253], v[32:47]
	global_load_lds_dwordx4 v254, s[42:43]
	s_add_u32 m0, m0, 0x1000
	v_mfma_f32_32x32x16_bf16 v[16:31], v[242:245], v[112:115], v[16:31]
	v_mfma_f32_32x32x16_bf16 v[0:15], v[242:245], v[158:161], v[0:15]
	global_load_lds_dwordx4 v254, s[44:45]
	v_add_u32_e32 v254, 0x80, v254
	s_sub_u32 s47, s47, 1
	s_cmp_lg_u32 s47, 0
	s_cbranch_scc1 .Lgk_loop_p14
	s_add_u32 s50, s3, s33
	s_cmp_gt_u32 s50, 0x5ff
	s_cbranch_scc1 .Lgk_tailplain_p14
.LBB0_1171_pf_p14:
	s_mul_hi_i32 s52, s50, 0x2aaaaaab
	s_lshr_b32 s53, s52, 31
	s_ashr_i32 s52, s52, 4
	s_add_i32 s52, s52, s53
	s_mul_i32 s61, s52, 0xffffffa0
	s_add_i32 s61, s61, s50
	s_lshl_b32 s53, s52, 3
	s_ashr_i32 s52, s61, 31
	s_lshr_b32 s52, s52, 29
	s_add_i32 s52, s61, s52
	s_ashr_i32 s60, s52, 3
	s_and_b32 s52, s52, -8
	s_sub_i32 s51, s61, s52
	s_add_i32 s51, s51, s53
	s_lshl_b32 s56, s51, 7
	s_lshl_b32 s54, s60, 7
	s_ashr_i32 s57, s56, 31
	s_ashr_i32 s55, s54, 31
	s_lshl_b64 s[52:53], s[56:57], 11
	s_lshl_b64 s[58:59], s[54:55], 11
	s_lshl_b32 s48, s56, 11
	s_add_u32 s28, s14, s48
	s_addc_u32 s29, s15, 0
	s_add_u32 s28, s28, 0x679f000
	s_addc_u32 s29, s29, 0
	s_add_u32 s30, s28, 0x10000
	s_addc_u32 s31, s29, 0
	s_add_u32 s34, s30, 0x10000
	s_addc_u32 s35, s31, 0
	s_add_u32 s36, s34, 0x10000
	s_addc_u32 s37, s35, 0
	s_lshl_b32 s48, s54, 11
	s_add_u32 s38, s14, s48
	s_addc_u32 s39, s15, 0
	s_add_u32 s38, s38, 0xda0000
	s_addc_u32 s39, s39, 0
	s_add_u32 s40, s38, 0x10000
	s_addc_u32 s41, s39, 0
	s_add_u32 s42, s40, 0x10000
	s_addc_u32 s43, s41, 0
	s_add_u32 s44, s42, 0x10000
	s_addc_u32 s45, s43, 0
	v_mov_b32_e32 v254, v110
	s_mov_b32 s49, 1
	s_waitcnt vmcnt(8)
	s_barrier
	ds_read_b128 v[64:67], v255
	ds_read_b128 v[76:79], v157 offset:16384
	ds_read_b128 v[80:83], v157 offset:20480
	ds_read_b128 v[84:87], v157 offset:24576
	ds_read_b128 v[88:91], v157 offset:28672
	ds_read_b128 v[92:95], v162
	ds_read_b128 v[96:99], v163 offset:16384
	ds_read_b128 v[100:103], v163 offset:20480
	ds_read_b128 v[118:121], v163 offset:24576
	ds_read_b128 v[122:125], v163 offset:28672
	ds_read_b128 v[172:175], v164
	ds_read_b128 v[226:229], v165 offset:16384
	ds_read_b128 v[230:233], v165 offset:20480
	ds_read_b128 v[234:237], v165 offset:24576
	ds_read_b128 v[238:241], v165 offset:28672
	ds_read_b128 v[242:245], v167
	ds_read_b128 v[246:249], v168 offset:16384
	ds_read_b128 v[250:253], v168 offset:20480
	ds_read_b128 v[112:115], v168 offset:24576
	ds_read_b128 v[158:161], v168 offset:28672
	s_waitcnt lgkmcnt(0)
	s_barrier
	s_mov_b32 m0, s46
	v_mfma_f32_32x32x16_bf16 v[48:63], v[64:67], v[76:79], v[48:63]
	v_mfma_f32_32x32x16_bf16 v[32:47], v[64:67], v[80:83], v[32:47]
	global_load_lds_dwordx4 v254, s[28:29]
	s_add_u32 m0, m0, 0x1000
	v_mfma_f32_32x32x16_bf16 v[16:31], v[64:67], v[84:87], v[16:31]
	v_mfma_f32_32x32x16_bf16 v[0:15], v[64:67], v[88:91], v[0:15]
	global_load_lds_dwordx4 v254, s[30:31]
	s_add_u32 m0, m0, 0x1000
	v_mfma_f32_32x32x16_bf16 v[48:63], v[92:95], v[96:99], v[48:63]
	v_mfma_f32_32x32x16_bf16 v[32:47], v[92:95], v[100:103], v[32:47]
	global_load_lds_dwordx4 v254, s[34:35]
	s_add_u32 m0, m0, 0x1000
	v_mfma_f32_32x32x16_bf16 v[16:31], v[92:95], v[118:121], v[16:31]
	v_mfma_f32_32x32x16_bf16 v[0:15], v[92:95], v[122:125], v[0:15]
	global_load_lds_dwordx4 v254, s[36:37]
	s_add_u32 m0, m0, 0x1000
	v_mfma_f32_32x32x16_bf16 v[48:63], v[172:175], v[226:229], v[48:63]
	v_mfma_f32_32x32x16_bf16 v[32:47], v[172:175], v[230:233], v[32:47]
	global_load_lds_dwordx4 v254, s[38:39]
	s_add_u32 m0, m0, 0x1000
	v_mfma_f32_32x32x16_bf16 v[16:31], v[172:175], v[234:237], v[16:31]
	v_mfma_f32_32x32x16_bf16 v[0:15], v[172:175], v[238:241], v[0:15]
	global_load_lds_dwordx4 v254, s[40:41]
	s_add_u32 m0, m0, 0x1000
	v_mfma_f32_32x32x16_bf16 v[48:63], v[242:245], v[246:249], v[48:63]
	v_mfma_f32_32x32x16_bf16 v[32:47], v[242:245], v[250:253], v[32:47]
	global_load_lds_dwordx4 v254, s[42:43]
	s_add_u32 m0, m0, 0x1000
	v_mfma_f32_32x32x16_bf16 v[16:31], v[242:245], v[112:115], v[16:31]
	v_mfma_f32_32x32x16_bf16 v[0:15], v[242:245], v[158:161], v[0:15]
	global_load_lds_dwordx4 v254, s[44:45]
	v_add_u32_e32 v254, 0x80, v254
	s_waitcnt vmcnt(8)
	s_barrier
	ds_read_b128 v[64:67], v255 offset:32768
	ds_read_b128 v[76:79], v157 offset:49152
	ds_read_b128 v[80:83], v157 offset:53248
	ds_read_b128 v[84:87], v157 offset:57344
	ds_read_b128 v[88:91], v157 offset:61440
	ds_read_b128 v[92:95], v162 offset:32768
	ds_read_b128 v[96:99], v163 offset:49152
	ds_read_b128 v[100:103], v163 offset:53248
	ds_read_b128 v[118:121], v163 offset:57344
	ds_read_b128 v[122:125], v163 offset:61440
	ds_read_b128 v[172:175], v164 offset:32768
	ds_read_b128 v[226:229], v165 offset:49152
	ds_read_b128 v[230:233], v165 offset:53248
	ds_read_b128 v[234:237], v165 offset:57344
	ds_read_b128 v[238:241], v165 offset:61440
	ds_read_b128 v[242:245], v167 offset:32768
	ds_read_b128 v[246:249], v168 offset:49152
	ds_read_b128 v[250:253], v168 offset:53248
	ds_read_b128 v[112:115], v168 offset:57344
	ds_read_b128 v[158:161], v168 offset:61440
	s_waitcnt lgkmcnt(0)
	s_barrier
	s_add_u32 m0, s46, 0x8000
	v_mfma_f32_32x32x16_bf16 v[48:63], v[64:67], v[76:79], v[48:63]
	v_mfma_f32_32x32x16_bf16 v[32:47], v[64:67], v[80:83], v[32:47]
	global_load_lds_dwordx4 v254, s[28:29]
	s_add_u32 m0, m0, 0x1000
	v_mfma_f32_32x32x16_bf16 v[16:31], v[64:67], v[84:87], v[16:31]
	v_mfma_f32_32x32x16_bf16 v[0:15], v[64:67], v[88:91], v[0:15]
	global_load_lds_dwordx4 v254, s[30:31]
	s_add_u32 m0, m0, 0x1000
	v_mfma_f32_32x32x16_bf16 v[48:63], v[92:95], v[96:99], v[48:63]
	v_mfma_f32_32x32x16_bf16 v[32:47], v[92:95], v[100:103], v[32:47]
	global_load_lds_dwordx4 v254, s[34:35]
	s_add_u32 m0, m0, 0x1000
	v_mfma_f32_32x32x16_bf16 v[16:31], v[92:95], v[118:121], v[16:31]
	v_mfma_f32_32x32x16_bf16 v[0:15], v[92:95], v[122:125], v[0:15]
	global_load_lds_dwordx4 v254, s[36:37]
	s_add_u32 m0, m0, 0x1000
	v_mfma_f32_32x32x16_bf16 v[48:63], v[172:175], v[226:229], v[48:63]
	v_mfma_f32_32x32x16_bf16 v[32:47], v[172:175], v[230:233], v[32:47]
	global_load_lds_dwordx4 v254, s[38:39]
	s_add_u32 m0, m0, 0x1000
	v_mfma_f32_32x32x16_bf16 v[16:31], v[172:175], v[234:237], v[16:31]
	v_mfma_f32_32x32x16_bf16 v[0:15], v[172:175], v[238:241], v[0:15]
	global_load_lds_dwordx4 v254, s[40:41]
	s_add_u32 m0, m0, 0x1000
	v_mfma_f32_32x32x16_bf16 v[48:63], v[242:245], v[246:249], v[48:63]
	v_mfma_f32_32x32x16_bf16 v[32:47], v[242:245], v[250:253], v[32:47]
	global_load_lds_dwordx4 v254, s[42:43]
	s_add_u32 m0, m0, 0x1000
	v_mfma_f32_32x32x16_bf16 v[16:31], v[242:245], v[112:115], v[16:31]
	v_mfma_f32_32x32x16_bf16 v[0:15], v[242:245], v[158:161], v[0:15]
	global_load_lds_dwordx4 v254, s[44:45]
	v_add_u32_e32 v254, 0x80, v254
	s_branch .LBB0_1175
.Lgk_tailplain_p14:
	s_mov_b32 s49, 0
	s_waitcnt vmcnt(8)
	s_barrier
	ds_read_b128 v[64:67], v255
	ds_read_b128 v[76:79], v157 offset:16384
	ds_read_b128 v[80:83], v157 offset:20480
	ds_read_b128 v[84:87], v157 offset:24576
	ds_read_b128 v[88:91], v157 offset:28672
	ds_read_b128 v[92:95], v162
	ds_read_b128 v[96:99], v163 offset:16384
	ds_read_b128 v[100:103], v163 offset:20480
	ds_read_b128 v[118:121], v163 offset:24576
	ds_read_b128 v[122:125], v163 offset:28672
	ds_read_b128 v[172:175], v164
	ds_read_b128 v[226:229], v165 offset:16384
	ds_read_b128 v[230:233], v165 offset:20480
	ds_read_b128 v[234:237], v165 offset:24576
	ds_read_b128 v[238:241], v165 offset:28672
	ds_read_b128 v[242:245], v167
	ds_read_b128 v[246:249], v168 offset:16384
	ds_read_b128 v[250:253], v168 offset:20480
	ds_read_b128 v[112:115], v168 offset:24576
	ds_read_b128 v[158:161], v168 offset:28672
	s_waitcnt lgkmcnt(0)
	s_barrier
	v_mfma_f32_32x32x16_bf16 v[48:63], v[64:67], v[76:79], v[48:63]
	v_mfma_f32_32x32x16_bf16 v[32:47], v[64:67], v[80:83], v[32:47]
	v_mfma_f32_32x32x16_bf16 v[16:31], v[64:67], v[84:87], v[16:31]
	v_mfma_f32_32x32x16_bf16 v[0:15], v[64:67], v[88:91], v[0:15]
	v_mfma_f32_32x32x16_bf16 v[48:63], v[92:95], v[96:99], v[48:63]
	v_mfma_f32_32x32x16_bf16 v[32:47], v[92:95], v[100:103], v[32:47]
	v_mfma_f32_32x32x16_bf16 v[16:31], v[92:95], v[118:121], v[16:31]
	v_mfma_f32_32x32x16_bf16 v[0:15], v[92:95], v[122:125], v[0:15]
	v_mfma_f32_32x32x16_bf16 v[48:63], v[172:175], v[226:229], v[48:63]
	v_mfma_f32_32x32x16_bf16 v[32:47], v[172:175], v[230:233], v[32:47]
	v_mfma_f32_32x32x16_bf16 v[16:31], v[172:175], v[234:237], v[16:31]
	v_mfma_f32_32x32x16_bf16 v[0:15], v[172:175], v[238:241], v[0:15]
	v_mfma_f32_32x32x16_bf16 v[48:63], v[242:245], v[246:249], v[48:63]
	v_mfma_f32_32x32x16_bf16 v[32:47], v[242:245], v[250:253], v[32:47]
	v_mfma_f32_32x32x16_bf16 v[16:31], v[242:245], v[112:115], v[16:31]
	v_mfma_f32_32x32x16_bf16 v[0:15], v[242:245], v[158:161], v[0:15]
	s_waitcnt vmcnt(0)
	s_barrier
	ds_read_b128 v[64:67], v255 offset:32768
	ds_read_b128 v[76:79], v157 offset:49152
	ds_read_b128 v[80:83], v157 offset:53248
	ds_read_b128 v[84:87], v157 offset:57344
	ds_read_b128 v[88:91], v157 offset:61440
	ds_read_b128 v[92:95], v162 offset:32768
	ds_read_b128 v[96:99], v163 offset:49152
	ds_read_b128 v[100:103], v163 offset:53248
	ds_read_b128 v[118:121], v163 offset:57344
	ds_read_b128 v[122:125], v163 offset:61440
	ds_read_b128 v[172:175], v164 offset:32768
	ds_read_b128 v[226:229], v165 offset:49152
	ds_read_b128 v[230:233], v165 offset:53248
	ds_read_b128 v[234:237], v165 offset:57344
	ds_read_b128 v[238:241], v165 offset:61440
	ds_read_b128 v[242:245], v167 offset:32768
	ds_read_b128 v[246:249], v168 offset:49152
	ds_read_b128 v[250:253], v168 offset:53248
	ds_read_b128 v[112:115], v168 offset:57344
	ds_read_b128 v[158:161], v168 offset:61440
	s_waitcnt lgkmcnt(0)
	s_barrier
	v_mfma_f32_32x32x16_bf16 v[48:63], v[64:67], v[76:79], v[48:63]
	v_mfma_f32_32x32x16_bf16 v[32:47], v[64:67], v[80:83], v[32:47]
	v_mfma_f32_32x32x16_bf16 v[16:31], v[64:67], v[84:87], v[16:31]
	v_mfma_f32_32x32x16_bf16 v[0:15], v[64:67], v[88:91], v[0:15]
	v_mfma_f32_32x32x16_bf16 v[48:63], v[92:95], v[96:99], v[48:63]
	v_mfma_f32_32x32x16_bf16 v[32:47], v[92:95], v[100:103], v[32:47]
	v_mfma_f32_32x32x16_bf16 v[16:31], v[92:95], v[118:121], v[16:31]
	v_mfma_f32_32x32x16_bf16 v[0:15], v[92:95], v[122:125], v[0:15]
	v_mfma_f32_32x32x16_bf16 v[48:63], v[172:175], v[226:229], v[48:63]
	v_mfma_f32_32x32x16_bf16 v[32:47], v[172:175], v[230:233], v[32:47]
	v_mfma_f32_32x32x16_bf16 v[16:31], v[172:175], v[234:237], v[16:31]
	v_mfma_f32_32x32x16_bf16 v[0:15], v[172:175], v[238:241], v[0:15]
	v_mfma_f32_32x32x16_bf16 v[48:63], v[242:245], v[246:249], v[48:63]
	v_mfma_f32_32x32x16_bf16 v[32:47], v[242:245], v[250:253], v[32:47]
	v_mfma_f32_32x32x16_bf16 v[16:31], v[242:245], v[112:115], v[16:31]
	v_mfma_f32_32x32x16_bf16 v[0:15], v[242:245], v[158:161], v[0:15]
	s_branch .LBB0_1175

.LBB0_1322_pf_p16:
	s_ashr_i32 s41, s40, 31
	s_lshr_b32 s41, s41, 26
	s_add_i32 s41, s40, s41
	s_ashr_i32 s42, s41, 6
	s_andn2_b32 s41, s41, 63
	s_sub_i32 s41, s40, s41
	s_ashr_i32 s43, s41, 31
	s_lshr_b32 s43, s43, 29
	s_add_i32 s43, s41, s43
	s_ashr_i32 s46, s43, 3
	s_and_b32 s43, s43, -8
	s_lshl_b32 s42, s42, 3
	s_sub_i32 s41, s41, s43
	s_add_i32 s41, s41, s42
	s_lshl_b32 s44, s41, 7
	s_ashr_i32 s45, s44, 31
	s_lshl_b32 s47, s46, 7
	s_lshl_b64 s[42:43], s[44:45], 11
	s_ashr_i32 s48, s47, 31
	s_lshl_b32 s38, s44, 11
	s_add_u32 s18, s14, s38
	s_addc_u32 s19, s15, 0
	s_add_u32 s18, s18, 0xb79f000
	s_addc_u32 s19, s19, 0
	s_add_u32 s20, s18, 0x10000
	s_addc_u32 s21, s19, 0
	s_add_u32 s22, s20, 0x10000
	s_addc_u32 s23, s21, 0
	s_add_u32 s24, s22, 0x10000
	s_addc_u32 s25, s23, 0
	s_lshl_b32 s38, s47, 11
	s_add_u32 s26, s14, s38
	s_addc_u32 s27, s15, 0
	s_add_u32 s26, s26, 0x10a0000
	s_addc_u32 s27, s27, 0
	s_add_u32 s28, s26, 0x10000
	s_addc_u32 s29, s27, 0
	s_add_u32 s30, s28, 0x10000
	s_addc_u32 s31, s29, 0
	s_add_u32 s34, s30, 0x10000
	s_addc_u32 s35, s31, 0
	v_mov_b32_e32 v254, v64
	s_mov_b32 s39, 1
	s_waitcnt vmcnt(8)
	s_barrier
	ds_read_b128 v[70:73], v156
	ds_read_b128 v[74:77], v157 offset:16384
	ds_read_b128 v[78:81], v157 offset:20480
	ds_read_b128 v[82:85], v157 offset:24576
	ds_read_b128 v[86:89], v157 offset:28672
	ds_read_b128 v[90:93], v158
	ds_read_b128 v[94:97], v159 offset:16384
	ds_read_b128 v[98:101], v159 offset:20480
	ds_read_b128 v[102:105], v159 offset:24576
	ds_read_b128 v[106:109], v159 offset:28672
	ds_read_b128 v[110:113], v160
	ds_read_b128 v[202:205], v161 offset:16384
	ds_read_b128 v[206:209], v161 offset:20480
	ds_read_b128 v[210:213], v161 offset:24576
	ds_read_b128 v[214:217], v161 offset:28672
	ds_read_b128 v[218:221], v162
	ds_read_b128 v[222:225], v163 offset:16384
	ds_read_b128 v[226:229], v163 offset:20480
	ds_read_b128 v[230:233], v163 offset:24576
	ds_read_b128 v[234:237], v163 offset:28672
	s_waitcnt lgkmcnt(0)
	s_barrier
	s_mov_b32 m0, s36
	v_mfma_f32_32x32x16_bf16 v[48:63], v[70:73], v[74:77], v[48:63]
	v_mfma_f32_32x32x16_bf16 v[32:47], v[70:73], v[78:81], v[32:47]
	global_load_lds_dwordx4 v254, s[18:19]
	s_add_u32 m0, m0, 0x1000
	v_mfma_f32_32x32x16_bf16 v[16:31], v[70:73], v[82:85], v[16:31]
	v_mfma_f32_32x32x16_bf16 v[0:15], v[70:73], v[86:89], v[0:15]
	global_load_lds_dwordx4 v254, s[20:21]
	s_add_u32 m0, m0, 0x1000
	v_mfma_f32_32x32x16_bf16 v[48:63], v[90:93], v[94:97], v[48:63]
	v_mfma_f32_32x32x16_bf16 v[32:47], v[90:93], v[98:101], v[32:47]
	global_load_lds_dwordx4 v254, s[22:23]
	s_add_u32 m0, m0, 0x1000
	v_mfma_f32_32x32x16_bf16 v[16:31], v[90:93], v[102:105], v[16:31]
	v_mfma_f32_32x32x16_bf16 v[0:15], v[90:93], v[106:109], v[0:15]
	global_load_lds_dwordx4 v254, s[24:25]
	s_add_u32 m0, m0, 0x1000
	v_mfma_f32_32x32x16_bf16 v[48:63], v[110:113], v[202:205], v[48:63]
	v_mfma_f32_32x32x16_bf16 v[32:47], v[110:113], v[206:209], v[32:47]
	global_load_lds_dwordx4 v254, s[26:27]
	s_add_u32 m0, m0, 0x1000
	v_mfma_f32_32x32x16_bf16 v[16:31], v[110:113], v[210:213], v[16:31]
	v_mfma_f32_32x32x16_bf16 v[0:15], v[110:113], v[214:217], v[0:15]
	global_load_lds_dwordx4 v254, s[28:29]
	s_add_u32 m0, m0, 0x1000
	v_mfma_f32_32x32x16_bf16 v[48:63], v[218:221], v[222:225], v[48:63]
	v_mfma_f32_32x32x16_bf16 v[32:47], v[218:221], v[226:229], v[32:47]
	global_load_lds_dwordx4 v254, s[30:31]
	s_add_u32 m0, m0, 0x1000
	v_mfma_f32_32x32x16_bf16 v[16:31], v[218:221], v[230:233], v[16:31]
	v_mfma_f32_32x32x16_bf16 v[0:15], v[218:221], v[234:237], v[0:15]
	global_load_lds_dwordx4 v254, s[34:35]
	v_add_u32_e32 v254, 0x80, v254
	s_waitcnt vmcnt(8)
	s_barrier
	ds_read_b128 v[70:73], v156 offset:32768
	ds_read_b128 v[74:77], v157 offset:49152
	ds_read_b128 v[78:81], v157 offset:53248
	ds_read_b128 v[82:85], v157 offset:57344
	ds_read_b128 v[86:89], v157 offset:61440
	ds_read_b128 v[90:93], v158 offset:32768
	ds_read_b128 v[94:97], v159 offset:49152
	ds_read_b128 v[98:101], v159 offset:53248
	ds_read_b128 v[102:105], v159 offset:57344
	ds_read_b128 v[106:109], v159 offset:61440
	ds_read_b128 v[110:113], v160 offset:32768
	ds_read_b128 v[202:205], v161 offset:49152
	ds_read_b128 v[206:209], v161 offset:53248
	ds_read_b128 v[210:213], v161 offset:57344
	ds_read_b128 v[214:217], v161 offset:61440
	ds_read_b128 v[218:221], v162 offset:32768
	ds_read_b128 v[222:225], v163 offset:49152
	ds_read_b128 v[226:229], v163 offset:53248
	ds_read_b128 v[230:233], v163 offset:57344
	ds_read_b128 v[234:237], v163 offset:61440
	s_waitcnt lgkmcnt(0)
	s_barrier
	s_add_u32 m0, s36, 0x8000
	v_mfma_f32_32x32x16_bf16 v[48:63], v[70:73], v[74:77], v[48:63]
	v_mfma_f32_32x32x16_bf16 v[32:47], v[70:73], v[78:81], v[32:47]
	global_load_lds_dwordx4 v254, s[18:19]
	s_add_u32 m0, m0, 0x1000
	v_mfma_f32_32x32x16_bf16 v[16:31], v[70:73], v[82:85], v[16:31]
	v_mfma_f32_32x32x16_bf16 v[0:15], v[70:73], v[86:89], v[0:15]
	global_load_lds_dwordx4 v254, s[20:21]
	s_add_u32 m0, m0, 0x1000
	v_mfma_f32_32x32x16_bf16 v[48:63], v[90:93], v[94:97], v[48:63]
	v_mfma_f32_32x32x16_bf16 v[32:47], v[90:93], v[98:101], v[32:47]
	global_load_lds_dwordx4 v254, s[22:23]
	s_add_u32 m0, m0, 0x1000
	v_mfma_f32_32x32x16_bf16 v[16:31], v[90:93], v[102:105], v[16:31]
	v_mfma_f32_32x32x16_bf16 v[0:15], v[90:93], v[106:109], v[0:15]
	global_load_lds_dwordx4 v254, s[24:25]
	s_add_u32 m0, m0, 0x1000
	v_mfma_f32_32x32x16_bf16 v[48:63], v[110:113], v[202:205], v[48:63]
	v_mfma_f32_32x32x16_bf16 v[32:47], v[110:113], v[206:209], v[32:47]
	global_load_lds_dwordx4 v254, s[26:27]
	s_add_u32 m0, m0, 0x1000
	v_mfma_f32_32x32x16_bf16 v[16:31], v[110:113], v[210:213], v[16:31]
	v_mfma_f32_32x32x16_bf16 v[0:15], v[110:113], v[214:217], v[0:15]
	global_load_lds_dwordx4 v254, s[28:29]
	s_add_u32 m0, m0, 0x1000
	v_mfma_f32_32x32x16_bf16 v[48:63], v[218:221], v[222:225], v[48:63]
	v_mfma_f32_32x32x16_bf16 v[32:47], v[218:221], v[226:229], v[32:47]
	global_load_lds_dwordx4 v254, s[30:31]
	s_add_u32 m0, m0, 0x1000
	v_mfma_f32_32x32x16_bf16 v[16:31], v[218:221], v[230:233], v[16:31]
	v_mfma_f32_32x32x16_bf16 v[0:15], v[218:221], v[234:237], v[0:15]
	global_load_lds_dwordx4 v254, s[34:35]
	v_add_u32_e32 v254, 0x80, v254
	s_branch .LBB0_1326

.Lmap_done_2_pf_p17:
	s_lshl_b32 s44, s41, 7
	s_lshl_b32 s42, s50, 7
	s_ashr_i32 s45, s44, 31
	s_ashr_i32 s43, s42, 31
	s_lshl_b64 s[46:47], s[44:45], 11
	s_lshl_b64 s[48:49], s[42:43], 11
	s_lshl_b32 s38, s44, 11
	s_add_u32 s18, s14, s38
	s_addc_u32 s19, s15, 0
	s_add_u32 s18, s18, 0x679f000
	s_addc_u32 s19, s19, 0
	s_add_u32 s20, s18, 0x10000
	s_addc_u32 s21, s19, 0
	s_add_u32 s22, s20, 0x10000
	s_addc_u32 s23, s21, 0
	s_add_u32 s24, s22, 0x10000
	s_addc_u32 s25, s23, 0
	s_lshl_b32 s38, s42, 11
	s_add_u32 s26, s14, s38
	s_addc_u32 s27, s15, 0
	s_add_u32 s26, s26, 0x2fa0000
	s_addc_u32 s27, s27, 0
	s_add_u32 s28, s26, 0x10000
	s_addc_u32 s29, s27, 0
	s_add_u32 s30, s28, 0x10000
	s_addc_u32 s31, s29, 0
	s_add_u32 s34, s30, 0x10000
	s_addc_u32 s35, s31, 0
	v_mov_b32_e32 v254, v76
	s_mov_b32 s39, 1
	s_waitcnt vmcnt(8)
	s_barrier
	ds_read_b128 v[64:67], v110
	ds_read_b128 v[68:71], v111 offset:16384
	ds_read_b128 v[72:75], v111 offset:20480
	ds_read_b128 v[82:85], v111 offset:24576
	ds_read_b128 v[86:89], v111 offset:28672
	ds_read_b128 v[120:123], v112
	ds_read_b128 v[124:127], v113 offset:16384
	ds_read_b128 v[128:131], v113 offset:20480
	ds_read_b128 v[132:135], v113 offset:24576
	ds_read_b128 v[136:139], v113 offset:28672
	ds_read_b128 v[140:143], v114
	ds_read_b128 v[218:221], v115 offset:16384
	ds_read_b128 v[222:225], v115 offset:20480
	ds_read_b128 v[226:229], v115 offset:24576
	ds_read_b128 v[230:233], v115 offset:28672
	ds_read_b128 v[234:237], v116
	ds_read_b128 v[238:241], v117 offset:16384
	ds_read_b128 v[242:245], v117 offset:20480
	ds_read_b128 v[246:249], v117 offset:24576
	ds_read_b128 v[250:253], v117 offset:28672
	s_waitcnt lgkmcnt(0)
	s_barrier
	s_mov_b32 m0, s36
	v_mfma_f32_32x32x16_bf16 v[48:63], v[64:67], v[68:71], v[48:63]
	v_mfma_f32_32x32x16_bf16 v[32:47], v[64:67], v[72:75], v[32:47]
	global_load_lds_dwordx4 v254, s[18:19]
	s_add_u32 m0, m0, 0x1000
	v_mfma_f32_32x32x16_bf16 v[16:31], v[64:67], v[82:85], v[16:31]
	v_mfma_f32_32x32x16_bf16 v[0:15], v[64:67], v[86:89], v[0:15]
	global_load_lds_dwordx4 v254, s[20:21]
	s_add_u32 m0, m0, 0x1000
	v_mfma_f32_32x32x16_bf16 v[48:63], v[120:123], v[124:127], v[48:63]
	v_mfma_f32_32x32x16_bf16 v[32:47], v[120:123], v[128:131], v[32:47]
	global_load_lds_dwordx4 v254, s[22:23]
	s_add_u32 m0, m0, 0x1000
	v_mfma_f32_32x32x16_bf16 v[16:31], v[120:123], v[132:135], v[16:31]
	v_mfma_f32_32x32x16_bf16 v[0:15], v[120:123], v[136:139], v[0:15]
	global_load_lds_dwordx4 v254, s[24:25]
	s_add_u32 m0, m0, 0x1000
	v_mfma_f32_32x32x16_bf16 v[48:63], v[140:143], v[218:221], v[48:63]
	v_mfma_f32_32x32x16_bf16 v[32:47], v[140:143], v[222:225], v[32:47]
	global_load_lds_dwordx4 v254, s[26:27]
	s_add_u32 m0, m0, 0x1000
	v_mfma_f32_32x32x16_bf16 v[16:31], v[140:143], v[226:229], v[16:31]
	v_mfma_f32_32x32x16_bf16 v[0:15], v[140:143], v[230:233], v[0:15]
	global_load_lds_dwordx4 v254, s[28:29]
	s_add_u32 m0, m0, 0x1000
	v_mfma_f32_32x32x16_bf16 v[48:63], v[234:237], v[238:241], v[48:63]
	v_mfma_f32_32x32x16_bf16 v[32:47], v[234:237], v[242:245], v[32:47]
	global_load_lds_dwordx4 v254, s[30:31]
	s_add_u32 m0, m0, 0x1000
	v_mfma_f32_32x32x16_bf16 v[16:31], v[234:237], v[246:249], v[16:31]
	v_mfma_f32_32x32x16_bf16 v[0:15], v[234:237], v[250:253], v[0:15]
	global_load_lds_dwordx4 v254, s[34:35]
	v_add_u32_e32 v254, 0x80, v254
	s_waitcnt vmcnt(8)
	s_barrier
	ds_read_b128 v[64:67], v110 offset:32768
	ds_read_b128 v[68:71], v111 offset:49152
	ds_read_b128 v[72:75], v111 offset:53248
	ds_read_b128 v[82:85], v111 offset:57344
	ds_read_b128 v[86:89], v111 offset:61440
	ds_read_b128 v[120:123], v112 offset:32768
	ds_read_b128 v[124:127], v113 offset:49152
	ds_read_b128 v[128:131], v113 offset:53248
	ds_read_b128 v[132:135], v113 offset:57344
	ds_read_b128 v[136:139], v113 offset:61440
	ds_read_b128 v[140:143], v114 offset:32768
	ds_read_b128 v[218:221], v115 offset:49152
	ds_read_b128 v[222:225], v115 offset:53248
	ds_read_b128 v[226:229], v115 offset:57344
	ds_read_b128 v[230:233], v115 offset:61440
	ds_read_b128 v[234:237], v116 offset:32768
	ds_read_b128 v[238:241], v117 offset:49152
	ds_read_b128 v[242:245], v117 offset:53248
	ds_read_b128 v[246:249], v117 offset:57344
	ds_read_b128 v[250:253], v117 offset:61440
	s_waitcnt lgkmcnt(0)
	s_barrier
	s_add_u32 m0, s36, 0x8000
	v_mfma_f32_32x32x16_bf16 v[48:63], v[64:67], v[68:71], v[48:63]
	v_add_f32_e32 v144, v144, v145
	v_add_f32_e32 v146, v146, v147
	v_mfma_f32_32x32x16_bf16 v[32:47], v[64:67], v[72:75], v[32:47]
	v_add_f32_e32 v148, v148, v149
	v_add_f32_e32 v150, v150, v151
	global_load_lds_dwordx4 v254, s[18:19]
	s_add_u32 m0, m0, 0x1000
	v_mfma_f32_32x32x16_bf16 v[16:31], v[64:67], v[82:85], v[16:31]
	v_add_f32_e32 v144, v144, v146
	v_add_f32_e32 v148, v148, v150
	v_mfma_f32_32x32x16_bf16 v[0:15], v[64:67], v[86:89], v[0:15]
	v_add_f32_e32 v144, v144, v148
	v_fmamk_f32 v144, v144, 0x3a800000, v118
	global_load_lds_dwordx4 v254, s[20:21]
	s_add_u32 m0, m0, 0x1000
	v_mfma_f32_32x32x16_bf16 v[48:63], v[120:123], v[124:127], v[48:63]
	v_rsq_f32_e32 v144, v144
	s_nop 1
	v_mfma_f32_32x32x16_bf16 v[32:47], v[120:123], v[128:131], v[32:47]
	ds_bpermute_b32 v156, v153, v144
	ds_bpermute_b32 v157, v153, v144 offset:4
	global_load_lds_dwordx4 v254, s[22:23]
	s_add_u32 m0, m0, 0x1000
	v_mfma_f32_32x32x16_bf16 v[16:31], v[120:123], v[132:135], v[16:31]
	ds_bpermute_b32 v158, v153, v144 offset:8
	ds_bpermute_b32 v159, v153, v144 offset:12
	v_mfma_f32_32x32x16_bf16 v[0:15], v[120:123], v[136:139], v[0:15]
	ds_bpermute_b32 v160, v153, v144 offset:32
	ds_bpermute_b32 v161, v153, v144 offset:36
	global_load_lds_dwordx4 v254, s[24:25]
	s_add_u32 m0, m0, 0x1000
	v_mfma_f32_32x32x16_bf16 v[48:63], v[140:143], v[218:221], v[48:63]
	ds_bpermute_b32 v162, v153, v144 offset:40
	ds_bpermute_b32 v163, v153, v144 offset:44
	v_mfma_f32_32x32x16_bf16 v[32:47], v[140:143], v[222:225], v[32:47]
	ds_bpermute_b32 v164, v153, v144 offset:64
	ds_bpermute_b32 v165, v153, v144 offset:68
	global_load_lds_dwordx4 v254, s[26:27]
	s_add_u32 m0, m0, 0x1000
	v_mfma_f32_32x32x16_bf16 v[16:31], v[140:143], v[226:229], v[16:31]
	ds_bpermute_b32 v166, v153, v144 offset:72
	ds_bpermute_b32 v167, v153, v144 offset:76
	v_mfma_f32_32x32x16_bf16 v[0:15], v[140:143], v[230:233], v[0:15]
	ds_bpermute_b32 v168, v153, v144 offset:96
	ds_bpermute_b32 v169, v153, v144 offset:100
	global_load_lds_dwordx4 v254, s[28:29]
	s_add_u32 m0, m0, 0x1000
	v_mfma_f32_32x32x16_bf16 v[48:63], v[234:237], v[238:241], v[48:63]
	ds_bpermute_b32 v170, v153, v144 offset:104
	ds_bpermute_b32 v171, v153, v144 offset:108
	v_mfma_f32_32x32x16_bf16 v[32:47], v[234:237], v[242:245], v[32:47]
	global_load_lds_dwordx4 v254, s[30:31]
	s_add_u32 m0, m0, 0x1000
	v_mfma_f32_32x32x16_bf16 v[16:31], v[234:237], v[246:249], v[16:31]
	v_mfma_f32_32x32x16_bf16 v[0:15], v[234:237], v[250:253], v[0:15]
	global_load_lds_dwordx4 v254, s[34:35]
	v_add_u32_e32 v254, 0x80, v254
	s_branch .LBB0_1373

.LBB0_1394_pf_p18:
	s_ashr_i32 s41, s40, 31
	s_lshr_b32 s41, s41, 26
	s_add_i32 s41, s40, s41
	s_ashr_i32 s42, s41, 6
	s_andn2_b32 s41, s41, 63
	s_sub_i32 s41, s40, s41
	s_ashr_i32 s43, s41, 31
	s_lshr_b32 s43, s43, 29
	s_add_i32 s43, s41, s43
	s_ashr_i32 s44, s43, 3
	s_and_b32 s43, s43, -8
	s_lshl_b32 s42, s42, 3
	s_sub_i32 s41, s41, s43
	s_add_i32 s41, s41, s42
	s_lshl_b32 s45, s41, 7
	s_lshl_b32 s46, s44, 7
	s_mul_i32 s38, s41, 0xb0000
	s_add_u32 s18, s14, s38
	s_addc_u32 s19, s15, 0
	s_add_u32 s18, s18, 0x879f000
	s_addc_u32 s19, s19, 0
	s_add_u32 s20, s18, 0x2c000
	s_addc_u32 s21, s19, 0
	s_add_u32 s22, s20, 0x2c000
	s_addc_u32 s23, s21, 0
	s_add_u32 s24, s22, 0x2c000
	s_addc_u32 s25, s23, 0
	s_mul_i32 s38, s44, 0xb0000
	s_add_u32 s26, s14, s38
	s_addc_u32 s27, s15, 0
	s_add_u32 s26, s26, 0x50a0000
	s_addc_u32 s27, s27, 0
	s_add_u32 s28, s26, 0x2c000
	s_addc_u32 s29, s27, 0
	s_add_u32 s30, s28, 0x2c000
	s_addc_u32 s31, s29, 0
	s_add_u32 s34, s30, 0x2c000
	s_addc_u32 s35, s31, 0
	v_mov_b32_e32 v254, v64
	s_mov_b32 s39, 1
	s_waitcnt vmcnt(8)
	s_barrier
	ds_read_b128 v[70:73], v157
	ds_read_b128 v[74:77], v158 offset:16384
	ds_read_b128 v[78:81], v158 offset:20480
	ds_read_b128 v[82:85], v158 offset:24576
	ds_read_b128 v[86:89], v158 offset:28672
	ds_read_b128 v[90:93], v159
	ds_read_b128 v[94:97], v160 offset:16384
	ds_read_b128 v[98:101], v160 offset:20480
	ds_read_b128 v[102:105], v160 offset:24576
	ds_read_b128 v[106:109], v160 offset:28672
	ds_read_b128 v[110:113], v161
	ds_read_b128 v[202:205], v162 offset:16384
	ds_read_b128 v[206:209], v162 offset:20480
	ds_read_b128 v[210:213], v162 offset:24576
	ds_read_b128 v[214:217], v162 offset:28672
	ds_read_b128 v[218:221], v163
	ds_read_b128 v[222:225], v164 offset:16384
	ds_read_b128 v[226:229], v164 offset:20480
	ds_read_b128 v[230:233], v164 offset:24576
	ds_read_b128 v[234:237], v164 offset:28672
	s_waitcnt lgkmcnt(0)
	s_barrier
	s_mov_b32 m0, s36
	v_mfma_f32_32x32x16_bf16 v[48:63], v[70:73], v[74:77], v[48:63]
	v_mfma_f32_32x32x16_bf16 v[32:47], v[70:73], v[78:81], v[32:47]
	global_load_lds_dwordx4 v254, s[18:19]
	s_add_u32 m0, m0, 0x1000
	v_mfma_f32_32x32x16_bf16 v[16:31], v[70:73], v[82:85], v[16:31]
	v_mfma_f32_32x32x16_bf16 v[0:15], v[70:73], v[86:89], v[0:15]
	global_load_lds_dwordx4 v254, s[20:21]
	s_add_u32 m0, m0, 0x1000
	v_mfma_f32_32x32x16_bf16 v[48:63], v[90:93], v[94:97], v[48:63]
	v_mfma_f32_32x32x16_bf16 v[32:47], v[90:93], v[98:101], v[32:47]
	global_load_lds_dwordx4 v254, s[22:23]
	s_add_u32 m0, m0, 0x1000
	v_mfma_f32_32x32x16_bf16 v[16:31], v[90:93], v[102:105], v[16:31]
	v_mfma_f32_32x32x16_bf16 v[0:15], v[90:93], v[106:109], v[0:15]
	global_load_lds_dwordx4 v254, s[24:25]
	s_add_u32 m0, m0, 0x1000
	v_mfma_f32_32x32x16_bf16 v[48:63], v[110:113], v[202:205], v[48:63]
	v_mfma_f32_32x32x16_bf16 v[32:47], v[110:113], v[206:209], v[32:47]
	global_load_lds_dwordx4 v254, s[26:27]
	s_add_u32 m0, m0, 0x1000
	v_mfma_f32_32x32x16_bf16 v[16:31], v[110:113], v[210:213], v[16:31]
	v_mfma_f32_32x32x16_bf16 v[0:15], v[110:113], v[214:217], v[0:15]
	global_load_lds_dwordx4 v254, s[28:29]
	s_add_u32 m0, m0, 0x1000
	v_mfma_f32_32x32x16_bf16 v[48:63], v[218:221], v[222:225], v[48:63]
	v_mfma_f32_32x32x16_bf16 v[32:47], v[218:221], v[226:229], v[32:47]
	global_load_lds_dwordx4 v254, s[30:31]
	s_add_u32 m0, m0, 0x1000
	v_mfma_f32_32x32x16_bf16 v[16:31], v[218:221], v[230:233], v[16:31]
	v_mfma_f32_32x32x16_bf16 v[0:15], v[218:221], v[234:237], v[0:15]
	global_load_lds_dwordx4 v254, s[34:35]
	v_add_u32_e32 v254, 0x80, v254
	s_waitcnt vmcnt(8)
	s_barrier
	ds_read_b128 v[70:73], v157 offset:32768
	ds_read_b128 v[74:77], v158 offset:49152
	ds_read_b128 v[78:81], v158 offset:53248
	ds_read_b128 v[82:85], v158 offset:57344
	ds_read_b128 v[86:89], v158 offset:61440
	ds_read_b128 v[90:93], v159 offset:32768
	ds_read_b128 v[94:97], v160 offset:49152
	ds_read_b128 v[98:101], v160 offset:53248
	ds_read_b128 v[102:105], v160 offset:57344
	ds_read_b128 v[106:109], v160 offset:61440
	ds_read_b128 v[110:113], v161 offset:32768
	ds_read_b128 v[202:205], v162 offset:49152
	ds_read_b128 v[206:209], v162 offset:53248
	ds_read_b128 v[210:213], v162 offset:57344
	ds_read_b128 v[214:217], v162 offset:61440
	ds_read_b128 v[218:221], v163 offset:32768
	ds_read_b128 v[222:225], v164 offset:49152
	ds_read_b128 v[226:229], v164 offset:53248
	ds_read_b128 v[230:233], v164 offset:57344
	ds_read_b128 v[234:237], v164 offset:61440
	s_waitcnt lgkmcnt(0)
	s_barrier
	s_add_u32 m0, s36, 0x8000
	v_mfma_f32_32x32x16_bf16 v[48:63], v[70:73], v[74:77], v[48:63]
	v_mfma_f32_32x32x16_bf16 v[32:47], v[70:73], v[78:81], v[32:47]
	global_load_lds_dwordx4 v254, s[18:19]
	s_add_u32 m0, m0, 0x1000
	v_mfma_f32_32x32x16_bf16 v[16:31], v[70:73], v[82:85], v[16:31]
	v_mfma_f32_32x32x16_bf16 v[0:15], v[70:73], v[86:89], v[0:15]
	global_load_lds_dwordx4 v254, s[20:21]
	s_add_u32 m0, m0, 0x1000
	v_mfma_f32_32x32x16_bf16 v[48:63], v[90:93], v[94:97], v[48:63]
	v_mfma_f32_32x32x16_bf16 v[32:47], v[90:93], v[98:101], v[32:47]
	global_load_lds_dwordx4 v254, s[22:23]
	s_add_u32 m0, m0, 0x1000
	v_mfma_f32_32x32x16_bf16 v[16:31], v[90:93], v[102:105], v[16:31]
	v_mfma_f32_32x32x16_bf16 v[0:15], v[90:93], v[106:109], v[0:15]
	global_load_lds_dwordx4 v254, s[24:25]
	s_add_u32 m0, m0, 0x1000
	v_mfma_f32_32x32x16_bf16 v[48:63], v[110:113], v[202:205], v[48:63]
	v_mfma_f32_32x32x16_bf16 v[32:47], v[110:113], v[206:209], v[32:47]
	global_load_lds_dwordx4 v254, s[26:27]
	s_add_u32 m0, m0, 0x1000
	v_mfma_f32_32x32x16_bf16 v[16:31], v[110:113], v[210:213], v[16:31]
	v_mfma_f32_32x32x16_bf16 v[0:15], v[110:113], v[214:217], v[0:15]
	global_load_lds_dwordx4 v254, s[28:29]
	s_add_u32 m0, m0, 0x1000
	v_mfma_f32_32x32x16_bf16 v[48:63], v[218:221], v[222:225], v[48:63]
	v_mfma_f32_32x32x16_bf16 v[32:47], v[218:221], v[226:229], v[32:47]
	global_load_lds_dwordx4 v254, s[30:31]
	s_add_u32 m0, m0, 0x1000
	v_mfma_f32_32x32x16_bf16 v[16:31], v[218:221], v[230:233], v[16:31]
	v_mfma_f32_32x32x16_bf16 v[0:15], v[218:221], v[234:237], v[0:15]
	global_load_lds_dwordx4 v254, s[34:35]
	v_add_u32_e32 v254, 0x80, v254
	s_branch .LBB0_1398

.Lgk_loop_p19:
	s_waitcnt vmcnt(8)
	s_barrier
	ds_read_b128 v[64:67], v113
	ds_read_b128 v[68:71], v114 offset:16384
	ds_read_b128 v[72:75], v114 offset:20480
	ds_read_b128 v[82:85], v114 offset:24576
	ds_read_b128 v[86:89], v114 offset:28672
	ds_read_b128 v[90:93], v115
	ds_read_b128 v[122:125], v116 offset:16384
	ds_read_b128 v[126:129], v116 offset:20480
	ds_read_b128 v[130:133], v116 offset:24576
	ds_read_b128 v[134:137], v116 offset:28672
	ds_read_b128 v[138:141], v117
	ds_read_b128 v[218:221], v118 offset:16384
	ds_read_b128 v[222:225], v118 offset:20480
	ds_read_b128 v[226:229], v118 offset:24576
	ds_read_b128 v[230:233], v118 offset:28672
	ds_read_b128 v[234:237], v119
	ds_read_b128 v[238:241], v120 offset:16384
	ds_read_b128 v[242:245], v120 offset:20480
	ds_read_b128 v[246:249], v120 offset:24576
	ds_read_b128 v[250:253], v120 offset:28672
	s_waitcnt lgkmcnt(0)
	s_barrier
	s_mov_b32 m0, s38
	v_mfma_f32_32x32x16_bf16 v[48:63], v[64:67], v[68:71], v[48:63]
	v_mfma_f32_32x32x16_bf16 v[32:47], v[64:67], v[72:75], v[32:47]
	global_load_lds_dwordx4 v254, s[20:21]
	s_add_u32 m0, m0, 0x1000
	v_mfma_f32_32x32x16_bf16 v[16:31], v[64:67], v[82:85], v[16:31]
	v_mfma_f32_32x32x16_bf16 v[0:15], v[64:67], v[86:89], v[0:15]
	global_load_lds_dwordx4 v254, s[22:23]
	s_add_u32 m0, m0, 0x1000
	v_mfma_f32_32x32x16_bf16 v[48:63], v[90:93], v[122:125], v[48:63]
	v_mfma_f32_32x32x16_bf16 v[32:47], v[90:93], v[126:129], v[32:47]
	global_load_lds_dwordx4 v254, s[24:25]
	s_add_u32 m0, m0, 0x1000
	v_mfma_f32_32x32x16_bf16 v[16:31], v[90:93], v[130:133], v[16:31]
	v_mfma_f32_32x32x16_bf16 v[0:15], v[90:93], v[134:137], v[0:15]
	global_load_lds_dwordx4 v254, s[26:27]
	s_add_u32 m0, m0, 0x1000
	v_mfma_f32_32x32x16_bf16 v[48:63], v[138:141], v[218:221], v[48:63]
	v_mfma_f32_32x32x16_bf16 v[32:47], v[138:141], v[222:225], v[32:47]
	global_load_lds_dwordx4 v254, s[28:29]
	s_add_u32 m0, m0, 0x1000
	v_mfma_f32_32x32x16_bf16 v[16:31], v[138:141], v[226:229], v[16:31]
	v_mfma_f32_32x32x16_bf16 v[0:15], v[138:141], v[230:233], v[0:15]
	global_load_lds_dwordx4 v254, s[30:31]
	s_add_u32 m0, m0, 0x1000
	v_mfma_f32_32x32x16_bf16 v[48:63], v[234:237], v[238:241], v[48:63]
	v_mfma_f32_32x32x16_bf16 v[32:47], v[234:237], v[242:245], v[32:47]
	global_load_lds_dwordx4 v254, s[34:35]
	s_add_u32 m0, m0, 0x1000
	v_mfma_f32_32x32x16_bf16 v[16:31], v[234:237], v[246:249], v[16:31]
	v_mfma_f32_32x32x16_bf16 v[0:15], v[234:237], v[250:253], v[0:15]
	global_load_lds_dwordx4 v254, s[36:37]
	v_add_u32_e32 v254, 0x80, v254
	s_waitcnt vmcnt(8)
	s_barrier
	ds_read_b128 v[64:67], v113 offset:32768
	ds_read_b128 v[68:71], v114 offset:49152
	ds_read_b128 v[72:75], v114 offset:53248
	ds_read_b128 v[82:85], v114 offset:57344
	ds_read_b128 v[86:89], v114 offset:61440
	ds_read_b128 v[90:93], v115 offset:32768
	ds_read_b128 v[122:125], v116 offset:49152
	ds_read_b128 v[126:129], v116 offset:53248
	ds_read_b128 v[130:133], v116 offset:57344
	ds_read_b128 v[134:137], v116 offset:61440
	ds_read_b128 v[138:141], v117 offset:32768
	ds_read_b128 v[218:221], v118 offset:49152
	ds_read_b128 v[222:225], v118 offset:53248
	ds_read_b128 v[226:229], v118 offset:57344
	ds_read_b128 v[230:233], v118 offset:61440
	ds_read_b128 v[234:237], v119 offset:32768
	ds_read_b128 v[238:241], v120 offset:49152
	ds_read_b128 v[242:245], v120 offset:53248
	ds_read_b128 v[246:249], v120 offset:57344
	ds_read_b128 v[250:253], v120 offset:61440
	s_waitcnt lgkmcnt(0)
	s_barrier
	s_add_u32 m0, s38, 0x8000
	v_mfma_f32_32x32x16_bf16 v[48:63], v[64:67], v[68:71], v[48:63]
	v_mfma_f32_32x32x16_bf16 v[32:47], v[64:67], v[72:75], v[32:47]
	global_load_lds_dwordx4 v254, s[20:21]
	s_add_u32 m0, m0, 0x1000
	v_mfma_f32_32x32x16_bf16 v[16:31], v[64:67], v[82:85], v[16:31]
	v_mfma_f32_32x32x16_bf16 v[0:15], v[64:67], v[86:89], v[0:15]
	global_load_lds_dwordx4 v254, s[22:23]
	s_add_u32 m0, m0, 0x1000
	v_mfma_f32_32x32x16_bf16 v[48:63], v[90:93], v[122:125], v[48:63]
	v_mfma_f32_32x32x16_bf16 v[32:47], v[90:93], v[126:129], v[32:47]
	global_load_lds_dwordx4 v254, s[24:25]
	s_add_u32 m0, m0, 0x1000
	v_mfma_f32_32x32x16_bf16 v[16:31], v[90:93], v[130:133], v[16:31]
	v_mfma_f32_32x32x16_bf16 v[0:15], v[90:93], v[134:137], v[0:15]
	global_load_lds_dwordx4 v254, s[26:27]
	s_add_u32 m0, m0, 0x1000
	v_mfma_f32_32x32x16_bf16 v[48:63], v[138:141], v[218:221], v[48:63]
	v_mfma_f32_32x32x16_bf16 v[32:47], v[138:141], v[222:225], v[32:47]
	global_load_lds_dwordx4 v254, s[28:29]
	s_add_u32 m0, m0, 0x1000
	v_mfma_f32_32x32x16_bf16 v[16:31], v[138:141], v[226:229], v[16:31]
	v_mfma_f32_32x32x16_bf16 v[0:15], v[138:141], v[230:233], v[0:15]
	global_load_lds_dwordx4 v254, s[30:31]
	s_add_u32 m0, m0, 0x1000
	v_mfma_f32_32x32x16_bf16 v[48:63], v[234:237], v[238:241], v[48:63]
	v_mfma_f32_32x32x16_bf16 v[32:47], v[234:237], v[242:245], v[32:47]
	global_load_lds_dwordx4 v254, s[34:35]
	s_add_u32 m0, m0, 0x1000
	v_mfma_f32_32x32x16_bf16 v[16:31], v[234:237], v[246:249], v[16:31]
	v_mfma_f32_32x32x16_bf16 v[0:15], v[234:237], v[250:253], v[0:15]
	global_load_lds_dwordx4 v254, s[36:37]
	v_add_u32_e32 v254, 0x80, v254
	s_sub_u32 s39, s39, 1
	s_cmp_lg_u32 s39, 0
	s_cbranch_scc1 .Lgk_loop_p19
	s_add_u32 s42, s3, s33
	s_cmp_gt_u32 s42, 0x7ff
	s_cbranch_scc1 .Lgk_tailplain_p19
.LBB0_1446_pf_p19:
	s_ashr_i32 s43, s42, 31
	s_lshr_b32 s43, s43, 25
	s_add_i32 s43, s42, s43
	s_ashr_i32 s44, s43, 7
	s_and_b32 s43, s43, 0xffffff80
	s_sub_i32 s52, s42, s43
	s_ashr_i32 s43, s52, 31
	s_lshr_b32 s43, s43, 29
	s_add_i32 s45, s52, s43
	s_and_b32 s43, s45, -8
	s_lshl_b32 s44, s44, 3
	s_sub_i32 s43, s52, s43
	s_add_i32 s43, s43, s44
	s_lshl_b32 s44, s45, 4
	s_lshl_b32 s46, s43, 7
	s_and_b32 s44, s44, 0xffffff80
	s_ashr_i32 s47, s46, 31
	s_ashr_i32 s45, s44, 31
	s_lshl_b64 s[48:49], s[46:47], 11
	s_lshl_b64 s[50:51], s[44:45], 11
	s_lshl_b32 s40, s46, 11
	s_add_u32 s20, s14, s40
	s_addc_u32 s21, s15, 0
	s_add_u32 s20, s20, 0x679f000
	s_addc_u32 s21, s21, 0
	s_add_u32 s22, s20, 0x10000
	s_addc_u32 s23, s21, 0
	s_add_u32 s24, s22, 0x10000
	s_addc_u32 s25, s23, 0
	s_add_u32 s26, s24, 0x10000
	s_addc_u32 s27, s25, 0
	s_lshl_b32 s40, s44, 11
	s_add_u32 s28, s14, s40
	s_addc_u32 s29, s15, 0
	s_add_u32 s28, s28, 0x12a0000
	s_addc_u32 s29, s29, 0
	s_add_u32 s30, s28, 0x10000
	s_addc_u32 s31, s29, 0
	s_add_u32 s34, s30, 0x10000
	s_addc_u32 s35, s31, 0
	s_add_u32 s36, s34, 0x10000
	s_addc_u32 s37, s35, 0
	v_mov_b32_e32 v254, v76
	s_mov_b32 s41, 1
	s_waitcnt vmcnt(8)
	s_barrier
	ds_read_b128 v[64:67], v113
	ds_read_b128 v[68:71], v114 offset:16384
	ds_read_b128 v[72:75], v114 offset:20480
	ds_read_b128 v[82:85], v114 offset:24576
	ds_read_b128 v[86:89], v114 offset:28672
	ds_read_b128 v[90:93], v115
	ds_read_b128 v[122:125], v116 offset:16384
	ds_read_b128 v[126:129], v116 offset:20480
	ds_read_b128 v[130:133], v116 offset:24576
	ds_read_b128 v[134:137], v116 offset:28672
	ds_read_b128 v[138:141], v117
	ds_read_b128 v[218:221], v118 offset:16384
	ds_read_b128 v[222:225], v118 offset:20480
	ds_read_b128 v[226:229], v118 offset:24576
	ds_read_b128 v[230:233], v118 offset:28672
	ds_read_b128 v[234:237], v119
	ds_read_b128 v[238:241], v120 offset:16384
	ds_read_b128 v[242:245], v120 offset:20480
	ds_read_b128 v[246:249], v120 offset:24576
	ds_read_b128 v[250:253], v120 offset:28672
	s_waitcnt lgkmcnt(0)
	s_barrier
	s_mov_b32 m0, s38
	v_mfma_f32_32x32x16_bf16 v[48:63], v[64:67], v[68:71], v[48:63]
	v_mfma_f32_32x32x16_bf16 v[32:47], v[64:67], v[72:75], v[32:47]
	global_load_lds_dwordx4 v254, s[20:21]
	s_add_u32 m0, m0, 0x1000
	v_mfma_f32_32x32x16_bf16 v[16:31], v[64:67], v[82:85], v[16:31]
	v_mfma_f32_32x32x16_bf16 v[0:15], v[64:67], v[86:89], v[0:15]
	global_load_lds_dwordx4 v254, s[22:23]
	s_add_u32 m0, m0, 0x1000
	v_mfma_f32_32x32x16_bf16 v[48:63], v[90:93], v[122:125], v[48:63]
	v_mfma_f32_32x32x16_bf16 v[32:47], v[90:93], v[126:129], v[32:47]
	global_load_lds_dwordx4 v254, s[24:25]
	s_add_u32 m0, m0, 0x1000
	v_mfma_f32_32x32x16_bf16 v[16:31], v[90:93], v[130:133], v[16:31]
	v_mfma_f32_32x32x16_bf16 v[0:15], v[90:93], v[134:137], v[0:15]
	global_load_lds_dwordx4 v254, s[26:27]
	s_add_u32 m0, m0, 0x1000
	v_mfma_f32_32x32x16_bf16 v[48:63], v[138:141], v[218:221], v[48:63]
	v_mfma_f32_32x32x16_bf16 v[32:47], v[138:141], v[222:225], v[32:47]
	global_load_lds_dwordx4 v254, s[28:29]
	s_add_u32 m0, m0, 0x1000
	v_mfma_f32_32x32x16_bf16 v[16:31], v[138:141], v[226:229], v[16:31]
	v_mfma_f32_32x32x16_bf16 v[0:15], v[138:141], v[230:233], v[0:15]
	global_load_lds_dwordx4 v254, s[30:31]
	s_add_u32 m0, m0, 0x1000
	v_mfma_f32_32x32x16_bf16 v[48:63], v[234:237], v[238:241], v[48:63]
	v_mfma_f32_32x32x16_bf16 v[32:47], v[234:237], v[242:245], v[32:47]
	global_load_lds_dwordx4 v254, s[34:35]
	s_add_u32 m0, m0, 0x1000
	v_mfma_f32_32x32x16_bf16 v[16:31], v[234:237], v[246:249], v[16:31]
	v_mfma_f32_32x32x16_bf16 v[0:15], v[234:237], v[250:253], v[0:15]
	global_load_lds_dwordx4 v254, s[36:37]
	v_add_u32_e32 v254, 0x80, v254
	s_waitcnt vmcnt(8)
	s_barrier
	ds_read_b128 v[64:67], v113 offset:32768
	ds_read_b128 v[68:71], v114 offset:49152
	ds_read_b128 v[72:75], v114 offset:53248
	ds_read_b128 v[82:85], v114 offset:57344
	ds_read_b128 v[86:89], v114 offset:61440
	ds_read_b128 v[90:93], v115 offset:32768
	ds_read_b128 v[122:125], v116 offset:49152
	ds_read_b128 v[126:129], v116 offset:53248
	ds_read_b128 v[130:133], v116 offset:57344
	ds_read_b128 v[134:137], v116 offset:61440
	ds_read_b128 v[138:141], v117 offset:32768
	ds_read_b128 v[218:221], v118 offset:49152
	ds_read_b128 v[222:225], v118 offset:53248
	ds_read_b128 v[226:229], v118 offset:57344
	ds_read_b128 v[230:233], v118 offset:61440
	ds_read_b128 v[234:237], v119 offset:32768
	ds_read_b128 v[238:241], v120 offset:49152
	ds_read_b128 v[242:245], v120 offset:53248
	ds_read_b128 v[246:249], v120 offset:57344
	ds_read_b128 v[250:253], v120 offset:61440
	s_waitcnt lgkmcnt(0)
	s_barrier
	s_add_u32 m0, s38, 0x8000
	v_mfma_f32_32x32x16_bf16 v[48:63], v[64:67], v[68:71], v[48:63]
	v_mfma_f32_32x32x16_bf16 v[32:47], v[64:67], v[72:75], v[32:47]
	global_load_lds_dwordx4 v254, s[20:21]
	s_add_u32 m0, m0, 0x1000
	v_mfma_f32_32x32x16_bf16 v[16:31], v[64:67], v[82:85], v[16:31]
	v_mfma_f32_32x32x16_bf16 v[0:15], v[64:67], v[86:89], v[0:15]
	global_load_lds_dwordx4 v254, s[22:23]
	s_add_u32 m0, m0, 0x1000
	v_mfma_f32_32x32x16_bf16 v[48:63], v[90:93], v[122:125], v[48:63]
	v_mfma_f32_32x32x16_bf16 v[32:47], v[90:93], v[126:129], v[32:47]
	global_load_lds_dwordx4 v254, s[24:25]
	s_add_u32 m0, m0, 0x1000
	v_mfma_f32_32x32x16_bf16 v[16:31], v[90:93], v[130:133], v[16:31]
	v_mfma_f32_32x32x16_bf16 v[0:15], v[90:93], v[134:137], v[0:15]
	global_load_lds_dwordx4 v254, s[26:27]
	s_add_u32 m0, m0, 0x1000
	v_mfma_f32_32x32x16_bf16 v[48:63], v[138:141], v[218:221], v[48:63]
	v_mfma_f32_32x32x16_bf16 v[32:47], v[138:141], v[222:225], v[32:47]
	global_load_lds_dwordx4 v254, s[28:29]
	s_add_u32 m0, m0, 0x1000
	v_mfma_f32_32x32x16_bf16 v[16:31], v[138:141], v[226:229], v[16:31]
	v_mfma_f32_32x32x16_bf16 v[0:15], v[138:141], v[230:233], v[0:15]
	global_load_lds_dwordx4 v254, s[30:31]
	s_add_u32 m0, m0, 0x1000
	v_mfma_f32_32x32x16_bf16 v[48:63], v[234:237], v[238:241], v[48:63]
	v_mfma_f32_32x32x16_bf16 v[32:47], v[234:237], v[242:245], v[32:47]
	global_load_lds_dwordx4 v254, s[34:35]
	s_add_u32 m0, m0, 0x1000
	v_mfma_f32_32x32x16_bf16 v[16:31], v[234:237], v[246:249], v[16:31]
	v_mfma_f32_32x32x16_bf16 v[0:15], v[234:237], v[250:253], v[0:15]
	global_load_lds_dwordx4 v254, s[36:37]
	v_add_u32_e32 v254, 0x80, v254
	s_branch .LBB0_1450
.Lgk_tailplain_p19:
	s_mov_b32 s41, 0
	s_waitcnt vmcnt(8)
	s_barrier
	ds_read_b128 v[64:67], v113
	ds_read_b128 v[68:71], v114 offset:16384
	ds_read_b128 v[72:75], v114 offset:20480
	ds_read_b128 v[82:85], v114 offset:24576
	ds_read_b128 v[86:89], v114 offset:28672
	ds_read_b128 v[90:93], v115
	ds_read_b128 v[122:125], v116 offset:16384
	ds_read_b128 v[126:129], v116 offset:20480
	ds_read_b128 v[130:133], v116 offset:24576
	ds_read_b128 v[134:137], v116 offset:28672
	ds_read_b128 v[138:141], v117
	ds_read_b128 v[218:221], v118 offset:16384
	ds_read_b128 v[222:225], v118 offset:20480
	ds_read_b128 v[226:229], v118 offset:24576
	ds_read_b128 v[230:233], v118 offset:28672
	ds_read_b128 v[234:237], v119
	ds_read_b128 v[238:241], v120 offset:16384
	ds_read_b128 v[242:245], v120 offset:20480
	ds_read_b128 v[246:249], v120 offset:24576
	ds_read_b128 v[250:253], v120 offset:28672
	s_waitcnt lgkmcnt(0)
	s_barrier
	v_mfma_f32_32x32x16_bf16 v[48:63], v[64:67], v[68:71], v[48:63]
	v_mfma_f32_32x32x16_bf16 v[32:47], v[64:67], v[72:75], v[32:47]
	v_mfma_f32_32x32x16_bf16 v[16:31], v[64:67], v[82:85], v[16:31]
	v_mfma_f32_32x32x16_bf16 v[0:15], v[64:67], v[86:89], v[0:15]
	v_mfma_f32_32x32x16_bf16 v[48:63], v[90:93], v[122:125], v[48:63]
	v_mfma_f32_32x32x16_bf16 v[32:47], v[90:93], v[126:129], v[32:47]
	v_mfma_f32_32x32x16_bf16 v[16:31], v[90:93], v[130:133], v[16:31]
	v_mfma_f32_32x32x16_bf16 v[0:15], v[90:93], v[134:137], v[0:15]
	v_mfma_f32_32x32x16_bf16 v[48:63], v[138:141], v[218:221], v[48:63]
	v_mfma_f32_32x32x16_bf16 v[32:47], v[138:141], v[222:225], v[32:47]
	v_mfma_f32_32x32x16_bf16 v[16:31], v[138:141], v[226:229], v[16:31]
	v_mfma_f32_32x32x16_bf16 v[0:15], v[138:141], v[230:233], v[0:15]
	v_mfma_f32_32x32x16_bf16 v[48:63], v[234:237], v[238:241], v[48:63]
	v_mfma_f32_32x32x16_bf16 v[32:47], v[234:237], v[242:245], v[32:47]
	v_mfma_f32_32x32x16_bf16 v[16:31], v[234:237], v[246:249], v[16:31]
	v_mfma_f32_32x32x16_bf16 v[0:15], v[234:237], v[250:253], v[0:15]
	s_waitcnt vmcnt(0)
	s_barrier
	ds_read_b128 v[64:67], v113 offset:32768
	ds_read_b128 v[68:71], v114 offset:49152
	ds_read_b128 v[72:75], v114 offset:53248
	ds_read_b128 v[82:85], v114 offset:57344
	ds_read_b128 v[86:89], v114 offset:61440
	ds_read_b128 v[90:93], v115 offset:32768
	ds_read_b128 v[122:125], v116 offset:49152
	ds_read_b128 v[126:129], v116 offset:53248
	ds_read_b128 v[130:133], v116 offset:57344
	ds_read_b128 v[134:137], v116 offset:61440
	ds_read_b128 v[138:141], v117 offset:32768
	ds_read_b128 v[218:221], v118 offset:49152
	ds_read_b128 v[222:225], v118 offset:53248
	ds_read_b128 v[226:229], v118 offset:57344
	ds_read_b128 v[230:233], v118 offset:61440
	ds_read_b128 v[234:237], v119 offset:32768
	ds_read_b128 v[238:241], v120 offset:49152
	ds_read_b128 v[242:245], v120 offset:53248
	ds_read_b128 v[246:249], v120 offset:57344
	ds_read_b128 v[250:253], v120 offset:61440
	s_waitcnt lgkmcnt(0)
	s_barrier
	v_mfma_f32_32x32x16_bf16 v[48:63], v[64:67], v[68:71], v[48:63]
	v_mfma_f32_32x32x16_bf16 v[32:47], v[64:67], v[72:75], v[32:47]
	v_mfma_f32_32x32x16_bf16 v[16:31], v[64:67], v[82:85], v[16:31]
	v_mfma_f32_32x32x16_bf16 v[0:15], v[64:67], v[86:89], v[0:15]
	v_mfma_f32_32x32x16_bf16 v[48:63], v[90:93], v[122:125], v[48:63]
	v_mfma_f32_32x32x16_bf16 v[32:47], v[90:93], v[126:129], v[32:47]
	v_mfma_f32_32x32x16_bf16 v[16:31], v[90:93], v[130:133], v[16:31]
	v_mfma_f32_32x32x16_bf16 v[0:15], v[90:93], v[134:137], v[0:15]
	v_mfma_f32_32x32x16_bf16 v[48:63], v[138:141], v[218:221], v[48:63]
	v_mfma_f32_32x32x16_bf16 v[32:47], v[138:141], v[222:225], v[32:47]
	v_mfma_f32_32x32x16_bf16 v[16:31], v[138:141], v[226:229], v[16:31]
	v_mfma_f32_32x32x16_bf16 v[0:15], v[138:141], v[230:233], v[0:15]
	v_mfma_f32_32x32x16_bf16 v[48:63], v[234:237], v[238:241], v[48:63]
	v_mfma_f32_32x32x16_bf16 v[32:47], v[234:237], v[242:245], v[32:47]
	v_mfma_f32_32x32x16_bf16 v[16:31], v[234:237], v[246:249], v[16:31]
	v_mfma_f32_32x32x16_bf16 v[0:15], v[234:237], v[250:253], v[0:15]
	s_branch .LBB0_1450

.LBB0_1494:
	s_ashr_i32 s0, s3, 31
	s_lshr_b32 s0, s0, 24
	s_add_i32 s0, s3, s0
	s_ashr_i32 s1, s0, 8
	s_and_b32 s0, s0, 0xffffff00
	s_sub_i32 s4, s3, s0
	s_ashr_i32 s0, s4, 31
	s_lshr_b32 s0, s0, 29
	s_add_i32 s0, s4, s0
	s_and_b32 s5, s0, -8
	s_lshl_b32 s1, s1, 3
	s_sub_i32 s60, s4, s5
	s_ashr_i32 s46, s0, 3
	s_add_i32 s60, s60, s1
	s_lshl_b32 s61, s46, 6
	s_lshl_b32 s4, s60, 7
	s_lshl_b32 s46, s46, 7
	s_ashr_i32 s5, s4, 31
	s_ashr_i32 s47, s46, 31
	s_lshl_b64 s[4:5], s[4:5], 11
	s_lshl_b64 s[48:49], s[46:47], 8
	s_add_u32 s1, s8, s4
	s_addc_u32 s5, s9, s5
	s_and_b32 s4, s46, 0x700
	s_add_u32 s4, s1, s4
	s_addc_u32 s5, s5, 0
	s_add_u32 s46, s10, s48
	v_readfirstlane_b32 s1, v87
	s_addc_u32 s47, s11, s49
	v_lshl_add_u64 v[0:1], s[4:5], 0, v[64:65]
	s_mov_b32 m0, s1
	v_readfirstlane_b32 s1, v88
	v_lshl_add_u64 v[2:3], s[46:47], 0, v[66:67]
	global_load_lds_dwordx4 v[0:1], off
	s_mov_b32 m0, s1
	v_readfirstlane_b32 s1, v89
	global_load_lds_dwordx4 v[2:3], off
	v_lshl_add_u64 v[4:5], v[0:1], 0, s[18:19]
	s_mov_b32 m0, s1
	v_readfirstlane_b32 s1, v90
	global_load_lds_dwordx4 v[4:5], off
	v_lshl_add_u64 v[4:5], v[2:3], 0, s[20:21]
	s_mov_b32 m0, s1
	v_readfirstlane_b32 s1, v91
	global_load_lds_dwordx4 v[4:5], off
	v_lshl_add_u64 v[4:5], v[0:1], 0, s[22:23]
	s_mov_b32 m0, s1
	v_readfirstlane_b32 s1, v92
	global_load_lds_dwordx4 v[4:5], off
	v_lshl_add_u64 v[4:5], v[2:3], 0, s[24:25]
	s_mov_b32 m0, s1
	v_readfirstlane_b32 s1, v93
	global_load_lds_dwordx4 v[4:5], off
	v_lshl_add_u64 v[4:5], v[0:1], 0, s[26:27]
	s_mov_b32 m0, s1
	v_readfirstlane_b32 s1, v94
	global_load_lds_dwordx4 v[4:5], off
	v_lshl_add_u64 v[4:5], v[2:3], 0, s[28:29]
	s_mov_b32 m0, s1
	v_readfirstlane_b32 s1, v95
	global_load_lds_dwordx4 v[4:5], off
	v_lshl_add_u64 v[4:5], v[0:1], 0, s[30:31]
	s_mov_b32 m0, s1
	v_readfirstlane_b32 s1, v96
	s_waitcnt vmcnt(0)
	s_waitcnt vmcnt(0) lgkmcnt(0)
	s_barrier
	global_load_lds_dwordx4 v[4:5], off
	v_lshl_add_u64 v[4:5], v[2:3], 0, s[30:31]
	s_mov_b32 m0, s1
	v_readfirstlane_b32 s1, v97
	global_load_lds_dwordx4 v[4:5], off
	v_lshl_add_u64 v[4:5], v[0:1], 0, s[34:35]
	s_mov_b32 m0, s1
	v_readfirstlane_b32 s1, v98
	global_load_lds_dwordx4 v[4:5], off
	v_lshl_add_u64 v[4:5], v[2:3], 0, s[36:37]
	s_mov_b32 m0, s1
	v_readfirstlane_b32 s1, v99
	global_load_lds_dwordx4 v[4:5], off
	v_lshl_add_u64 v[4:5], v[0:1], 0, s[38:39]
	s_mov_b32 m0, s1
	v_readfirstlane_b32 s1, v100
	global_load_lds_dwordx4 v[4:5], off
	v_lshl_add_u64 v[4:5], v[2:3], 0, s[40:41]
	s_mov_b32 m0, s1
	v_readfirstlane_b32 s1, v101
	global_load_lds_dwordx4 v[4:5], off
	v_lshl_add_u64 v[0:1], v[0:1], 0, s[42:43]
	s_mov_b32 m0, s1
	v_readfirstlane_b32 s1, v102
	global_load_lds_dwordx4 v[0:1], off
	v_lshl_add_u64 v[0:1], v[2:3], 0, s[44:45]
	s_mov_b32 m0, s1
	s_nop 0
	global_load_lds_dwordx4 v[0:1], off
	ds_read_b128 v[0:3], v103
	ds_read_b128 v[4:7], v104 offset:16384
	ds_read_b128 v[8:11], v104 offset:20480
	ds_read_b128 v[12:15], v104 offset:24576
	ds_read_b128 v[118:121], v104 offset:28672
	ds_read_b128 v[122:125], v105
	ds_read_b128 v[126:129], v106 offset:16384
	ds_read_b128 v[130:133], v106 offset:20480
	ds_read_b128 v[134:137], v106 offset:24576
	ds_read_b128 v[138:141], v106 offset:28672
	s_waitcnt lgkmcnt(0)
	v_mfma_f32_32x32x16_bf16 v[16:31], v[0:3], v[4:7], 0
	v_mfma_f32_32x32x16_bf16 v[32:47], v[0:3], v[8:11], 0
	v_mfma_f32_32x32x16_bf16 v[48:63], v[0:3], v[12:15], 0
	v_mfma_f32_32x32x16_bf16 v[0:15], v[0:3], v[118:121], 0
	ds_read_b128 v[118:121], v107
	ds_read_b128 v[142:145], v108 offset:16384
	ds_read_b128 v[146:149], v108 offset:20480
	ds_read_b128 v[150:153], v108 offset:24576
	ds_read_b128 v[154:157], v108 offset:28672
	v_mfma_f32_32x32x16_bf16 v[16:31], v[122:125], v[126:129], v[16:31]
	v_mfma_f32_32x32x16_bf16 v[32:47], v[122:125], v[130:133], v[32:47]
	v_mfma_f32_32x32x16_bf16 v[48:63], v[122:125], v[134:137], v[48:63]
	v_mfma_f32_32x32x16_bf16 v[0:15], v[122:125], v[138:141], v[0:15]
	ds_read_b128 v[122:125], v109
	ds_read_b128 v[126:129], v110 offset:16384
	ds_read_b128 v[130:133], v110 offset:20480
	ds_read_b128 v[134:137], v110 offset:24576
	ds_read_b128 v[138:141], v110 offset:28672
	s_waitcnt lgkmcnt(0)
	v_mfma_f32_32x32x16_bf16 v[16:31], v[118:121], v[142:145], v[16:31]
	v_mfma_f32_32x32x16_bf16 v[32:47], v[118:121], v[146:149], v[32:47]
	v_mfma_f32_32x32x16_bf16 v[48:63], v[118:121], v[150:153], v[48:63]
	v_mfma_f32_32x32x16_bf16 v[0:15], v[118:121], v[154:157], v[0:15]
	v_mfma_f32_32x32x16_bf16 v[16:31], v[122:125], v[126:129], v[16:31]
	v_mfma_f32_32x32x16_bf16 v[32:47], v[122:125], v[130:133], v[32:47]
	v_mfma_f32_32x32x16_bf16 v[48:63], v[122:125], v[134:137], v[48:63]
	v_mfma_f32_32x32x16_bf16 v[0:15], v[122:125], v[138:141], v[0:15]
	s_waitcnt vmcnt(0)
	s_waitcnt vmcnt(0)
	s_barrier
	ds_read_b128 v[118:121], v103 offset:32768
	ds_read_b128 v[122:125], v104 offset:49152
	ds_read_b128 v[126:129], v104 offset:53248
	ds_read_b128 v[130:133], v104 offset:57344
	ds_read_b128 v[134:137], v104 offset:61440
	ds_read_b128 v[138:141], v105 offset:32768
	ds_read_b128 v[142:145], v106 offset:49152
	ds_read_b128 v[146:149], v106 offset:53248
	ds_read_b128 v[150:153], v106 offset:57344
	ds_read_b128 v[154:157], v106 offset:61440
	s_waitcnt lgkmcnt(8)
	v_mfma_f32_32x32x16_bf16 v[16:31], v[118:121], v[122:125], v[16:31]
	s_waitcnt lgkmcnt(7)
	v_mfma_f32_32x32x16_bf16 v[32:47], v[118:121], v[126:129], v[32:47]
	s_waitcnt lgkmcnt(6)
	v_mfma_f32_32x32x16_bf16 v[48:63], v[118:121], v[130:133], v[48:63]
	s_waitcnt lgkmcnt(5)
	v_mfma_f32_32x32x16_bf16 v[0:15], v[118:121], v[134:137], v[0:15]
	ds_read_b128 v[118:121], v107 offset:32768
	ds_read_b128 v[122:125], v108 offset:49152
	ds_read_b128 v[126:129], v108 offset:53248
	ds_read_b128 v[130:133], v108 offset:57344
	ds_read_b128 v[134:137], v108 offset:61440
	s_waitcnt lgkmcnt(8)
	v_mfma_f32_32x32x16_bf16 v[16:31], v[138:141], v[142:145], v[16:31]
	s_waitcnt lgkmcnt(7)
	v_mfma_f32_32x32x16_bf16 v[32:47], v[138:141], v[146:149], v[32:47]
	s_waitcnt lgkmcnt(6)
	v_mfma_f32_32x32x16_bf16 v[48:63], v[138:141], v[150:153], v[48:63]
	s_waitcnt lgkmcnt(5)
	v_mfma_f32_32x32x16_bf16 v[0:15], v[138:141], v[154:157], v[0:15]
	ds_read_b128 v[138:141], v109 offset:32768
	ds_read_b128 v[142:145], v110 offset:49152
	ds_read_b128 v[146:149], v110 offset:53248
	ds_read_b128 v[150:153], v110 offset:57344
	ds_read_b128 v[154:157], v110 offset:61440
	s_waitcnt lgkmcnt(8)
	v_mfma_f32_32x32x16_bf16 v[16:31], v[118:121], v[122:125], v[16:31]
	s_waitcnt lgkmcnt(7)
	v_mfma_f32_32x32x16_bf16 v[32:47], v[118:121], v[126:129], v[32:47]
	s_waitcnt lgkmcnt(6)
	v_mfma_f32_32x32x16_bf16 v[48:63], v[118:121], v[130:133], v[48:63]
	s_waitcnt lgkmcnt(5)
	v_mfma_f32_32x32x16_bf16 v[0:15], v[118:121], v[134:137], v[0:15]
	s_waitcnt lgkmcnt(3)
	v_mfma_f32_32x32x16_bf16 v[16:31], v[138:141], v[142:145], v[16:31]
	s_waitcnt lgkmcnt(2)
	v_mfma_f32_32x32x16_bf16 v[32:47], v[138:141], v[146:149], v[32:47]
	s_waitcnt lgkmcnt(1)
	v_mfma_f32_32x32x16_bf16 v[48:63], v[138:141], v[150:153], v[48:63]
	s_waitcnt lgkmcnt(0)
	v_mfma_f32_32x32x16_bf16 v[0:15], v[138:141], v[154:157], v[0:15]
	ds_read_b128 v[118:121], v111
	s_ashr_i32 s46, s0, 7
	s_lshl_b32 s0, s46, 11
	s_ashr_i32 s1, s0, 31
	s_lshl_b64 s[0:1], s[0:1], 2
	s_waitcnt lgkmcnt(0)
	v_readfirstlane_b32 s4, v118
	v_readfirstlane_b32 s5, v119
	s_add_u32 s0, s4, s0
	s_addc_u32 s1, s5, s1
	s_lshl_b32 s4, s46, 10
	s_ashr_i32 s5, s4, 31
	v_readfirstlane_b32 s47, v120
	s_lshl_b64 s[4:5], s[4:5], 2
	v_readfirstlane_b32 s48, v121
	s_add_u32 s4, s47, s4
	s_addc_u32 s5, s48, s5
	s_ashr_i32 s47, s46, 31
	s_lshl_b64 s[46:47], s[46:47], 25
	s_add_u32 s48, s50, s46
	s_addc_u32 s49, s51, s47
	s_add_u32 s46, s52, s46
	s_addc_u32 s47, s53, s47
	s_and_b32 s61, s61, 0x3c0
	v_or_b32_e32 v124, s61, v70
	v_lshlrev_b32_e32 v68, 2, v124
	global_load_dword v119, v68, s[4:5]
	global_load_dword v122, v68, s[4:5] offset:128
	global_load_dword v117, v68, s[0:1]
	global_load_dword v118, v68, s[0:1] offset:128
	v_lshl_add_u64 v[120:121], s[0:1], 0, v[68:69]
	v_add_co_u32_e32 v120, vcc, s54, v120
	s_waitcnt vmcnt(3)
	v_mul_f32_e32 v68, 0xbfb8aa3b, v119
	v_exp_f32_e32 v125, v68
	s_waitcnt vmcnt(2)
	v_mul_f32_e32 v119, 0xbfb8aa3b, v122
	v_exp_f32_e32 v128, v119
	v_addc_co_u32_e32 v121, vcc, 0, v121, vcc
	v_add_f32_e32 v126, 1.0, v125
	global_load_dword v119, v[120:121], off
	global_load_dword v68, v[120:121], off offset:128
	v_frexp_mant_f32_e32 v130, v126
	v_cvt_f64_f32_e32 v[120:121], v126
	v_add_f32_e32 v127, 1.0, v128
	v_add_f32_e32 v129, -1.0, v126
	v_frexp_exp_i32_f64_e32 v120, v[120:121]
	v_cmp_gt_f32_e32 vcc, s55, v130
	v_add_f32_e32 v131, -1.0, v127
	v_frexp_mant_f32_e32 v132, v127
	v_cvt_f64_f32_e32 v[122:123], v127
	v_sub_f32_e32 v133, v129, v126
	v_subbrev_co_u32_e32 v120, vcc, 0, v120, vcc
	v_sub_f32_e32 v129, v125, v129
	v_sub_f32_e32 v121, v131, v127
	v_frexp_exp_i32_f64_e32 v122, v[122:123]
	v_add_f32_e32 v123, 1.0, v133
	v_cmp_gt_f32_e32 vcc, s55, v132
	v_sub_f32_e32 v131, v128, v131
	v_add_f32_e32 v121, 1.0, v121
	v_subbrev_co_u32_e32 v122, vcc, 0, v122, vcc
	v_add_f32_e32 v123, v129, v123
	v_sub_u32_e32 v129, 0, v120
	v_cvt_f32_i32_e32 v120, v120
	v_add_f32_e32 v121, v131, v121
	v_sub_u32_e32 v130, 0, v122
	v_ldexp_f32 v126, v126, v129
	v_ldexp_f32 v123, v123, v129
	v_ldexp_f32 v127, v127, v130
	v_ldexp_f32 v121, v121, v130
	v_add_f32_e32 v129, -1.0, v126
	v_add_f32_e32 v130, 1.0, v126
	v_add_f32_e32 v131, 1.0, v129
	v_add_f32_e32 v132, -1.0, v130
	v_sub_f32_e32 v131, v126, v131
	v_sub_f32_e32 v126, v126, v132
	v_mul_f32_e32 v132, 0x3f317218, v120
	v_add_f32_e32 v131, v123, v131
	v_add_f32_e32 v123, v123, v126
	v_fma_f32 v126, v120, s56, -v132
	v_add_f32_e32 v133, v129, v131
	v_add_f32_e32 v134, v130, v123
	v_fmac_f32_e32 v126, 0xb102e308, v120
	v_sub_f32_e32 v120, v133, v129
	v_sub_f32_e32 v129, v134, v130
	v_rcp_f32_e32 v130, v134
	v_add_f32_e32 v135, v132, v126
	v_sub_f32_e32 v123, v123, v129
	v_sub_f32_e32 v129, v135, v132
	v_sub_f32_e32 v126, v126, v129
	v_mul_f32_e32 v129, v133, v130
	v_sub_f32_e32 v120, v131, v120
	v_mul_f32_e32 v131, v134, v129
	v_fma_f32 v132, v129, v134, -v131
	v_fmac_f32_e32 v132, v129, v123
	v_add_f32_e32 v136, v131, v132
	v_sub_f32_e32 v137, v133, v136
	v_sub_f32_e32 v131, v136, v131
	v_sub_f32_e32 v133, v133, v137
	v_sub_f32_e32 v131, v131, v132
	v_sub_f32_e32 v132, v133, v136
	v_add_f32_e32 v120, v120, v132
	v_add_f32_e32 v120, v131, v120
	v_add_f32_e32 v131, v137, v120
	v_mul_f32_e32 v132, v130, v131
	v_sub_f32_e32 v133, v137, v131
	v_mul_f32_e32 v136, v134, v132
	v_add_f32_e32 v120, v120, v133
	v_add_f32_e32 v133, v129, v132
	v_fma_f32 v134, v132, v134, -v136
	v_sub_f32_e32 v129, v133, v129
	v_fmac_f32_e32 v134, v132, v123
	v_sub_f32_e32 v123, v132, v129
	v_add_f32_e32 v129, v136, v134
	v_sub_f32_e32 v132, v129, v136
	v_sub_f32_e32 v136, v131, v129
	v_sub_f32_e32 v131, v131, v136
	v_sub_f32_e32 v129, v131, v129
	v_sub_f32_e32 v132, v132, v134
	v_add_f32_e32 v120, v120, v129
	v_add_f32_e32 v120, v132, v120
	v_add_f32_e32 v120, v136, v120
	v_mul_f32_e32 v120, v130, v120
	v_add_f32_e32 v120, v123, v120
	v_add_f32_e32 v123, v133, v120
	v_mul_f32_e32 v129, v123, v123
	v_fmamk_f32 v132, v129, 0x3e9b6dac, v112
	v_sub_f32_e32 v130, v123, v133
	v_ldexp_f32 v131, v123, 1
	v_mul_f32_e32 v123, v123, v129
	v_fmaak_f32 v129, v129, v132, 0x3f2aaada
	v_mul_f32_e32 v123, v123, v129
	v_add_f32_e32 v129, v131, v123
	v_sub_f32_e32 v120, v120, v130
	v_sub_f32_e32 v130, v129, v131
	v_ldexp_f32 v120, v120, 1
	v_sub_f32_e32 v123, v123, v130
	v_add_f32_e32 v120, v120, v123
	v_add_f32_e32 v123, v129, v120
	v_sub_f32_e32 v129, v123, v129
	v_add_f32_e32 v130, v135, v123
	v_sub_f32_e32 v120, v120, v129
	v_sub_f32_e32 v129, v130, v135
	v_sub_f32_e32 v131, v130, v129
	v_sub_f32_e32 v123, v123, v129
	v_add_f32_e32 v129, v126, v120
	v_sub_f32_e32 v131, v135, v131
	v_sub_f32_e32 v132, v129, v126
	v_add_f32_e32 v123, v123, v131
	v_sub_f32_e32 v131, v129, v132
	v_sub_f32_e32 v120, v120, v132
	v_sub_f32_e32 v126, v126, v131
	v_add_f32_e32 v123, v129, v123
	v_add_f32_e32 v120, v120, v126
	v_add_f32_e32 v126, v130, v123
	v_sub_f32_e32 v129, v126, v130
	v_sub_f32_e32 v123, v123, v129
	v_add_f32_e32 v120, v120, v123
	v_add_f32_e32 v120, v126, v120
	v_cmp_neq_f32_e32 vcc, s57, v125
	v_add_f32_e32 v123, -1.0, v127
	v_add_f32_e32 v129, 1.0, v127
	v_cndmask_b32_e32 v120, v114, v120, vcc
	v_cmp_ngt_f32_e32 vcc, -1.0, v125
	v_add_f32_e32 v130, -1.0, v129
	v_cvt_f32_i32_e32 v122, v122
	v_cndmask_b32_e32 v120, v115, v120, vcc
	v_cmp_neq_f32_e32 vcc, -1.0, v125
	s_waitcnt vmcnt(3)
	v_add_f32_e32 v16, v16, v117
	v_mul_f32_e32 v16, 0xbfb8aa3b, v16
	v_cndmask_b32_e32 v120, v116, v120, vcc
	v_cmp_lt_f32_e64 vcc, |v125|, s58
	v_exp_f32_e32 v16, v16
	v_cmp_lt_f32_e64 s[0:1], |v128|, s58
	v_cndmask_b32_e32 v120, v120, v125, vcc
	v_add_f32_e32 v125, 1.0, v123
	v_sub_f32_e32 v125, v127, v125
	v_sub_f32_e32 v127, v127, v130
	v_add_f32_e32 v125, v121, v125
	v_add_f32_e32 v121, v121, v127
	v_add_f32_e32 v127, v129, v121
	v_rcp_f32_e32 v130, v127
	v_add_f32_e32 v126, v123, v125
	v_sub_f32_e32 v123, v126, v123
	v_sub_f32_e32 v123, v125, v123
	v_sub_f32_e32 v125, v127, v129
	v_sub_f32_e32 v121, v121, v125
	v_mul_f32_e32 v125, v126, v130
	v_mul_f32_e32 v129, v127, v125
	v_fma_f32 v131, v125, v127, -v129
	v_fmac_f32_e32 v131, v125, v121
	v_add_f32_e32 v132, v129, v131
	v_sub_f32_e32 v133, v126, v132
	v_sub_f32_e32 v126, v126, v133
	v_sub_f32_e32 v129, v132, v129
	v_sub_f32_e32 v126, v126, v132
	v_add_f32_e32 v123, v123, v126
	v_sub_f32_e32 v126, v129, v131
	v_add_f32_e32 v123, v126, v123
	v_add_f32_e32 v126, v133, v123
	v_mul_f32_e32 v129, v130, v126
	v_mul_f32_e32 v131, v127, v129
	v_fma_f32 v127, v129, v127, -v131
	v_fmac_f32_e32 v127, v129, v121
	v_sub_f32_e32 v121, v133, v126
	v_add_f32_e32 v121, v123, v121
	v_add_f32_e32 v123, v131, v127
	v_sub_f32_e32 v132, v126, v123
	v_sub_f32_e32 v126, v126, v132
	v_sub_f32_e32 v131, v123, v131
	v_sub_f32_e32 v123, v126, v123
	v_add_f32_e32 v121, v121, v123
	v_sub_f32_e32 v123, v131, v127
	v_add_f32_e32 v121, v123, v121
	v_add_f32_e32 v123, v125, v129
	v_add_f32_e32 v121, v132, v121
	v_sub_f32_e32 v125, v123, v125
	v_mul_f32_e32 v121, v130, v121
	v_sub_f32_e32 v125, v129, v125
	v_add_f32_e32 v121, v125, v121
	v_mul_f32_e32 v129, 0x3f317218, v122
	v_add_f32_e32 v125, v123, v121
	v_fma_f32 v130, v122, s56, -v129
	v_mul_f32_e32 v126, v125, v125
	v_fmac_f32_e32 v130, 0xb102e308, v122
	v_fmamk_f32 v127, v126, 0x3e9b6dac, v112
	v_sub_f32_e32 v122, v125, v123
	v_add_f32_e32 v131, v129, v130
	v_fmaak_f32 v127, v126, v127, 0x3f2aaada
	v_sub_f32_e32 v121, v121, v122
	v_sub_f32_e32 v122, v131, v129
	v_mul_f32_e32 v123, v125, v126
	v_sub_f32_e32 v129, v130, v122
	v_ldexp_f32 v122, v125, 1
	v_mul_f32_e32 v123, v123, v127
	v_add_f32_e32 v125, v122, v123
	v_sub_f32_e32 v122, v125, v122
	v_ldexp_f32 v121, v121, 1
	v_sub_f32_e32 v122, v123, v122
	v_add_f32_e32 v121, v121, v122
	v_add_f32_e32 v130, v125, v121
	v_sub_f32_e32 v122, v130, v125
	v_sub_f32_e32 v132, v121, v122
	v_lshl_or_b32 v121, s60, 17, v124
	v_add_lshl_u32 v167, v121, v71, 1
	global_load_ushort v134, v167, s[8:9]
	global_load_ushort v135, v167, s[8:9] offset:64
	v_add_lshl_u32 v167, v121, v72, 1
	global_load_ushort v136, v167, s[8:9]
	global_load_ushort v137, v167, s[8:9] offset:64
	v_add_lshl_u32 v167, v121, v73, 1
	global_load_ushort v138, v167, s[8:9]
	global_load_ushort v139, v167, s[8:9] offset:64
	v_add_lshl_u32 v167, v121, v74, 1
	global_load_ushort v140, v167, s[8:9]
	global_load_ushort v141, v167, s[8:9] offset:64
	v_add_lshl_u32 v167, v121, v75, 1
	global_load_ushort v142, v167, s[8:9]
	global_load_ushort v143, v167, s[8:9] offset:64
	v_add_lshl_u32 v167, v121, v76, 1
	global_load_ushort v144, v167, s[8:9]
	global_load_ushort v145, v167, s[8:9] offset:64
	v_add_lshl_u32 v167, v121, v77, 1
	global_load_ushort v146, v167, s[8:9]
	global_load_ushort v147, v167, s[8:9] offset:64
	v_add_lshl_u32 v167, v121, v78, 1
	global_load_ushort v148, v167, s[8:9]
	global_load_ushort v149, v167, s[8:9] offset:64
	v_add_lshl_u32 v167, v121, v79, 1
	global_load_ushort v150, v167, s[8:9]
	global_load_ushort v151, v167, s[8:9] offset:64
	v_add_lshl_u32 v167, v121, v80, 1
	global_load_ushort v152, v167, s[8:9]
	global_load_ushort v153, v167, s[8:9] offset:64
	v_add_lshl_u32 v167, v121, v81, 1
	global_load_ushort v154, v167, s[8:9]
	global_load_ushort v156, v167, s[8:9] offset:64
	v_add_lshl_u32 v167, v121, v82, 1
	global_load_ushort v157, v167, s[8:9]
	global_load_ushort v158, v167, s[8:9] offset:64
	v_add_lshl_u32 v167, v121, v83, 1
	global_load_ushort v159, v167, s[8:9]
	global_load_ushort v160, v167, s[8:9] offset:64
	v_add_lshl_u32 v167, v121, v84, 1
	global_load_ushort v161, v167, s[8:9]
	global_load_ushort v162, v167, s[8:9] offset:64
	v_add_lshl_u32 v167, v121, v85, 1
	global_load_ushort v163, v167, s[8:9]
	global_load_ushort v164, v167, s[8:9] offset:64
	v_add_lshl_u32 v167, v121, v86, 1
	global_load_ushort v165, v167, s[8:9]
	global_load_ushort v166, v167, s[8:9] offset:64
	s_waitcnt vmcnt(0)
	v_add_u32_e32 v122, v121, v71
	v_ashrrev_i32_e32 v123, 31, v122
	v_lshlrev_b64 v[124:125], 1, v[122:123]
	v_lshl_add_u64 v[126:127], s[8:9], 0, v[124:125]
	v_mov_b32_e32 v126, v134
	v_add_f32_e32 v123, v131, v130
	v_sub_f32_e32 v127, v123, v131
	v_sub_f32_e32 v133, v123, v127
	v_sub_f32_e32 v131, v131, v133
	v_sub_f32_e32 v127, v130, v127
	v_add_f32_e32 v130, v129, v132
	v_add_f32_e32 v127, v127, v131
	v_sub_f32_e32 v131, v130, v129
	v_sub_f32_e32 v133, v130, v131
	v_add_f32_e32 v127, v130, v127
	v_sub_f32_e32 v129, v129, v133
	v_sub_f32_e32 v131, v132, v131
	v_add_f32_e32 v130, v123, v127
	v_or_b32_e32 v122, 32, v122
	v_add_f32_e32 v129, v131, v129
	v_sub_f32_e32 v131, v130, v123
	v_ashrrev_i32_e32 v123, 31, v122
	v_lshl_add_u64 v[122:123], v[122:123], 1, s[8:9]
	v_mov_b32_e32 v122, v135
	v_add_f32_e32 v16, 1.0, v16
	v_rcp_f32_e32 v16, v16
	v_mul_f32_e32 v120, 0xc1000000, v120
	v_sub_f32_e32 v123, v127, v131
	v_add_f32_e32 v123, v129, v123
	v_mul_f32_e32 v127, v16, v120
	v_add_f32_e32 v16, v32, v118
	v_mul_f32_e32 v16, 0xbfb8aa3b, v16
	v_add_f32_e32 v32, v127, v127
	v_exp_f32_e32 v16, v16
	v_mul_f32_e32 v32, 0x3fb8aa3b, v32
	v_exp_f32_e32 v32, v32
	v_add_f32_e32 v123, v130, v123
	v_cmp_neq_f32_e32 vcc, s57, v128
	v_add_f32_e32 v16, 1.0, v16
	v_rcp_f32_e32 v129, v16
	v_cndmask_b32_e32 v123, v114, v123, vcc
	v_cmp_ngt_f32_e32 vcc, -1.0, v128
	v_sub_f32_e32 v16, 1.0, v32
	v_max_f32_e32 v16, 0, v16
	v_cndmask_b32_e32 v123, v115, v123, vcc
	v_cmp_neq_f32_e32 vcc, -1.0, v128
	v_mul_f32_e32 v32, 0x4f800000, v16
	v_add_f32_e32 v48, v48, v119
	v_cndmask_b32_e32 v123, v116, v123, vcc
	v_cmp_gt_f32_e32 vcc, s59, v16
	v_mul_f32_e32 v48, 0xbfb8aa3b, v48
	v_exp_f32_e32 v48, v48
	v_cndmask_b32_e32 v32, v16, v32, vcc
	v_sqrt_f32_e32 v130, v32
	v_cndmask_b32_e64 v16, v123, v128, s[0:1]
	v_mul_f32_e32 v16, 0xc1000000, v16
	v_mul_f32_e32 v128, v129, v16
	v_add_u32_e32 v123, -1, v130
	v_fma_f32 v129, -v123, v130, v32
	v_cmp_ge_f32_e64 s[0:1], 0, v129
	v_add_u32_e32 v129, 1, v130
	v_add_f32_e32 v48, 1.0, v48
	v_cndmask_b32_e64 v123, v130, v123, s[0:1]
	v_fma_f32 v130, -v129, v130, v32
	v_cmp_lt_f32_e64 s[0:1], 0, v130
	v_rcp_f32_e32 v48, v48
	v_add_f32_e32 v0, v0, v68
	v_cndmask_b32_e64 v123, v123, v129, s[0:1]
	v_mul_f32_e32 v129, 0x37800000, v123
	v_cndmask_b32_e32 v123, v123, v129, vcc
	v_add_f32_e32 v129, v128, v128
	v_mul_f32_e32 v129, 0x3fb8aa3b, v129
	v_exp_f32_e32 v129, v129
	v_cmp_class_f32_e32 vcc, v32, v113
	v_mul_f32_e32 v0, 0xbfb8aa3b, v0
	v_exp_f32_e32 v0, v0
	v_cndmask_b32_e32 v32, v123, v32, vcc
	v_sub_f32_e32 v123, 1.0, v129
	v_max_f32_e32 v123, 0, v123
	v_mul_f32_e32 v129, 0x4f800000, v123
	v_cmp_gt_f32_e32 vcc, s59, v123
	v_mul_f32_e32 v32, v48, v32
	v_add_f32_e32 v0, 1.0, v0
	v_cndmask_b32_e32 v123, v123, v129, vcc
	v_sqrt_f32_e32 v129, v123
	v_lshlrev_b32_e32 v48, 16, v126
	v_mul_f32_e32 v32, v32, v48
	v_rcp_f32_e32 v0, v0
	v_add_u32_e32 v48, -1, v129
	v_fma_f32 v126, -v48, v129, v123
	v_cmp_ge_f32_e64 s[0:1], 0, v126
	v_add_u32_e32 v126, 1, v129
	v_add_f32_e32 v17, v17, v117
	v_cndmask_b32_e64 v48, v129, v48, s[0:1]
	v_fma_f32 v129, -v126, v129, v123
	v_cmp_lt_f32_e64 s[0:1], 0, v129
	v_mul_f32_e32 v17, 0xbfb8aa3b, v17
	v_exp_f32_e32 v17, v17
	v_cndmask_b32_e64 v48, v48, v126, s[0:1]
	v_mul_f32_e32 v126, 0x37800000, v48
	v_cndmask_b32_e32 v48, v48, v126, vcc
	v_cmp_class_f32_e32 vcc, v123, v113
	v_cvt_pk_bf16_f32 v32, v32, s0
	v_add_f32_e32 v17, 1.0, v17
	v_cndmask_b32_e32 v48, v48, v123, vcc
	v_mul_f32_e32 v0, v0, v48
	v_lshlrev_b32_e32 v48, 16, v122
	v_mul_f32_e32 v0, v0, v48
	v_cvt_pk_bf16_f32 v48, v127, s0
	v_lshl_add_u64 v[122:123], s[48:49], 0, v[124:125]
	global_store_short v[122:123], v48, off sc1
	v_cvt_pk_bf16_f32 v48, v128, s0
	global_store_short v[122:123], v48, off offset:64 sc1
	v_lshl_add_u64 v[122:123], s[46:47], 0, v[124:125]
	v_cvt_pk_bf16_f32 v0, v0, s0
	global_store_short v[122:123], v32, off sc1
	global_store_short v[122:123], v0, off offset:64 sc1
	v_add_u32_e32 v122, v121, v72
	v_ashrrev_i32_e32 v123, 31, v122
	v_lshlrev_b64 v[124:125], 1, v[122:123]
	v_lshl_add_u64 v[126:127], s[8:9], 0, v[124:125]
	v_mov_b32_e32 v0, v136
	v_or_b32_e32 v122, 32, v122
	v_ashrrev_i32_e32 v123, 31, v122
	v_lshl_add_u64 v[122:123], v[122:123], 1, s[8:9]
	v_mov_b32_e32 v32, v137
	v_rcp_f32_e32 v17, v17
	v_add_f32_e32 v33, v33, v118
	v_mul_f32_e32 v33, 0xbfb8aa3b, v33
	v_exp_f32_e32 v33, v33
	v_mul_f32_e32 v17, v17, v120
	v_add_f32_e32 v48, v17, v17
	v_mul_f32_e32 v48, 0x3fb8aa3b, v48
	v_exp_f32_e32 v48, v48
	v_add_f32_e32 v33, 1.0, v33
	v_rcp_f32_e32 v33, v33
	v_add_f32_e32 v49, v49, v119
	v_sub_f32_e32 v48, 1.0, v48
	v_max_f32_e32 v48, 0, v48
	v_mul_f32_e32 v122, 0x4f800000, v48
	v_cmp_gt_f32_e32 vcc, s59, v48
	v_mul_f32_e32 v33, v33, v16
	v_mul_f32_e32 v49, 0xbfb8aa3b, v49
	v_cndmask_b32_e32 v48, v48, v122, vcc
	v_sqrt_f32_e32 v122, v48
	v_exp_f32_e32 v49, v49
	v_add_f32_e32 v1, v1, v68
	v_mul_f32_e32 v1, 0xbfb8aa3b, v1
	v_add_u32_e32 v123, -1, v122
	v_fma_f32 v126, -v123, v122, v48
	v_cmp_ge_f32_e64 s[0:1], 0, v126
	v_add_u32_e32 v126, 1, v122
	v_add_f32_e32 v49, 1.0, v49
	v_cndmask_b32_e64 v123, v122, v123, s[0:1]
	v_fma_f32 v122, -v126, v122, v48
	v_cmp_lt_f32_e64 s[0:1], 0, v122
	v_rcp_f32_e32 v49, v49
	v_exp_f32_e32 v1, v1
	v_cndmask_b32_e64 v122, v123, v126, s[0:1]
	v_mul_f32_e32 v123, 0x37800000, v122
	v_cndmask_b32_e32 v122, v122, v123, vcc
	v_add_f32_e32 v123, v33, v33
	v_mul_f32_e32 v123, 0x3fb8aa3b, v123
	v_exp_f32_e32 v123, v123
	v_cmp_class_f32_e32 vcc, v48, v113
	v_add_f32_e32 v1, 1.0, v1
	v_rcp_f32_e32 v1, v1
	v_cndmask_b32_e32 v48, v122, v48, vcc
	v_sub_f32_e32 v122, 1.0, v123
	v_max_f32_e32 v122, 0, v122
	v_mul_f32_e32 v123, 0x4f800000, v122
	v_cmp_gt_f32_e32 vcc, s59, v122
	v_mul_f32_e32 v48, v49, v48
	v_add_f32_e32 v2, v2, v68
	v_cndmask_b32_e32 v122, v122, v123, vcc
	v_sqrt_f32_e32 v123, v122
	v_mul_f32_e32 v2, 0xbfb8aa3b, v2
	v_exp_f32_e32 v2, v2
	v_add_f32_e32 v3, v3, v68
	v_mul_f32_e32 v3, 0xbfb8aa3b, v3
	v_exp_f32_e32 v3, v3
	v_add_f32_e32 v2, 1.0, v2
	v_rcp_f32_e32 v2, v2
	v_add_f32_e32 v3, 1.0, v3
	v_rcp_f32_e32 v3, v3
	v_lshlrev_b32_e32 v0, 16, v0
	v_mul_f32_e32 v48, v48, v0
	v_add_u32_e32 v0, -1, v123
	v_fma_f32 v49, -v0, v123, v122
	v_cmp_ge_f32_e64 s[0:1], 0, v49
	v_add_u32_e32 v49, 1, v123
	s_nop 0
	v_cndmask_b32_e64 v0, v123, v0, s[0:1]
	v_fma_f32 v123, -v49, v123, v122
	v_cmp_lt_f32_e64 s[0:1], 0, v123
	s_nop 1
	v_cndmask_b32_e64 v0, v0, v49, s[0:1]
	v_mul_f32_e32 v49, 0x37800000, v0
	v_cndmask_b32_e32 v0, v0, v49, vcc
	v_cmp_class_f32_e32 vcc, v122, v113
	v_cvt_pk_bf16_f32 v17, v17, s0
	s_nop 0
	v_cndmask_b32_e32 v0, v0, v122, vcc
	v_mul_f32_e32 v0, v1, v0
	v_lshlrev_b32_e32 v1, 16, v32
	v_mul_f32_e32 v32, v0, v1
	v_lshl_add_u64 v[0:1], s[48:49], 0, v[124:125]
	global_store_short v[0:1], v17, off sc1
	v_cvt_pk_bf16_f32 v17, v33, s0
	global_store_short v[0:1], v17, off offset:64 sc1
	v_cvt_pk_bf16_f32 v17, v48, s0
	v_lshl_add_u64 v[0:1], s[46:47], 0, v[124:125]
	global_store_short v[0:1], v17, off sc1
	v_cvt_pk_bf16_f32 v17, v32, s0
	global_store_short v[0:1], v17, off offset:64 sc1
	v_add_u32_e32 v0, v121, v73
	v_ashrrev_i32_e32 v1, 31, v0
	v_lshlrev_b64 v[32:33], 1, v[0:1]
	v_lshl_add_u64 v[48:49], s[8:9], 0, v[32:33]
	v_mov_b32_e32 v17, v138
	v_or_b32_e32 v0, 32, v0
	v_ashrrev_i32_e32 v1, 31, v0
	v_lshl_add_u64 v[0:1], v[0:1], 1, s[8:9]
	v_mov_b32_e32 v0, v139
	v_add_f32_e32 v1, v18, v117
	v_mul_f32_e32 v1, 0xbfb8aa3b, v1
	v_exp_f32_e32 v1, v1
	v_add_f32_e32 v18, v34, v118
	v_mul_f32_e32 v18, 0xbfb8aa3b, v18
	v_exp_f32_e32 v18, v18
	v_add_f32_e32 v1, 1.0, v1
	v_rcp_f32_e32 v1, v1
	v_add_f32_e32 v18, 1.0, v18
	v_rcp_f32_e32 v18, v18
	v_mul_f32_e32 v1, v1, v120
	v_add_f32_e32 v34, v1, v1
	v_mul_f32_e32 v34, 0x3fb8aa3b, v34
	v_exp_f32_e32 v34, v34
	v_mul_f32_e32 v18, v18, v16
	v_sub_f32_e32 v34, 1.0, v34
	v_max_f32_e32 v34, 0, v34
	v_mul_f32_e32 v48, 0x4f800000, v34
	v_cmp_gt_f32_e32 vcc, s59, v34
	v_lshlrev_b32_e32 v17, 16, v17
	v_cndmask_b32_e32 v34, v34, v48, vcc
	v_sqrt_f32_e32 v48, v34
	v_lshlrev_b32_e32 v0, 16, v0
	v_add_u32_e32 v49, -1, v48
	v_fma_f32 v122, -v49, v48, v34
	v_cmp_ge_f32_e64 s[0:1], 0, v122
	v_add_u32_e32 v122, 1, v48
	s_nop 0
	v_cndmask_b32_e64 v49, v48, v49, s[0:1]
	v_fma_f32 v48, -v122, v48, v34
	v_cmp_lt_f32_e64 s[0:1], 0, v48
	s_nop 1
	v_cndmask_b32_e64 v48, v49, v122, s[0:1]
	v_mul_f32_e32 v49, 0x37800000, v48
	v_cndmask_b32_e32 v48, v48, v49, vcc
	v_add_f32_e32 v49, v50, v119
	v_add_f32_e32 v50, v18, v18
	v_mul_f32_e32 v49, 0xbfb8aa3b, v49
	v_mul_f32_e32 v50, 0x3fb8aa3b, v50
	v_exp_f32_e32 v49, v49
	v_exp_f32_e32 v50, v50
	v_cmp_class_f32_e32 vcc, v34, v113
	s_nop 1
	v_cndmask_b32_e32 v34, v48, v34, vcc
	v_add_f32_e32 v48, 1.0, v49
	v_sub_f32_e32 v49, 1.0, v50
	v_max_f32_e32 v49, 0, v49
	v_mul_f32_e32 v50, 0x4f800000, v49
	v_cmp_gt_f32_e32 vcc, s59, v49
	v_rcp_f32_e32 v48, v48
	s_nop 0
	v_cndmask_b32_e32 v49, v49, v50, vcc
	v_sqrt_f32_e32 v50, v49
	v_mul_f32_e32 v34, v48, v34
	v_mul_f32_e32 v17, v34, v17
	v_add_u32_e32 v34, -1, v50
	v_fma_f32 v48, -v34, v50, v49
	v_cmp_ge_f32_e64 s[0:1], 0, v48
	v_add_u32_e32 v48, 1, v50
	s_nop 0
	v_cndmask_b32_e64 v34, v50, v34, s[0:1]
	v_fma_f32 v50, -v48, v50, v49
	v_cmp_lt_f32_e64 s[0:1], 0, v50
	s_nop 1
	v_cndmask_b32_e64 v34, v34, v48, s[0:1]
	v_mul_f32_e32 v48, 0x37800000, v34
	v_cndmask_b32_e32 v34, v34, v48, vcc
	v_cmp_class_f32_e32 vcc, v49, v113
	v_cvt_pk_bf16_f32 v18, v18, s0
	v_cvt_pk_bf16_f32 v17, v17, s0
	v_cndmask_b32_e32 v34, v34, v49, vcc
	v_mul_f32_e32 v2, v2, v34
	v_mul_f32_e32 v2, v2, v0
	v_cvt_pk_bf16_f32 v34, v1, s0
	v_lshl_add_u64 v[0:1], s[48:49], 0, v[32:33]
	global_store_short v[0:1], v34, off sc1
	global_store_short v[0:1], v18, off offset:64 sc1
	v_lshl_add_u64 v[0:1], s[46:47], 0, v[32:33]
	v_cvt_pk_bf16_f32 v2, v2, s0
	global_store_short v[0:1], v17, off sc1
	global_store_short v[0:1], v2, off offset:64 sc1
	v_add_u32_e32 v0, v121, v74
	v_ashrrev_i32_e32 v1, 31, v0
	v_lshlrev_b64 v[32:33], 1, v[0:1]
	v_lshl_add_u64 v[48:49], s[8:9], 0, v[32:33]
	v_mov_b32_e32 v2, v140
	v_or_b32_e32 v0, 32, v0
	v_ashrrev_i32_e32 v1, 31, v0
	v_lshl_add_u64 v[0:1], v[0:1], 1, s[8:9]
	v_mov_b32_e32 v0, v141
	v_add_f32_e32 v1, v19, v117
	v_mul_f32_e32 v1, 0xbfb8aa3b, v1
	v_exp_f32_e32 v1, v1
	v_add_f32_e32 v17, v35, v118
	v_mul_f32_e32 v17, 0xbfb8aa3b, v17
	v_exp_f32_e32 v17, v17
	v_add_f32_e32 v1, 1.0, v1
	v_rcp_f32_e32 v1, v1
	v_add_f32_e32 v17, 1.0, v17
	v_rcp_f32_e32 v17, v17
	v_mul_f32_e32 v1, v1, v120
	v_add_f32_e32 v18, v1, v1
	v_mul_f32_e32 v18, 0x3fb8aa3b, v18
	v_exp_f32_e32 v18, v18
	v_mul_f32_e32 v17, v17, v16
	v_sub_f32_e32 v18, 1.0, v18
	v_max_f32_e32 v18, 0, v18
	v_mul_f32_e32 v19, 0x4f800000, v18
	v_cmp_gt_f32_e32 vcc, s59, v18
	v_lshlrev_b32_e32 v2, 16, v2
	v_cndmask_b32_e32 v18, v18, v19, vcc
	v_sqrt_f32_e32 v19, v18
	v_lshlrev_b32_e32 v0, 16, v0
	v_add_u32_e32 v34, -1, v19
	v_fma_f32 v35, -v34, v19, v18
	v_cmp_ge_f32_e64 s[0:1], 0, v35
	v_add_u32_e32 v35, 1, v19
	s_nop 0
	v_cndmask_b32_e64 v34, v19, v34, s[0:1]
	v_fma_f32 v19, -v35, v19, v18
	v_cmp_lt_f32_e64 s[0:1], 0, v19
	s_nop 1
	v_cndmask_b32_e64 v19, v34, v35, s[0:1]
	v_mul_f32_e32 v34, 0x37800000, v19
	v_cndmask_b32_e32 v19, v19, v34, vcc
	v_add_f32_e32 v34, v51, v119
	v_add_f32_e32 v35, v17, v17
	v_mul_f32_e32 v34, 0xbfb8aa3b, v34
	v_mul_f32_e32 v35, 0x3fb8aa3b, v35
	v_exp_f32_e32 v34, v34
	v_exp_f32_e32 v35, v35
	v_cmp_class_f32_e32 vcc, v18, v113
	s_nop 1
	v_cndmask_b32_e32 v18, v19, v18, vcc
	v_add_f32_e32 v19, 1.0, v34
	v_sub_f32_e32 v34, 1.0, v35
	v_max_f32_e32 v34, 0, v34
	v_mul_f32_e32 v35, 0x4f800000, v34
	v_cmp_gt_f32_e32 vcc, s59, v34
	v_rcp_f32_e32 v19, v19
	s_nop 0
	v_cndmask_b32_e32 v34, v34, v35, vcc
	v_sqrt_f32_e32 v35, v34
	v_mul_f32_e32 v18, v19, v18
	v_mul_f32_e32 v2, v18, v2
	v_add_u32_e32 v18, -1, v35
	v_fma_f32 v19, -v18, v35, v34
	v_cmp_ge_f32_e64 s[0:1], 0, v19
	v_add_u32_e32 v19, 1, v35
	s_nop 0
	v_cndmask_b32_e64 v18, v35, v18, s[0:1]
	v_fma_f32 v35, -v19, v35, v34
	v_cmp_lt_f32_e64 s[0:1], 0, v35
	s_nop 1
	v_cndmask_b32_e64 v18, v18, v19, s[0:1]
	v_mul_f32_e32 v19, 0x37800000, v18
	v_cndmask_b32_e32 v18, v18, v19, vcc
	v_cmp_class_f32_e32 vcc, v34, v113
	v_cvt_pk_bf16_f32 v17, v17, s0
	v_cvt_pk_bf16_f32 v2, v2, s0
	v_cndmask_b32_e32 v18, v18, v34, vcc
	v_mul_f32_e32 v3, v3, v18
	v_mul_f32_e32 v3, v3, v0
	v_cvt_pk_bf16_f32 v18, v1, s0
	v_lshl_add_u64 v[0:1], s[48:49], 0, v[32:33]
	global_store_short v[0:1], v18, off sc1
	global_store_short v[0:1], v17, off offset:64 sc1
	v_lshl_add_u64 v[0:1], s[46:47], 0, v[32:33]
	global_store_short v[0:1], v2, off sc1
	v_cvt_pk_bf16_f32 v2, v3, s0
	global_store_short v[0:1], v2, off offset:64 sc1
	v_add_u32_e32 v0, v121, v75
	v_ashrrev_i32_e32 v1, 31, v0
	v_lshlrev_b64 v[2:3], 1, v[0:1]
	v_or_b32_e32 v0, 32, v0
	v_lshl_add_u64 v[18:19], s[8:9], 0, v[2:3]
	v_ashrrev_i32_e32 v1, 31, v0
	v_lshl_add_u64 v[0:1], v[0:1], 1, s[8:9]
	v_mov_b32_e32 v17, v142
	s_nop 0
	v_mov_b32_e32 v18, v143
	v_add_f32_e32 v0, v20, v117
	v_add_f32_e32 v1, v36, v118
	v_mul_f32_e32 v0, 0xbfb8aa3b, v0
	v_mul_f32_e32 v1, 0xbfb8aa3b, v1
	v_exp_f32_e32 v20, v0
	v_exp_f32_e32 v32, v1
	v_lshl_add_u64 v[0:1], s[48:49], 0, v[2:3]
	v_add_f32_e32 v19, v52, v119
	v_add_f32_e32 v20, 1.0, v20
	v_add_f32_e32 v32, 1.0, v32
	v_rcp_f32_e32 v20, v20
	v_rcp_f32_e32 v32, v32
	v_add_f32_e32 v4, v4, v68
	v_mul_f32_e32 v19, 0xbfb8aa3b, v19
	v_mul_f32_e32 v20, v20, v120
	v_mul_f32_e32 v32, v32, v16
	v_add_f32_e32 v33, v20, v20
	v_add_f32_e32 v34, v32, v32
	v_mul_f32_e32 v33, 0x3fb8aa3b, v33
	v_mul_f32_e32 v34, 0x3fb8aa3b, v34
	v_exp_f32_e32 v33, v33
	v_exp_f32_e32 v34, v34
	v_cvt_pk_bf16_f32 v20, v20, s0
	global_store_short v[0:1], v20, off sc1
	v_sub_f32_e32 v20, 1.0, v33
	v_sub_f32_e32 v33, 1.0, v34
	v_max_f32_e32 v20, 0, v20
	v_max_f32_e32 v33, 0, v33
	v_mul_f32_e32 v34, 0x4f800000, v20
	v_cmp_gt_f32_e32 vcc, s59, v20
	v_cvt_pk_bf16_f32 v32, v32, s0
	v_mul_f32_e32 v35, 0x4f800000, v33
	v_cndmask_b32_e32 v20, v20, v34, vcc
	v_cmp_gt_f32_e64 s[0:1], s59, v33
	v_sqrt_f32_e32 v34, v20
	v_mul_f32_e32 v4, 0xbfb8aa3b, v4
	v_cndmask_b32_e64 v33, v33, v35, s[0:1]
	v_sqrt_f32_e32 v35, v33
	global_store_short v[0:1], v32, off offset:64 sc1
	v_add_u32_e32 v0, -1, v34
	v_exp_f32_e32 v19, v19
	v_exp_f32_e32 v4, v4
	v_add_u32_e32 v32, -1, v35
	v_fma_f32 v48, -v0, v34, v20
	v_add_u32_e32 v1, 1, v34
	v_fma_f32 v50, -v32, v35, v33
	v_cmp_ge_f32_e64 s[4:5], 0, v48
	v_add_u32_e32 v36, 1, v35
	v_fma_f32 v49, -v1, v34, v20
	v_cndmask_b32_e64 v0, v34, v0, s[4:5]
	v_cmp_ge_f32_e64 s[4:5], 0, v50
	v_fma_f32 v51, -v36, v35, v33
	v_add_f32_e32 v19, 1.0, v19
	v_cndmask_b32_e64 v32, v35, v32, s[4:5]
	v_cmp_lt_f32_e64 s[4:5], 0, v49
	v_add_f32_e32 v4, 1.0, v4
	v_rcp_f32_e32 v19, v19
	v_cndmask_b32_e64 v0, v0, v1, s[4:5]
	v_cmp_lt_f32_e64 s[4:5], 0, v51
	v_rcp_f32_e32 v4, v4
	v_lshl_add_u64 v[2:3], s[46:47], 0, v[2:3]
	v_cndmask_b32_e64 v1, v32, v36, s[4:5]
	v_mul_f32_e32 v32, 0x37800000, v0
	v_mul_f32_e32 v34, 0x37800000, v1
	v_cndmask_b32_e32 v0, v0, v32, vcc
	v_cmp_class_f32_e32 vcc, v20, v113
	v_cndmask_b32_e64 v1, v1, v34, s[0:1]
	v_add_f32_e32 v5, v5, v68
	v_cndmask_b32_e32 v0, v0, v20, vcc
	v_cmp_class_f32_e32 vcc, v33, v113
	v_mul_f32_e32 v0, v19, v0
	v_mul_f32_e32 v5, 0xbfb8aa3b, v5
	v_cndmask_b32_e32 v1, v1, v33, vcc
	v_mul_f32_e32 v1, v4, v1
	v_exp_f32_e32 v5, v5
	v_add_f32_e32 v6, v6, v68
	v_mul_f32_e32 v6, 0xbfb8aa3b, v6
	v_exp_f32_e32 v6, v6
	v_lshlrev_b32_e32 v4, 16, v17
	v_lshlrev_b32_e32 v17, 16, v18
	v_mul_f32_e32 v0, v0, v4
	v_mul_f32_e32 v1, v1, v17
	v_cvt_pk_bf16_f32 v0, v0, s0
	v_cvt_pk_bf16_f32 v1, v1, s0
	global_store_short v[2:3], v0, off sc1
	global_store_short v[2:3], v1, off offset:64 sc1
	v_add_u32_e32 v0, v121, v76
	v_ashrrev_i32_e32 v1, 31, v0
	v_lshlrev_b64 v[2:3], 1, v[0:1]
	v_or_b32_e32 v0, 32, v0
	v_lshl_add_u64 v[18:19], s[8:9], 0, v[2:3]
	v_ashrrev_i32_e32 v1, 31, v0
	v_lshl_add_u64 v[0:1], v[0:1], 1, s[8:9]
	v_mov_b32_e32 v4, v144
	v_mov_b32_e32 v17, v145
	v_add_f32_e32 v0, v21, v117
	v_add_f32_e32 v1, v37, v118
	v_mul_f32_e32 v0, 0xbfb8aa3b, v0
	v_mul_f32_e32 v1, 0xbfb8aa3b, v1
	v_exp_f32_e32 v19, v0
	v_exp_f32_e32 v20, v1
	v_add_f32_e32 v18, v53, v119
	v_mul_f32_e32 v18, 0xbfb8aa3b, v18
	v_add_f32_e32 v19, 1.0, v19
	v_add_f32_e32 v20, 1.0, v20
	v_rcp_f32_e32 v19, v19
	v_rcp_f32_e32 v20, v20
	v_exp_f32_e32 v18, v18
	v_add_f32_e32 v5, 1.0, v5
	v_mul_f32_e32 v19, v19, v120
	v_mul_f32_e32 v20, v20, v16
	v_add_f32_e32 v21, v19, v19
	v_add_f32_e32 v32, v20, v20
	v_mul_f32_e32 v21, 0x3fb8aa3b, v21
	v_mul_f32_e32 v32, 0x3fb8aa3b, v32
	v_exp_f32_e32 v21, v21
	v_exp_f32_e32 v32, v32
	v_add_f32_e32 v18, 1.0, v18
	v_rcp_f32_e32 v18, v18
	v_sub_f32_e32 v21, 1.0, v21
	v_sub_f32_e32 v32, 1.0, v32
	v_max_f32_e32 v21, 0, v21
	v_max_f32_e32 v32, 0, v32
	v_mul_f32_e32 v33, 0x4f800000, v21
	v_cmp_gt_f32_e32 vcc, s59, v21
	v_mul_f32_e32 v34, 0x4f800000, v32
	v_cmp_gt_f32_e64 s[0:1], s59, v32
	v_cndmask_b32_e32 v21, v21, v33, vcc
	v_sqrt_f32_e32 v33, v21
	v_cndmask_b32_e64 v32, v32, v34, s[0:1]
	v_sqrt_f32_e32 v34, v32
	v_rcp_f32_e32 v5, v5
	v_add_u32_e32 v35, -1, v33
	v_fma_f32 v49, -v35, v33, v21
	v_add_u32_e32 v37, -1, v34
	v_add_u32_e32 v36, 1, v33
	v_fma_f32 v51, -v37, v34, v32
	v_cmp_ge_f32_e64 s[4:5], 0, v49
	v_add_u32_e32 v48, 1, v34
	v_fma_f32 v50, -v36, v33, v21
	v_cndmask_b32_e64 v33, v33, v35, s[4:5]
	v_cmp_ge_f32_e64 s[4:5], 0, v51
	v_fma_f32 v52, -v48, v34, v32
	v_lshl_add_u64 v[0:1], s[48:49], 0, v[2:3]
	v_cndmask_b32_e64 v34, v34, v37, s[4:5]
	v_cmp_lt_f32_e64 s[4:5], 0, v50
	v_cvt_pk_bf16_f32 v19, v19, s0
	global_store_short v[0:1], v19, off sc1
	v_cndmask_b32_e64 v33, v33, v36, s[4:5]
	v_cmp_lt_f32_e64 s[4:5], 0, v52
	v_mul_f32_e32 v35, 0x37800000, v33
	v_cndmask_b32_e32 v33, v33, v35, vcc
	v_cndmask_b32_e64 v34, v34, v48, s[4:5]
	v_mul_f32_e32 v36, 0x37800000, v34
	v_cmp_class_f32_e32 vcc, v21, v113
	v_cndmask_b32_e64 v34, v34, v36, s[0:1]
	v_add_f32_e32 v6, 1.0, v6
	v_cndmask_b32_e32 v21, v33, v21, vcc
	v_cmp_class_f32_e32 vcc, v32, v113
	v_mul_f32_e32 v18, v18, v21
	v_rcp_f32_e32 v6, v6
	v_cndmask_b32_e32 v32, v34, v32, vcc
	v_mul_f32_e32 v5, v5, v32
	v_add_f32_e32 v7, v7, v68
	v_mul_f32_e32 v7, 0xbfb8aa3b, v7
	v_exp_f32_e32 v7, v7
	v_lshlrev_b32_e32 v4, 16, v4
	v_lshlrev_b32_e32 v17, 16, v17
	v_mul_f32_e32 v4, v18, v4
	v_mul_f32_e32 v5, v5, v17
	v_cvt_pk_bf16_f32 v17, v20, s0
	global_store_short v[0:1], v17, off offset:64 sc1
	v_cvt_pk_bf16_f32 v4, v4, s0
	v_lshl_add_u64 v[0:1], s[46:47], 0, v[2:3]
	v_cvt_pk_bf16_f32 v2, v5, s0
	global_store_short v[0:1], v4, off sc1
	global_store_short v[0:1], v2, off offset:64 sc1
	v_add_u32_e32 v0, v121, v77
	v_ashrrev_i32_e32 v1, 31, v0
	v_lshlrev_b64 v[2:3], 1, v[0:1]
	v_or_b32_e32 v0, 32, v0
	v_ashrrev_i32_e32 v1, 31, v0
	v_lshl_add_u64 v[4:5], s[8:9], 0, v[2:3]
	v_lshl_add_u64 v[0:1], v[0:1], 1, s[8:9]
	v_mov_b32_e32 v4, v146
	v_add_f32_e32 v17, v54, v119
	v_mov_b32_e32 v0, v147
	v_add_f32_e32 v1, v22, v117
	v_add_f32_e32 v5, v38, v118
	v_mul_f32_e32 v1, 0xbfb8aa3b, v1
	v_mul_f32_e32 v5, 0xbfb8aa3b, v5
	v_exp_f32_e32 v1, v1
	v_exp_f32_e32 v5, v5
	v_mul_f32_e32 v17, 0xbfb8aa3b, v17
	v_exp_f32_e32 v17, v17
	v_add_f32_e32 v1, 1.0, v1
	v_add_f32_e32 v5, 1.0, v5
	v_rcp_f32_e32 v1, v1
	v_rcp_f32_e32 v5, v5
	v_add_f32_e32 v17, 1.0, v17
	v_rcp_f32_e32 v17, v17
	v_mul_f32_e32 v1, v1, v120
	v_mul_f32_e32 v5, v5, v16
	v_add_f32_e32 v18, v1, v1
	v_add_f32_e32 v19, v5, v5
	v_mul_f32_e32 v18, 0x3fb8aa3b, v18
	v_mul_f32_e32 v19, 0x3fb8aa3b, v19
	v_exp_f32_e32 v18, v18
	v_exp_f32_e32 v19, v19
	v_sub_f32_e32 v18, 1.0, v18
	v_sub_f32_e32 v19, 1.0, v19
	v_max_f32_e32 v18, 0, v18
	v_max_f32_e32 v19, 0, v19
	v_mul_f32_e32 v20, 0x4f800000, v18
	v_cmp_gt_f32_e32 vcc, s59, v18
	v_mul_f32_e32 v21, 0x4f800000, v19
	v_cmp_gt_f32_e64 s[0:1], s59, v19
	v_cndmask_b32_e32 v18, v18, v20, vcc
	v_sqrt_f32_e32 v20, v18
	v_cndmask_b32_e64 v19, v19, v21, s[0:1]
	v_sqrt_f32_e32 v21, v19
	v_cvt_pk_bf16_f32 v5, v5, s0
	v_add_u32_e32 v22, -1, v20
	v_fma_f32 v35, -v22, v20, v18
	v_add_u32_e32 v33, -1, v21
	v_add_u32_e32 v32, 1, v20
	v_fma_f32 v37, -v33, v21, v19
	v_cmp_ge_f32_e64 s[4:5], 0, v35
	v_add_u32_e32 v34, 1, v21
	v_fma_f32 v36, -v32, v20, v18
	v_cndmask_b32_e64 v20, v20, v22, s[4:5]
	v_cmp_ge_f32_e64 s[4:5], 0, v37
	v_fma_f32 v38, -v34, v21, v19
	v_lshlrev_b32_e32 v4, 16, v4
	v_cndmask_b32_e64 v21, v21, v33, s[4:5]
	v_cmp_lt_f32_e64 s[4:5], 0, v36
	v_lshlrev_b32_e32 v0, 16, v0
	v_cndmask_b32_e64 v20, v20, v32, s[4:5]
	v_cmp_lt_f32_e64 s[4:5], 0, v38
	v_mul_f32_e32 v22, 0x37800000, v20
	v_cndmask_b32_e32 v20, v20, v22, vcc
	v_cndmask_b32_e64 v21, v21, v34, s[4:5]
	v_mul_f32_e32 v32, 0x37800000, v21
	v_cmp_class_f32_e32 vcc, v18, v113
	v_cndmask_b32_e64 v21, v21, v32, s[0:1]
	s_nop 0
	v_cndmask_b32_e32 v18, v20, v18, vcc
	v_cmp_class_f32_e32 vcc, v19, v113
	v_mul_f32_e32 v17, v17, v18
	v_mul_f32_e32 v4, v17, v4
	v_cndmask_b32_e32 v19, v21, v19, vcc
	v_mul_f32_e32 v6, v6, v19
	v_mul_f32_e32 v6, v6, v0
	v_cvt_pk_bf16_f32 v17, v1, s0
	v_lshl_add_u64 v[0:1], s[48:49], 0, v[2:3]
	global_store_short v[0:1], v17, off sc1
	global_store_short v[0:1], v5, off offset:64 sc1
	v_cvt_pk_bf16_f32 v4, v4, s0
	v_lshl_add_u64 v[0:1], s[46:47], 0, v[2:3]
	v_cvt_pk_bf16_f32 v2, v6, s0
	global_store_short v[0:1], v4, off sc1
	global_store_short v[0:1], v2, off offset:64 sc1
	v_add_u32_e32 v0, v121, v78
	v_ashrrev_i32_e32 v1, 31, v0
	v_lshlrev_b64 v[2:3], 1, v[0:1]
	v_lshl_add_u64 v[4:5], s[8:9], 0, v[2:3]
	v_mov_b32_e32 v4, v148
	v_or_b32_e32 v0, 32, v0
	v_ashrrev_i32_e32 v1, 31, v0
	v_lshl_add_u64 v[0:1], v[0:1], 1, s[8:9]
	v_mov_b32_e32 v0, v149
	v_add_f32_e32 v1, v23, v117
	v_add_f32_e32 v5, v39, v118
	v_mul_f32_e32 v1, 0xbfb8aa3b, v1
	v_mul_f32_e32 v5, 0xbfb8aa3b, v5
	v_exp_f32_e32 v1, v1
	v_exp_f32_e32 v5, v5
	v_add_f32_e32 v6, v55, v119
	v_mul_f32_e32 v6, 0xbfb8aa3b, v6
	v_add_f32_e32 v1, 1.0, v1
	v_add_f32_e32 v5, 1.0, v5
	v_rcp_f32_e32 v1, v1
	v_rcp_f32_e32 v5, v5
	v_exp_f32_e32 v6, v6
	v_mul_f32_e32 v1, v1, v120
	v_mul_f32_e32 v5, v5, v16
	v_add_f32_e32 v17, v1, v1
	v_add_f32_e32 v18, v5, v5
	v_mul_f32_e32 v17, 0x3fb8aa3b, v17
	v_mul_f32_e32 v18, 0x3fb8aa3b, v18
	v_exp_f32_e32 v17, v17
	v_exp_f32_e32 v18, v18
	v_add_f32_e32 v6, 1.0, v6
	v_rcp_f32_e32 v6, v6
	v_sub_f32_e32 v17, 1.0, v17
	v_sub_f32_e32 v18, 1.0, v18
	v_max_f32_e32 v17, 0, v17
	v_max_f32_e32 v18, 0, v18
	v_mul_f32_e32 v19, 0x4f800000, v17
	v_cmp_gt_f32_e32 vcc, s59, v17
	v_mul_f32_e32 v20, 0x4f800000, v18
	v_cmp_gt_f32_e64 s[0:1], s59, v18
	v_cndmask_b32_e32 v17, v17, v19, vcc
	v_sqrt_f32_e32 v19, v17
	v_cndmask_b32_e64 v18, v18, v20, s[0:1]
	v_sqrt_f32_e32 v20, v18
	v_cvt_pk_bf16_f32 v5, v5, s0
	v_add_u32_e32 v21, -1, v19
	v_fma_f32 v33, -v21, v19, v17
	v_add_u32_e32 v23, -1, v20
	v_add_u32_e32 v22, 1, v19
	v_fma_f32 v35, -v23, v20, v18
	v_cmp_ge_f32_e64 s[4:5], 0, v33
	v_add_u32_e32 v32, 1, v20
	v_fma_f32 v34, -v22, v19, v17
	v_cndmask_b32_e64 v19, v19, v21, s[4:5]
	v_cmp_ge_f32_e64 s[4:5], 0, v35
	v_fma_f32 v36, -v32, v20, v18
	v_lshlrev_b32_e32 v4, 16, v4
	v_cndmask_b32_e64 v20, v20, v23, s[4:5]
	v_cmp_lt_f32_e64 s[4:5], 0, v34
	v_lshlrev_b32_e32 v0, 16, v0
	v_cndmask_b32_e64 v19, v19, v22, s[4:5]
	v_mul_f32_e32 v21, 0x37800000, v19
	v_cndmask_b32_e32 v19, v19, v21, vcc
	v_cmp_class_f32_e32 vcc, v17, v113
	v_cmp_lt_f32_e64 s[4:5], 0, v36
	s_nop 0
	v_cndmask_b32_e32 v17, v19, v17, vcc
	v_mul_f32_e32 v6, v6, v17
	v_mul_f32_e32 v4, v6, v4
	v_add_f32_e32 v6, 1.0, v7
	v_cndmask_b32_e64 v20, v20, v32, s[4:5]
	v_rcp_f32_e32 v6, v6
	v_mul_f32_e32 v22, 0x37800000, v20
	v_cndmask_b32_e64 v7, v20, v22, s[0:1]
	v_cmp_class_f32_e32 vcc, v18, v113
	v_cvt_pk_bf16_f32 v4, v4, s0
	s_nop 0
	v_cndmask_b32_e32 v7, v7, v18, vcc
	v_mul_f32_e32 v6, v6, v7
	v_mul_f32_e32 v6, v6, v0
	v_cvt_pk_bf16_f32 v7, v1, s0
	v_lshl_add_u64 v[0:1], s[48:49], 0, v[2:3]
	global_store_short v[0:1], v7, off sc1
	global_store_short v[0:1], v5, off offset:64 sc1
	v_lshl_add_u64 v[0:1], s[46:47], 0, v[2:3]
	v_cvt_pk_bf16_f32 v2, v6, s0
	global_store_short v[0:1], v4, off sc1
	global_store_short v[0:1], v2, off offset:64 sc1
	v_add_u32_e32 v0, v121, v79
	v_ashrrev_i32_e32 v1, 31, v0
	v_lshlrev_b64 v[2:3], 1, v[0:1]
	v_or_b32_e32 v0, 32, v0
	v_lshl_add_u64 v[4:5], s[8:9], 0, v[2:3]
	v_ashrrev_i32_e32 v1, 31, v0
	v_lshl_add_u64 v[0:1], v[0:1], 1, s[8:9]
	v_mov_b32_e32 v4, v150
	s_nop 0
	v_mov_b32_e32 v5, v151
	v_add_f32_e32 v0, v24, v117
	v_add_f32_e32 v1, v40, v118
	v_mul_f32_e32 v0, 0xbfb8aa3b, v0
	v_add_f32_e32 v7, v8, v68
	v_mul_f32_e32 v1, 0xbfb8aa3b, v1
	v_exp_f32_e32 v8, v0
	v_exp_f32_e32 v17, v1
	v_lshl_add_u64 v[0:1], s[48:49], 0, v[2:3]
	v_add_f32_e32 v6, v56, v119
	v_add_f32_e32 v8, 1.0, v8
	v_add_f32_e32 v17, 1.0, v17
	v_rcp_f32_e32 v8, v8
	v_rcp_f32_e32 v17, v17
	v_mul_f32_e32 v6, 0xbfb8aa3b, v6
	v_mul_f32_e32 v7, 0xbfb8aa3b, v7
	v_mul_f32_e32 v8, v8, v120
	v_mul_f32_e32 v17, v17, v16
	v_add_f32_e32 v18, v8, v8
	v_add_f32_e32 v19, v17, v17
	v_mul_f32_e32 v18, 0x3fb8aa3b, v18
	v_mul_f32_e32 v19, 0x3fb8aa3b, v19
	v_exp_f32_e32 v18, v18
	v_exp_f32_e32 v19, v19
	v_cvt_pk_bf16_f32 v8, v8, s0
	global_store_short v[0:1], v8, off sc1
	v_sub_f32_e32 v8, 1.0, v18
	v_sub_f32_e32 v18, 1.0, v19
	v_max_f32_e32 v8, 0, v8
	v_max_f32_e32 v18, 0, v18
	v_mul_f32_e32 v19, 0x4f800000, v8
	v_cmp_gt_f32_e32 vcc, s59, v8
	v_cvt_pk_bf16_f32 v17, v17, s0
	v_mul_f32_e32 v20, 0x4f800000, v18
	v_cndmask_b32_e32 v8, v8, v19, vcc
	v_cmp_gt_f32_e64 s[0:1], s59, v18
	v_sqrt_f32_e32 v19, v8
	v_exp_f32_e32 v6, v6
	v_cndmask_b32_e64 v18, v18, v20, s[0:1]
	v_sqrt_f32_e32 v20, v18
	global_store_short v[0:1], v17, off offset:64 sc1
	v_add_u32_e32 v0, -1, v19
	v_exp_f32_e32 v7, v7
	v_add_u32_e32 v17, -1, v20
	v_fma_f32 v22, -v0, v19, v8
	v_add_u32_e32 v1, 1, v19
	v_fma_f32 v24, -v17, v20, v18
	v_cmp_ge_f32_e64 s[4:5], 0, v22
	v_add_u32_e32 v21, 1, v20
	v_fma_f32 v23, -v1, v19, v8
	v_cndmask_b32_e64 v0, v19, v0, s[4:5]
	v_cmp_ge_f32_e64 s[4:5], 0, v24
	v_add_f32_e32 v6, 1.0, v6
	v_fma_f32 v32, -v21, v20, v18
	v_cndmask_b32_e64 v17, v20, v17, s[4:5]
	v_cmp_lt_f32_e64 s[4:5], 0, v23
	v_add_f32_e32 v7, 1.0, v7
	v_rcp_f32_e32 v6, v6
	v_cndmask_b32_e64 v0, v0, v1, s[4:5]
	v_cmp_lt_f32_e64 s[4:5], 0, v32
	v_rcp_f32_e32 v7, v7
	v_lshl_add_u64 v[2:3], s[46:47], 0, v[2:3]
	v_cndmask_b32_e64 v1, v17, v21, s[4:5]
	v_mul_f32_e32 v17, 0x37800000, v0
	v_mul_f32_e32 v19, 0x37800000, v1
	v_cndmask_b32_e32 v0, v0, v17, vcc
	v_cmp_class_f32_e32 vcc, v8, v113
	v_cndmask_b32_e64 v1, v1, v19, s[0:1]
	v_lshlrev_b32_e32 v4, 16, v4
	v_cndmask_b32_e32 v0, v0, v8, vcc
	v_cmp_class_f32_e32 vcc, v18, v113
	v_mul_f32_e32 v0, v6, v0
	v_lshlrev_b32_e32 v5, 16, v5
	v_cndmask_b32_e32 v1, v1, v18, vcc
	v_mul_f32_e32 v1, v7, v1
	v_mul_f32_e32 v0, v0, v4
	v_mul_f32_e32 v1, v1, v5
	v_cvt_pk_bf16_f32 v0, v0, s0
	v_cvt_pk_bf16_f32 v1, v1, s0
	global_store_short v[2:3], v0, off sc1
	global_store_short v[2:3], v1, off offset:64 sc1
	v_add_u32_e32 v0, v121, v80
	v_ashrrev_i32_e32 v1, 31, v0
	v_lshlrev_b64 v[2:3], 1, v[0:1]
	v_or_b32_e32 v0, 32, v0
	v_lshl_add_u64 v[4:5], s[8:9], 0, v[2:3]
	v_ashrrev_i32_e32 v1, 31, v0
	v_lshl_add_u64 v[0:1], v[0:1], 1, s[8:9]
	v_mov_b32_e32 v4, v152
	s_nop 0
	v_mov_b32_e32 v5, v153
	v_add_f32_e32 v0, v25, v117
	v_add_f32_e32 v1, v41, v118
	v_mul_f32_e32 v0, 0xbfb8aa3b, v0
	v_mul_f32_e32 v1, 0xbfb8aa3b, v1
	v_exp_f32_e32 v8, v0
	v_add_f32_e32 v7, v9, v68
	v_exp_f32_e32 v9, v1
	v_add_f32_e32 v6, v57, v119
	v_add_f32_e32 v8, 1.0, v8
	v_rcp_f32_e32 v8, v8
	v_add_f32_e32 v9, 1.0, v9
	v_rcp_f32_e32 v9, v9
	v_mul_f32_e32 v6, 0xbfb8aa3b, v6
	v_mul_f32_e32 v8, v8, v120
	v_add_f32_e32 v17, v8, v8
	v_mul_f32_e32 v9, v9, v16
	v_add_f32_e32 v18, v9, v9
	v_mul_f32_e32 v17, 0x3fb8aa3b, v17
	v_mul_f32_e32 v18, 0x3fb8aa3b, v18
	v_exp_f32_e32 v17, v17
	v_exp_f32_e32 v18, v18
	v_mul_f32_e32 v7, 0xbfb8aa3b, v7
	v_exp_f32_e32 v6, v6
	v_sub_f32_e32 v17, 1.0, v17
	v_sub_f32_e32 v18, 1.0, v18
	v_max_f32_e32 v17, 0, v17
	v_max_f32_e32 v18, 0, v18
	v_mul_f32_e32 v19, 0x4f800000, v17
	v_cmp_gt_f32_e32 vcc, s59, v17
	v_mul_f32_e32 v20, 0x4f800000, v18
	v_cmp_gt_f32_e64 s[0:1], s59, v18
	v_cndmask_b32_e32 v17, v17, v19, vcc
	v_sqrt_f32_e32 v19, v17
	v_cndmask_b32_e64 v18, v18, v20, s[0:1]
	v_sqrt_f32_e32 v20, v18
	v_exp_f32_e32 v7, v7
	v_add_u32_e32 v21, -1, v19
	v_fma_f32 v25, -v21, v19, v17
	v_add_u32_e32 v23, -1, v20
	v_add_u32_e32 v22, 1, v19
	v_fma_f32 v33, -v23, v20, v18
	v_cmp_ge_f32_e64 s[4:5], 0, v25
	v_add_u32_e32 v24, 1, v20
	v_fma_f32 v32, -v22, v19, v17
	v_cndmask_b32_e64 v19, v19, v21, s[4:5]
	v_cmp_ge_f32_e64 s[4:5], 0, v33
	v_fma_f32 v34, -v24, v20, v18
	v_add_f32_e32 v6, 1.0, v6
	v_cndmask_b32_e64 v20, v20, v23, s[4:5]
	v_cmp_lt_f32_e64 s[4:5], 0, v32
	v_add_f32_e32 v7, 1.0, v7
	v_rcp_f32_e32 v6, v6
	v_cndmask_b32_e64 v19, v19, v22, s[4:5]
	v_cmp_lt_f32_e64 s[4:5], 0, v34
	v_rcp_f32_e32 v7, v7
	v_mul_f32_e32 v21, 0x37800000, v19
	v_cndmask_b32_e64 v20, v20, v24, s[4:5]
	v_mul_f32_e32 v22, 0x37800000, v20
	v_cndmask_b32_e32 v19, v19, v21, vcc
	v_cmp_class_f32_e32 vcc, v17, v113
	v_cndmask_b32_e64 v20, v20, v22, s[0:1]
	v_lshl_add_u64 v[0:1], s[48:49], 0, v[2:3]
	v_cndmask_b32_e32 v17, v19, v17, vcc
	v_cmp_class_f32_e32 vcc, v18, v113
	v_mul_f32_e32 v6, v6, v17
	v_cvt_pk_bf16_f32 v8, v8, s0
	v_cndmask_b32_e32 v18, v20, v18, vcc
	v_mul_f32_e32 v7, v7, v18
	global_store_short v[0:1], v8, off sc1
	v_lshlrev_b32_e32 v4, 16, v4
	v_lshlrev_b32_e32 v5, 16, v5
	v_mul_f32_e32 v4, v6, v4
	v_mul_f32_e32 v5, v7, v5
	v_cvt_pk_bf16_f32 v6, v9, s0
	global_store_short v[0:1], v6, off offset:64 sc1
	v_cvt_pk_bf16_f32 v4, v4, s0
	v_lshl_add_u64 v[0:1], s[46:47], 0, v[2:3]
	v_cvt_pk_bf16_f32 v2, v5, s0
	global_store_short v[0:1], v4, off sc1
	global_store_short v[0:1], v2, off offset:64 sc1
	v_add_u32_e32 v0, v121, v81
	v_ashrrev_i32_e32 v1, 31, v0
	v_lshlrev_b64 v[2:3], 1, v[0:1]
	v_or_b32_e32 v0, 32, v0
	v_lshl_add_u64 v[4:5], s[8:9], 0, v[2:3]
	v_ashrrev_i32_e32 v1, 31, v0
	v_mov_b32_e32 v4, v154
	v_lshl_add_u64 v[0:1], v[0:1], 1, s[8:9]
	v_mov_b32_e32 v0, v156
	v_add_f32_e32 v1, v26, v117
	v_add_f32_e32 v5, v42, v118
	v_mul_f32_e32 v1, 0xbfb8aa3b, v1
	v_mul_f32_e32 v5, 0xbfb8aa3b, v5
	v_exp_f32_e32 v1, v1
	v_exp_f32_e32 v5, v5
	v_add_f32_e32 v7, v10, v68
	v_add_f32_e32 v6, v58, v119
	v_add_f32_e32 v1, 1.0, v1
	v_add_f32_e32 v5, 1.0, v5
	v_rcp_f32_e32 v1, v1
	v_rcp_f32_e32 v5, v5
	v_mul_f32_e32 v6, 0xbfb8aa3b, v6
	v_mul_f32_e32 v7, 0xbfb8aa3b, v7
	v_mul_f32_e32 v1, v1, v120
	v_mul_f32_e32 v5, v5, v16
	v_add_f32_e32 v8, v1, v1
	v_add_f32_e32 v9, v5, v5
	v_mul_f32_e32 v8, 0x3fb8aa3b, v8
	v_mul_f32_e32 v9, 0x3fb8aa3b, v9
	v_exp_f32_e32 v8, v8
	v_exp_f32_e32 v9, v9
	v_exp_f32_e32 v6, v6
	v_exp_f32_e32 v7, v7
	v_sub_f32_e32 v8, 1.0, v8
	v_sub_f32_e32 v9, 1.0, v9
	v_max_f32_e32 v8, 0, v8
	v_max_f32_e32 v9, 0, v9
	v_mul_f32_e32 v10, 0x4f800000, v8
	v_cmp_gt_f32_e32 vcc, s59, v8
	v_mul_f32_e32 v17, 0x4f800000, v9
	v_cmp_gt_f32_e64 s[0:1], s59, v9
	v_cndmask_b32_e32 v8, v8, v10, vcc
	v_sqrt_f32_e32 v10, v8
	v_cndmask_b32_e64 v9, v9, v17, s[0:1]
	v_sqrt_f32_e32 v17, v9
	v_add_f32_e32 v6, 1.0, v6
	v_add_u32_e32 v18, -1, v10
	v_fma_f32 v22, -v18, v10, v8
	v_add_u32_e32 v20, -1, v17
	v_add_u32_e32 v19, 1, v10
	v_fma_f32 v24, -v20, v17, v9
	v_cmp_ge_f32_e64 s[4:5], 0, v22
	v_add_u32_e32 v21, 1, v17
	v_fma_f32 v23, -v19, v10, v8
	v_cndmask_b32_e64 v10, v10, v18, s[4:5]
	v_cmp_ge_f32_e64 s[4:5], 0, v24
	v_fma_f32 v25, -v21, v17, v9
	v_add_f32_e32 v7, 1.0, v7
	v_cndmask_b32_e64 v17, v17, v20, s[4:5]
	v_cmp_lt_f32_e64 s[4:5], 0, v23
	v_rcp_f32_e32 v6, v6
	v_rcp_f32_e32 v7, v7
	v_cndmask_b32_e64 v10, v10, v19, s[4:5]
	v_cmp_lt_f32_e64 s[4:5], 0, v25
	v_mul_f32_e32 v18, 0x37800000, v10
	v_cndmask_b32_e32 v10, v10, v18, vcc
	v_cndmask_b32_e64 v17, v17, v21, s[4:5]
	v_mul_f32_e32 v19, 0x37800000, v17
	v_cmp_class_f32_e32 vcc, v8, v113
	v_cndmask_b32_e64 v17, v17, v19, s[0:1]
	v_cvt_pk_bf16_f32 v5, v5, s0
	v_cndmask_b32_e32 v8, v10, v8, vcc
	v_cmp_class_f32_e32 vcc, v9, v113
	v_mul_f32_e32 v6, v6, v8
	v_lshlrev_b32_e32 v4, 16, v4
	v_cndmask_b32_e32 v9, v17, v9, vcc
	v_mul_f32_e32 v4, v6, v4
	v_mul_f32_e32 v6, v7, v9
	v_lshlrev_b32_e32 v0, 16, v0
	v_mul_f32_e32 v6, v6, v0
	v_cvt_pk_bf16_f32 v7, v1, s0
	v_lshl_add_u64 v[0:1], s[48:49], 0, v[2:3]
	global_store_short v[0:1], v7, off sc1
	global_store_short v[0:1], v5, off offset:64 sc1
	v_cvt_pk_bf16_f32 v4, v4, s0
	v_lshl_add_u64 v[0:1], s[46:47], 0, v[2:3]
	v_cvt_pk_bf16_f32 v2, v6, s0
	global_store_short v[0:1], v4, off sc1
	global_store_short v[0:1], v2, off offset:64 sc1
	v_add_u32_e32 v0, v121, v82
	v_ashrrev_i32_e32 v1, 31, v0
	v_lshlrev_b64 v[2:3], 1, v[0:1]
	v_lshl_add_u64 v[4:5], s[8:9], 0, v[2:3]
	v_mov_b32_e32 v4, v157
	v_or_b32_e32 v0, 32, v0
	v_ashrrev_i32_e32 v1, 31, v0
	v_lshl_add_u64 v[0:1], v[0:1], 1, s[8:9]
	v_mov_b32_e32 v0, v158
	v_add_f32_e32 v1, v27, v117
	v_add_f32_e32 v5, v43, v118
	v_mul_f32_e32 v1, 0xbfb8aa3b, v1
	v_mul_f32_e32 v5, 0xbfb8aa3b, v5
	v_exp_f32_e32 v1, v1
	v_exp_f32_e32 v5, v5
	v_add_f32_e32 v7, v11, v68
	v_add_f32_e32 v6, v59, v119
	v_add_f32_e32 v1, 1.0, v1
	v_add_f32_e32 v5, 1.0, v5
	v_rcp_f32_e32 v1, v1
	v_rcp_f32_e32 v5, v5
	v_mul_f32_e32 v6, 0xbfb8aa3b, v6
	v_exp_f32_e32 v6, v6
	v_mul_f32_e32 v1, v1, v120
	v_mul_f32_e32 v5, v5, v16
	v_add_f32_e32 v8, v1, v1
	v_add_f32_e32 v9, v5, v5
	v_mul_f32_e32 v8, 0x3fb8aa3b, v8
	v_mul_f32_e32 v9, 0x3fb8aa3b, v9
	v_exp_f32_e32 v8, v8
	v_exp_f32_e32 v9, v9
	v_add_f32_e32 v6, 1.0, v6
	v_mul_f32_e32 v7, 0xbfb8aa3b, v7
	v_sub_f32_e32 v8, 1.0, v8
	v_sub_f32_e32 v9, 1.0, v9
	v_max_f32_e32 v8, 0, v8
	v_max_f32_e32 v9, 0, v9
	v_mul_f32_e32 v10, 0x4f800000, v8
	v_cmp_gt_f32_e32 vcc, s59, v8
	v_mul_f32_e32 v11, 0x4f800000, v9
	v_cmp_gt_f32_e64 s[0:1], s59, v9
	v_cndmask_b32_e32 v8, v8, v10, vcc
	v_sqrt_f32_e32 v10, v8
	v_cndmask_b32_e64 v9, v9, v11, s[0:1]
	v_sqrt_f32_e32 v11, v9
	v_rcp_f32_e32 v6, v6
	v_add_u32_e32 v17, -1, v10
	v_fma_f32 v21, -v17, v10, v8
	v_add_u32_e32 v19, -1, v11
	v_add_u32_e32 v18, 1, v10
	v_fma_f32 v23, -v19, v11, v9
	v_cmp_ge_f32_e64 s[4:5], 0, v21
	v_add_u32_e32 v20, 1, v11
	v_fma_f32 v22, -v18, v10, v8
	v_cndmask_b32_e64 v10, v10, v17, s[4:5]
	v_cmp_ge_f32_e64 s[4:5], 0, v23
	v_fma_f32 v24, -v20, v11, v9
	v_exp_f32_e32 v7, v7
	v_cndmask_b32_e64 v11, v11, v19, s[4:5]
	v_cmp_lt_f32_e64 s[4:5], 0, v22
	v_cvt_pk_bf16_f32 v5, v5, s0
	v_lshlrev_b32_e32 v4, 16, v4
	v_cndmask_b32_e64 v10, v10, v18, s[4:5]
	v_mul_f32_e32 v17, 0x37800000, v10
	v_cndmask_b32_e32 v10, v10, v17, vcc
	v_cmp_class_f32_e32 vcc, v8, v113
	v_cmp_lt_f32_e64 s[4:5], 0, v24
	v_lshlrev_b32_e32 v0, 16, v0
	v_cndmask_b32_e32 v8, v10, v8, vcc
	v_mul_f32_e32 v6, v6, v8
	v_mul_f32_e32 v4, v6, v4
	v_add_f32_e32 v6, 1.0, v7
	v_cndmask_b32_e64 v11, v11, v20, s[4:5]
	v_rcp_f32_e32 v6, v6
	v_mul_f32_e32 v18, 0x37800000, v11
	v_cndmask_b32_e64 v7, v11, v18, s[0:1]
	v_cmp_class_f32_e32 vcc, v9, v113
	v_cvt_pk_bf16_f32 v4, v4, s0
	s_nop 0
	v_cndmask_b32_e32 v7, v7, v9, vcc
	v_mul_f32_e32 v6, v6, v7
	v_mul_f32_e32 v6, v6, v0
	v_cvt_pk_bf16_f32 v7, v1, s0
	v_lshl_add_u64 v[0:1], s[48:49], 0, v[2:3]
	global_store_short v[0:1], v7, off sc1
	global_store_short v[0:1], v5, off offset:64 sc1
	v_lshl_add_u64 v[0:1], s[46:47], 0, v[2:3]
	v_cvt_pk_bf16_f32 v2, v6, s0
	global_store_short v[0:1], v4, off sc1
	global_store_short v[0:1], v2, off offset:64 sc1
	v_add_u32_e32 v0, v121, v83
	v_ashrrev_i32_e32 v1, 31, v0
	v_lshlrev_b64 v[2:3], 1, v[0:1]
	v_or_b32_e32 v0, 32, v0
	v_lshl_add_u64 v[4:5], s[8:9], 0, v[2:3]
	v_ashrrev_i32_e32 v1, 31, v0
	v_lshl_add_u64 v[0:1], v[0:1], 1, s[8:9]
	v_mov_b32_e32 v4, v159
	s_nop 0
	v_mov_b32_e32 v5, v160
	v_add_f32_e32 v0, v28, v117
	v_add_f32_e32 v1, v44, v118
	v_mul_f32_e32 v0, 0xbfb8aa3b, v0
	v_mul_f32_e32 v1, 0xbfb8aa3b, v1
	v_exp_f32_e32 v8, v0
	v_exp_f32_e32 v9, v1
	v_lshl_add_u64 v[0:1], s[48:49], 0, v[2:3]
	v_add_f32_e32 v7, v12, v68
	v_add_f32_e32 v8, 1.0, v8
	v_add_f32_e32 v9, 1.0, v9
	v_rcp_f32_e32 v8, v8
	v_rcp_f32_e32 v9, v9
	v_add_f32_e32 v6, v60, v119
	v_mul_f32_e32 v6, 0xbfb8aa3b, v6
	v_mul_f32_e32 v8, v8, v120
	v_mul_f32_e32 v9, v9, v16
	v_add_f32_e32 v10, v8, v8
	v_add_f32_e32 v11, v9, v9
	v_mul_f32_e32 v10, 0x3fb8aa3b, v10
	v_mul_f32_e32 v11, 0x3fb8aa3b, v11
	v_exp_f32_e32 v10, v10
	v_exp_f32_e32 v11, v11
	v_cvt_pk_bf16_f32 v8, v8, s0
	global_store_short v[0:1], v8, off sc1
	v_sub_f32_e32 v8, 1.0, v10
	v_sub_f32_e32 v10, 1.0, v11
	v_max_f32_e32 v8, 0, v8
	v_max_f32_e32 v10, 0, v10
	v_mul_f32_e32 v11, 0x4f800000, v8
	v_cmp_gt_f32_e32 vcc, s59, v8
	v_cvt_pk_bf16_f32 v9, v9, s0
	v_mul_f32_e32 v12, 0x4f800000, v10
	v_cndmask_b32_e32 v8, v8, v11, vcc
	v_cmp_gt_f32_e64 s[0:1], s59, v10
	v_sqrt_f32_e32 v11, v8
	v_mul_f32_e32 v7, 0xbfb8aa3b, v7
	v_cndmask_b32_e64 v10, v10, v12, s[0:1]
	v_sqrt_f32_e32 v12, v10
	v_exp_f32_e32 v6, v6
	global_store_short v[0:1], v9, off offset:64 sc1
	v_add_u32_e32 v0, -1, v11
	v_exp_f32_e32 v7, v7
	v_add_u32_e32 v9, -1, v12
	v_fma_f32 v18, -v0, v11, v8
	v_add_u32_e32 v1, 1, v11
	v_fma_f32 v20, -v9, v12, v10
	v_cmp_ge_f32_e64 s[4:5], 0, v18
	v_add_u32_e32 v17, 1, v12
	v_fma_f32 v19, -v1, v11, v8
	v_cndmask_b32_e64 v0, v11, v0, s[4:5]
	v_cmp_ge_f32_e64 s[4:5], 0, v20
	v_add_f32_e32 v6, 1.0, v6
	v_fma_f32 v21, -v17, v12, v10
	v_cndmask_b32_e64 v9, v12, v9, s[4:5]
	v_cmp_lt_f32_e64 s[4:5], 0, v19
	v_add_f32_e32 v7, 1.0, v7
	v_rcp_f32_e32 v6, v6
	v_cndmask_b32_e64 v0, v0, v1, s[4:5]
	v_cmp_lt_f32_e64 s[4:5], 0, v21
	v_rcp_f32_e32 v7, v7
	v_lshl_add_u64 v[2:3], s[46:47], 0, v[2:3]
	v_cndmask_b32_e64 v1, v9, v17, s[4:5]
	v_mul_f32_e32 v9, 0x37800000, v0
	v_mul_f32_e32 v11, 0x37800000, v1
	v_cndmask_b32_e32 v0, v0, v9, vcc
	v_cmp_class_f32_e32 vcc, v8, v113
	v_cndmask_b32_e64 v1, v1, v11, s[0:1]
	v_lshlrev_b32_e32 v4, 16, v4
	v_cndmask_b32_e32 v0, v0, v8, vcc
	v_cmp_class_f32_e32 vcc, v10, v113
	v_mul_f32_e32 v0, v6, v0
	v_lshlrev_b32_e32 v5, 16, v5
	v_cndmask_b32_e32 v1, v1, v10, vcc
	v_mul_f32_e32 v1, v7, v1
	v_mul_f32_e32 v0, v0, v4
	v_mul_f32_e32 v1, v1, v5
	v_cvt_pk_bf16_f32 v0, v0, s0
	v_cvt_pk_bf16_f32 v1, v1, s0
	global_store_short v[2:3], v0, off sc1
	global_store_short v[2:3], v1, off offset:64 sc1
	v_add_u32_e32 v0, v121, v84
	v_ashrrev_i32_e32 v1, 31, v0
	v_lshlrev_b64 v[2:3], 1, v[0:1]
	v_or_b32_e32 v0, 32, v0
	v_lshl_add_u64 v[4:5], s[8:9], 0, v[2:3]
	v_ashrrev_i32_e32 v1, 31, v0
	v_lshl_add_u64 v[0:1], v[0:1], 1, s[8:9]
	v_mov_b32_e32 v4, v161
	s_nop 0
	v_mov_b32_e32 v5, v162
	v_add_f32_e32 v0, v29, v117
	v_add_f32_e32 v1, v45, v118
	v_mul_f32_e32 v0, 0xbfb8aa3b, v0
	v_mul_f32_e32 v1, 0xbfb8aa3b, v1
	v_exp_f32_e32 v8, v0
	v_exp_f32_e32 v9, v1
	v_add_f32_e32 v7, v13, v68
	v_add_f32_e32 v6, v61, v119
	v_add_f32_e32 v8, 1.0, v8
	v_add_f32_e32 v9, 1.0, v9
	v_rcp_f32_e32 v8, v8
	v_rcp_f32_e32 v9, v9
	v_mul_f32_e32 v6, 0xbfb8aa3b, v6
	v_mul_f32_e32 v7, 0xbfb8aa3b, v7
	v_mul_f32_e32 v8, v8, v120
	v_mul_f32_e32 v9, v9, v16
	v_add_f32_e32 v10, v8, v8
	v_add_f32_e32 v11, v9, v9
	v_mul_f32_e32 v10, 0x3fb8aa3b, v10
	v_mul_f32_e32 v11, 0x3fb8aa3b, v11
	v_exp_f32_e32 v10, v10
	v_exp_f32_e32 v11, v11
	v_exp_f32_e32 v6, v6
	v_exp_f32_e32 v7, v7
	v_sub_f32_e32 v10, 1.0, v10
	v_sub_f32_e32 v11, 1.0, v11
	v_max_f32_e32 v10, 0, v10
	v_max_f32_e32 v11, 0, v11
	v_mul_f32_e32 v12, 0x4f800000, v10
	v_cmp_gt_f32_e32 vcc, s59, v10
	v_mul_f32_e32 v13, 0x4f800000, v11
	v_cmp_gt_f32_e64 s[0:1], s59, v11
	v_cndmask_b32_e32 v10, v10, v12, vcc
	v_sqrt_f32_e32 v12, v10
	v_cndmask_b32_e64 v11, v11, v13, s[0:1]
	v_sqrt_f32_e32 v13, v11
	v_add_f32_e32 v6, 1.0, v6
	v_add_u32_e32 v17, -1, v12
	v_fma_f32 v21, -v17, v12, v10
	v_add_u32_e32 v19, -1, v13
	v_add_u32_e32 v18, 1, v12
	v_fma_f32 v23, -v19, v13, v11
	v_cmp_ge_f32_e64 s[4:5], 0, v21
	v_add_u32_e32 v20, 1, v13
	v_fma_f32 v22, -v18, v12, v10
	v_cndmask_b32_e64 v12, v12, v17, s[4:5]
	v_cmp_ge_f32_e64 s[4:5], 0, v23
	v_fma_f32 v24, -v20, v13, v11
	v_add_f32_e32 v7, 1.0, v7
	v_cndmask_b32_e64 v13, v13, v19, s[4:5]
	v_cmp_lt_f32_e64 s[4:5], 0, v22
	v_rcp_f32_e32 v6, v6
	v_rcp_f32_e32 v7, v7
	v_cndmask_b32_e64 v12, v12, v18, s[4:5]
	v_cmp_lt_f32_e64 s[4:5], 0, v24
	v_mul_f32_e32 v17, 0x37800000, v12
	v_cndmask_b32_e32 v12, v12, v17, vcc
	v_cndmask_b32_e64 v13, v13, v20, s[4:5]
	v_mul_f32_e32 v18, 0x37800000, v13
	v_cmp_class_f32_e32 vcc, v10, v113
	v_cndmask_b32_e64 v13, v13, v18, s[0:1]
	v_lshl_add_u64 v[0:1], s[48:49], 0, v[2:3]
	v_cndmask_b32_e32 v10, v12, v10, vcc
	v_cmp_class_f32_e32 vcc, v11, v113
	v_mul_f32_e32 v6, v6, v10
	v_cvt_pk_bf16_f32 v8, v8, s0
	v_cndmask_b32_e32 v11, v13, v11, vcc
	v_mul_f32_e32 v7, v7, v11
	global_store_short v[0:1], v8, off sc1
	v_lshlrev_b32_e32 v4, 16, v4
	v_lshlrev_b32_e32 v5, 16, v5
	v_mul_f32_e32 v4, v6, v4
	v_mul_f32_e32 v5, v7, v5
	v_cvt_pk_bf16_f32 v6, v9, s0
	global_store_short v[0:1], v6, off offset:64 sc1
	v_cvt_pk_bf16_f32 v4, v4, s0
	v_lshl_add_u64 v[0:1], s[46:47], 0, v[2:3]
	v_cvt_pk_bf16_f32 v2, v5, s0
	global_store_short v[0:1], v4, off sc1
	global_store_short v[0:1], v2, off offset:64 sc1
	v_add_u32_e32 v0, v121, v85
	v_ashrrev_i32_e32 v1, 31, v0
	v_lshlrev_b64 v[2:3], 1, v[0:1]
	v_or_b32_e32 v0, 32, v0
	v_lshl_add_u64 v[4:5], s[8:9], 0, v[2:3]
	v_ashrrev_i32_e32 v1, 31, v0
	v_mov_b32_e32 v4, v163
	v_lshl_add_u64 v[0:1], v[0:1], 1, s[8:9]
	v_mov_b32_e32 v0, v164
	v_add_f32_e32 v1, v30, v117
	v_add_f32_e32 v5, v46, v118
	v_mul_f32_e32 v1, 0xbfb8aa3b, v1
	v_mul_f32_e32 v5, 0xbfb8aa3b, v5
	v_exp_f32_e32 v1, v1
	v_exp_f32_e32 v5, v5
	v_add_f32_e32 v6, v62, v119
	v_add_f32_e32 v7, v14, v68
	v_add_f32_e32 v1, 1.0, v1
	v_add_f32_e32 v5, 1.0, v5
	v_rcp_f32_e32 v1, v1
	v_rcp_f32_e32 v5, v5
	v_mul_f32_e32 v6, 0xbfb8aa3b, v6
	v_mul_f32_e32 v7, 0xbfb8aa3b, v7
	v_mul_f32_e32 v1, v1, v120
	v_mul_f32_e32 v5, v5, v16
	v_add_f32_e32 v8, v1, v1
	v_add_f32_e32 v9, v5, v5
	v_mul_f32_e32 v8, 0x3fb8aa3b, v8
	v_mul_f32_e32 v9, 0x3fb8aa3b, v9
	v_exp_f32_e32 v8, v8
	v_exp_f32_e32 v9, v9
	v_exp_f32_e32 v6, v6
	v_exp_f32_e32 v7, v7
	v_sub_f32_e32 v8, 1.0, v8
	v_sub_f32_e32 v9, 1.0, v9
	v_max_f32_e32 v8, 0, v8
	v_max_f32_e32 v9, 0, v9
	v_mul_f32_e32 v10, 0x4f800000, v8
	v_cmp_gt_f32_e32 vcc, s59, v8
	v_mul_f32_e32 v11, 0x4f800000, v9
	v_cmp_gt_f32_e64 s[0:1], s59, v9
	v_cndmask_b32_e32 v8, v8, v10, vcc
	v_sqrt_f32_e32 v10, v8
	v_cndmask_b32_e64 v9, v9, v11, s[0:1]
	v_sqrt_f32_e32 v11, v9
	v_add_f32_e32 v6, 1.0, v6
	v_add_u32_e32 v12, -1, v10
	v_fma_f32 v18, -v12, v10, v8
	v_add_u32_e32 v14, -1, v11
	v_add_u32_e32 v13, 1, v10
	v_fma_f32 v20, -v14, v11, v9
	v_cmp_ge_f32_e64 s[4:5], 0, v18
	v_add_u32_e32 v17, 1, v11
	v_fma_f32 v19, -v13, v10, v8
	v_cndmask_b32_e64 v10, v10, v12, s[4:5]
	v_cmp_ge_f32_e64 s[4:5], 0, v20
	v_fma_f32 v21, -v17, v11, v9
	v_add_f32_e32 v7, 1.0, v7
	v_cndmask_b32_e64 v11, v11, v14, s[4:5]
	v_cmp_lt_f32_e64 s[4:5], 0, v19
	v_rcp_f32_e32 v6, v6
	v_rcp_f32_e32 v7, v7
	v_cndmask_b32_e64 v10, v10, v13, s[4:5]
	v_cmp_lt_f32_e64 s[4:5], 0, v21
	v_mul_f32_e32 v12, 0x37800000, v10
	v_cndmask_b32_e32 v10, v10, v12, vcc
	v_cndmask_b32_e64 v11, v11, v17, s[4:5]
	v_mul_f32_e32 v13, 0x37800000, v11
	v_cmp_class_f32_e32 vcc, v8, v113
	v_cndmask_b32_e64 v11, v11, v13, s[0:1]
	v_cvt_pk_bf16_f32 v5, v5, s0
	v_cndmask_b32_e32 v8, v10, v8, vcc
	v_cmp_class_f32_e32 vcc, v9, v113
	v_mul_f32_e32 v6, v6, v8
	v_lshlrev_b32_e32 v4, 16, v4
	v_cndmask_b32_e32 v9, v11, v9, vcc
	v_mul_f32_e32 v4, v6, v4
	v_mul_f32_e32 v6, v7, v9
	v_lshlrev_b32_e32 v0, 16, v0
	v_mul_f32_e32 v6, v6, v0
	v_cvt_pk_bf16_f32 v7, v1, s0
	v_lshl_add_u64 v[0:1], s[48:49], 0, v[2:3]
	global_store_short v[0:1], v7, off sc1
	global_store_short v[0:1], v5, off offset:64 sc1
	v_cvt_pk_bf16_f32 v4, v4, s0
	v_lshl_add_u64 v[0:1], s[46:47], 0, v[2:3]
	v_cvt_pk_bf16_f32 v2, v6, s0
	global_store_short v[0:1], v4, off sc1
	global_store_short v[0:1], v2, off offset:64 sc1
	v_add_u32_e32 v0, v121, v86
	v_ashrrev_i32_e32 v1, 31, v0
	v_lshlrev_b64 v[2:3], 1, v[0:1]
	v_lshl_add_u64 v[4:5], s[8:9], 0, v[2:3]
	v_mov_b32_e32 v4, v165
	v_or_b32_e32 v0, 32, v0
	v_ashrrev_i32_e32 v1, 31, v0
	v_lshl_add_u64 v[0:1], v[0:1], 1, s[8:9]
	v_mov_b32_e32 v0, v166
	v_add_f32_e32 v1, v31, v117
	v_add_f32_e32 v5, v47, v118
	v_mul_f32_e32 v1, 0xbfb8aa3b, v1
	v_mul_f32_e32 v5, 0xbfb8aa3b, v5
	v_exp_f32_e32 v1, v1
	v_exp_f32_e32 v5, v5
	v_add_f32_e32 v6, v63, v119
	v_mul_f32_e32 v6, 0xbfb8aa3b, v6
	v_add_f32_e32 v1, 1.0, v1
	v_add_f32_e32 v5, 1.0, v5
	v_rcp_f32_e32 v1, v1
	v_rcp_f32_e32 v5, v5
	v_exp_f32_e32 v6, v6
	v_add_f32_e32 v7, v15, v68
	v_mul_f32_e32 v1, v1, v120
	v_mul_f32_e32 v5, v5, v16
	v_add_f32_e32 v8, v1, v1
	v_add_f32_e32 v9, v5, v5
	v_mul_f32_e32 v8, 0x3fb8aa3b, v8
	v_mul_f32_e32 v9, 0x3fb8aa3b, v9
	v_exp_f32_e32 v8, v8
	v_exp_f32_e32 v9, v9
	v_add_f32_e32 v6, 1.0, v6
	v_mul_f32_e32 v7, 0xbfb8aa3b, v7
	v_sub_f32_e32 v8, 1.0, v8
	v_sub_f32_e32 v9, 1.0, v9
	v_max_f32_e32 v8, 0, v8
	v_max_f32_e32 v9, 0, v9
	v_mul_f32_e32 v10, 0x4f800000, v8
	v_cmp_gt_f32_e32 vcc, s59, v8
	v_mul_f32_e32 v11, 0x4f800000, v9
	v_cmp_gt_f32_e64 s[0:1], s59, v9
	v_cndmask_b32_e32 v8, v8, v10, vcc
	v_sqrt_f32_e32 v10, v8
	v_cndmask_b32_e64 v9, v9, v11, s[0:1]
	v_sqrt_f32_e32 v11, v9
	v_rcp_f32_e32 v6, v6
	v_add_u32_e32 v12, -1, v10
	v_fma_f32 v16, -v12, v10, v8
	v_add_u32_e32 v14, -1, v11
	v_add_u32_e32 v13, 1, v10
	v_fma_f32 v18, -v14, v11, v9
	v_cmp_ge_f32_e64 s[4:5], 0, v16
	v_add_u32_e32 v15, 1, v11
	v_fma_f32 v17, -v13, v10, v8
	v_cndmask_b32_e64 v10, v10, v12, s[4:5]
	v_cmp_ge_f32_e64 s[4:5], 0, v18
	v_fma_f32 v19, -v15, v11, v9
	v_exp_f32_e32 v7, v7
	v_cndmask_b32_e64 v11, v11, v14, s[4:5]
	v_cmp_lt_f32_e64 s[4:5], 0, v17
	v_cvt_pk_bf16_f32 v5, v5, s0
	v_lshlrev_b32_e32 v4, 16, v4
	v_cndmask_b32_e64 v10, v10, v13, s[4:5]
	v_mul_f32_e32 v12, 0x37800000, v10
	v_cndmask_b32_e32 v10, v10, v12, vcc
	v_cmp_class_f32_e32 vcc, v8, v113
	v_cmp_lt_f32_e64 s[4:5], 0, v19
	v_lshlrev_b32_e32 v0, 16, v0
	v_cndmask_b32_e32 v8, v10, v8, vcc
	v_mul_f32_e32 v6, v6, v8
	v_mul_f32_e32 v4, v6, v4
	v_add_f32_e32 v6, 1.0, v7
	v_cndmask_b32_e64 v11, v11, v15, s[4:5]
	v_rcp_f32_e32 v6, v6
	v_mul_f32_e32 v13, 0x37800000, v11
	v_cndmask_b32_e64 v7, v11, v13, s[0:1]
	v_cmp_class_f32_e32 vcc, v9, v113
	v_cvt_pk_bf16_f32 v4, v4, s0
	s_nop 0
	v_cndmask_b32_e32 v7, v7, v9, vcc
	v_mul_f32_e32 v6, v6, v7
	v_mul_f32_e32 v6, v6, v0
	v_cvt_pk_bf16_f32 v7, v1, s0
	v_lshl_add_u64 v[0:1], s[48:49], 0, v[2:3]
	global_store_short v[0:1], v7, off sc1
	global_store_short v[0:1], v5, off offset:64 sc1
	v_lshl_add_u64 v[0:1], s[46:47], 0, v[2:3]
	v_cvt_pk_bf16_f32 v2, v6, s0
	global_store_short v[0:1], v4, off sc1
	global_store_short v[0:1], v2, off offset:64 sc1
	s_add_i32 s3, s3, s33
	s_cmpk_lt_i32 s3, 0x1000
	s_cbranch_scc1 .LBB0_1494

.LBB0_1565_pf_p24:
	s_ashr_i32 s41, s40, 31
	s_lshr_b32 s41, s41, 26
	s_add_i32 s41, s40, s41
	s_ashr_i32 s42, s41, 6
	s_andn2_b32 s41, s41, 63
	s_sub_i32 s41, s40, s41
	s_ashr_i32 s43, s41, 31
	s_lshr_b32 s43, s43, 29
	s_add_i32 s43, s41, s43
	s_ashr_i32 s46, s43, 3
	s_and_b32 s43, s43, -8
	s_lshl_b32 s42, s42, 3
	s_sub_i32 s41, s41, s43
	s_add_i32 s41, s41, s42
	s_lshl_b32 s44, s41, 7
	s_ashr_i32 s45, s44, 31
	s_lshl_b32 s47, s46, 7
	s_lshl_b64 s[42:43], s[44:45], 11
	s_ashr_i32 s48, s47, 31
	s_lshl_b32 s38, s44, 11
	s_add_u32 s18, s14, s38
	s_addc_u32 s19, s15, 0
	s_add_u32 s18, s18, 0xdf9f000
	s_addc_u32 s19, s19, 0
	s_add_u32 s20, s18, 0x10000
	s_addc_u32 s21, s19, 0
	s_add_u32 s22, s20, 0x10000
	s_addc_u32 s23, s21, 0
	s_add_u32 s24, s22, 0x10000
	s_addc_u32 s25, s23, 0
	s_lshl_b32 s38, s47, 11
	s_add_u32 s26, s14, s38
	s_addc_u32 s27, s15, 0
	s_add_u32 s26, s26, 0x17a0000
	s_addc_u32 s27, s27, 0
	s_add_u32 s28, s26, 0x10000
	s_addc_u32 s29, s27, 0
	s_add_u32 s30, s28, 0x10000
	s_addc_u32 s31, s29, 0
	s_add_u32 s34, s30, 0x10000
	s_addc_u32 s35, s31, 0
	v_mov_b32_e32 v254, v64
	s_mov_b32 s39, 1
	s_waitcnt vmcnt(8)
	s_barrier
	ds_read_b128 v[70:73], v156
	ds_read_b128 v[74:77], v157 offset:16384
	ds_read_b128 v[78:81], v157 offset:20480
	ds_read_b128 v[82:85], v157 offset:24576
	ds_read_b128 v[86:89], v157 offset:28672
	ds_read_b128 v[90:93], v158
	ds_read_b128 v[94:97], v159 offset:16384
	ds_read_b128 v[98:101], v159 offset:20480
	ds_read_b128 v[102:105], v159 offset:24576
	ds_read_b128 v[106:109], v159 offset:28672
	ds_read_b128 v[110:113], v160
	ds_read_b128 v[202:205], v161 offset:16384
	ds_read_b128 v[206:209], v161 offset:20480
	ds_read_b128 v[210:213], v161 offset:24576
	ds_read_b128 v[214:217], v161 offset:28672
	ds_read_b128 v[218:221], v162
	ds_read_b128 v[222:225], v163 offset:16384
	ds_read_b128 v[226:229], v163 offset:20480
	ds_read_b128 v[230:233], v163 offset:24576
	ds_read_b128 v[234:237], v163 offset:28672
	s_waitcnt lgkmcnt(0)
	s_barrier
	s_mov_b32 m0, s36
	v_mfma_f32_32x32x16_bf16 v[48:63], v[70:73], v[74:77], v[48:63]
	v_mfma_f32_32x32x16_bf16 v[32:47], v[70:73], v[78:81], v[32:47]
	global_load_lds_dwordx4 v254, s[18:19]
	s_add_u32 m0, m0, 0x1000
	v_mfma_f32_32x32x16_bf16 v[16:31], v[70:73], v[82:85], v[16:31]
	v_mfma_f32_32x32x16_bf16 v[0:15], v[70:73], v[86:89], v[0:15]
	global_load_lds_dwordx4 v254, s[20:21]
	s_add_u32 m0, m0, 0x1000
	v_mfma_f32_32x32x16_bf16 v[48:63], v[90:93], v[94:97], v[48:63]
	v_mfma_f32_32x32x16_bf16 v[32:47], v[90:93], v[98:101], v[32:47]
	global_load_lds_dwordx4 v254, s[22:23]
	s_add_u32 m0, m0, 0x1000
	v_mfma_f32_32x32x16_bf16 v[16:31], v[90:93], v[102:105], v[16:31]
	v_mfma_f32_32x32x16_bf16 v[0:15], v[90:93], v[106:109], v[0:15]
	global_load_lds_dwordx4 v254, s[24:25]
	s_add_u32 m0, m0, 0x1000
	v_mfma_f32_32x32x16_bf16 v[48:63], v[110:113], v[202:205], v[48:63]
	v_mfma_f32_32x32x16_bf16 v[32:47], v[110:113], v[206:209], v[32:47]
	global_load_lds_dwordx4 v254, s[26:27]
	s_add_u32 m0, m0, 0x1000
	v_mfma_f32_32x32x16_bf16 v[16:31], v[110:113], v[210:213], v[16:31]
	v_mfma_f32_32x32x16_bf16 v[0:15], v[110:113], v[214:217], v[0:15]
	global_load_lds_dwordx4 v254, s[28:29]
	s_add_u32 m0, m0, 0x1000
	v_mfma_f32_32x32x16_bf16 v[48:63], v[218:221], v[222:225], v[48:63]
	v_mfma_f32_32x32x16_bf16 v[32:47], v[218:221], v[226:229], v[32:47]
	global_load_lds_dwordx4 v254, s[30:31]
	s_add_u32 m0, m0, 0x1000
	v_mfma_f32_32x32x16_bf16 v[16:31], v[218:221], v[230:233], v[16:31]
	v_mfma_f32_32x32x16_bf16 v[0:15], v[218:221], v[234:237], v[0:15]
	global_load_lds_dwordx4 v254, s[34:35]
	v_add_u32_e32 v254, 0x80, v254
	s_waitcnt vmcnt(8)
	s_barrier
	ds_read_b128 v[70:73], v156 offset:32768
	ds_read_b128 v[74:77], v157 offset:49152
	ds_read_b128 v[78:81], v157 offset:53248
	ds_read_b128 v[82:85], v157 offset:57344
	ds_read_b128 v[86:89], v157 offset:61440
	ds_read_b128 v[90:93], v158 offset:32768
	ds_read_b128 v[94:97], v159 offset:49152
	ds_read_b128 v[98:101], v159 offset:53248
	ds_read_b128 v[102:105], v159 offset:57344
	ds_read_b128 v[106:109], v159 offset:61440
	ds_read_b128 v[110:113], v160 offset:32768
	ds_read_b128 v[202:205], v161 offset:49152
	ds_read_b128 v[206:209], v161 offset:53248
	ds_read_b128 v[210:213], v161 offset:57344
	ds_read_b128 v[214:217], v161 offset:61440
	ds_read_b128 v[218:221], v162 offset:32768
	ds_read_b128 v[222:225], v163 offset:49152
	ds_read_b128 v[226:229], v163 offset:53248
	ds_read_b128 v[230:233], v163 offset:57344
	ds_read_b128 v[234:237], v163 offset:61440
	s_waitcnt lgkmcnt(0)
	s_barrier
	s_add_u32 m0, s36, 0x8000
	v_mfma_f32_32x32x16_bf16 v[48:63], v[70:73], v[74:77], v[48:63]
	v_mfma_f32_32x32x16_bf16 v[32:47], v[70:73], v[78:81], v[32:47]
	global_load_lds_dwordx4 v254, s[18:19]
	s_add_u32 m0, m0, 0x1000
	v_mfma_f32_32x32x16_bf16 v[16:31], v[70:73], v[82:85], v[16:31]
	v_mfma_f32_32x32x16_bf16 v[0:15], v[70:73], v[86:89], v[0:15]
	global_load_lds_dwordx4 v254, s[20:21]
	s_add_u32 m0, m0, 0x1000
	v_mfma_f32_32x32x16_bf16 v[48:63], v[90:93], v[94:97], v[48:63]
	v_mfma_f32_32x32x16_bf16 v[32:47], v[90:93], v[98:101], v[32:47]
	global_load_lds_dwordx4 v254, s[22:23]
	s_add_u32 m0, m0, 0x1000
	v_mfma_f32_32x32x16_bf16 v[16:31], v[90:93], v[102:105], v[16:31]
	v_mfma_f32_32x32x16_bf16 v[0:15], v[90:93], v[106:109], v[0:15]
	global_load_lds_dwordx4 v254, s[24:25]
	s_add_u32 m0, m0, 0x1000
	v_mfma_f32_32x32x16_bf16 v[48:63], v[110:113], v[202:205], v[48:63]
	v_mfma_f32_32x32x16_bf16 v[32:47], v[110:113], v[206:209], v[32:47]
	global_load_lds_dwordx4 v254, s[26:27]
	s_add_u32 m0, m0, 0x1000
	v_mfma_f32_32x32x16_bf16 v[16:31], v[110:113], v[210:213], v[16:31]
	v_mfma_f32_32x32x16_bf16 v[0:15], v[110:113], v[214:217], v[0:15]
	global_load_lds_dwordx4 v254, s[28:29]
	s_add_u32 m0, m0, 0x1000
	v_mfma_f32_32x32x16_bf16 v[48:63], v[218:221], v[222:225], v[48:63]
	v_mfma_f32_32x32x16_bf16 v[32:47], v[218:221], v[226:229], v[32:47]
	global_load_lds_dwordx4 v254, s[30:31]
	s_add_u32 m0, m0, 0x1000
	v_mfma_f32_32x32x16_bf16 v[16:31], v[218:221], v[230:233], v[16:31]
	v_mfma_f32_32x32x16_bf16 v[0:15], v[218:221], v[234:237], v[0:15]
	global_load_lds_dwordx4 v254, s[34:35]
	v_add_u32_e32 v254, 0x80, v254
	s_branch .LBB0_1569

.Lmap_done_3_pf_p25:
	s_lshl_b32 s44, s41, 7
	s_lshl_b32 s42, s50, 7
	s_ashr_i32 s45, s44, 31
	s_ashr_i32 s43, s42, 31
	s_lshl_b64 s[46:47], s[44:45], 11
	s_lshl_b64 s[48:49], s[42:43], 11
	s_lshl_b32 s38, s44, 11
	s_add_u32 s18, s14, s38
	s_addc_u32 s19, s15, 0
	s_add_u32 s18, s18, 0x679f000
	s_addc_u32 s19, s19, 0
	s_add_u32 s20, s18, 0x10000
	s_addc_u32 s21, s19, 0
	s_add_u32 s22, s20, 0x10000
	s_addc_u32 s23, s21, 0
	s_add_u32 s24, s22, 0x10000
	s_addc_u32 s25, s23, 0
	s_lshl_b32 s38, s42, 11
	s_add_u32 s26, s14, s38
	s_addc_u32 s27, s15, 0
	s_add_u32 s26, s26, 0x3aa0000
	s_addc_u32 s27, s27, 0
	s_add_u32 s28, s26, 0x10000
	s_addc_u32 s29, s27, 0
	s_add_u32 s30, s28, 0x10000
	s_addc_u32 s31, s29, 0
	s_add_u32 s34, s30, 0x10000
	s_addc_u32 s35, s31, 0
	v_mov_b32_e32 v254, v76
	s_mov_b32 s39, 1
	s_waitcnt vmcnt(8)
	s_barrier
	ds_read_b128 v[64:67], v110
	ds_read_b128 v[68:71], v111 offset:16384
	ds_read_b128 v[72:75], v111 offset:20480
	ds_read_b128 v[82:85], v111 offset:24576
	ds_read_b128 v[86:89], v111 offset:28672
	ds_read_b128 v[120:123], v112
	ds_read_b128 v[124:127], v113 offset:16384
	ds_read_b128 v[128:131], v113 offset:20480
	ds_read_b128 v[132:135], v113 offset:24576
	ds_read_b128 v[136:139], v113 offset:28672
	ds_read_b128 v[140:143], v114
	ds_read_b128 v[218:221], v115 offset:16384
	ds_read_b128 v[222:225], v115 offset:20480
	ds_read_b128 v[226:229], v115 offset:24576
	ds_read_b128 v[230:233], v115 offset:28672
	ds_read_b128 v[234:237], v116
	ds_read_b128 v[238:241], v117 offset:16384
	ds_read_b128 v[242:245], v117 offset:20480
	ds_read_b128 v[246:249], v117 offset:24576
	ds_read_b128 v[250:253], v117 offset:28672
	s_waitcnt lgkmcnt(0)
	s_barrier
	s_mov_b32 m0, s36
	v_mfma_f32_32x32x16_bf16 v[48:63], v[64:67], v[68:71], v[48:63]
	v_mfma_f32_32x32x16_bf16 v[32:47], v[64:67], v[72:75], v[32:47]
	global_load_lds_dwordx4 v254, s[18:19]
	s_add_u32 m0, m0, 0x1000
	v_mfma_f32_32x32x16_bf16 v[16:31], v[64:67], v[82:85], v[16:31]
	v_mfma_f32_32x32x16_bf16 v[0:15], v[64:67], v[86:89], v[0:15]
	global_load_lds_dwordx4 v254, s[20:21]
	s_add_u32 m0, m0, 0x1000
	v_mfma_f32_32x32x16_bf16 v[48:63], v[120:123], v[124:127], v[48:63]
	v_mfma_f32_32x32x16_bf16 v[32:47], v[120:123], v[128:131], v[32:47]
	global_load_lds_dwordx4 v254, s[22:23]
	s_add_u32 m0, m0, 0x1000
	v_mfma_f32_32x32x16_bf16 v[16:31], v[120:123], v[132:135], v[16:31]
	v_mfma_f32_32x32x16_bf16 v[0:15], v[120:123], v[136:139], v[0:15]
	global_load_lds_dwordx4 v254, s[24:25]
	s_add_u32 m0, m0, 0x1000
	v_mfma_f32_32x32x16_bf16 v[48:63], v[140:143], v[218:221], v[48:63]
	v_mfma_f32_32x32x16_bf16 v[32:47], v[140:143], v[222:225], v[32:47]
	global_load_lds_dwordx4 v254, s[26:27]
	s_add_u32 m0, m0, 0x1000
	v_mfma_f32_32x32x16_bf16 v[16:31], v[140:143], v[226:229], v[16:31]
	v_mfma_f32_32x32x16_bf16 v[0:15], v[140:143], v[230:233], v[0:15]
	global_load_lds_dwordx4 v254, s[28:29]
	s_add_u32 m0, m0, 0x1000
	v_mfma_f32_32x32x16_bf16 v[48:63], v[234:237], v[238:241], v[48:63]
	v_mfma_f32_32x32x16_bf16 v[32:47], v[234:237], v[242:245], v[32:47]
	global_load_lds_dwordx4 v254, s[30:31]
	s_add_u32 m0, m0, 0x1000
	v_mfma_f32_32x32x16_bf16 v[16:31], v[234:237], v[246:249], v[16:31]
	v_mfma_f32_32x32x16_bf16 v[0:15], v[234:237], v[250:253], v[0:15]
	global_load_lds_dwordx4 v254, s[34:35]
	v_add_u32_e32 v254, 0x80, v254
	s_waitcnt vmcnt(8)
	s_barrier
	ds_read_b128 v[64:67], v110 offset:32768
	ds_read_b128 v[68:71], v111 offset:49152
	ds_read_b128 v[72:75], v111 offset:53248
	ds_read_b128 v[82:85], v111 offset:57344
	ds_read_b128 v[86:89], v111 offset:61440
	ds_read_b128 v[120:123], v112 offset:32768
	ds_read_b128 v[124:127], v113 offset:49152
	ds_read_b128 v[128:131], v113 offset:53248
	ds_read_b128 v[132:135], v113 offset:57344
	ds_read_b128 v[136:139], v113 offset:61440
	ds_read_b128 v[140:143], v114 offset:32768
	ds_read_b128 v[218:221], v115 offset:49152
	ds_read_b128 v[222:225], v115 offset:53248
	ds_read_b128 v[226:229], v115 offset:57344
	ds_read_b128 v[230:233], v115 offset:61440
	ds_read_b128 v[234:237], v116 offset:32768
	ds_read_b128 v[238:241], v117 offset:49152
	ds_read_b128 v[242:245], v117 offset:53248
	ds_read_b128 v[246:249], v117 offset:57344
	ds_read_b128 v[250:253], v117 offset:61440
	s_waitcnt lgkmcnt(0)
	s_barrier
	s_add_u32 m0, s36, 0x8000
	v_mfma_f32_32x32x16_bf16 v[48:63], v[64:67], v[68:71], v[48:63]
	v_add_f32_e32 v144, v144, v145
	v_add_f32_e32 v146, v146, v147
	v_mfma_f32_32x32x16_bf16 v[32:47], v[64:67], v[72:75], v[32:47]
	v_add_f32_e32 v148, v148, v149
	v_add_f32_e32 v150, v150, v151
	global_load_lds_dwordx4 v254, s[18:19]
	s_add_u32 m0, m0, 0x1000
	v_mfma_f32_32x32x16_bf16 v[16:31], v[64:67], v[82:85], v[16:31]
	v_add_f32_e32 v144, v144, v146
	v_add_f32_e32 v148, v148, v150
	v_mfma_f32_32x32x16_bf16 v[0:15], v[64:67], v[86:89], v[0:15]
	v_add_f32_e32 v144, v144, v148
	v_fmamk_f32 v144, v144, 0x3a800000, v118
	global_load_lds_dwordx4 v254, s[20:21]
	s_add_u32 m0, m0, 0x1000
	v_mfma_f32_32x32x16_bf16 v[48:63], v[120:123], v[124:127], v[48:63]
	v_rsq_f32_e32 v144, v144
	s_nop 1
	v_mfma_f32_32x32x16_bf16 v[32:47], v[120:123], v[128:131], v[32:47]
	ds_bpermute_b32 v156, v153, v144
	ds_bpermute_b32 v157, v153, v144 offset:4
	global_load_lds_dwordx4 v254, s[22:23]
	s_add_u32 m0, m0, 0x1000
	v_mfma_f32_32x32x16_bf16 v[16:31], v[120:123], v[132:135], v[16:31]
	ds_bpermute_b32 v158, v153, v144 offset:8
	ds_bpermute_b32 v159, v153, v144 offset:12
	v_mfma_f32_32x32x16_bf16 v[0:15], v[120:123], v[136:139], v[0:15]
	ds_bpermute_b32 v160, v153, v144 offset:32
	ds_bpermute_b32 v161, v153, v144 offset:36
	global_load_lds_dwordx4 v254, s[24:25]
	s_add_u32 m0, m0, 0x1000
	v_mfma_f32_32x32x16_bf16 v[48:63], v[140:143], v[218:221], v[48:63]
	ds_bpermute_b32 v162, v153, v144 offset:40
	ds_bpermute_b32 v163, v153, v144 offset:44
	v_mfma_f32_32x32x16_bf16 v[32:47], v[140:143], v[222:225], v[32:47]
	ds_bpermute_b32 v164, v153, v144 offset:64
	ds_bpermute_b32 v165, v153, v144 offset:68
	global_load_lds_dwordx4 v254, s[26:27]
	s_add_u32 m0, m0, 0x1000
	v_mfma_f32_32x32x16_bf16 v[16:31], v[140:143], v[226:229], v[16:31]
	ds_bpermute_b32 v166, v153, v144 offset:72
	ds_bpermute_b32 v167, v153, v144 offset:76
	v_mfma_f32_32x32x16_bf16 v[0:15], v[140:143], v[230:233], v[0:15]
	ds_bpermute_b32 v168, v153, v144 offset:96
	ds_bpermute_b32 v169, v153, v144 offset:100
	global_load_lds_dwordx4 v254, s[28:29]
	s_add_u32 m0, m0, 0x1000
	v_mfma_f32_32x32x16_bf16 v[48:63], v[234:237], v[238:241], v[48:63]
	ds_bpermute_b32 v170, v153, v144 offset:104
	ds_bpermute_b32 v171, v153, v144 offset:108
	v_mfma_f32_32x32x16_bf16 v[32:47], v[234:237], v[242:245], v[32:47]
	global_load_lds_dwordx4 v254, s[30:31]
	s_add_u32 m0, m0, 0x1000
	v_mfma_f32_32x32x16_bf16 v[16:31], v[234:237], v[246:249], v[16:31]
	v_mfma_f32_32x32x16_bf16 v[0:15], v[234:237], v[250:253], v[0:15]
	global_load_lds_dwordx4 v254, s[34:35]
	v_add_u32_e32 v254, 0x80, v254
	s_branch .LBB0_1616

.Lgk_loop_p26:
	s_waitcnt vmcnt(8)
	s_barrier
	ds_read_b128 v[70:73], v93
	ds_read_b128 v[102:105], v94 offset:16384
	ds_read_b128 v[106:109], v94 offset:20480
	ds_read_b128 v[110:113], v94 offset:24576
	ds_read_b128 v[114:117], v94 offset:28672
	ds_read_b128 v[118:121], v95
	ds_read_b128 v[122:125], v96 offset:16384
	ds_read_b128 v[126:129], v96 offset:20480
	ds_read_b128 v[130:133], v96 offset:24576
	ds_read_b128 v[134:137], v96 offset:28672
	ds_read_b128 v[138:141], v97
	ds_read_b128 v[162:165], v98 offset:16384
	ds_read_b128 v[166:169], v98 offset:20480
	ds_read_b128 v[170:173], v98 offset:24576
	ds_read_b128 v[174:177], v98 offset:28672
	ds_read_b128 v[178:181], v99
	ds_read_b128 v[182:185], v100 offset:16384
	ds_read_b128 v[186:189], v100 offset:20480
	ds_read_b128 v[190:193], v100 offset:24576
	ds_read_b128 v[194:197], v100 offset:28672
	s_waitcnt lgkmcnt(0)
	s_barrier
	s_mov_b32 m0, s36
	v_mfma_f32_32x32x16_bf16 v[48:63], v[70:73], v[102:105], v[48:63]
	v_mfma_f32_32x32x16_bf16 v[32:47], v[70:73], v[106:109], v[32:47]
	global_load_lds_dwordx4 v254, s[18:19]
	s_add_u32 m0, m0, 0x1000
	v_mfma_f32_32x32x16_bf16 v[16:31], v[70:73], v[110:113], v[16:31]
	v_mfma_f32_32x32x16_bf16 v[0:15], v[70:73], v[114:117], v[0:15]
	global_load_lds_dwordx4 v254, s[20:21]
	s_add_u32 m0, m0, 0x1000
	v_mfma_f32_32x32x16_bf16 v[48:63], v[118:121], v[122:125], v[48:63]
	v_mfma_f32_32x32x16_bf16 v[32:47], v[118:121], v[126:129], v[32:47]
	global_load_lds_dwordx4 v254, s[22:23]
	s_add_u32 m0, m0, 0x1000
	v_mfma_f32_32x32x16_bf16 v[16:31], v[118:121], v[130:133], v[16:31]
	v_mfma_f32_32x32x16_bf16 v[0:15], v[118:121], v[134:137], v[0:15]
	global_load_lds_dwordx4 v254, s[24:25]
	s_add_u32 m0, m0, 0x1000
	v_mfma_f32_32x32x16_bf16 v[48:63], v[138:141], v[162:165], v[48:63]
	v_mfma_f32_32x32x16_bf16 v[32:47], v[138:141], v[166:169], v[32:47]
	global_load_lds_dwordx4 v254, s[26:27]
	s_add_u32 m0, m0, 0x1000
	v_mfma_f32_32x32x16_bf16 v[16:31], v[138:141], v[170:173], v[16:31]
	v_mfma_f32_32x32x16_bf16 v[0:15], v[138:141], v[174:177], v[0:15]
	global_load_lds_dwordx4 v254, s[28:29]
	s_add_u32 m0, m0, 0x1000
	v_mfma_f32_32x32x16_bf16 v[48:63], v[178:181], v[182:185], v[48:63]
	v_mfma_f32_32x32x16_bf16 v[32:47], v[178:181], v[186:189], v[32:47]
	global_load_lds_dwordx4 v254, s[30:31]
	s_add_u32 m0, m0, 0x1000
	v_mfma_f32_32x32x16_bf16 v[16:31], v[178:181], v[190:193], v[16:31]
	v_mfma_f32_32x32x16_bf16 v[0:15], v[178:181], v[194:197], v[0:15]
	global_load_lds_dwordx4 v254, s[34:35]
	v_add_u32_e32 v254, 0x80, v254
	s_waitcnt vmcnt(8)
	s_barrier
	ds_read_b128 v[70:73], v93 offset:32768
	ds_read_b128 v[102:105], v94 offset:49152
	ds_read_b128 v[106:109], v94 offset:53248
	ds_read_b128 v[110:113], v94 offset:57344
	ds_read_b128 v[114:117], v94 offset:61440
	ds_read_b128 v[118:121], v95 offset:32768
	ds_read_b128 v[122:125], v96 offset:49152
	ds_read_b128 v[126:129], v96 offset:53248
	ds_read_b128 v[130:133], v96 offset:57344
	ds_read_b128 v[134:137], v96 offset:61440
	ds_read_b128 v[138:141], v97 offset:32768
	ds_read_b128 v[162:165], v98 offset:49152
	ds_read_b128 v[166:169], v98 offset:53248
	ds_read_b128 v[170:173], v98 offset:57344
	ds_read_b128 v[174:177], v98 offset:61440
	ds_read_b128 v[178:181], v99 offset:32768
	ds_read_b128 v[182:185], v100 offset:49152
	ds_read_b128 v[186:189], v100 offset:53248
	ds_read_b128 v[190:193], v100 offset:57344
	ds_read_b128 v[194:197], v100 offset:61440
	s_waitcnt lgkmcnt(0)
	s_barrier
	s_add_u32 m0, s36, 0x8000
	v_mfma_f32_32x32x16_bf16 v[48:63], v[70:73], v[102:105], v[48:63]
	v_mfma_f32_32x32x16_bf16 v[32:47], v[70:73], v[106:109], v[32:47]
	global_load_lds_dwordx4 v254, s[18:19]
	s_add_u32 m0, m0, 0x1000
	v_mfma_f32_32x32x16_bf16 v[16:31], v[70:73], v[110:113], v[16:31]
	v_mfma_f32_32x32x16_bf16 v[0:15], v[70:73], v[114:117], v[0:15]
	global_load_lds_dwordx4 v254, s[20:21]
	s_add_u32 m0, m0, 0x1000
	v_mfma_f32_32x32x16_bf16 v[48:63], v[118:121], v[122:125], v[48:63]
	v_mfma_f32_32x32x16_bf16 v[32:47], v[118:121], v[126:129], v[32:47]
	global_load_lds_dwordx4 v254, s[22:23]
	s_add_u32 m0, m0, 0x1000
	v_mfma_f32_32x32x16_bf16 v[16:31], v[118:121], v[130:133], v[16:31]
	v_mfma_f32_32x32x16_bf16 v[0:15], v[118:121], v[134:137], v[0:15]
	global_load_lds_dwordx4 v254, s[24:25]
	s_add_u32 m0, m0, 0x1000
	v_mfma_f32_32x32x16_bf16 v[48:63], v[138:141], v[162:165], v[48:63]
	v_mfma_f32_32x32x16_bf16 v[32:47], v[138:141], v[166:169], v[32:47]
	global_load_lds_dwordx4 v254, s[26:27]
	s_add_u32 m0, m0, 0x1000
	v_mfma_f32_32x32x16_bf16 v[16:31], v[138:141], v[170:173], v[16:31]
	v_mfma_f32_32x32x16_bf16 v[0:15], v[138:141], v[174:177], v[0:15]
	global_load_lds_dwordx4 v254, s[28:29]
	s_add_u32 m0, m0, 0x1000
	v_mfma_f32_32x32x16_bf16 v[48:63], v[178:181], v[182:185], v[48:63]
	v_mfma_f32_32x32x16_bf16 v[32:47], v[178:181], v[186:189], v[32:47]
	global_load_lds_dwordx4 v254, s[30:31]
	s_add_u32 m0, m0, 0x1000
	v_mfma_f32_32x32x16_bf16 v[16:31], v[178:181], v[190:193], v[16:31]
	v_mfma_f32_32x32x16_bf16 v[0:15], v[178:181], v[194:197], v[0:15]
	global_load_lds_dwordx4 v254, s[34:35]
	v_add_u32_e32 v254, 0x80, v254
	s_sub_u32 s37, s37, 1
	s_cmp_lg_u32 s37, 0
	s_cbranch_scc1 .Lgk_loop_p26
	s_add_u32 s40, s10, s33
	s_cmp_gt_u32 s40, 0x3ff
	s_cbranch_scc1 .Lgk_tailplain_p26
.LBB0_1637_pf_p26:
	s_ashr_i32 s41, s40, 31
	s_lshr_b32 s41, s41, 26
	s_add_i32 s41, s40, s41
	s_ashr_i32 s42, s41, 6
	s_andn2_b32 s41, s41, 63
	s_sub_i32 s41, s40, s41
	s_ashr_i32 s43, s41, 31
	s_lshr_b32 s43, s43, 29
	s_add_i32 s43, s41, s43
	s_and_b32 s44, s43, -8
	s_lshl_b32 s42, s42, 3
	s_sub_i32 s41, s41, s44
	s_add_i32 s41, s41, s42
	s_lshl_b32 s43, s43, 4
	s_lshl_b32 s42, s41, 7
	s_and_b32 s43, s43, 0xffffff80
	s_mul_i32 s38, s41, 0xb0000
	s_add_u32 s18, s14, s38
	s_addc_u32 s19, s15, 0
	s_add_u32 s18, s18, 0x879f000
	s_addc_u32 s19, s19, 0
	s_add_u32 s20, s18, 0x2c000
	s_addc_u32 s21, s19, 0
	s_add_u32 s22, s20, 0x2c000
	s_addc_u32 s23, s21, 0
	s_add_u32 s24, s22, 0x2c000
	s_addc_u32 s25, s23, 0
	s_mul_i32 s38, s43, 0x1600
	s_add_u32 s26, s14, s38
	s_addc_u32 s27, s15, 0
	s_add_u32 s26, s26, 0x5620000
	s_addc_u32 s27, s27, 0
	s_add_u32 s28, s26, 0x2c000
	s_addc_u32 s29, s27, 0
	s_add_u32 s30, s28, 0x2c000
	s_addc_u32 s31, s29, 0
	s_add_u32 s34, s30, 0x2c000
	s_addc_u32 s35, s31, 0
	v_mov_b32_e32 v254, v64
	s_mov_b32 s39, 1
	s_waitcnt vmcnt(8)
	s_barrier
	ds_read_b128 v[70:73], v93
	ds_read_b128 v[102:105], v94 offset:16384
	ds_read_b128 v[106:109], v94 offset:20480
	ds_read_b128 v[110:113], v94 offset:24576
	ds_read_b128 v[114:117], v94 offset:28672
	ds_read_b128 v[118:121], v95
	ds_read_b128 v[122:125], v96 offset:16384
	ds_read_b128 v[126:129], v96 offset:20480
	ds_read_b128 v[130:133], v96 offset:24576
	ds_read_b128 v[134:137], v96 offset:28672
	ds_read_b128 v[138:141], v97
	ds_read_b128 v[162:165], v98 offset:16384
	ds_read_b128 v[166:169], v98 offset:20480
	ds_read_b128 v[170:173], v98 offset:24576
	ds_read_b128 v[174:177], v98 offset:28672
	ds_read_b128 v[178:181], v99
	ds_read_b128 v[182:185], v100 offset:16384
	ds_read_b128 v[186:189], v100 offset:20480
	ds_read_b128 v[190:193], v100 offset:24576
	ds_read_b128 v[194:197], v100 offset:28672
	s_waitcnt lgkmcnt(0)
	s_barrier
	s_mov_b32 m0, s36
	v_mfma_f32_32x32x16_bf16 v[48:63], v[70:73], v[102:105], v[48:63]
	v_mfma_f32_32x32x16_bf16 v[32:47], v[70:73], v[106:109], v[32:47]
	global_load_lds_dwordx4 v254, s[18:19]
	s_add_u32 m0, m0, 0x1000
	v_mfma_f32_32x32x16_bf16 v[16:31], v[70:73], v[110:113], v[16:31]
	v_mfma_f32_32x32x16_bf16 v[0:15], v[70:73], v[114:117], v[0:15]
	global_load_lds_dwordx4 v254, s[20:21]
	s_add_u32 m0, m0, 0x1000
	v_mfma_f32_32x32x16_bf16 v[48:63], v[118:121], v[122:125], v[48:63]
	v_mfma_f32_32x32x16_bf16 v[32:47], v[118:121], v[126:129], v[32:47]
	global_load_lds_dwordx4 v254, s[22:23]
	s_add_u32 m0, m0, 0x1000
	v_mfma_f32_32x32x16_bf16 v[16:31], v[118:121], v[130:133], v[16:31]
	v_mfma_f32_32x32x16_bf16 v[0:15], v[118:121], v[134:137], v[0:15]
	global_load_lds_dwordx4 v254, s[24:25]
	s_add_u32 m0, m0, 0x1000
	v_mfma_f32_32x32x16_bf16 v[48:63], v[138:141], v[162:165], v[48:63]
	v_mfma_f32_32x32x16_bf16 v[32:47], v[138:141], v[166:169], v[32:47]
	global_load_lds_dwordx4 v254, s[26:27]
	s_add_u32 m0, m0, 0x1000
	v_mfma_f32_32x32x16_bf16 v[16:31], v[138:141], v[170:173], v[16:31]
	v_mfma_f32_32x32x16_bf16 v[0:15], v[138:141], v[174:177], v[0:15]
	global_load_lds_dwordx4 v254, s[28:29]
	s_add_u32 m0, m0, 0x1000
	v_mfma_f32_32x32x16_bf16 v[48:63], v[178:181], v[182:185], v[48:63]
	v_mfma_f32_32x32x16_bf16 v[32:47], v[178:181], v[186:189], v[32:47]
	global_load_lds_dwordx4 v254, s[30:31]
	s_add_u32 m0, m0, 0x1000
	v_mfma_f32_32x32x16_bf16 v[16:31], v[178:181], v[190:193], v[16:31]
	v_mfma_f32_32x32x16_bf16 v[0:15], v[178:181], v[194:197], v[0:15]
	global_load_lds_dwordx4 v254, s[34:35]
	v_add_u32_e32 v254, 0x80, v254
	s_waitcnt vmcnt(8)
	s_barrier
	ds_read_b128 v[70:73], v93 offset:32768
	ds_read_b128 v[102:105], v94 offset:49152
	ds_read_b128 v[106:109], v94 offset:53248
	ds_read_b128 v[110:113], v94 offset:57344
	ds_read_b128 v[114:117], v94 offset:61440
	ds_read_b128 v[118:121], v95 offset:32768
	ds_read_b128 v[122:125], v96 offset:49152
	ds_read_b128 v[126:129], v96 offset:53248
	ds_read_b128 v[130:133], v96 offset:57344
	ds_read_b128 v[134:137], v96 offset:61440
	ds_read_b128 v[138:141], v97 offset:32768
	ds_read_b128 v[162:165], v98 offset:49152
	ds_read_b128 v[166:169], v98 offset:53248
	ds_read_b128 v[170:173], v98 offset:57344
	ds_read_b128 v[174:177], v98 offset:61440
	ds_read_b128 v[178:181], v99 offset:32768
	ds_read_b128 v[182:185], v100 offset:49152
	ds_read_b128 v[186:189], v100 offset:53248
	ds_read_b128 v[190:193], v100 offset:57344
	ds_read_b128 v[194:197], v100 offset:61440
	s_waitcnt lgkmcnt(0)
	s_barrier
	s_add_u32 m0, s36, 0x8000
	v_mfma_f32_32x32x16_bf16 v[48:63], v[70:73], v[102:105], v[48:63]
	v_mfma_f32_32x32x16_bf16 v[32:47], v[70:73], v[106:109], v[32:47]
	global_load_lds_dwordx4 v254, s[18:19]
	s_add_u32 m0, m0, 0x1000
	v_mfma_f32_32x32x16_bf16 v[16:31], v[70:73], v[110:113], v[16:31]
	v_mfma_f32_32x32x16_bf16 v[0:15], v[70:73], v[114:117], v[0:15]
	global_load_lds_dwordx4 v254, s[20:21]
	s_add_u32 m0, m0, 0x1000
	v_mfma_f32_32x32x16_bf16 v[48:63], v[118:121], v[122:125], v[48:63]
	v_mfma_f32_32x32x16_bf16 v[32:47], v[118:121], v[126:129], v[32:47]
	global_load_lds_dwordx4 v254, s[22:23]
	s_add_u32 m0, m0, 0x1000
	v_mfma_f32_32x32x16_bf16 v[16:31], v[118:121], v[130:133], v[16:31]
	v_mfma_f32_32x32x16_bf16 v[0:15], v[118:121], v[134:137], v[0:15]
	global_load_lds_dwordx4 v254, s[24:25]
	s_add_u32 m0, m0, 0x1000
	v_mfma_f32_32x32x16_bf16 v[48:63], v[138:141], v[162:165], v[48:63]
	v_mfma_f32_32x32x16_bf16 v[32:47], v[138:141], v[166:169], v[32:47]
	global_load_lds_dwordx4 v254, s[26:27]
	s_add_u32 m0, m0, 0x1000
	v_mfma_f32_32x32x16_bf16 v[16:31], v[138:141], v[170:173], v[16:31]
	v_mfma_f32_32x32x16_bf16 v[0:15], v[138:141], v[174:177], v[0:15]
	global_load_lds_dwordx4 v254, s[28:29]
	s_add_u32 m0, m0, 0x1000
	v_mfma_f32_32x32x16_bf16 v[48:63], v[178:181], v[182:185], v[48:63]
	v_mfma_f32_32x32x16_bf16 v[32:47], v[178:181], v[186:189], v[32:47]
	global_load_lds_dwordx4 v254, s[30:31]
	s_add_u32 m0, m0, 0x1000
	v_mfma_f32_32x32x16_bf16 v[16:31], v[178:181], v[190:193], v[16:31]
	v_mfma_f32_32x32x16_bf16 v[0:15], v[178:181], v[194:197], v[0:15]
	global_load_lds_dwordx4 v254, s[34:35]
	v_add_u32_e32 v254, 0x80, v254
	s_branch .LBB0_1636
.Lgk_tailplain_p26:
	s_mov_b32 s39, 0
	s_waitcnt vmcnt(8)
	s_barrier
	ds_read_b128 v[70:73], v93
	ds_read_b128 v[102:105], v94 offset:16384
	ds_read_b128 v[106:109], v94 offset:20480
	ds_read_b128 v[110:113], v94 offset:24576
	ds_read_b128 v[114:117], v94 offset:28672
	ds_read_b128 v[118:121], v95
	ds_read_b128 v[122:125], v96 offset:16384
	ds_read_b128 v[126:129], v96 offset:20480
	ds_read_b128 v[130:133], v96 offset:24576
	ds_read_b128 v[134:137], v96 offset:28672
	ds_read_b128 v[138:141], v97
	ds_read_b128 v[162:165], v98 offset:16384
	ds_read_b128 v[166:169], v98 offset:20480
	ds_read_b128 v[170:173], v98 offset:24576
	ds_read_b128 v[174:177], v98 offset:28672
	ds_read_b128 v[178:181], v99
	ds_read_b128 v[182:185], v100 offset:16384
	ds_read_b128 v[186:189], v100 offset:20480
	ds_read_b128 v[190:193], v100 offset:24576
	ds_read_b128 v[194:197], v100 offset:28672
	s_waitcnt lgkmcnt(0)
	s_barrier
	v_mfma_f32_32x32x16_bf16 v[48:63], v[70:73], v[102:105], v[48:63]
	v_mfma_f32_32x32x16_bf16 v[32:47], v[70:73], v[106:109], v[32:47]
	v_mfma_f32_32x32x16_bf16 v[16:31], v[70:73], v[110:113], v[16:31]
	v_mfma_f32_32x32x16_bf16 v[0:15], v[70:73], v[114:117], v[0:15]
	v_mfma_f32_32x32x16_bf16 v[48:63], v[118:121], v[122:125], v[48:63]
	v_mfma_f32_32x32x16_bf16 v[32:47], v[118:121], v[126:129], v[32:47]
	v_mfma_f32_32x32x16_bf16 v[16:31], v[118:121], v[130:133], v[16:31]
	v_mfma_f32_32x32x16_bf16 v[0:15], v[118:121], v[134:137], v[0:15]
	v_mfma_f32_32x32x16_bf16 v[48:63], v[138:141], v[162:165], v[48:63]
	v_mfma_f32_32x32x16_bf16 v[32:47], v[138:141], v[166:169], v[32:47]
	v_mfma_f32_32x32x16_bf16 v[16:31], v[138:141], v[170:173], v[16:31]
	v_mfma_f32_32x32x16_bf16 v[0:15], v[138:141], v[174:177], v[0:15]
	v_mfma_f32_32x32x16_bf16 v[48:63], v[178:181], v[182:185], v[48:63]
	v_mfma_f32_32x32x16_bf16 v[32:47], v[178:181], v[186:189], v[32:47]
	v_mfma_f32_32x32x16_bf16 v[16:31], v[178:181], v[190:193], v[16:31]
	v_mfma_f32_32x32x16_bf16 v[0:15], v[178:181], v[194:197], v[0:15]
	s_waitcnt vmcnt(0)
	s_barrier
	ds_read_b128 v[70:73], v93 offset:32768
	ds_read_b128 v[102:105], v94 offset:49152
	ds_read_b128 v[106:109], v94 offset:53248
	ds_read_b128 v[110:113], v94 offset:57344
	ds_read_b128 v[114:117], v94 offset:61440
	ds_read_b128 v[118:121], v95 offset:32768
	ds_read_b128 v[122:125], v96 offset:49152
	ds_read_b128 v[126:129], v96 offset:53248
	ds_read_b128 v[130:133], v96 offset:57344
	ds_read_b128 v[134:137], v96 offset:61440
	ds_read_b128 v[138:141], v97 offset:32768
	ds_read_b128 v[162:165], v98 offset:49152
	ds_read_b128 v[166:169], v98 offset:53248
	ds_read_b128 v[170:173], v98 offset:57344
	ds_read_b128 v[174:177], v98 offset:61440
	ds_read_b128 v[178:181], v99 offset:32768
	ds_read_b128 v[182:185], v100 offset:49152
	ds_read_b128 v[186:189], v100 offset:53248
	ds_read_b128 v[190:193], v100 offset:57344
	ds_read_b128 v[194:197], v100 offset:61440
	s_waitcnt lgkmcnt(0)
	s_barrier
	v_mfma_f32_32x32x16_bf16 v[48:63], v[70:73], v[102:105], v[48:63]
	v_mfma_f32_32x32x16_bf16 v[32:47], v[70:73], v[106:109], v[32:47]
	v_mfma_f32_32x32x16_bf16 v[16:31], v[70:73], v[110:113], v[16:31]
	v_mfma_f32_32x32x16_bf16 v[0:15], v[70:73], v[114:117], v[0:15]
	v_mfma_f32_32x32x16_bf16 v[48:63], v[118:121], v[122:125], v[48:63]
	v_mfma_f32_32x32x16_bf16 v[32:47], v[118:121], v[126:129], v[32:47]
	v_mfma_f32_32x32x16_bf16 v[16:31], v[118:121], v[130:133], v[16:31]
	v_mfma_f32_32x32x16_bf16 v[0:15], v[118:121], v[134:137], v[0:15]
	v_mfma_f32_32x32x16_bf16 v[48:63], v[138:141], v[162:165], v[48:63]
	v_mfma_f32_32x32x16_bf16 v[32:47], v[138:141], v[166:169], v[32:47]
	v_mfma_f32_32x32x16_bf16 v[16:31], v[138:141], v[170:173], v[16:31]
	v_mfma_f32_32x32x16_bf16 v[0:15], v[138:141], v[174:177], v[0:15]
	v_mfma_f32_32x32x16_bf16 v[48:63], v[178:181], v[182:185], v[48:63]
	v_mfma_f32_32x32x16_bf16 v[32:47], v[178:181], v[186:189], v[32:47]
	v_mfma_f32_32x32x16_bf16 v[16:31], v[178:181], v[190:193], v[16:31]
	v_mfma_f32_32x32x16_bf16 v[0:15], v[178:181], v[194:197], v[0:15]
	s_branch .LBB0_1636
